# speedup vs baseline: 1.0081x; 1.0005x over previous
;     DI size_t aoff(const Unit& u, size_t tstep) const { return (size_t)u.pm * tstep; }
;     DI size_t boff(const Unit& u, size_t tstep) const { return (size_t)u.pn * tstep; }
;     DI bool next(int i, Unit& u) const { const long L = (long)i * G + c; if (L >= np) return false; u.pm = pmv; u.pn = (int)(L % nN); u.ks = (int)(L / nN); return true; }
;     DI size_t aoff(const Unit& u, size_t) const { return (size_t)u.ks * kbytes; }
;     DI size_t boff(const Unit& u, size_t tstep) const { return (size_t)u.pn * tstep + (size_t)u.ks * kbytes; }
;     DI bool next(int i, Unit& u) const { Unit t; if (!S.next(i / 3, t)) return false; u.pm = t.pm; u.pn = t.pn; u.ks = i % 3; return true; }
;     DI size_t aoff(const Unit& u, size_t tstep) const { return (u.ks < 2 ? offU : offOA) + (size_t)u.pm * tstep; }
; #define PG8_LDA(dst, b, h) do { _Pragma("unroll") for (int m = 0; m < 4; ++m) _Pragma("unroll") for (int k = 0; k < 2; ++k) dst[m][k] = *(const LAS bf16x8*)(lds + PG8_SA(b, h) + aoff + m * 2048 + k * 1024); } while (0)
; template <class Epi, class Sched>
; DI void gemm_phase(LAS unsigned char* lds, const Gemm g, const Sched& S, const Epi& E) {
;     ...
;         const bool has_next = S.next(ui + 1, nxt);
;         const char* nA = has_next ? (const char*)g.A + S.aoff(nxt, tstep) : cA; const char* nB = has_next ? (const char*)g.Bt + S.boff(nxt, tstep) : cB;
;         for (int t = 0; t < nt; t += 2) {
;             if constexpr (Epi::HAS_MID) { if (t == E.mid_t(nt)) { int fr3 = fr, fq3 = fq; asm volatile("" : "+v"(fr3), "+v"(fq3)); E.mid(acc, cur, wr, wc, fr3, fq3); } }
;             const bool last = (t == nt - 2);
;             const char* a1 = cA + (size_t)(t + 1) * kstep;
;             const char* a2 = last ? nA : cA + (size_t)(t + 2) * kstep; const char* b2 = last ? nB : cB + (size_t)(t + 2) * kstep;
;             const char* a3 = a2 + kstep; const char* b3 = b2 + kstep;
;             PG8_LDB(B0, 0, 0); PG8_SCHED; PG8_LDA(At, 0, 0); PG8_STAGE(PG8_SA(1, 1), a1 + hstep, voffA);
;             PG8_WAIT_L(8); PG8_BAR; PG8_WAIT_L(0); PG8_MMA(0, 0, At, B0); PG8_BAR; PG8_SCHED;
;             PG8_LDB(B1, 0, 1); PG8_STAGE(PG8_SB(0, 0), b2, voffB);
;             PG8_BAR; PG8_WAIT_L(0); PG8_MMA(0, 1, At, B1); PG8_BAR;
;             PG8_LDA(At, 0, 1); PG8_STAGE(PG8_SA(0, 0), a2, voffA);
;             PG8_BAR; PG8_WAIT_L(0); PG8_MMA(1, 0, At, B0); PG8_BAR; PG8_SCHED;
.LBB0_218:
	s_ashr_i32 s17, s16, 31
	s_lshl_b64 s[0:1], s[16:17], 20
	v_cmp_lt_i64_e32 vcc, s[18:19], v[140:141]
	s_add_u32 s18, s47, s0
	s_addc_u32 s19, s48, s1
	s_and_b64 s[0:1], vcc, exec
	s_cselect_b32 s17, s19, s41
	s_cselect_b32 s65, s18, s40
	s_ashr_i32 s15, s14, 31
	s_lshl_b64 s[0:1], s[14:15], 20
	s_add_u32 s36, s49, s0
	s_addc_u32 s37, s50, s1
	s_and_b64 s[0:1], vcc, exec
	s_cselect_b32 s15, s37, s43
	s_cselect_b32 s66, s36, s42
	s_add_u32 s40, s40, 0x80080
	s_addc_u32 s41, s41, 0
	s_add_u32 s67, s42, 0x100
	v_mov_b32_e32 v0, 0
	s_addc_u32 s68, s43, 0
	s_mov_b32 s69, -2
	ds_read_b128 v[150:153], v147
	ds_read_b128 v[154:157], v147 offset:1024
	ds_read_b128 v[162:165], v147 offset:2048
	ds_read_b128 v[166:169], v147 offset:3072
	s_add_i32 m0, s39, 0xc000
	ds_read_b128 v[170:173], v148
	ds_read_b128 v[174:177], v148 offset:1024
	ds_read_b128 v[178:181], v148 offset:2048
	ds_read_b128 v[188:191], v148 offset:3072
	ds_read_b128 v[194:197], v148 offset:4096
	ds_read_b128 v[198:201], v148 offset:5120
	ds_read_b128 v[202:205], v148 offset:6144
	global_load_lds_dwordx4 v136, s[40:41]
	s_add_i32 m0, s39, 0xe000
	ds_read_b128 v[206:209], v148 offset:7168
	global_load_lds_dwordx4 v138, s[40:41]
	s_add_u32 s0, s40, 0xfff80080
	s_addc_u32 s1, s41, -1
	s_cmp_eq_u32 s69, 28
	s_cselect_b32 s45, s17, s1
	s_cselect_b32 s44, s65, s0
	s_cselect_b32 s43, s15, s68
	s_cselect_b32 s42, s66, s67
	s_waitcnt lgkmcnt(8)
	s_barrier
	s_waitcnt lgkmcnt(0)
	s_setprio 1
	v_mfma_f32_16x16x32_bf16 v[124:127], v[150:153], v[170:173], 0
	v_mfma_f32_16x16x32_bf16 v[120:123], v[162:165], v[170:173], 0
	v_mfma_f32_16x16x32_bf16 v[108:111], v[150:153], v[178:181], 0
	v_mfma_f32_16x16x32_bf16 v[104:107], v[162:165], v[178:181], 0
	v_mfma_f32_16x16x32_bf16 v[92:95], v[150:153], v[194:197], 0
	v_mfma_f32_16x16x32_bf16 v[88:91], v[162:165], v[194:197], 0
	v_mfma_f32_16x16x32_bf16 v[76:79], v[150:153], v[202:205], 0
	v_mfma_f32_16x16x32_bf16 v[72:75], v[162:165], v[202:205], 0
	v_mfma_f32_16x16x32_bf16 v[124:127], v[154:157], v[174:177], v[124:127]
	v_mfma_f32_16x16x32_bf16 v[120:123], v[166:169], v[174:177], v[120:123]
	v_mfma_f32_16x16x32_bf16 v[108:111], v[154:157], v[188:191], v[108:111]
	v_mfma_f32_16x16x32_bf16 v[104:107], v[166:169], v[188:191], v[104:107]
	v_mfma_f32_16x16x32_bf16 v[92:95], v[154:157], v[198:201], v[92:95]
	v_mfma_f32_16x16x32_bf16 v[88:91], v[166:169], v[198:201], v[88:91]
	v_mfma_f32_16x16x32_bf16 v[76:79], v[154:157], v[206:209], v[76:79]
	v_mfma_f32_16x16x32_bf16 v[72:75], v[166:169], v[206:209], v[72:75]
	s_setprio 0
	s_barrier
	s_add_i32 s0, s34, s52
	s_mov_b32 m0, s0
	ds_read_b128 v[210:213], v149
	ds_read_b128 v[214:217], v149 offset:1024
	ds_read_b128 v[218:221], v149 offset:2048
	global_load_lds_dwordx4 v130, s[42:43]
	s_add_i32 m0, s0, 0x2000
	ds_read_b128 v[222:225], v149 offset:3072
	global_load_lds_dwordx4 v134, s[42:43]
	s_barrier
	s_waitcnt lgkmcnt(0)
	s_setprio 1
	v_mfma_f32_16x16x32_bf16 v[116:119], v[210:213], v[170:173], 0
	v_mfma_f32_16x16x32_bf16 v[112:115], v[218:221], v[170:173], 0
	v_mfma_f32_16x16x32_bf16 v[100:103], v[210:213], v[178:181], 0
	v_mfma_f32_16x16x32_bf16 v[96:99], v[218:221], v[178:181], 0
	v_mfma_f32_16x16x32_bf16 v[84:87], v[210:213], v[194:197], 0
	v_mfma_f32_16x16x32_bf16 v[80:83], v[218:221], v[194:197], 0
	v_mfma_f32_16x16x32_bf16 v[68:71], v[210:213], v[202:205], 0
	v_mfma_f32_16x16x32_bf16 v[64:67], v[218:221], v[202:205], 0
	v_mfma_f32_16x16x32_bf16 v[116:119], v[214:217], v[174:177], v[116:119]
	v_mfma_f32_16x16x32_bf16 v[112:115], v[222:225], v[174:177], v[112:115]
	v_mfma_f32_16x16x32_bf16 v[100:103], v[214:217], v[188:191], v[100:103]
	v_mfma_f32_16x16x32_bf16 v[96:99], v[222:225], v[188:191], v[96:99]
	v_mfma_f32_16x16x32_bf16 v[84:87], v[214:217], v[198:201], v[84:87]
	v_mfma_f32_16x16x32_bf16 v[80:83], v[222:225], v[198:201], v[80:83]
	v_mfma_f32_16x16x32_bf16 v[68:71], v[214:217], v[206:209], v[68:71]
	v_mfma_f32_16x16x32_bf16 v[64:67], v[222:225], v[206:209], v[64:67]
	s_setprio 0
	s_mov_b32 m0, s39
	s_barrier
	ds_read_b128 v[170:173], v148 offset:16384
	ds_read_b128 v[174:177], v148 offset:17408
	ds_read_b128 v[178:181], v148 offset:18432
	ds_read_b128 v[188:191], v148 offset:19456
	ds_read_b128 v[194:197], v148 offset:20480
	ds_read_b128 v[198:201], v148 offset:21504
	ds_read_b128 v[202:205], v148 offset:22528
	global_load_lds_dwordx4 v128, s[44:45]
	s_mov_b32 m0, s53
	ds_read_b128 v[206:209], v148 offset:23552
	global_load_lds_dwordx4 v132, s[44:45]
	s_barrier
	s_waitcnt lgkmcnt(0)
	s_setprio 1
	v_mfma_f32_16x16x32_bf16 v[60:63], v[150:153], v[170:173], 0
	v_mfma_f32_16x16x32_bf16 v[56:59], v[162:165], v[170:173], 0
	v_mfma_f32_16x16x32_bf16 v[44:47], v[150:153], v[178:181], 0
	v_mfma_f32_16x16x32_bf16 v[40:43], v[162:165], v[178:181], 0
	v_mfma_f32_16x16x32_bf16 v[28:31], v[150:153], v[194:197], 0
	v_mfma_f32_16x16x32_bf16 v[24:27], v[162:165], v[194:197], 0
	v_mfma_f32_16x16x32_bf16 v[12:15], v[150:153], v[202:205], 0
	v_mfma_f32_16x16x32_bf16 v[8:11], v[162:165], v[202:205], 0
	v_mfma_f32_16x16x32_bf16 v[60:63], v[154:157], v[174:177], v[60:63]
	v_mfma_f32_16x16x32_bf16 v[56:59], v[166:169], v[174:177], v[56:59]
	v_mfma_f32_16x16x32_bf16 v[44:47], v[154:157], v[188:191], v[44:47]
	v_mfma_f32_16x16x32_bf16 v[40:43], v[166:169], v[188:191], v[40:43]
	v_mfma_f32_16x16x32_bf16 v[28:31], v[154:157], v[198:201], v[28:31]
	v_mfma_f32_16x16x32_bf16 v[24:27], v[166:169], v[198:201], v[24:27]
	v_mfma_f32_16x16x32_bf16 v[12:15], v[154:157], v[206:209], v[12:15]
	v_mfma_f32_16x16x32_bf16 v[8:11], v[166:169], v[206:209], v[8:11]
	s_setprio 0
	s_barrier
; #define PG8_STAGE(bufoff, gbase, voff) do { _Pragma("unroll") for (int _i = 0; _i < 2; ++_i) \
;         __builtin_amdgcn_global_load_lds((const unsigned*)((const char*)(gbase) + (voff)[_i]), (LAS unsigned*)(lds + (bufoff) + ldsw + _i * 8192), 16, 0, 0); } while (0)
; #define PG8_LDA(dst, b, h) do { _Pragma("unroll") for (int m = 0; m < 4; ++m) _Pragma("unroll") for (int k = 0; k < 2; ++k) dst[m][k] = *(const LAS bf16x8*)(lds + PG8_SA(b, h) + aoff + m * 2048 + k * 1024); } while (0)
; #define PG8_LDB(dst, b, h) do { _Pragma("unroll") for (int n = 0; n < 2; ++n) _Pragma("unroll") for (int k = 0; k < 2; ++k) dst[n][k] = *(const LAS bf16x8*)(lds + PG8_SB(b, h) + boff + n * 2048 + k * 1024); } while (0)
; #define PG8_MMA(ai, bj, At, Bt) do { __builtin_amdgcn_s_setprio(1); _Pragma("unroll") for (int m = 0; m < 4; ++m) _Pragma("unroll") for (int n = 0; n < 2; ++n) _Pragma("unroll") for (int k = 0; k < 2; ++k) \
;         acc[ai][bj][m][n] = __builtin_amdgcn_mfma_f32_16x16x32_bf16(Bt[n][k], At[m][k], acc[ai][bj][m][n], 0, 0, 0); __builtin_amdgcn_s_setprio(0); } while (0)
; #define PG8_WAIT_V(n) asm volatile("s_waitcnt vmcnt(" #n ")" ::: "memory")
; #define PG8_WAIT_L(n) asm volatile("s_waitcnt lgkmcnt(" #n ")" ::: "memory")
; #define PG8_BAR __builtin_amdgcn_s_barrier()
; #define PG8_SCHED __builtin_amdgcn_sched_barrier(0)
; template <class Epi, class Sched>
; DI void gemm_phase(LAS unsigned char* lds, const Gemm g, const Sched& S, const Epi& E) {
;     ...
;             PG8_STAGE(PG8_SB(0, 1), b2 + hstep, voffB);
;             PG8_WAIT_V(6); PG8_BAR; PG8_MMA(1, 1, At, B1); PG8_BAR;
;             PG8_LDB(B0, 1, 0); PG8_SCHED; PG8_LDA(At, 1, 0); PG8_STAGE(PG8_SA(0, 1), a2 + hstep, voffA);
;             PG8_WAIT_L(8); PG8_BAR; PG8_WAIT_L(0); PG8_MMA(0, 0, At, B0); PG8_BAR; PG8_SCHED;
;             PG8_LDB(B1, 1, 1); PG8_STAGE(PG8_SB(1, 0), b3, voffB);
;             PG8_BAR; PG8_WAIT_L(0); PG8_MMA(0, 1, At, B1); PG8_BAR;
;             PG8_LDA(At, 1, 1); PG8_STAGE(PG8_SA(1, 0), a3, voffA);
;             PG8_BAR; PG8_WAIT_L(0); PG8_MMA(1, 0, At, B0); PG8_BAR; PG8_SCHED;
	s_add_i32 s4, s35, s52
	s_mov_b32 m0, s4
	s_add_u32 s0, s42, 0x80000
	s_addc_u32 s1, s43, 0
	global_load_lds_dwordx4 v130, s[0:1]
	s_add_i32 m0, s4, 0x2000
	s_nop 0
	global_load_lds_dwordx4 v134, s[0:1]
	s_waitcnt vmcnt(6)
	s_barrier
	s_setprio 1
	v_mfma_f32_16x16x32_bf16 v[52:55], v[210:213], v[170:173], 0
	v_mfma_f32_16x16x32_bf16 v[48:51], v[218:221], v[170:173], 0
	v_mfma_f32_16x16x32_bf16 v[36:39], v[210:213], v[178:181], 0
	v_mfma_f32_16x16x32_bf16 v[32:35], v[218:221], v[178:181], 0
	v_mfma_f32_16x16x32_bf16 v[20:23], v[210:213], v[194:197], 0
	v_mfma_f32_16x16x32_bf16 v[16:19], v[218:221], v[194:197], 0
	v_mfma_f32_16x16x32_bf16 v[4:7], v[210:213], v[202:205], 0
	v_mfma_f32_16x16x32_bf16 v[0:3], v[218:221], v[202:205], 0
	v_mfma_f32_16x16x32_bf16 v[52:55], v[214:217], v[174:177], v[52:55]
	v_mfma_f32_16x16x32_bf16 v[48:51], v[222:225], v[174:177], v[48:51]
	v_mfma_f32_16x16x32_bf16 v[36:39], v[214:217], v[188:191], v[36:39]
	v_mfma_f32_16x16x32_bf16 v[32:35], v[222:225], v[188:191], v[32:35]
	v_mfma_f32_16x16x32_bf16 v[20:23], v[214:217], v[198:201], v[20:23]
	v_mfma_f32_16x16x32_bf16 v[16:19], v[222:225], v[198:201], v[16:19]
	v_mfma_f32_16x16x32_bf16 v[4:7], v[214:217], v[206:209], v[4:7]
	v_mfma_f32_16x16x32_bf16 v[0:3], v[222:225], v[206:209], v[0:3]
	s_setprio 0
	s_add_i32 s4, 0, 0x18000
	v_add_u32_e32 v158, s4, v146
	s_barrier
	ds_read_b128 v[150:153], v158
	ds_read_b128 v[154:157], v158 offset:1024
	ds_read_b128 v[162:165], v158 offset:2048
	ds_read_b128 v[166:169], v158 offset:3072
	s_add_u32 s0, s44, 0x80000
	s_addc_u32 s1, s45, 0
	s_mov_b32 m0, s54
	ds_read_b128 v[170:173], v148 offset:32768
	ds_read_b128 v[174:177], v148 offset:33792
	ds_read_b128 v[178:181], v148 offset:34816
	ds_read_b128 v[188:191], v148 offset:35840
	ds_read_b128 v[194:197], v148 offset:36864
	ds_read_b128 v[198:201], v148 offset:37888
	ds_read_b128 v[202:205], v148 offset:38912
	global_load_lds_dwordx4 v128, s[0:1]
	s_mov_b32 m0, s55
	ds_read_b128 v[206:209], v148 offset:39936
	global_load_lds_dwordx4 v132, s[0:1]
	s_waitcnt lgkmcnt(8)
	s_barrier
	s_waitcnt lgkmcnt(0)
	s_setprio 1
	v_mfma_f32_16x16x32_bf16 v[124:127], v[150:153], v[170:173], v[124:127]
	v_mfma_f32_16x16x32_bf16 v[120:123], v[162:165], v[170:173], v[120:123]
	v_mfma_f32_16x16x32_bf16 v[108:111], v[150:153], v[178:181], v[108:111]
	v_mfma_f32_16x16x32_bf16 v[104:107], v[162:165], v[178:181], v[104:107]
	v_mfma_f32_16x16x32_bf16 v[92:95], v[150:153], v[194:197], v[92:95]
	v_mfma_f32_16x16x32_bf16 v[88:91], v[162:165], v[194:197], v[88:91]
	v_mfma_f32_16x16x32_bf16 v[76:79], v[150:153], v[202:205], v[76:79]
	v_mfma_f32_16x16x32_bf16 v[72:75], v[162:165], v[202:205], v[72:75]
	v_mfma_f32_16x16x32_bf16 v[124:127], v[154:157], v[174:177], v[124:127]
	v_mfma_f32_16x16x32_bf16 v[120:123], v[166:169], v[174:177], v[120:123]
	v_mfma_f32_16x16x32_bf16 v[108:111], v[154:157], v[188:191], v[108:111]
	v_mfma_f32_16x16x32_bf16 v[104:107], v[166:169], v[188:191], v[104:107]
	v_mfma_f32_16x16x32_bf16 v[92:95], v[154:157], v[198:201], v[92:95]
	v_mfma_f32_16x16x32_bf16 v[88:91], v[166:169], v[198:201], v[88:91]
	v_mfma_f32_16x16x32_bf16 v[76:79], v[154:157], v[206:209], v[76:79]
	v_mfma_f32_16x16x32_bf16 v[72:75], v[166:169], v[206:209], v[72:75]
	s_setprio 0
	s_barrier
	s_add_i32 s5, 0, 0x1c000
	s_add_i32 s0, s4, s52
	v_add_u32_e32 v159, s5, v146
	s_add_i32 m0, s0, 0xffffff80
	ds_read_b128 v[210:213], v159
	ds_read_b128 v[214:217], v159 offset:1024
	ds_read_b128 v[218:221], v159 offset:2048
	global_load_lds_dwordx4 v130, s[42:43] offset:128
	s_add_i32 m0, s0, 0x1f80
	ds_read_b128 v[222:225], v159 offset:3072
	global_load_lds_dwordx4 v134, s[42:43] offset:128
	s_barrier
	s_waitcnt lgkmcnt(0)
	s_setprio 1
	v_mfma_f32_16x16x32_bf16 v[116:119], v[210:213], v[170:173], v[116:119]
	v_mfma_f32_16x16x32_bf16 v[112:115], v[218:221], v[170:173], v[112:115]
	v_mfma_f32_16x16x32_bf16 v[100:103], v[210:213], v[178:181], v[100:103]
	v_mfma_f32_16x16x32_bf16 v[96:99], v[218:221], v[178:181], v[96:99]
	v_mfma_f32_16x16x32_bf16 v[84:87], v[210:213], v[194:197], v[84:87]
	v_mfma_f32_16x16x32_bf16 v[80:83], v[218:221], v[194:197], v[80:83]
	v_mfma_f32_16x16x32_bf16 v[68:71], v[210:213], v[202:205], v[68:71]
	v_mfma_f32_16x16x32_bf16 v[64:67], v[218:221], v[202:205], v[64:67]
	v_mfma_f32_16x16x32_bf16 v[116:119], v[214:217], v[174:177], v[116:119]
	v_mfma_f32_16x16x32_bf16 v[112:115], v[222:225], v[174:177], v[112:115]
	v_mfma_f32_16x16x32_bf16 v[100:103], v[214:217], v[188:191], v[100:103]
	v_mfma_f32_16x16x32_bf16 v[96:99], v[222:225], v[188:191], v[96:99]
	v_mfma_f32_16x16x32_bf16 v[84:87], v[214:217], v[198:201], v[84:87]
	v_mfma_f32_16x16x32_bf16 v[80:83], v[222:225], v[198:201], v[80:83]
	v_mfma_f32_16x16x32_bf16 v[68:71], v[214:217], v[206:209], v[68:71]
	v_mfma_f32_16x16x32_bf16 v[64:67], v[222:225], v[206:209], v[64:67]
	s_setprio 0
	s_add_i32 m0, s59, 0xffffff80
	s_barrier
	ds_read_b128 v[170:173], v148 offset:49152
	ds_read_b128 v[174:177], v148 offset:50176
	ds_read_b128 v[178:181], v148 offset:51200
	ds_read_b128 v[188:191], v148 offset:52224
	ds_read_b128 v[194:197], v148 offset:53248
	ds_read_b128 v[198:201], v148 offset:54272
	ds_read_b128 v[202:205], v148 offset:55296
	global_load_lds_dwordx4 v128, s[44:45] offset:128
	s_add_i32 m0, s60, 0xffffff80
	ds_read_b128 v[206:209], v148 offset:56320
	global_load_lds_dwordx4 v132, s[44:45] offset:128
	s_barrier
; #define PG8_STAGE(bufoff, gbase, voff) do { _Pragma("unroll") for (int _i = 0; _i < 2; ++_i) \
;         __builtin_amdgcn_global_load_lds((const unsigned*)((const char*)(gbase) + (voff)[_i]), (LAS unsigned*)(lds + (bufoff) + ldsw + _i * 8192), 16, 0, 0); } while (0)
; #define PG8_LDA(dst, b, h) do { _Pragma("unroll") for (int m = 0; m < 4; ++m) _Pragma("unroll") for (int k = 0; k < 2; ++k) dst[m][k] = *(const LAS bf16x8*)(lds + PG8_SA(b, h) + aoff + m * 2048 + k * 1024); } while (0)
; #define PG8_LDB(dst, b, h) do { _Pragma("unroll") for (int n = 0; n < 2; ++n) _Pragma("unroll") for (int k = 0; k < 2; ++k) dst[n][k] = *(const LAS bf16x8*)(lds + PG8_SB(b, h) + boff + n * 2048 + k * 1024); } while (0)
; #define PG8_MMA(ai, bj, At, Bt) do { __builtin_amdgcn_s_setprio(1); _Pragma("unroll") for (int m = 0; m < 4; ++m) _Pragma("unroll") for (int n = 0; n < 2; ++n) _Pragma("unroll") for (int k = 0; k < 2; ++k) \
;         acc[ai][bj][m][n] = __builtin_amdgcn_mfma_f32_16x16x32_bf16(Bt[n][k], At[m][k], acc[ai][bj][m][n], 0, 0, 0); __builtin_amdgcn_s_setprio(0); } while (0)
; #define PG8_WAIT_V(n) asm volatile("s_waitcnt vmcnt(" #n ")" ::: "memory")
; #define PG8_WAIT_L(n) asm volatile("s_waitcnt lgkmcnt(" #n ")" ::: "memory")
; #define PG8_BAR __builtin_amdgcn_s_barrier()
; #define PG8_SCHED __builtin_amdgcn_sched_barrier(0)
; template <class Epi, class Sched>
; DI void gemm_phase(LAS unsigned char* lds, const Gemm g, const Sched& S, const Epi& E) {
;     ...
;             PG8_LDB(B0, 0, 0); PG8_SCHED; PG8_LDA(At, 0, 0); PG8_STAGE(PG8_SA(1, 1), a1 + hstep, voffA);
;             PG8_WAIT_L(8); PG8_BAR; PG8_WAIT_L(0); PG8_MMA(0, 0, At, B0); PG8_BAR; PG8_SCHED;
;             PG8_LDB(B1, 0, 1); PG8_STAGE(PG8_SB(0, 0), b2, voffB);
;             PG8_BAR; PG8_WAIT_L(0); PG8_MMA(0, 1, At, B1); PG8_BAR;
;     ...
;             PG8_WAIT_L(8); PG8_BAR; PG8_WAIT_L(0); PG8_MMA(0, 0, At, B0); PG8_BAR; PG8_SCHED;
;             PG8_LDB(B1, 1, 1); PG8_STAGE(PG8_SB(1, 0), b3, voffB);
;             PG8_BAR; PG8_WAIT_L(0); PG8_MMA(0, 1, At, B1); PG8_BAR;
;             PG8_LDA(At, 1, 1); PG8_STAGE(PG8_SA(1, 0), a3, voffA);
;             PG8_BAR; PG8_WAIT_L(0); PG8_MMA(1, 0, At, B0); PG8_BAR; PG8_SCHED;
;             PG8_STAGE(PG8_SB(1, 1), b3 + hstep, voffB);
;             PG8_WAIT_V(6); PG8_BAR; PG8_MMA(1, 1, At, B1); PG8_BAR;
	s_waitcnt lgkmcnt(0)
	s_setprio 1
	v_mfma_f32_16x16x32_bf16 v[60:63], v[150:153], v[170:173], v[60:63]
	v_mfma_f32_16x16x32_bf16 v[56:59], v[162:165], v[170:173], v[56:59]
	v_mfma_f32_16x16x32_bf16 v[44:47], v[150:153], v[178:181], v[44:47]
	v_mfma_f32_16x16x32_bf16 v[40:43], v[162:165], v[178:181], v[40:43]
	v_mfma_f32_16x16x32_bf16 v[28:31], v[150:153], v[194:197], v[28:31]
	v_mfma_f32_16x16x32_bf16 v[24:27], v[162:165], v[194:197], v[24:27]
	v_mfma_f32_16x16x32_bf16 v[12:15], v[150:153], v[202:205], v[12:15]
	v_mfma_f32_16x16x32_bf16 v[8:11], v[162:165], v[202:205], v[8:11]
	v_mfma_f32_16x16x32_bf16 v[60:63], v[154:157], v[174:177], v[60:63]
	v_mfma_f32_16x16x32_bf16 v[56:59], v[166:169], v[174:177], v[56:59]
	v_mfma_f32_16x16x32_bf16 v[44:47], v[154:157], v[188:191], v[44:47]
	v_mfma_f32_16x16x32_bf16 v[40:43], v[166:169], v[188:191], v[40:43]
	v_mfma_f32_16x16x32_bf16 v[28:31], v[154:157], v[198:201], v[28:31]
	v_mfma_f32_16x16x32_bf16 v[24:27], v[166:169], v[198:201], v[24:27]
	v_mfma_f32_16x16x32_bf16 v[12:15], v[154:157], v[206:209], v[12:15]
	v_mfma_f32_16x16x32_bf16 v[8:11], v[166:169], v[206:209], v[8:11]
	s_setprio 0
	s_barrier
	s_add_i32 s4, s5, s52
	s_mov_b32 m0, s4
	s_add_u32 s0, s42, 0x80080
	s_addc_u32 s1, s43, 0
	global_load_lds_dwordx4 v130, s[0:1]
	s_add_i32 m0, s4, 0x2000
	s_nop 0
	global_load_lds_dwordx4 v134, s[0:1]
	s_add_i32 s69, s69, 2
	s_add_u32 s40, s40, 0x100
	s_addc_u32 s41, s41, 0
	s_add_u32 s67, s67, 0x100
	s_addc_u32 s68, s68, 0
	s_cmp_gt_u32 s69, 29
	s_waitcnt vmcnt(6)
	s_barrier
	s_setprio 1
	v_mfma_f32_16x16x32_bf16 v[52:55], v[210:213], v[170:173], v[52:55]
	v_mfma_f32_16x16x32_bf16 v[48:51], v[218:221], v[170:173], v[48:51]
	v_mfma_f32_16x16x32_bf16 v[36:39], v[210:213], v[178:181], v[36:39]
	v_mfma_f32_16x16x32_bf16 v[32:35], v[218:221], v[178:181], v[32:35]
	v_mfma_f32_16x16x32_bf16 v[20:23], v[210:213], v[194:197], v[20:23]
	v_mfma_f32_16x16x32_bf16 v[16:19], v[218:221], v[194:197], v[16:19]
	v_mfma_f32_16x16x32_bf16 v[4:7], v[210:213], v[202:205], v[4:7]
	v_mfma_f32_16x16x32_bf16 v[0:3], v[218:221], v[202:205], v[0:3]
	v_mfma_f32_16x16x32_bf16 v[52:55], v[214:217], v[174:177], v[52:55]
	v_mfma_f32_16x16x32_bf16 v[48:51], v[222:225], v[174:177], v[48:51]
	v_mfma_f32_16x16x32_bf16 v[36:39], v[214:217], v[188:191], v[36:39]
	v_mfma_f32_16x16x32_bf16 v[32:35], v[222:225], v[188:191], v[32:35]
	v_mfma_f32_16x16x32_bf16 v[20:23], v[214:217], v[198:201], v[20:23]
	v_mfma_f32_16x16x32_bf16 v[16:19], v[222:225], v[198:201], v[16:19]
	v_mfma_f32_16x16x32_bf16 v[4:7], v[214:217], v[206:209], v[4:7]
	v_mfma_f32_16x16x32_bf16 v[0:3], v[222:225], v[206:209], v[0:3]
	s_setprio 0
	s_barrier
	s_cbranch_scc0 .LBB0_219
	s_branch .Lpeel_done_219
.LBB0_219:
	ds_read_b128 v[150:153], v147
	ds_read_b128 v[154:157], v147 offset:1024
	ds_read_b128 v[162:165], v147 offset:2048
	ds_read_b128 v[166:169], v147 offset:3072
	s_add_i32 m0, s39, 0xc000
	ds_read_b128 v[170:173], v148
	ds_read_b128 v[174:177], v148 offset:1024
	ds_read_b128 v[178:181], v148 offset:2048
	ds_read_b128 v[188:191], v148 offset:3072
	ds_read_b128 v[194:197], v148 offset:4096
	ds_read_b128 v[198:201], v148 offset:5120
	ds_read_b128 v[202:205], v148 offset:6144
	global_load_lds_dwordx4 v136, s[40:41]
	s_add_i32 m0, s39, 0xe000
	ds_read_b128 v[206:209], v148 offset:7168
	global_load_lds_dwordx4 v138, s[40:41]
	s_add_u32 s0, s40, 0xfff80080
	s_addc_u32 s1, s41, -1
	s_cmp_eq_u32 s69, 28
	s_cselect_b32 s45, s17, s1
	s_cselect_b32 s44, s65, s0
	s_cselect_b32 s43, s15, s68
	s_cselect_b32 s42, s66, s67
	s_waitcnt lgkmcnt(8)
	s_barrier
	s_waitcnt lgkmcnt(0)
	s_setprio 1
	v_mfma_f32_16x16x32_bf16 v[124:127], v[150:153], v[170:173], v[124:127]
	v_mfma_f32_16x16x32_bf16 v[120:123], v[162:165], v[170:173], v[120:123]
	v_mfma_f32_16x16x32_bf16 v[108:111], v[150:153], v[178:181], v[108:111]
	v_mfma_f32_16x16x32_bf16 v[104:107], v[162:165], v[178:181], v[104:107]
	v_mfma_f32_16x16x32_bf16 v[92:95], v[150:153], v[194:197], v[92:95]
	v_mfma_f32_16x16x32_bf16 v[88:91], v[162:165], v[194:197], v[88:91]
	v_mfma_f32_16x16x32_bf16 v[76:79], v[150:153], v[202:205], v[76:79]
	v_mfma_f32_16x16x32_bf16 v[72:75], v[162:165], v[202:205], v[72:75]
	v_mfma_f32_16x16x32_bf16 v[124:127], v[154:157], v[174:177], v[124:127]
	v_mfma_f32_16x16x32_bf16 v[120:123], v[166:169], v[174:177], v[120:123]
	v_mfma_f32_16x16x32_bf16 v[108:111], v[154:157], v[188:191], v[108:111]
	v_mfma_f32_16x16x32_bf16 v[104:107], v[166:169], v[188:191], v[104:107]
	v_mfma_f32_16x16x32_bf16 v[92:95], v[154:157], v[198:201], v[92:95]
	v_mfma_f32_16x16x32_bf16 v[88:91], v[166:169], v[198:201], v[88:91]
	v_mfma_f32_16x16x32_bf16 v[76:79], v[154:157], v[206:209], v[76:79]
	v_mfma_f32_16x16x32_bf16 v[72:75], v[166:169], v[206:209], v[72:75]
	s_setprio 0
	s_barrier
	s_add_i32 s0, s34, s52
	s_mov_b32 m0, s0
	ds_read_b128 v[210:213], v149
	ds_read_b128 v[214:217], v149 offset:1024
	ds_read_b128 v[218:221], v149 offset:2048
	global_load_lds_dwordx4 v130, s[42:43]
	s_add_i32 m0, s0, 0x2000
	ds_read_b128 v[222:225], v149 offset:3072
	global_load_lds_dwordx4 v134, s[42:43]
	s_barrier
; #define PG8_STAGE(bufoff, gbase, voff) do { _Pragma("unroll") for (int _i = 0; _i < 2; ++_i) \
;         __builtin_amdgcn_global_load_lds((const unsigned*)((const char*)(gbase) + (voff)[_i]), (LAS unsigned*)(lds + (bufoff) + ldsw + _i * 8192), 16, 0, 0); } while (0)
; #define PG8_LDA(dst, b, h) do { _Pragma("unroll") for (int m = 0; m < 4; ++m) _Pragma("unroll") for (int k = 0; k < 2; ++k) dst[m][k] = *(const LAS bf16x8*)(lds + PG8_SA(b, h) + aoff + m * 2048 + k * 1024); } while (0)
; #define PG8_LDB(dst, b, h) do { _Pragma("unroll") for (int n = 0; n < 2; ++n) _Pragma("unroll") for (int k = 0; k < 2; ++k) dst[n][k] = *(const LAS bf16x8*)(lds + PG8_SB(b, h) + boff + n * 2048 + k * 1024); } while (0)
; #define PG8_MMA(ai, bj, At, Bt) do { __builtin_amdgcn_s_setprio(1); _Pragma("unroll") for (int m = 0; m < 4; ++m) _Pragma("unroll") for (int n = 0; n < 2; ++n) _Pragma("unroll") for (int k = 0; k < 2; ++k) \
;         acc[ai][bj][m][n] = __builtin_amdgcn_mfma_f32_16x16x32_bf16(Bt[n][k], At[m][k], acc[ai][bj][m][n], 0, 0, 0); __builtin_amdgcn_s_setprio(0); } while (0)
; #define PG8_WAIT_V(n) asm volatile("s_waitcnt vmcnt(" #n ")" ::: "memory")
; #define PG8_WAIT_L(n) asm volatile("s_waitcnt lgkmcnt(" #n ")" ::: "memory")
; #define PG8_BAR __builtin_amdgcn_s_barrier()
; #define PG8_SCHED __builtin_amdgcn_sched_barrier(0)
; template <class Epi, class Sched>
; DI void gemm_phase(LAS unsigned char* lds, const Gemm g, const Sched& S, const Epi& E) {
;     ...
;             PG8_BAR; PG8_WAIT_L(0); PG8_MMA(0, 1, At, B1); PG8_BAR;
;             PG8_LDA(At, 0, 1); PG8_STAGE(PG8_SA(0, 0), a2, voffA);
;             PG8_BAR; PG8_WAIT_L(0); PG8_MMA(1, 0, At, B0); PG8_BAR; PG8_SCHED;
;             PG8_STAGE(PG8_SB(0, 1), b2 + hstep, voffB);
;             PG8_WAIT_V(6); PG8_BAR; PG8_MMA(1, 1, At, B1); PG8_BAR;
;             PG8_LDB(B0, 1, 0); PG8_SCHED; PG8_LDA(At, 1, 0); PG8_STAGE(PG8_SA(0, 1), a2 + hstep, voffA);
	s_waitcnt lgkmcnt(0)
	s_setprio 1
	v_mfma_f32_16x16x32_bf16 v[116:119], v[210:213], v[170:173], v[116:119]
	v_mfma_f32_16x16x32_bf16 v[112:115], v[218:221], v[170:173], v[112:115]
	v_mfma_f32_16x16x32_bf16 v[100:103], v[210:213], v[178:181], v[100:103]
	v_mfma_f32_16x16x32_bf16 v[96:99], v[218:221], v[178:181], v[96:99]
	v_mfma_f32_16x16x32_bf16 v[84:87], v[210:213], v[194:197], v[84:87]
	v_mfma_f32_16x16x32_bf16 v[80:83], v[218:221], v[194:197], v[80:83]
	v_mfma_f32_16x16x32_bf16 v[68:71], v[210:213], v[202:205], v[68:71]
	v_mfma_f32_16x16x32_bf16 v[64:67], v[218:221], v[202:205], v[64:67]
	v_mfma_f32_16x16x32_bf16 v[116:119], v[214:217], v[174:177], v[116:119]
	v_mfma_f32_16x16x32_bf16 v[112:115], v[222:225], v[174:177], v[112:115]
	v_mfma_f32_16x16x32_bf16 v[100:103], v[214:217], v[188:191], v[100:103]
	v_mfma_f32_16x16x32_bf16 v[96:99], v[222:225], v[188:191], v[96:99]
	v_mfma_f32_16x16x32_bf16 v[84:87], v[214:217], v[198:201], v[84:87]
	v_mfma_f32_16x16x32_bf16 v[80:83], v[222:225], v[198:201], v[80:83]
	v_mfma_f32_16x16x32_bf16 v[68:71], v[214:217], v[206:209], v[68:71]
	v_mfma_f32_16x16x32_bf16 v[64:67], v[222:225], v[206:209], v[64:67]
	s_setprio 0
	s_mov_b32 m0, s39
	s_barrier
	ds_read_b128 v[170:173], v148 offset:16384
	ds_read_b128 v[174:177], v148 offset:17408
	ds_read_b128 v[178:181], v148 offset:18432
	ds_read_b128 v[188:191], v148 offset:19456
	ds_read_b128 v[194:197], v148 offset:20480
	ds_read_b128 v[198:201], v148 offset:21504
	ds_read_b128 v[202:205], v148 offset:22528
	global_load_lds_dwordx4 v128, s[44:45]
	s_mov_b32 m0, s53
	ds_read_b128 v[206:209], v148 offset:23552
	global_load_lds_dwordx4 v132, s[44:45]
	s_barrier
	s_waitcnt lgkmcnt(0)
	s_setprio 1
	v_mfma_f32_16x16x32_bf16 v[60:63], v[150:153], v[170:173], v[60:63]
	v_mfma_f32_16x16x32_bf16 v[56:59], v[162:165], v[170:173], v[56:59]
	v_mfma_f32_16x16x32_bf16 v[44:47], v[150:153], v[178:181], v[44:47]
	v_mfma_f32_16x16x32_bf16 v[40:43], v[162:165], v[178:181], v[40:43]
	v_mfma_f32_16x16x32_bf16 v[28:31], v[150:153], v[194:197], v[28:31]
	v_mfma_f32_16x16x32_bf16 v[24:27], v[162:165], v[194:197], v[24:27]
	v_mfma_f32_16x16x32_bf16 v[12:15], v[150:153], v[202:205], v[12:15]
	v_mfma_f32_16x16x32_bf16 v[8:11], v[162:165], v[202:205], v[8:11]
	v_mfma_f32_16x16x32_bf16 v[60:63], v[154:157], v[174:177], v[60:63]
	v_mfma_f32_16x16x32_bf16 v[56:59], v[166:169], v[174:177], v[56:59]
	v_mfma_f32_16x16x32_bf16 v[44:47], v[154:157], v[188:191], v[44:47]
	v_mfma_f32_16x16x32_bf16 v[40:43], v[166:169], v[188:191], v[40:43]
	v_mfma_f32_16x16x32_bf16 v[28:31], v[154:157], v[198:201], v[28:31]
	v_mfma_f32_16x16x32_bf16 v[24:27], v[166:169], v[198:201], v[24:27]
	v_mfma_f32_16x16x32_bf16 v[12:15], v[154:157], v[206:209], v[12:15]
	v_mfma_f32_16x16x32_bf16 v[8:11], v[166:169], v[206:209], v[8:11]
	s_setprio 0
	s_barrier
	s_add_i32 s4, s35, s52
	s_mov_b32 m0, s4
	s_add_u32 s0, s42, 0x80000
	s_addc_u32 s1, s43, 0
	global_load_lds_dwordx4 v130, s[0:1]
	s_add_i32 m0, s4, 0x2000
	s_nop 0
	global_load_lds_dwordx4 v134, s[0:1]
	s_waitcnt vmcnt(6)
	s_barrier
	s_setprio 1
	v_mfma_f32_16x16x32_bf16 v[52:55], v[210:213], v[170:173], v[52:55]
	v_mfma_f32_16x16x32_bf16 v[48:51], v[218:221], v[170:173], v[48:51]
	v_mfma_f32_16x16x32_bf16 v[36:39], v[210:213], v[178:181], v[36:39]
	v_mfma_f32_16x16x32_bf16 v[32:35], v[218:221], v[178:181], v[32:35]
	v_mfma_f32_16x16x32_bf16 v[20:23], v[210:213], v[194:197], v[20:23]
	v_mfma_f32_16x16x32_bf16 v[16:19], v[218:221], v[194:197], v[16:19]
	v_mfma_f32_16x16x32_bf16 v[4:7], v[210:213], v[202:205], v[4:7]
	v_mfma_f32_16x16x32_bf16 v[0:3], v[218:221], v[202:205], v[0:3]
	v_mfma_f32_16x16x32_bf16 v[52:55], v[214:217], v[174:177], v[52:55]
	v_mfma_f32_16x16x32_bf16 v[48:51], v[222:225], v[174:177], v[48:51]
	v_mfma_f32_16x16x32_bf16 v[36:39], v[214:217], v[188:191], v[36:39]
	v_mfma_f32_16x16x32_bf16 v[32:35], v[222:225], v[188:191], v[32:35]
	v_mfma_f32_16x16x32_bf16 v[20:23], v[214:217], v[198:201], v[20:23]
	v_mfma_f32_16x16x32_bf16 v[16:19], v[222:225], v[198:201], v[16:19]
	v_mfma_f32_16x16x32_bf16 v[4:7], v[214:217], v[206:209], v[4:7]
	v_mfma_f32_16x16x32_bf16 v[0:3], v[222:225], v[206:209], v[0:3]
	s_setprio 0
	s_add_i32 s4, 0, 0x18000
	s_barrier
	ds_read_b128 v[150:153], v158
	ds_read_b128 v[154:157], v158 offset:1024
	ds_read_b128 v[162:165], v158 offset:2048
	ds_read_b128 v[166:169], v158 offset:3072
	s_add_u32 s0, s44, 0x80000
	s_addc_u32 s1, s45, 0
	s_mov_b32 m0, s54
	ds_read_b128 v[170:173], v148 offset:32768
	ds_read_b128 v[174:177], v148 offset:33792
	ds_read_b128 v[178:181], v148 offset:34816
	ds_read_b128 v[188:191], v148 offset:35840
	ds_read_b128 v[194:197], v148 offset:36864
	ds_read_b128 v[198:201], v148 offset:37888
	ds_read_b128 v[202:205], v148 offset:38912
	global_load_lds_dwordx4 v128, s[0:1]
	s_mov_b32 m0, s55
	ds_read_b128 v[206:209], v148 offset:39936
	global_load_lds_dwordx4 v132, s[0:1]
	s_waitcnt lgkmcnt(8)
	s_barrier
; #define PG8_STAGE(bufoff, gbase, voff) do { _Pragma("unroll") for (int _i = 0; _i < 2; ++_i) \
;         __builtin_amdgcn_global_load_lds((const unsigned*)((const char*)(gbase) + (voff)[_i]), (LAS unsigned*)(lds + (bufoff) + ldsw + _i * 8192), 16, 0, 0); } while (0)
; #define PG8_LDA(dst, b, h) do { _Pragma("unroll") for (int m = 0; m < 4; ++m) _Pragma("unroll") for (int k = 0; k < 2; ++k) dst[m][k] = *(const LAS bf16x8*)(lds + PG8_SA(b, h) + aoff + m * 2048 + k * 1024); } while (0)
; #define PG8_LDB(dst, b, h) do { _Pragma("unroll") for (int n = 0; n < 2; ++n) _Pragma("unroll") for (int k = 0; k < 2; ++k) dst[n][k] = *(const LAS bf16x8*)(lds + PG8_SB(b, h) + boff + n * 2048 + k * 1024); } while (0)
; #define PG8_MMA(ai, bj, At, Bt) do { __builtin_amdgcn_s_setprio(1); _Pragma("unroll") for (int m = 0; m < 4; ++m) _Pragma("unroll") for (int n = 0; n < 2; ++n) _Pragma("unroll") for (int k = 0; k < 2; ++k) \
;         acc[ai][bj][m][n] = __builtin_amdgcn_mfma_f32_16x16x32_bf16(Bt[n][k], At[m][k], acc[ai][bj][m][n], 0, 0, 0); __builtin_amdgcn_s_setprio(0); } while (0)
; #define PG8_WAIT_V(n) asm volatile("s_waitcnt vmcnt(" #n ")" ::: "memory")
; #define PG8_WAIT_L(n) asm volatile("s_waitcnt lgkmcnt(" #n ")" ::: "memory")
; #define PG8_BAR __builtin_amdgcn_s_barrier()
; #define PG8_SCHED __builtin_amdgcn_sched_barrier(0)
; template <class Epi, class Sched>
; DI void gemm_phase(LAS unsigned char* lds, const Gemm g, const Sched& S, const Epi& E) {
;     ...
;             PG8_WAIT_L(8); PG8_BAR; PG8_WAIT_L(0); PG8_MMA(0, 0, At, B0); PG8_BAR; PG8_SCHED;
;             PG8_LDB(B1, 1, 1); PG8_STAGE(PG8_SB(1, 0), b3, voffB);
;             PG8_BAR; PG8_WAIT_L(0); PG8_MMA(0, 1, At, B1); PG8_BAR;
;             PG8_LDA(At, 1, 1); PG8_STAGE(PG8_SA(1, 0), a3, voffA);
;             PG8_BAR; PG8_WAIT_L(0); PG8_MMA(1, 0, At, B0); PG8_BAR; PG8_SCHED;
;             PG8_STAGE(PG8_SB(1, 1), b3 + hstep, voffB);
;             PG8_WAIT_V(6); PG8_BAR; PG8_MMA(1, 1, At, B1); PG8_BAR;
	s_waitcnt lgkmcnt(0)
	s_setprio 1
	v_mfma_f32_16x16x32_bf16 v[124:127], v[150:153], v[170:173], v[124:127]
	v_mfma_f32_16x16x32_bf16 v[120:123], v[162:165], v[170:173], v[120:123]
	v_mfma_f32_16x16x32_bf16 v[108:111], v[150:153], v[178:181], v[108:111]
	v_mfma_f32_16x16x32_bf16 v[104:107], v[162:165], v[178:181], v[104:107]
	v_mfma_f32_16x16x32_bf16 v[92:95], v[150:153], v[194:197], v[92:95]
	v_mfma_f32_16x16x32_bf16 v[88:91], v[162:165], v[194:197], v[88:91]
	v_mfma_f32_16x16x32_bf16 v[76:79], v[150:153], v[202:205], v[76:79]
	v_mfma_f32_16x16x32_bf16 v[72:75], v[162:165], v[202:205], v[72:75]
	v_mfma_f32_16x16x32_bf16 v[124:127], v[154:157], v[174:177], v[124:127]
	v_mfma_f32_16x16x32_bf16 v[120:123], v[166:169], v[174:177], v[120:123]
	v_mfma_f32_16x16x32_bf16 v[108:111], v[154:157], v[188:191], v[108:111]
	v_mfma_f32_16x16x32_bf16 v[104:107], v[166:169], v[188:191], v[104:107]
	v_mfma_f32_16x16x32_bf16 v[92:95], v[154:157], v[198:201], v[92:95]
	v_mfma_f32_16x16x32_bf16 v[88:91], v[166:169], v[198:201], v[88:91]
	v_mfma_f32_16x16x32_bf16 v[76:79], v[154:157], v[206:209], v[76:79]
	v_mfma_f32_16x16x32_bf16 v[72:75], v[166:169], v[206:209], v[72:75]
	s_setprio 0
	s_barrier
	s_add_i32 s5, 0, 0x1c000
	s_add_i32 s0, s4, s52
	s_add_i32 m0, s0, 0xffffff80
	ds_read_b128 v[210:213], v159
	ds_read_b128 v[214:217], v159 offset:1024
	ds_read_b128 v[218:221], v159 offset:2048
	global_load_lds_dwordx4 v130, s[42:43] offset:128
	s_add_i32 m0, s0, 0x1f80
	ds_read_b128 v[222:225], v159 offset:3072
	global_load_lds_dwordx4 v134, s[42:43] offset:128
	s_barrier
	s_waitcnt lgkmcnt(0)
	s_setprio 1
	v_mfma_f32_16x16x32_bf16 v[116:119], v[210:213], v[170:173], v[116:119]
	v_mfma_f32_16x16x32_bf16 v[112:115], v[218:221], v[170:173], v[112:115]
	v_mfma_f32_16x16x32_bf16 v[100:103], v[210:213], v[178:181], v[100:103]
	v_mfma_f32_16x16x32_bf16 v[96:99], v[218:221], v[178:181], v[96:99]
	v_mfma_f32_16x16x32_bf16 v[84:87], v[210:213], v[194:197], v[84:87]
	v_mfma_f32_16x16x32_bf16 v[80:83], v[218:221], v[194:197], v[80:83]
	v_mfma_f32_16x16x32_bf16 v[68:71], v[210:213], v[202:205], v[68:71]
	v_mfma_f32_16x16x32_bf16 v[64:67], v[218:221], v[202:205], v[64:67]
	v_mfma_f32_16x16x32_bf16 v[116:119], v[214:217], v[174:177], v[116:119]
	v_mfma_f32_16x16x32_bf16 v[112:115], v[222:225], v[174:177], v[112:115]
	v_mfma_f32_16x16x32_bf16 v[100:103], v[214:217], v[188:191], v[100:103]
	v_mfma_f32_16x16x32_bf16 v[96:99], v[222:225], v[188:191], v[96:99]
	v_mfma_f32_16x16x32_bf16 v[84:87], v[214:217], v[198:201], v[84:87]
	v_mfma_f32_16x16x32_bf16 v[80:83], v[222:225], v[198:201], v[80:83]
	v_mfma_f32_16x16x32_bf16 v[68:71], v[214:217], v[206:209], v[68:71]
	v_mfma_f32_16x16x32_bf16 v[64:67], v[222:225], v[206:209], v[64:67]
	s_setprio 0
	s_add_i32 m0, s59, 0xffffff80
	s_barrier
	ds_read_b128 v[170:173], v148 offset:49152
	ds_read_b128 v[174:177], v148 offset:50176
	ds_read_b128 v[178:181], v148 offset:51200
	ds_read_b128 v[188:191], v148 offset:52224
	ds_read_b128 v[194:197], v148 offset:53248
	ds_read_b128 v[198:201], v148 offset:54272
	ds_read_b128 v[202:205], v148 offset:55296
	global_load_lds_dwordx4 v128, s[44:45] offset:128
	s_add_i32 m0, s60, 0xffffff80
	ds_read_b128 v[206:209], v148 offset:56320
	global_load_lds_dwordx4 v132, s[44:45] offset:128
	s_barrier
	s_waitcnt lgkmcnt(0)
	s_setprio 1
	v_mfma_f32_16x16x32_bf16 v[60:63], v[150:153], v[170:173], v[60:63]
	v_mfma_f32_16x16x32_bf16 v[56:59], v[162:165], v[170:173], v[56:59]
	v_mfma_f32_16x16x32_bf16 v[44:47], v[150:153], v[178:181], v[44:47]
	v_mfma_f32_16x16x32_bf16 v[40:43], v[162:165], v[178:181], v[40:43]
	v_mfma_f32_16x16x32_bf16 v[28:31], v[150:153], v[194:197], v[28:31]
	v_mfma_f32_16x16x32_bf16 v[24:27], v[162:165], v[194:197], v[24:27]
	v_mfma_f32_16x16x32_bf16 v[12:15], v[150:153], v[202:205], v[12:15]
	v_mfma_f32_16x16x32_bf16 v[8:11], v[162:165], v[202:205], v[8:11]
	v_mfma_f32_16x16x32_bf16 v[60:63], v[154:157], v[174:177], v[60:63]
	v_mfma_f32_16x16x32_bf16 v[56:59], v[166:169], v[174:177], v[56:59]
	v_mfma_f32_16x16x32_bf16 v[44:47], v[154:157], v[188:191], v[44:47]
	v_mfma_f32_16x16x32_bf16 v[40:43], v[166:169], v[188:191], v[40:43]
	v_mfma_f32_16x16x32_bf16 v[28:31], v[154:157], v[198:201], v[28:31]
	v_mfma_f32_16x16x32_bf16 v[24:27], v[166:169], v[198:201], v[24:27]
	v_mfma_f32_16x16x32_bf16 v[12:15], v[154:157], v[206:209], v[12:15]
	v_mfma_f32_16x16x32_bf16 v[8:11], v[166:169], v[206:209], v[8:11]
	s_setprio 0
	s_barrier
	s_add_i32 s4, s5, s52
	s_mov_b32 m0, s4
	s_add_u32 s0, s42, 0x80080
	s_addc_u32 s1, s43, 0
	global_load_lds_dwordx4 v130, s[0:1]
	s_add_i32 m0, s4, 0x2000
	s_nop 0
	global_load_lds_dwordx4 v134, s[0:1]
	s_add_i32 s69, s69, 2
	s_add_u32 s40, s40, 0x100
	s_addc_u32 s41, s41, 0
	s_add_u32 s67, s67, 0x100
	s_addc_u32 s68, s68, 0
	s_cmp_gt_u32 s69, 29
	s_waitcnt vmcnt(6)
	s_barrier
	s_setprio 1
	v_mfma_f32_16x16x32_bf16 v[52:55], v[210:213], v[170:173], v[52:55]
	v_mfma_f32_16x16x32_bf16 v[48:51], v[218:221], v[170:173], v[48:51]
	v_mfma_f32_16x16x32_bf16 v[36:39], v[210:213], v[178:181], v[36:39]
	v_mfma_f32_16x16x32_bf16 v[32:35], v[218:221], v[178:181], v[32:35]
	v_mfma_f32_16x16x32_bf16 v[20:23], v[210:213], v[194:197], v[20:23]
	v_mfma_f32_16x16x32_bf16 v[16:19], v[218:221], v[194:197], v[16:19]
	v_mfma_f32_16x16x32_bf16 v[4:7], v[210:213], v[202:205], v[4:7]
	v_mfma_f32_16x16x32_bf16 v[0:3], v[218:221], v[202:205], v[0:3]
	v_mfma_f32_16x16x32_bf16 v[52:55], v[214:217], v[174:177], v[52:55]
	v_mfma_f32_16x16x32_bf16 v[48:51], v[222:225], v[174:177], v[48:51]
	v_mfma_f32_16x16x32_bf16 v[36:39], v[214:217], v[188:191], v[36:39]
	v_mfma_f32_16x16x32_bf16 v[32:35], v[222:225], v[188:191], v[32:35]
	v_mfma_f32_16x16x32_bf16 v[20:23], v[214:217], v[198:201], v[20:23]
	v_mfma_f32_16x16x32_bf16 v[16:19], v[222:225], v[198:201], v[16:19]
	v_mfma_f32_16x16x32_bf16 v[4:7], v[214:217], v[206:209], v[4:7]
	v_mfma_f32_16x16x32_bf16 v[0:3], v[222:225], v[206:209], v[0:3]
	s_setprio 0
	s_barrier
	s_cbranch_scc0 .LBB0_219

;     DI size_t aoff(const Unit& u, size_t tstep) const { return (size_t)u.pm * tstep; }
;     DI size_t boff(const Unit& u, size_t tstep) const { return (size_t)u.pn * tstep; }
;     DI bool next(int i, Unit& u) const { const long L = (long)i * G + c; if (L >= np) return false; u.pm = pmv; u.pn = (int)(L % nN); u.ks = (int)(L / nN); return true; }
;     DI size_t aoff(const Unit& u, size_t) const { return (size_t)u.ks * kbytes; }
;     DI size_t boff(const Unit& u, size_t tstep) const { return (size_t)u.pn * tstep + (size_t)u.ks * kbytes; }
;     DI bool next(int i, Unit& u) const { Unit t; if (!S.next(i / 3, t)) return false; u.pm = t.pm; u.pn = t.pn; u.ks = i % 3; return true; }
;     DI size_t aoff(const Unit& u, size_t tstep) const { return (u.ks < 2 ? offU : offOA) + (size_t)u.pm * tstep; }
; #define PG8_WAIT_V(n) asm volatile("s_waitcnt vmcnt(" #n ")" ::: "memory")
; template <class Epi, class Sched>
; DI void gemm_phase(LAS unsigned char* lds, const Gemm g, const Sched& S, const Epi& E) {
;     ...
;         const bool has_next = S.next(ui + 1, nxt);
;         const char* nA = has_next ? (const char*)g.A + S.aoff(nxt, tstep) : cA; const char* nB = has_next ? (const char*)g.Bt + S.boff(nxt, tstep) : cB;
;         for (int t = 0; t < nt; t += 2) {
;             if constexpr (Epi::HAS_MID) { if (t == E.mid_t(nt)) { int fr3 = fr, fq3 = fq; asm volatile("" : "+v"(fr3), "+v"(fq3)); E.mid(acc, cur, wr, wc, fr3, fq3); } }
;             const bool last = (t == nt - 2);
;             const char* a1 = cA + (size_t)(t + 1) * kstep;
;             const char* a2 = last ? nA : cA + (size_t)(t + 2) * kstep; const char* b2 = last ? nB : cB + (size_t)(t + 2) * kstep;
;             const char* a3 = a2 + kstep; const char* b3 = b2 + kstep;
;             PG8_LDB(B0, 0, 0); PG8_SCHED; PG8_LDA(At, 0, 0); PG8_STAGE(PG8_SA(1, 1), a1 + hstep, voffA);
;             PG8_WAIT_L(8); PG8_BAR; PG8_WAIT_L(0); PG8_MMA(0, 0, At, B0); PG8_BAR; PG8_SCHED;
;             PG8_LDB(B1, 0, 1); PG8_STAGE(PG8_SB(0, 0), b2, voffB);
;             PG8_BAR; PG8_WAIT_L(0); PG8_MMA(0, 1, At, B1); PG8_BAR;
;             PG8_LDA(At, 0, 1); PG8_STAGE(PG8_SA(0, 0), a2, voffA);
;             PG8_BAR; PG8_WAIT_L(0); PG8_MMA(1, 0, At, B0); PG8_BAR; PG8_SCHED;
;             PG8_STAGE(PG8_SB(0, 1), b2 + hstep, voffB);
;             PG8_WAIT_V(6); PG8_BAR; PG8_MMA(1, 1, At, B1); PG8_BAR;
.LBB0_325:
	s_add_u32 s28, s40, s28
	s_addc_u32 s29, s41, s29
	s_and_b64 s[0:1], s[8:9], exec
	s_cselect_b32 s15, s29, s39
	s_cselect_b32 s17, s28, s38
	s_add_u32 s8, s38, 0x160080
	s_addc_u32 s9, s39, 0
	s_add_u32 s66, s36, 0x100
	v_mov_b32_e32 v0, 0
	s_addc_u32 s67, s37, 0
	s_mov_b32 s68, -2
	ds_read_b128 v[150:153], v141
	ds_read_b128 v[154:157], v141 offset:1024
	ds_read_b128 v[162:165], v141 offset:2048
	ds_read_b128 v[166:169], v141 offset:3072
	s_mov_b32 m0, s58
	ds_read_b128 v[170:173], v142
	ds_read_b128 v[174:177], v142 offset:1024
	ds_read_b128 v[178:181], v142 offset:2048
	ds_read_b128 v[188:191], v142 offset:3072
	ds_read_b128 v[194:197], v142 offset:4096
	ds_read_b128 v[198:201], v142 offset:5120
	ds_read_b128 v[202:205], v142 offset:6144
	global_load_lds_dwordx4 v132, s[8:9]
	s_mov_b32 m0, s59
	ds_read_b128 v[206:209], v142 offset:7168
	global_load_lds_dwordx4 v134, s[8:9]
	s_add_u32 s0, s8, 0xffea0080
	s_addc_u32 s1, s9, -1
	s_cmp_eq_u32 s68, 4
	s_cselect_b32 s39, s15, s1
	s_cselect_b32 s38, s17, s0
	s_cselect_b32 s37, s19, s67
	s_cselect_b32 s36, s18, s66
	s_waitcnt lgkmcnt(8)
	s_barrier
	s_waitcnt lgkmcnt(0)
	s_setprio 1
	v_mfma_f32_16x16x32_bf16 v[124:127], v[150:153], v[170:173], 0
	v_mfma_f32_16x16x32_bf16 v[120:123], v[162:165], v[170:173], 0
	v_mfma_f32_16x16x32_bf16 v[116:119], v[150:153], v[178:181], 0
	v_mfma_f32_16x16x32_bf16 v[112:115], v[162:165], v[178:181], 0
	v_mfma_f32_16x16x32_bf16 v[104:107], v[150:153], v[194:197], 0
	v_mfma_f32_16x16x32_bf16 v[96:99], v[162:165], v[194:197], 0
	v_mfma_f32_16x16x32_bf16 v[88:91], v[150:153], v[202:205], 0
	v_mfma_f32_16x16x32_bf16 v[80:83], v[162:165], v[202:205], 0
	v_mfma_f32_16x16x32_bf16 v[124:127], v[154:157], v[174:177], v[124:127]
	v_mfma_f32_16x16x32_bf16 v[120:123], v[166:169], v[174:177], v[120:123]
	v_mfma_f32_16x16x32_bf16 v[116:119], v[154:157], v[188:191], v[116:119]
	v_mfma_f32_16x16x32_bf16 v[112:115], v[166:169], v[188:191], v[112:115]
	v_mfma_f32_16x16x32_bf16 v[104:107], v[154:157], v[198:201], v[104:107]
	v_mfma_f32_16x16x32_bf16 v[96:99], v[166:169], v[198:201], v[96:99]
	v_mfma_f32_16x16x32_bf16 v[88:91], v[154:157], v[206:209], v[88:91]
	v_mfma_f32_16x16x32_bf16 v[80:83], v[166:169], v[206:209], v[80:83]
	s_setprio 0
	s_barrier
	s_mov_b32 m0, s60
	ds_read_b128 v[210:213], v143
	ds_read_b128 v[214:217], v143 offset:1024
	ds_read_b128 v[218:221], v143 offset:2048
	global_load_lds_dwordx4 v130, s[36:37]
	s_mov_b32 m0, s61
	ds_read_b128 v[222:225], v143 offset:3072
	global_load_lds_dwordx4 v128, s[36:37]
	s_barrier
	s_waitcnt lgkmcnt(0)
	s_setprio 1
	v_mfma_f32_16x16x32_bf16 v[108:111], v[210:213], v[170:173], 0
	v_mfma_f32_16x16x32_bf16 v[100:103], v[218:221], v[170:173], 0
	v_mfma_f32_16x16x32_bf16 v[92:95], v[210:213], v[178:181], 0
	v_mfma_f32_16x16x32_bf16 v[84:87], v[218:221], v[178:181], 0
	v_mfma_f32_16x16x32_bf16 v[76:79], v[210:213], v[194:197], 0
	v_mfma_f32_16x16x32_bf16 v[72:75], v[218:221], v[194:197], 0
	v_mfma_f32_16x16x32_bf16 v[68:71], v[210:213], v[202:205], 0
	v_mfma_f32_16x16x32_bf16 v[64:67], v[218:221], v[202:205], 0
	v_mfma_f32_16x16x32_bf16 v[108:111], v[214:217], v[174:177], v[108:111]
	v_mfma_f32_16x16x32_bf16 v[100:103], v[222:225], v[174:177], v[100:103]
	v_mfma_f32_16x16x32_bf16 v[92:95], v[214:217], v[188:191], v[92:95]
	v_mfma_f32_16x16x32_bf16 v[84:87], v[222:225], v[188:191], v[84:87]
	v_mfma_f32_16x16x32_bf16 v[76:79], v[214:217], v[198:201], v[76:79]
	v_mfma_f32_16x16x32_bf16 v[72:75], v[222:225], v[198:201], v[72:75]
	v_mfma_f32_16x16x32_bf16 v[68:71], v[214:217], v[206:209], v[68:71]
	v_mfma_f32_16x16x32_bf16 v[64:67], v[222:225], v[206:209], v[64:67]
	s_setprio 0
	s_mov_b32 m0, s42
	s_barrier
	ds_read_b128 v[170:173], v142 offset:16384
	ds_read_b128 v[174:177], v142 offset:17408
	ds_read_b128 v[178:181], v142 offset:18432
	ds_read_b128 v[188:191], v142 offset:19456
	ds_read_b128 v[194:197], v142 offset:20480
	ds_read_b128 v[198:201], v142 offset:21504
	ds_read_b128 v[202:205], v142 offset:22528
	global_load_lds_dwordx4 v130, s[38:39]
	s_mov_b32 m0, s43
	ds_read_b128 v[206:209], v142 offset:23552
	global_load_lds_dwordx4 v128, s[38:39]
	s_barrier
	s_waitcnt lgkmcnt(0)
	s_setprio 1
	v_mfma_f32_16x16x32_bf16 v[60:63], v[150:153], v[170:173], 0
	v_mfma_f32_16x16x32_bf16 v[56:59], v[162:165], v[170:173], 0
	v_mfma_f32_16x16x32_bf16 v[52:55], v[150:153], v[178:181], 0
	v_mfma_f32_16x16x32_bf16 v[48:51], v[162:165], v[178:181], 0
	v_mfma_f32_16x16x32_bf16 v[40:43], v[150:153], v[194:197], 0
	v_mfma_f32_16x16x32_bf16 v[32:35], v[162:165], v[194:197], 0
	v_mfma_f32_16x16x32_bf16 v[24:27], v[150:153], v[202:205], 0
	v_mfma_f32_16x16x32_bf16 v[16:19], v[162:165], v[202:205], 0
	v_mfma_f32_16x16x32_bf16 v[60:63], v[154:157], v[174:177], v[60:63]
	v_mfma_f32_16x16x32_bf16 v[56:59], v[166:169], v[174:177], v[56:59]
	v_mfma_f32_16x16x32_bf16 v[52:55], v[154:157], v[188:191], v[52:55]
	v_mfma_f32_16x16x32_bf16 v[48:51], v[166:169], v[188:191], v[48:51]
	v_mfma_f32_16x16x32_bf16 v[40:43], v[154:157], v[198:201], v[40:43]
	v_mfma_f32_16x16x32_bf16 v[32:35], v[166:169], v[198:201], v[32:35]
	v_mfma_f32_16x16x32_bf16 v[24:27], v[154:157], v[206:209], v[24:27]
	v_mfma_f32_16x16x32_bf16 v[16:19], v[166:169], v[206:209], v[16:19]
	s_setprio 0
	s_barrier
	s_add_u32 s0, s36, 0x160000
	s_addc_u32 s1, s37, 0
	s_mov_b32 m0, s62
	s_nop 0
	global_load_lds_dwordx4 v130, s[0:1]
	s_mov_b32 m0, s63
	s_nop 0
	global_load_lds_dwordx4 v128, s[0:1]
	s_waitcnt vmcnt(6)
	s_barrier
; #define PG8_STAGE(bufoff, gbase, voff) do { _Pragma("unroll") for (int _i = 0; _i < 2; ++_i) \
;         __builtin_amdgcn_global_load_lds((const unsigned*)((const char*)(gbase) + (voff)[_i]), (LAS unsigned*)(lds + (bufoff) + ldsw + _i * 8192), 16, 0, 0); } while (0)
; #define PG8_LDA(dst, b, h) do { _Pragma("unroll") for (int m = 0; m < 4; ++m) _Pragma("unroll") for (int k = 0; k < 2; ++k) dst[m][k] = *(const LAS bf16x8*)(lds + PG8_SA(b, h) + aoff + m * 2048 + k * 1024); } while (0)
; #define PG8_LDB(dst, b, h) do { _Pragma("unroll") for (int n = 0; n < 2; ++n) _Pragma("unroll") for (int k = 0; k < 2; ++k) dst[n][k] = *(const LAS bf16x8*)(lds + PG8_SB(b, h) + boff + n * 2048 + k * 1024); } while (0)
; #define PG8_MMA(ai, bj, At, Bt) do { __builtin_amdgcn_s_setprio(1); _Pragma("unroll") for (int m = 0; m < 4; ++m) _Pragma("unroll") for (int n = 0; n < 2; ++n) _Pragma("unroll") for (int k = 0; k < 2; ++k) \
;         acc[ai][bj][m][n] = __builtin_amdgcn_mfma_f32_16x16x32_bf16(Bt[n][k], At[m][k], acc[ai][bj][m][n], 0, 0, 0); __builtin_amdgcn_s_setprio(0); } while (0)
; #define PG8_WAIT_V(n) asm volatile("s_waitcnt vmcnt(" #n ")" ::: "memory")
; #define PG8_WAIT_L(n) asm volatile("s_waitcnt lgkmcnt(" #n ")" ::: "memory")
; #define PG8_BAR __builtin_amdgcn_s_barrier()
; #define PG8_SCHED __builtin_amdgcn_sched_barrier(0)
; template <class Epi, class Sched>
; DI void gemm_phase(LAS unsigned char* lds, const Gemm g, const Sched& S, const Epi& E) {
;     ...
;             PG8_WAIT_V(6); PG8_BAR; PG8_MMA(1, 1, At, B1); PG8_BAR;
;             PG8_LDB(B0, 1, 0); PG8_SCHED; PG8_LDA(At, 1, 0); PG8_STAGE(PG8_SA(0, 1), a2 + hstep, voffA);
;             PG8_WAIT_L(8); PG8_BAR; PG8_WAIT_L(0); PG8_MMA(0, 0, At, B0); PG8_BAR; PG8_SCHED;
;             PG8_LDB(B1, 1, 1); PG8_STAGE(PG8_SB(1, 0), b3, voffB);
;             PG8_BAR; PG8_WAIT_L(0); PG8_MMA(0, 1, At, B1); PG8_BAR;
;             PG8_LDA(At, 1, 1); PG8_STAGE(PG8_SA(1, 0), a3, voffA);
;             PG8_BAR; PG8_WAIT_L(0); PG8_MMA(1, 0, At, B0); PG8_BAR; PG8_SCHED;
;             PG8_STAGE(PG8_SB(1, 1), b3 + hstep, voffB);
;             PG8_WAIT_V(6); PG8_BAR; PG8_MMA(1, 1, At, B1); PG8_BAR;
	s_setprio 1
	v_mfma_f32_16x16x32_bf16 v[44:47], v[210:213], v[170:173], 0
	v_mfma_f32_16x16x32_bf16 v[36:39], v[218:221], v[170:173], 0
	v_mfma_f32_16x16x32_bf16 v[28:31], v[210:213], v[178:181], 0
	v_mfma_f32_16x16x32_bf16 v[20:23], v[218:221], v[178:181], 0
	v_mfma_f32_16x16x32_bf16 v[12:15], v[210:213], v[194:197], 0
	v_mfma_f32_16x16x32_bf16 v[8:11], v[218:221], v[194:197], 0
	v_mfma_f32_16x16x32_bf16 v[4:7], v[210:213], v[202:205], 0
	v_mfma_f32_16x16x32_bf16 v[0:3], v[218:221], v[202:205], 0
	v_mfma_f32_16x16x32_bf16 v[44:47], v[214:217], v[174:177], v[44:47]
	v_mfma_f32_16x16x32_bf16 v[36:39], v[222:225], v[174:177], v[36:39]
	v_mfma_f32_16x16x32_bf16 v[28:31], v[214:217], v[188:191], v[28:31]
	v_mfma_f32_16x16x32_bf16 v[20:23], v[222:225], v[188:191], v[20:23]
	v_mfma_f32_16x16x32_bf16 v[12:15], v[214:217], v[198:201], v[12:15]
	v_mfma_f32_16x16x32_bf16 v[8:11], v[222:225], v[198:201], v[8:11]
	v_mfma_f32_16x16x32_bf16 v[4:7], v[214:217], v[206:209], v[4:7]
	v_mfma_f32_16x16x32_bf16 v[0:3], v[222:225], v[206:209], v[0:3]
	s_setprio 0
	s_barrier
	ds_read_b128 v[150:153], v144
	ds_read_b128 v[154:157], v144 offset:1024
	ds_read_b128 v[162:165], v144 offset:2048
	ds_read_b128 v[166:169], v144 offset:3072
	s_add_u32 s0, s38, 0x160000
	s_addc_u32 s1, s39, 0
	s_mov_b32 m0, s44
	ds_read_b128 v[170:173], v142 offset:32768
	ds_read_b128 v[174:177], v142 offset:33792
	ds_read_b128 v[178:181], v142 offset:34816
	ds_read_b128 v[188:191], v142 offset:35840
	ds_read_b128 v[194:197], v142 offset:36864
	ds_read_b128 v[198:201], v142 offset:37888
	ds_read_b128 v[202:205], v142 offset:38912
	global_load_lds_dwordx4 v130, s[0:1]
	s_mov_b32 m0, s45
	ds_read_b128 v[206:209], v142 offset:39936
	global_load_lds_dwordx4 v128, s[0:1]
	s_waitcnt lgkmcnt(8)
	s_barrier
	s_waitcnt lgkmcnt(0)
	s_setprio 1
	v_mfma_f32_16x16x32_bf16 v[124:127], v[150:153], v[170:173], v[124:127]
	v_mfma_f32_16x16x32_bf16 v[120:123], v[162:165], v[170:173], v[120:123]
	v_mfma_f32_16x16x32_bf16 v[116:119], v[150:153], v[178:181], v[116:119]
	v_mfma_f32_16x16x32_bf16 v[112:115], v[162:165], v[178:181], v[112:115]
	v_mfma_f32_16x16x32_bf16 v[104:107], v[150:153], v[194:197], v[104:107]
	v_mfma_f32_16x16x32_bf16 v[96:99], v[162:165], v[194:197], v[96:99]
	v_mfma_f32_16x16x32_bf16 v[88:91], v[150:153], v[202:205], v[88:91]
	v_mfma_f32_16x16x32_bf16 v[80:83], v[162:165], v[202:205], v[80:83]
	v_mfma_f32_16x16x32_bf16 v[124:127], v[154:157], v[174:177], v[124:127]
	v_mfma_f32_16x16x32_bf16 v[120:123], v[166:169], v[174:177], v[120:123]
	v_mfma_f32_16x16x32_bf16 v[116:119], v[154:157], v[188:191], v[116:119]
	v_mfma_f32_16x16x32_bf16 v[112:115], v[166:169], v[188:191], v[112:115]
	v_mfma_f32_16x16x32_bf16 v[104:107], v[154:157], v[198:201], v[104:107]
	v_mfma_f32_16x16x32_bf16 v[96:99], v[166:169], v[198:201], v[96:99]
	v_mfma_f32_16x16x32_bf16 v[88:91], v[154:157], v[206:209], v[88:91]
	v_mfma_f32_16x16x32_bf16 v[80:83], v[166:169], v[206:209], v[80:83]
	s_setprio 0
	s_barrier
	s_add_i32 s4, 0, 0x1c000
	s_add_i32 s0, s64, s35
	v_add_u32_e32 v145, s4, v140
	s_add_i32 m0, s0, 0xffffff80
	ds_read_b128 v[210:213], v145
	ds_read_b128 v[214:217], v145 offset:1024
	ds_read_b128 v[218:221], v145 offset:2048
	global_load_lds_dwordx4 v130, s[36:37] offset:128
	s_add_i32 m0, s0, 0x1f80
	ds_read_b128 v[222:225], v145 offset:3072
	global_load_lds_dwordx4 v128, s[36:37] offset:128
	s_barrier
	s_waitcnt lgkmcnt(0)
	s_setprio 1
	v_mfma_f32_16x16x32_bf16 v[108:111], v[210:213], v[170:173], v[108:111]
	v_mfma_f32_16x16x32_bf16 v[100:103], v[218:221], v[170:173], v[100:103]
	v_mfma_f32_16x16x32_bf16 v[92:95], v[210:213], v[178:181], v[92:95]
	v_mfma_f32_16x16x32_bf16 v[84:87], v[218:221], v[178:181], v[84:87]
	v_mfma_f32_16x16x32_bf16 v[76:79], v[210:213], v[194:197], v[76:79]
	v_mfma_f32_16x16x32_bf16 v[72:75], v[218:221], v[194:197], v[72:75]
	v_mfma_f32_16x16x32_bf16 v[68:71], v[210:213], v[202:205], v[68:71]
	v_mfma_f32_16x16x32_bf16 v[64:67], v[218:221], v[202:205], v[64:67]
	v_mfma_f32_16x16x32_bf16 v[108:111], v[214:217], v[174:177], v[108:111]
	v_mfma_f32_16x16x32_bf16 v[100:103], v[222:225], v[174:177], v[100:103]
	v_mfma_f32_16x16x32_bf16 v[92:95], v[214:217], v[188:191], v[92:95]
	v_mfma_f32_16x16x32_bf16 v[84:87], v[222:225], v[188:191], v[84:87]
	v_mfma_f32_16x16x32_bf16 v[76:79], v[214:217], v[198:201], v[76:79]
	v_mfma_f32_16x16x32_bf16 v[72:75], v[222:225], v[198:201], v[72:75]
	v_mfma_f32_16x16x32_bf16 v[68:71], v[214:217], v[206:209], v[68:71]
	v_mfma_f32_16x16x32_bf16 v[64:67], v[222:225], v[206:209], v[64:67]
	s_setprio 0
	s_add_i32 m0, s56, 0xffffff80
	s_barrier
	ds_read_b128 v[170:173], v142 offset:49152
	ds_read_b128 v[174:177], v142 offset:50176
	ds_read_b128 v[178:181], v142 offset:51200
	ds_read_b128 v[188:191], v142 offset:52224
	ds_read_b128 v[194:197], v142 offset:53248
	ds_read_b128 v[198:201], v142 offset:54272
	ds_read_b128 v[202:205], v142 offset:55296
	global_load_lds_dwordx4 v130, s[38:39] offset:128
	s_add_i32 m0, s57, 0xffffff80
	ds_read_b128 v[206:209], v142 offset:56320
	global_load_lds_dwordx4 v128, s[38:39] offset:128
	s_barrier
; #define PG8_STAGE(bufoff, gbase, voff) do { _Pragma("unroll") for (int _i = 0; _i < 2; ++_i) \
;         __builtin_amdgcn_global_load_lds((const unsigned*)((const char*)(gbase) + (voff)[_i]), (LAS unsigned*)(lds + (bufoff) + ldsw + _i * 8192), 16, 0, 0); } while (0)
; #define PG8_LDA(dst, b, h) do { _Pragma("unroll") for (int m = 0; m < 4; ++m) _Pragma("unroll") for (int k = 0; k < 2; ++k) dst[m][k] = *(const LAS bf16x8*)(lds + PG8_SA(b, h) + aoff + m * 2048 + k * 1024); } while (0)
; #define PG8_LDB(dst, b, h) do { _Pragma("unroll") for (int n = 0; n < 2; ++n) _Pragma("unroll") for (int k = 0; k < 2; ++k) dst[n][k] = *(const LAS bf16x8*)(lds + PG8_SB(b, h) + boff + n * 2048 + k * 1024); } while (0)
; #define PG8_MMA(ai, bj, At, Bt) do { __builtin_amdgcn_s_setprio(1); _Pragma("unroll") for (int m = 0; m < 4; ++m) _Pragma("unroll") for (int n = 0; n < 2; ++n) _Pragma("unroll") for (int k = 0; k < 2; ++k) \
;         acc[ai][bj][m][n] = __builtin_amdgcn_mfma_f32_16x16x32_bf16(Bt[n][k], At[m][k], acc[ai][bj][m][n], 0, 0, 0); __builtin_amdgcn_s_setprio(0); } while (0)
; #define PG8_WAIT_V(n) asm volatile("s_waitcnt vmcnt(" #n ")" ::: "memory")
; #define PG8_WAIT_L(n) asm volatile("s_waitcnt lgkmcnt(" #n ")" ::: "memory")
; #define PG8_BAR __builtin_amdgcn_s_barrier()
; #define PG8_SCHED __builtin_amdgcn_sched_barrier(0)
; template <class Epi, class Sched>
; DI void gemm_phase(LAS unsigned char* lds, const Gemm g, const Sched& S, const Epi& E) {
;     ...
;             PG8_LDB(B0, 0, 0); PG8_SCHED; PG8_LDA(At, 0, 0); PG8_STAGE(PG8_SA(1, 1), a1 + hstep, voffA);
;             PG8_WAIT_L(8); PG8_BAR; PG8_WAIT_L(0); PG8_MMA(0, 0, At, B0); PG8_BAR; PG8_SCHED;
;             PG8_LDB(B1, 0, 1); PG8_STAGE(PG8_SB(0, 0), b2, voffB);
;     ...
;             PG8_BAR; PG8_WAIT_L(0); PG8_MMA(0, 1, At, B1); PG8_BAR;
;             PG8_LDA(At, 1, 1); PG8_STAGE(PG8_SA(1, 0), a3, voffA);
;             PG8_BAR; PG8_WAIT_L(0); PG8_MMA(1, 0, At, B0); PG8_BAR; PG8_SCHED;
;             PG8_STAGE(PG8_SB(1, 1), b3 + hstep, voffB);
;             PG8_WAIT_V(6); PG8_BAR; PG8_MMA(1, 1, At, B1); PG8_BAR;
	s_waitcnt lgkmcnt(0)
	s_setprio 1
	v_mfma_f32_16x16x32_bf16 v[60:63], v[150:153], v[170:173], v[60:63]
	v_mfma_f32_16x16x32_bf16 v[56:59], v[162:165], v[170:173], v[56:59]
	v_mfma_f32_16x16x32_bf16 v[52:55], v[150:153], v[178:181], v[52:55]
	v_mfma_f32_16x16x32_bf16 v[48:51], v[162:165], v[178:181], v[48:51]
	v_mfma_f32_16x16x32_bf16 v[40:43], v[150:153], v[194:197], v[40:43]
	v_mfma_f32_16x16x32_bf16 v[32:35], v[162:165], v[194:197], v[32:35]
	v_mfma_f32_16x16x32_bf16 v[24:27], v[150:153], v[202:205], v[24:27]
	v_mfma_f32_16x16x32_bf16 v[16:19], v[162:165], v[202:205], v[16:19]
	v_mfma_f32_16x16x32_bf16 v[60:63], v[154:157], v[174:177], v[60:63]
	v_mfma_f32_16x16x32_bf16 v[56:59], v[166:169], v[174:177], v[56:59]
	v_mfma_f32_16x16x32_bf16 v[52:55], v[154:157], v[188:191], v[52:55]
	v_mfma_f32_16x16x32_bf16 v[48:51], v[166:169], v[188:191], v[48:51]
	v_mfma_f32_16x16x32_bf16 v[40:43], v[154:157], v[198:201], v[40:43]
	v_mfma_f32_16x16x32_bf16 v[32:35], v[166:169], v[198:201], v[32:35]
	v_mfma_f32_16x16x32_bf16 v[24:27], v[154:157], v[206:209], v[24:27]
	v_mfma_f32_16x16x32_bf16 v[16:19], v[166:169], v[206:209], v[16:19]
	s_setprio 0
	s_barrier
	s_add_i32 s4, s4, s35
	s_mov_b32 m0, s4
	s_add_u32 s0, s36, 0x160080
	s_addc_u32 s1, s37, 0
	global_load_lds_dwordx4 v130, s[0:1]
	s_add_i32 m0, s4, 0x2000
	s_nop 0
	global_load_lds_dwordx4 v128, s[0:1]
	s_add_i32 s68, s68, 2
	s_add_u32 s8, s8, 0x100
	s_addc_u32 s9, s9, 0
	s_add_u32 s66, s66, 0x100
	s_addc_u32 s67, s67, 0
	s_cmp_gt_u32 s68, 5
	s_waitcnt vmcnt(6)
	s_barrier
	s_setprio 1
	v_mfma_f32_16x16x32_bf16 v[44:47], v[210:213], v[170:173], v[44:47]
	v_mfma_f32_16x16x32_bf16 v[36:39], v[218:221], v[170:173], v[36:39]
	v_mfma_f32_16x16x32_bf16 v[28:31], v[210:213], v[178:181], v[28:31]
	v_mfma_f32_16x16x32_bf16 v[20:23], v[218:221], v[178:181], v[20:23]
	v_mfma_f32_16x16x32_bf16 v[12:15], v[210:213], v[194:197], v[12:15]
	v_mfma_f32_16x16x32_bf16 v[8:11], v[218:221], v[194:197], v[8:11]
	v_mfma_f32_16x16x32_bf16 v[4:7], v[210:213], v[202:205], v[4:7]
	v_mfma_f32_16x16x32_bf16 v[0:3], v[218:221], v[202:205], v[0:3]
	v_mfma_f32_16x16x32_bf16 v[44:47], v[214:217], v[174:177], v[44:47]
	v_mfma_f32_16x16x32_bf16 v[36:39], v[222:225], v[174:177], v[36:39]
	v_mfma_f32_16x16x32_bf16 v[28:31], v[214:217], v[188:191], v[28:31]
	v_mfma_f32_16x16x32_bf16 v[20:23], v[222:225], v[188:191], v[20:23]
	v_mfma_f32_16x16x32_bf16 v[12:15], v[214:217], v[198:201], v[12:15]
	v_mfma_f32_16x16x32_bf16 v[8:11], v[222:225], v[198:201], v[8:11]
	v_mfma_f32_16x16x32_bf16 v[4:7], v[214:217], v[206:209], v[4:7]
	v_mfma_f32_16x16x32_bf16 v[0:3], v[222:225], v[206:209], v[0:3]
	s_setprio 0
	s_barrier
	s_cbranch_scc0 .LBB0_326
	s_branch .Lpeel_done_326
.LBB0_326:
	ds_read_b128 v[150:153], v141
	ds_read_b128 v[154:157], v141 offset:1024
	ds_read_b128 v[162:165], v141 offset:2048
	ds_read_b128 v[166:169], v141 offset:3072
	s_mov_b32 m0, s58
	ds_read_b128 v[170:173], v142
	ds_read_b128 v[174:177], v142 offset:1024
	ds_read_b128 v[178:181], v142 offset:2048
	ds_read_b128 v[188:191], v142 offset:3072
	ds_read_b128 v[194:197], v142 offset:4096
	ds_read_b128 v[198:201], v142 offset:5120
	ds_read_b128 v[202:205], v142 offset:6144
	global_load_lds_dwordx4 v132, s[8:9]
	s_mov_b32 m0, s59
	ds_read_b128 v[206:209], v142 offset:7168
	global_load_lds_dwordx4 v134, s[8:9]
	s_add_u32 s0, s8, 0xffea0080
	s_addc_u32 s1, s9, -1
	s_cmp_eq_u32 s68, 4
	s_cselect_b32 s39, s15, s1
	s_cselect_b32 s38, s17, s0
	s_cselect_b32 s37, s19, s67
	s_cselect_b32 s36, s18, s66
	s_waitcnt lgkmcnt(8)
	s_barrier
	s_waitcnt lgkmcnt(0)
	s_setprio 1
	v_mfma_f32_16x16x32_bf16 v[124:127], v[150:153], v[170:173], v[124:127]
	v_mfma_f32_16x16x32_bf16 v[120:123], v[162:165], v[170:173], v[120:123]
	v_mfma_f32_16x16x32_bf16 v[116:119], v[150:153], v[178:181], v[116:119]
	v_mfma_f32_16x16x32_bf16 v[112:115], v[162:165], v[178:181], v[112:115]
	v_mfma_f32_16x16x32_bf16 v[104:107], v[150:153], v[194:197], v[104:107]
	v_mfma_f32_16x16x32_bf16 v[96:99], v[162:165], v[194:197], v[96:99]
	v_mfma_f32_16x16x32_bf16 v[88:91], v[150:153], v[202:205], v[88:91]
	v_mfma_f32_16x16x32_bf16 v[80:83], v[162:165], v[202:205], v[80:83]
	v_mfma_f32_16x16x32_bf16 v[124:127], v[154:157], v[174:177], v[124:127]
	v_mfma_f32_16x16x32_bf16 v[120:123], v[166:169], v[174:177], v[120:123]
	v_mfma_f32_16x16x32_bf16 v[116:119], v[154:157], v[188:191], v[116:119]
	v_mfma_f32_16x16x32_bf16 v[112:115], v[166:169], v[188:191], v[112:115]
	v_mfma_f32_16x16x32_bf16 v[104:107], v[154:157], v[198:201], v[104:107]
	v_mfma_f32_16x16x32_bf16 v[96:99], v[166:169], v[198:201], v[96:99]
	v_mfma_f32_16x16x32_bf16 v[88:91], v[154:157], v[206:209], v[88:91]
	v_mfma_f32_16x16x32_bf16 v[80:83], v[166:169], v[206:209], v[80:83]
	s_setprio 0
	s_barrier
	s_mov_b32 m0, s60
	ds_read_b128 v[210:213], v143
	ds_read_b128 v[214:217], v143 offset:1024
	ds_read_b128 v[218:221], v143 offset:2048
	global_load_lds_dwordx4 v130, s[36:37]
	s_mov_b32 m0, s61
	ds_read_b128 v[222:225], v143 offset:3072
	global_load_lds_dwordx4 v128, s[36:37]
	s_barrier
; #define PG8_STAGE(bufoff, gbase, voff) do { _Pragma("unroll") for (int _i = 0; _i < 2; ++_i) \
;         __builtin_amdgcn_global_load_lds((const unsigned*)((const char*)(gbase) + (voff)[_i]), (LAS unsigned*)(lds + (bufoff) + ldsw + _i * 8192), 16, 0, 0); } while (0)
; #define PG8_LDA(dst, b, h) do { _Pragma("unroll") for (int m = 0; m < 4; ++m) _Pragma("unroll") for (int k = 0; k < 2; ++k) dst[m][k] = *(const LAS bf16x8*)(lds + PG8_SA(b, h) + aoff + m * 2048 + k * 1024); } while (0)
; #define PG8_LDB(dst, b, h) do { _Pragma("unroll") for (int n = 0; n < 2; ++n) _Pragma("unroll") for (int k = 0; k < 2; ++k) dst[n][k] = *(const LAS bf16x8*)(lds + PG8_SB(b, h) + boff + n * 2048 + k * 1024); } while (0)
; #define PG8_MMA(ai, bj, At, Bt) do { __builtin_amdgcn_s_setprio(1); _Pragma("unroll") for (int m = 0; m < 4; ++m) _Pragma("unroll") for (int n = 0; n < 2; ++n) _Pragma("unroll") for (int k = 0; k < 2; ++k) \
;         acc[ai][bj][m][n] = __builtin_amdgcn_mfma_f32_16x16x32_bf16(Bt[n][k], At[m][k], acc[ai][bj][m][n], 0, 0, 0); __builtin_amdgcn_s_setprio(0); } while (0)
; #define PG8_WAIT_V(n) asm volatile("s_waitcnt vmcnt(" #n ")" ::: "memory")
; #define PG8_WAIT_L(n) asm volatile("s_waitcnt lgkmcnt(" #n ")" ::: "memory")
; #define PG8_BAR __builtin_amdgcn_s_barrier()
; #define PG8_SCHED __builtin_amdgcn_sched_barrier(0)
; template <class Epi, class Sched>
; DI void gemm_phase(LAS unsigned char* lds, const Gemm g, const Sched& S, const Epi& E) {
;     ...
;             PG8_BAR; PG8_WAIT_L(0); PG8_MMA(0, 1, At, B1); PG8_BAR;
;             PG8_LDA(At, 0, 1); PG8_STAGE(PG8_SA(0, 0), a2, voffA);
;             PG8_BAR; PG8_WAIT_L(0); PG8_MMA(1, 0, At, B0); PG8_BAR; PG8_SCHED;
;             PG8_STAGE(PG8_SB(0, 1), b2 + hstep, voffB);
;             PG8_WAIT_V(6); PG8_BAR; PG8_MMA(1, 1, At, B1); PG8_BAR;
;             PG8_LDB(B0, 1, 0); PG8_SCHED; PG8_LDA(At, 1, 0); PG8_STAGE(PG8_SA(0, 1), a2 + hstep, voffA);
;             PG8_WAIT_L(8); PG8_BAR; PG8_WAIT_L(0); PG8_MMA(0, 0, At, B0); PG8_BAR; PG8_SCHED;
	s_waitcnt lgkmcnt(0)
	s_setprio 1
	v_mfma_f32_16x16x32_bf16 v[108:111], v[210:213], v[170:173], v[108:111]
	v_mfma_f32_16x16x32_bf16 v[100:103], v[218:221], v[170:173], v[100:103]
	v_mfma_f32_16x16x32_bf16 v[92:95], v[210:213], v[178:181], v[92:95]
	v_mfma_f32_16x16x32_bf16 v[84:87], v[218:221], v[178:181], v[84:87]
	v_mfma_f32_16x16x32_bf16 v[76:79], v[210:213], v[194:197], v[76:79]
	v_mfma_f32_16x16x32_bf16 v[72:75], v[218:221], v[194:197], v[72:75]
	v_mfma_f32_16x16x32_bf16 v[68:71], v[210:213], v[202:205], v[68:71]
	v_mfma_f32_16x16x32_bf16 v[64:67], v[218:221], v[202:205], v[64:67]
	v_mfma_f32_16x16x32_bf16 v[108:111], v[214:217], v[174:177], v[108:111]
	v_mfma_f32_16x16x32_bf16 v[100:103], v[222:225], v[174:177], v[100:103]
	v_mfma_f32_16x16x32_bf16 v[92:95], v[214:217], v[188:191], v[92:95]
	v_mfma_f32_16x16x32_bf16 v[84:87], v[222:225], v[188:191], v[84:87]
	v_mfma_f32_16x16x32_bf16 v[76:79], v[214:217], v[198:201], v[76:79]
	v_mfma_f32_16x16x32_bf16 v[72:75], v[222:225], v[198:201], v[72:75]
	v_mfma_f32_16x16x32_bf16 v[68:71], v[214:217], v[206:209], v[68:71]
	v_mfma_f32_16x16x32_bf16 v[64:67], v[222:225], v[206:209], v[64:67]
	s_setprio 0
	s_mov_b32 m0, s42
	s_barrier
	ds_read_b128 v[170:173], v142 offset:16384
	ds_read_b128 v[174:177], v142 offset:17408
	ds_read_b128 v[178:181], v142 offset:18432
	ds_read_b128 v[188:191], v142 offset:19456
	ds_read_b128 v[194:197], v142 offset:20480
	ds_read_b128 v[198:201], v142 offset:21504
	ds_read_b128 v[202:205], v142 offset:22528
	global_load_lds_dwordx4 v130, s[38:39]
	s_mov_b32 m0, s43
	ds_read_b128 v[206:209], v142 offset:23552
	global_load_lds_dwordx4 v128, s[38:39]
	s_barrier
	s_waitcnt lgkmcnt(0)
	s_setprio 1
	v_mfma_f32_16x16x32_bf16 v[60:63], v[150:153], v[170:173], v[60:63]
	v_mfma_f32_16x16x32_bf16 v[56:59], v[162:165], v[170:173], v[56:59]
	v_mfma_f32_16x16x32_bf16 v[52:55], v[150:153], v[178:181], v[52:55]
	v_mfma_f32_16x16x32_bf16 v[48:51], v[162:165], v[178:181], v[48:51]
	v_mfma_f32_16x16x32_bf16 v[40:43], v[150:153], v[194:197], v[40:43]
	v_mfma_f32_16x16x32_bf16 v[32:35], v[162:165], v[194:197], v[32:35]
	v_mfma_f32_16x16x32_bf16 v[24:27], v[150:153], v[202:205], v[24:27]
	v_mfma_f32_16x16x32_bf16 v[16:19], v[162:165], v[202:205], v[16:19]
	v_mfma_f32_16x16x32_bf16 v[60:63], v[154:157], v[174:177], v[60:63]
	v_mfma_f32_16x16x32_bf16 v[56:59], v[166:169], v[174:177], v[56:59]
	v_mfma_f32_16x16x32_bf16 v[52:55], v[154:157], v[188:191], v[52:55]
	v_mfma_f32_16x16x32_bf16 v[48:51], v[166:169], v[188:191], v[48:51]
	v_mfma_f32_16x16x32_bf16 v[40:43], v[154:157], v[198:201], v[40:43]
	v_mfma_f32_16x16x32_bf16 v[32:35], v[166:169], v[198:201], v[32:35]
	v_mfma_f32_16x16x32_bf16 v[24:27], v[154:157], v[206:209], v[24:27]
	v_mfma_f32_16x16x32_bf16 v[16:19], v[166:169], v[206:209], v[16:19]
	s_setprio 0
	s_barrier
	s_add_u32 s0, s36, 0x160000
	s_addc_u32 s1, s37, 0
	s_mov_b32 m0, s62
	s_nop 0
	global_load_lds_dwordx4 v130, s[0:1]
	s_mov_b32 m0, s63
	s_nop 0
	global_load_lds_dwordx4 v128, s[0:1]
	s_waitcnt vmcnt(6)
	s_barrier
	s_setprio 1
	v_mfma_f32_16x16x32_bf16 v[44:47], v[210:213], v[170:173], v[44:47]
	v_mfma_f32_16x16x32_bf16 v[36:39], v[218:221], v[170:173], v[36:39]
	v_mfma_f32_16x16x32_bf16 v[28:31], v[210:213], v[178:181], v[28:31]
	v_mfma_f32_16x16x32_bf16 v[20:23], v[218:221], v[178:181], v[20:23]
	v_mfma_f32_16x16x32_bf16 v[12:15], v[210:213], v[194:197], v[12:15]
	v_mfma_f32_16x16x32_bf16 v[8:11], v[218:221], v[194:197], v[8:11]
	v_mfma_f32_16x16x32_bf16 v[4:7], v[210:213], v[202:205], v[4:7]
	v_mfma_f32_16x16x32_bf16 v[0:3], v[218:221], v[202:205], v[0:3]
	v_mfma_f32_16x16x32_bf16 v[44:47], v[214:217], v[174:177], v[44:47]
	v_mfma_f32_16x16x32_bf16 v[36:39], v[222:225], v[174:177], v[36:39]
	v_mfma_f32_16x16x32_bf16 v[28:31], v[214:217], v[188:191], v[28:31]
	v_mfma_f32_16x16x32_bf16 v[20:23], v[222:225], v[188:191], v[20:23]
	v_mfma_f32_16x16x32_bf16 v[12:15], v[214:217], v[198:201], v[12:15]
	v_mfma_f32_16x16x32_bf16 v[8:11], v[222:225], v[198:201], v[8:11]
	v_mfma_f32_16x16x32_bf16 v[4:7], v[214:217], v[206:209], v[4:7]
	v_mfma_f32_16x16x32_bf16 v[0:3], v[222:225], v[206:209], v[0:3]
	s_setprio 0
	s_barrier
	ds_read_b128 v[150:153], v144
	ds_read_b128 v[154:157], v144 offset:1024
	ds_read_b128 v[162:165], v144 offset:2048
	ds_read_b128 v[166:169], v144 offset:3072
	s_add_u32 s0, s38, 0x160000
	s_addc_u32 s1, s39, 0
	s_mov_b32 m0, s44
	ds_read_b128 v[170:173], v142 offset:32768
	ds_read_b128 v[174:177], v142 offset:33792
	ds_read_b128 v[178:181], v142 offset:34816
	ds_read_b128 v[188:191], v142 offset:35840
	ds_read_b128 v[194:197], v142 offset:36864
	ds_read_b128 v[198:201], v142 offset:37888
	ds_read_b128 v[202:205], v142 offset:38912
	global_load_lds_dwordx4 v130, s[0:1]
	s_mov_b32 m0, s45
	ds_read_b128 v[206:209], v142 offset:39936
	global_load_lds_dwordx4 v128, s[0:1]
	s_waitcnt lgkmcnt(8)
	s_barrier
; #define PG8_STAGE(bufoff, gbase, voff) do { _Pragma("unroll") for (int _i = 0; _i < 2; ++_i) \
;         __builtin_amdgcn_global_load_lds((const unsigned*)((const char*)(gbase) + (voff)[_i]), (LAS unsigned*)(lds + (bufoff) + ldsw + _i * 8192), 16, 0, 0); } while (0)
; #define PG8_LDA(dst, b, h) do { _Pragma("unroll") for (int m = 0; m < 4; ++m) _Pragma("unroll") for (int k = 0; k < 2; ++k) dst[m][k] = *(const LAS bf16x8*)(lds + PG8_SA(b, h) + aoff + m * 2048 + k * 1024); } while (0)
; #define PG8_LDB(dst, b, h) do { _Pragma("unroll") for (int n = 0; n < 2; ++n) _Pragma("unroll") for (int k = 0; k < 2; ++k) dst[n][k] = *(const LAS bf16x8*)(lds + PG8_SB(b, h) + boff + n * 2048 + k * 1024); } while (0)
; #define PG8_MMA(ai, bj, At, Bt) do { __builtin_amdgcn_s_setprio(1); _Pragma("unroll") for (int m = 0; m < 4; ++m) _Pragma("unroll") for (int n = 0; n < 2; ++n) _Pragma("unroll") for (int k = 0; k < 2; ++k) \
;         acc[ai][bj][m][n] = __builtin_amdgcn_mfma_f32_16x16x32_bf16(Bt[n][k], At[m][k], acc[ai][bj][m][n], 0, 0, 0); __builtin_amdgcn_s_setprio(0); } while (0)
; #define PG8_WAIT_V(n) asm volatile("s_waitcnt vmcnt(" #n ")" ::: "memory")
; #define PG8_WAIT_L(n) asm volatile("s_waitcnt lgkmcnt(" #n ")" ::: "memory")
; #define PG8_BAR __builtin_amdgcn_s_barrier()
; #define PG8_SCHED __builtin_amdgcn_sched_barrier(0)
; template <class Epi, class Sched>
; DI void gemm_phase(LAS unsigned char* lds, const Gemm g, const Sched& S, const Epi& E) {
;     ...
;             PG8_WAIT_L(8); PG8_BAR; PG8_WAIT_L(0); PG8_MMA(0, 0, At, B0); PG8_BAR; PG8_SCHED;
;             PG8_LDB(B1, 1, 1); PG8_STAGE(PG8_SB(1, 0), b3, voffB);
;             PG8_BAR; PG8_WAIT_L(0); PG8_MMA(0, 1, At, B1); PG8_BAR;
;             PG8_LDA(At, 1, 1); PG8_STAGE(PG8_SA(1, 0), a3, voffA);
;             PG8_BAR; PG8_WAIT_L(0); PG8_MMA(1, 0, At, B0); PG8_BAR; PG8_SCHED;
;             PG8_STAGE(PG8_SB(1, 1), b3 + hstep, voffB);
;             PG8_WAIT_V(6); PG8_BAR; PG8_MMA(1, 1, At, B1); PG8_BAR;
	s_waitcnt lgkmcnt(0)
	s_setprio 1
	v_mfma_f32_16x16x32_bf16 v[124:127], v[150:153], v[170:173], v[124:127]
	v_mfma_f32_16x16x32_bf16 v[120:123], v[162:165], v[170:173], v[120:123]
	v_mfma_f32_16x16x32_bf16 v[116:119], v[150:153], v[178:181], v[116:119]
	v_mfma_f32_16x16x32_bf16 v[112:115], v[162:165], v[178:181], v[112:115]
	v_mfma_f32_16x16x32_bf16 v[104:107], v[150:153], v[194:197], v[104:107]
	v_mfma_f32_16x16x32_bf16 v[96:99], v[162:165], v[194:197], v[96:99]
	v_mfma_f32_16x16x32_bf16 v[88:91], v[150:153], v[202:205], v[88:91]
	v_mfma_f32_16x16x32_bf16 v[80:83], v[162:165], v[202:205], v[80:83]
	v_mfma_f32_16x16x32_bf16 v[124:127], v[154:157], v[174:177], v[124:127]
	v_mfma_f32_16x16x32_bf16 v[120:123], v[166:169], v[174:177], v[120:123]
	v_mfma_f32_16x16x32_bf16 v[116:119], v[154:157], v[188:191], v[116:119]
	v_mfma_f32_16x16x32_bf16 v[112:115], v[166:169], v[188:191], v[112:115]
	v_mfma_f32_16x16x32_bf16 v[104:107], v[154:157], v[198:201], v[104:107]
	v_mfma_f32_16x16x32_bf16 v[96:99], v[166:169], v[198:201], v[96:99]
	v_mfma_f32_16x16x32_bf16 v[88:91], v[154:157], v[206:209], v[88:91]
	v_mfma_f32_16x16x32_bf16 v[80:83], v[166:169], v[206:209], v[80:83]
	s_setprio 0
	s_barrier
	s_add_i32 s4, 0, 0x1c000
	s_add_i32 s0, s64, s35
	v_add_u32_e32 v145, s4, v140
	s_add_i32 m0, s0, 0xffffff80
	ds_read_b128 v[210:213], v145
	ds_read_b128 v[214:217], v145 offset:1024
	ds_read_b128 v[218:221], v145 offset:2048
	global_load_lds_dwordx4 v130, s[36:37] offset:128
	s_add_i32 m0, s0, 0x1f80
	ds_read_b128 v[222:225], v145 offset:3072
	global_load_lds_dwordx4 v128, s[36:37] offset:128
	s_barrier
	s_waitcnt lgkmcnt(0)
	s_setprio 1
	v_mfma_f32_16x16x32_bf16 v[108:111], v[210:213], v[170:173], v[108:111]
	v_mfma_f32_16x16x32_bf16 v[100:103], v[218:221], v[170:173], v[100:103]
	v_mfma_f32_16x16x32_bf16 v[92:95], v[210:213], v[178:181], v[92:95]
	v_mfma_f32_16x16x32_bf16 v[84:87], v[218:221], v[178:181], v[84:87]
	v_mfma_f32_16x16x32_bf16 v[76:79], v[210:213], v[194:197], v[76:79]
	v_mfma_f32_16x16x32_bf16 v[72:75], v[218:221], v[194:197], v[72:75]
	v_mfma_f32_16x16x32_bf16 v[68:71], v[210:213], v[202:205], v[68:71]
	v_mfma_f32_16x16x32_bf16 v[64:67], v[218:221], v[202:205], v[64:67]
	v_mfma_f32_16x16x32_bf16 v[108:111], v[214:217], v[174:177], v[108:111]
	v_mfma_f32_16x16x32_bf16 v[100:103], v[222:225], v[174:177], v[100:103]
	v_mfma_f32_16x16x32_bf16 v[92:95], v[214:217], v[188:191], v[92:95]
	v_mfma_f32_16x16x32_bf16 v[84:87], v[222:225], v[188:191], v[84:87]
	v_mfma_f32_16x16x32_bf16 v[76:79], v[214:217], v[198:201], v[76:79]
	v_mfma_f32_16x16x32_bf16 v[72:75], v[222:225], v[198:201], v[72:75]
	v_mfma_f32_16x16x32_bf16 v[68:71], v[214:217], v[206:209], v[68:71]
	v_mfma_f32_16x16x32_bf16 v[64:67], v[222:225], v[206:209], v[64:67]
	s_setprio 0
	s_add_i32 m0, s56, 0xffffff80
	s_barrier
	ds_read_b128 v[170:173], v142 offset:49152
	ds_read_b128 v[174:177], v142 offset:50176
	ds_read_b128 v[178:181], v142 offset:51200
	ds_read_b128 v[188:191], v142 offset:52224
	ds_read_b128 v[194:197], v142 offset:53248
	ds_read_b128 v[198:201], v142 offset:54272
	ds_read_b128 v[202:205], v142 offset:55296
	global_load_lds_dwordx4 v130, s[38:39] offset:128
	s_add_i32 m0, s57, 0xffffff80
	ds_read_b128 v[206:209], v142 offset:56320
	global_load_lds_dwordx4 v128, s[38:39] offset:128
	s_barrier
	s_waitcnt lgkmcnt(0)
	s_setprio 1
	v_mfma_f32_16x16x32_bf16 v[60:63], v[150:153], v[170:173], v[60:63]
	v_mfma_f32_16x16x32_bf16 v[56:59], v[162:165], v[170:173], v[56:59]
	v_mfma_f32_16x16x32_bf16 v[52:55], v[150:153], v[178:181], v[52:55]
	v_mfma_f32_16x16x32_bf16 v[48:51], v[162:165], v[178:181], v[48:51]
	v_mfma_f32_16x16x32_bf16 v[40:43], v[150:153], v[194:197], v[40:43]
	v_mfma_f32_16x16x32_bf16 v[32:35], v[162:165], v[194:197], v[32:35]
	v_mfma_f32_16x16x32_bf16 v[24:27], v[150:153], v[202:205], v[24:27]
	v_mfma_f32_16x16x32_bf16 v[16:19], v[162:165], v[202:205], v[16:19]
	v_mfma_f32_16x16x32_bf16 v[60:63], v[154:157], v[174:177], v[60:63]
	v_mfma_f32_16x16x32_bf16 v[56:59], v[166:169], v[174:177], v[56:59]
	v_mfma_f32_16x16x32_bf16 v[52:55], v[154:157], v[188:191], v[52:55]
	v_mfma_f32_16x16x32_bf16 v[48:51], v[166:169], v[188:191], v[48:51]
	v_mfma_f32_16x16x32_bf16 v[40:43], v[154:157], v[198:201], v[40:43]
	v_mfma_f32_16x16x32_bf16 v[32:35], v[166:169], v[198:201], v[32:35]
	v_mfma_f32_16x16x32_bf16 v[24:27], v[154:157], v[206:209], v[24:27]
	v_mfma_f32_16x16x32_bf16 v[16:19], v[166:169], v[206:209], v[16:19]
	s_setprio 0
	s_barrier
	s_add_i32 s4, s4, s35
	s_mov_b32 m0, s4
	s_add_u32 s0, s36, 0x160080
	s_addc_u32 s1, s37, 0
	global_load_lds_dwordx4 v130, s[0:1]
	s_add_i32 m0, s4, 0x2000
	s_nop 0
	global_load_lds_dwordx4 v128, s[0:1]
	s_add_i32 s68, s68, 2
	s_add_u32 s8, s8, 0x100
	s_addc_u32 s9, s9, 0
	s_add_u32 s66, s66, 0x100
	s_addc_u32 s67, s67, 0
	s_cmp_gt_u32 s68, 5
	s_waitcnt vmcnt(6)
	s_barrier
	s_setprio 1
	v_mfma_f32_16x16x32_bf16 v[44:47], v[210:213], v[170:173], v[44:47]
	v_mfma_f32_16x16x32_bf16 v[36:39], v[218:221], v[170:173], v[36:39]
	v_mfma_f32_16x16x32_bf16 v[28:31], v[210:213], v[178:181], v[28:31]
	v_mfma_f32_16x16x32_bf16 v[20:23], v[218:221], v[178:181], v[20:23]
	v_mfma_f32_16x16x32_bf16 v[12:15], v[210:213], v[194:197], v[12:15]
	v_mfma_f32_16x16x32_bf16 v[8:11], v[218:221], v[194:197], v[8:11]
	v_mfma_f32_16x16x32_bf16 v[4:7], v[210:213], v[202:205], v[4:7]
	v_mfma_f32_16x16x32_bf16 v[0:3], v[218:221], v[202:205], v[0:3]
	v_mfma_f32_16x16x32_bf16 v[44:47], v[214:217], v[174:177], v[44:47]
	v_mfma_f32_16x16x32_bf16 v[36:39], v[222:225], v[174:177], v[36:39]
	v_mfma_f32_16x16x32_bf16 v[28:31], v[214:217], v[188:191], v[28:31]
	v_mfma_f32_16x16x32_bf16 v[20:23], v[222:225], v[188:191], v[20:23]
	v_mfma_f32_16x16x32_bf16 v[12:15], v[214:217], v[198:201], v[12:15]
	v_mfma_f32_16x16x32_bf16 v[8:11], v[222:225], v[198:201], v[8:11]
	v_mfma_f32_16x16x32_bf16 v[4:7], v[214:217], v[206:209], v[4:7]
	v_mfma_f32_16x16x32_bf16 v[0:3], v[222:225], v[206:209], v[0:3]
	s_setprio 0
	s_barrier
	s_cbranch_scc0 .LBB0_326

;     DI size_t aoff(const Unit& u, size_t tstep) const { return (size_t)u.pm * tstep; }
;     DI size_t boff(const Unit& u, size_t tstep) const { return (size_t)u.pn * tstep; }
;     DI bool next(int i, Unit& u) const { const long L = (long)i * G + c; if (L >= np) return false; u.pm = pmv; u.pn = (int)(L % nN); u.ks = (int)(L / nN); return true; }
;     DI size_t aoff(const Unit& u, size_t) const { return (size_t)u.ks * kbytes; }
;     DI size_t boff(const Unit& u, size_t tstep) const { return (size_t)u.pn * tstep + (size_t)u.ks * kbytes; }
;     DI bool next(int i, Unit& u) const { Unit t; if (!S.next(i / 3, t)) return false; u.pm = t.pm; u.pn = t.pn; u.ks = i % 3; return true; }
; template <class Epi, class Sched>
; DI void gemm_phase(LAS unsigned char* lds, const Gemm g, const Sched& S, const Epi& E) {
;     ...
;         const bool has_next = S.next(ui + 1, nxt);
;         const char* nA = has_next ? (const char*)g.A + S.aoff(nxt, tstep) : cA; const char* nB = has_next ? (const char*)g.Bt + S.boff(nxt, tstep) : cB;
;         for (int t = 0; t < nt; t += 2) {
;             if constexpr (Epi::HAS_MID) { if (t == E.mid_t(nt)) { int fr3 = fr, fq3 = fq; asm volatile("" : "+v"(fr3), "+v"(fq3)); E.mid(acc, cur, wr, wc, fr3, fq3); } }
;             const bool last = (t == nt - 2);
;             const char* a1 = cA + (size_t)(t + 1) * kstep;
;             const char* a2 = last ? nA : cA + (size_t)(t + 2) * kstep; const char* b2 = last ? nB : cB + (size_t)(t + 2) * kstep;
;             const char* a3 = a2 + kstep; const char* b3 = b2 + kstep;
;             PG8_LDB(B0, 0, 0); PG8_SCHED; PG8_LDA(At, 0, 0); PG8_STAGE(PG8_SA(1, 1), a1 + hstep, voffA);
;             PG8_WAIT_L(8); PG8_BAR; PG8_WAIT_L(0); PG8_MMA(0, 0, At, B0); PG8_BAR; PG8_SCHED;
;             PG8_LDB(B1, 0, 1); PG8_STAGE(PG8_SB(0, 0), b2, voffB);
;             PG8_BAR; PG8_WAIT_L(0); PG8_MMA(0, 1, At, B1); PG8_BAR;
;             PG8_LDA(At, 0, 1); PG8_STAGE(PG8_SA(0, 0), a2, voffA);
;             PG8_BAR; PG8_WAIT_L(0); PG8_MMA(1, 0, At, B0); PG8_BAR; PG8_SCHED;
;             PG8_STAGE(PG8_SB(0, 1), b2 + hstep, voffB);
;             PG8_WAIT_V(6); PG8_BAR; PG8_MMA(1, 1, At, B1); PG8_BAR;
;             PG8_LDB(B0, 1, 0); PG8_SCHED; PG8_LDA(At, 1, 0); PG8_STAGE(PG8_SA(0, 1), a2 + hstep, voffA);
;             PG8_WAIT_L(8); PG8_BAR; PG8_WAIT_L(0); PG8_MMA(0, 0, At, B0); PG8_BAR; PG8_SCHED;
.LBB0_526:
	s_ashr_i32 s51, s50, 31
	s_lshl_b64 s[0:1], s[50:51], 20
	s_add_u32 s52, s70, s0
	v_cmp_lt_i64_e32 vcc, s[12:13], v[142:143]
	s_addc_u32 s53, s71, s1
	s_and_b64 s[0:1], vcc, exec
	s_cselect_b32 s14, s53, s9
	s_cselect_b32 s15, s52, s8
	s_ashr_i32 s49, s48, 31
	s_lshl_b64 s[0:1], s[48:49], 20
	s_add_u32 s54, s72, s0
	s_addc_u32 s55, s73, s1
	s_and_b64 s[0:1], vcc, exec
	s_cselect_b32 s16, s55, s11
	s_cselect_b32 s17, s54, s10
	s_add_u32 s8, s8, 0x80080
	s_addc_u32 s9, s9, 0
	s_add_u32 s28, s10, 0x100
	v_mov_b32_e32 v0, 0
	s_addc_u32 s34, s11, 0
	s_mov_b32 s35, -2
	ds_read_b128 v[146:149], v164
	ds_read_b128 v[150:153], v164 offset:1024
	ds_read_b128 v[154:157], v164 offset:2048
	ds_read_b128 v[170:173], v164 offset:3072
	s_add_i32 m0, s59, 0xc000
	ds_read_b128 v[174:177], v165
	ds_read_b128 v[178:181], v165 offset:1024
	ds_read_b128 v[188:191], v165 offset:2048
	ds_read_b128 v[194:197], v165 offset:3072
	ds_read_b128 v[198:201], v165 offset:4096
	ds_read_b128 v[202:205], v165 offset:5120
	ds_read_b128 v[206:209], v165 offset:6144
	global_load_lds_dwordx4 v138, s[8:9]
	s_add_i32 m0, s59, 0xe000
	ds_read_b128 v[210:213], v165 offset:7168
	global_load_lds_dwordx4 v140, s[8:9]
	s_add_u32 s0, s8, 0xfff80080
	s_addc_u32 s1, s9, -1
	s_cmp_eq_u32 s35, 28
	s_cselect_b32 s13, s14, s1
	s_cselect_b32 s12, s15, s0
	s_cselect_b32 s11, s16, s34
	s_cselect_b32 s10, s17, s28
	s_waitcnt lgkmcnt(8)
	s_barrier
	s_waitcnt lgkmcnt(0)
	s_setprio 1
	v_mfma_f32_16x16x32_bf16 v[124:127], v[146:149], v[174:177], 0
	v_mfma_f32_16x16x32_bf16 v[120:123], v[154:157], v[174:177], 0
	v_mfma_f32_16x16x32_bf16 v[108:111], v[146:149], v[188:191], 0
	v_mfma_f32_16x16x32_bf16 v[104:107], v[154:157], v[188:191], 0
	v_mfma_f32_16x16x32_bf16 v[92:95], v[146:149], v[198:201], 0
	v_mfma_f32_16x16x32_bf16 v[88:91], v[154:157], v[198:201], 0
	v_mfma_f32_16x16x32_bf16 v[76:79], v[146:149], v[206:209], 0
	v_mfma_f32_16x16x32_bf16 v[72:75], v[154:157], v[206:209], 0
	v_mfma_f32_16x16x32_bf16 v[124:127], v[150:153], v[178:181], v[124:127]
	v_mfma_f32_16x16x32_bf16 v[120:123], v[170:173], v[178:181], v[120:123]
	v_mfma_f32_16x16x32_bf16 v[108:111], v[150:153], v[194:197], v[108:111]
	v_mfma_f32_16x16x32_bf16 v[104:107], v[170:173], v[194:197], v[104:107]
	v_mfma_f32_16x16x32_bf16 v[92:95], v[150:153], v[202:205], v[92:95]
	v_mfma_f32_16x16x32_bf16 v[88:91], v[170:173], v[202:205], v[88:91]
	v_mfma_f32_16x16x32_bf16 v[76:79], v[150:153], v[210:213], v[76:79]
	v_mfma_f32_16x16x32_bf16 v[72:75], v[170:173], v[210:213], v[72:75]
	s_setprio 0
	s_barrier
	s_add_i32 s0, s47, s74
	s_mov_b32 m0, s0
	ds_read_b128 v[214:217], v166
	ds_read_b128 v[218:221], v166 offset:1024
	ds_read_b128 v[222:225], v166 offset:2048
	global_load_lds_dwordx4 v130, s[10:11]
	s_add_i32 m0, s0, 0x2000
	ds_read_b128 v[226:229], v166 offset:3072
	global_load_lds_dwordx4 v134, s[10:11]
	s_barrier
	s_waitcnt lgkmcnt(0)
	s_setprio 1
	v_mfma_f32_16x16x32_bf16 v[116:119], v[214:217], v[174:177], 0
	v_mfma_f32_16x16x32_bf16 v[112:115], v[222:225], v[174:177], 0
	v_mfma_f32_16x16x32_bf16 v[100:103], v[214:217], v[188:191], 0
	v_mfma_f32_16x16x32_bf16 v[96:99], v[222:225], v[188:191], 0
	v_mfma_f32_16x16x32_bf16 v[84:87], v[214:217], v[198:201], 0
	v_mfma_f32_16x16x32_bf16 v[80:83], v[222:225], v[198:201], 0
	v_mfma_f32_16x16x32_bf16 v[68:71], v[214:217], v[206:209], 0
	v_mfma_f32_16x16x32_bf16 v[64:67], v[222:225], v[206:209], 0
	v_mfma_f32_16x16x32_bf16 v[116:119], v[218:221], v[178:181], v[116:119]
	v_mfma_f32_16x16x32_bf16 v[112:115], v[226:229], v[178:181], v[112:115]
	v_mfma_f32_16x16x32_bf16 v[100:103], v[218:221], v[194:197], v[100:103]
	v_mfma_f32_16x16x32_bf16 v[96:99], v[226:229], v[194:197], v[96:99]
	v_mfma_f32_16x16x32_bf16 v[84:87], v[218:221], v[202:205], v[84:87]
	v_mfma_f32_16x16x32_bf16 v[80:83], v[226:229], v[202:205], v[80:83]
	v_mfma_f32_16x16x32_bf16 v[68:71], v[218:221], v[210:213], v[68:71]
	v_mfma_f32_16x16x32_bf16 v[64:67], v[226:229], v[210:213], v[64:67]
	s_setprio 0
	s_mov_b32 m0, s59
	s_barrier
	ds_read_b128 v[174:177], v165 offset:16384
	ds_read_b128 v[178:181], v165 offset:17408
	ds_read_b128 v[188:191], v165 offset:18432
	ds_read_b128 v[194:197], v165 offset:19456
	ds_read_b128 v[198:201], v165 offset:20480
	ds_read_b128 v[202:205], v165 offset:21504
	ds_read_b128 v[206:209], v165 offset:22528
	global_load_lds_dwordx4 v128, s[12:13]
	s_mov_b32 m0, s75
	ds_read_b128 v[210:213], v165 offset:23552
	global_load_lds_dwordx4 v132, s[12:13]
	s_barrier
	s_waitcnt lgkmcnt(0)
	s_setprio 1
	v_mfma_f32_16x16x32_bf16 v[60:63], v[146:149], v[174:177], 0
	v_mfma_f32_16x16x32_bf16 v[56:59], v[154:157], v[174:177], 0
	v_mfma_f32_16x16x32_bf16 v[44:47], v[146:149], v[188:191], 0
	v_mfma_f32_16x16x32_bf16 v[40:43], v[154:157], v[188:191], 0
	v_mfma_f32_16x16x32_bf16 v[28:31], v[146:149], v[198:201], 0
	v_mfma_f32_16x16x32_bf16 v[24:27], v[154:157], v[198:201], 0
	v_mfma_f32_16x16x32_bf16 v[12:15], v[146:149], v[206:209], 0
	v_mfma_f32_16x16x32_bf16 v[8:11], v[154:157], v[206:209], 0
	v_mfma_f32_16x16x32_bf16 v[60:63], v[150:153], v[178:181], v[60:63]
	v_mfma_f32_16x16x32_bf16 v[56:59], v[170:173], v[178:181], v[56:59]
	v_mfma_f32_16x16x32_bf16 v[44:47], v[150:153], v[194:197], v[44:47]
	v_mfma_f32_16x16x32_bf16 v[40:43], v[170:173], v[194:197], v[40:43]
	v_mfma_f32_16x16x32_bf16 v[28:31], v[150:153], v[202:205], v[28:31]
	v_mfma_f32_16x16x32_bf16 v[24:27], v[170:173], v[202:205], v[24:27]
	v_mfma_f32_16x16x32_bf16 v[12:15], v[150:153], v[210:213], v[12:15]
	v_mfma_f32_16x16x32_bf16 v[8:11], v[170:173], v[210:213], v[8:11]
	s_setprio 0
	s_barrier
; #define PG8_STAGE(bufoff, gbase, voff) do { _Pragma("unroll") for (int _i = 0; _i < 2; ++_i) \
;         __builtin_amdgcn_global_load_lds((const unsigned*)((const char*)(gbase) + (voff)[_i]), (LAS unsigned*)(lds + (bufoff) + ldsw + _i * 8192), 16, 0, 0); } while (0)
; #define PG8_LDA(dst, b, h) do { _Pragma("unroll") for (int m = 0; m < 4; ++m) _Pragma("unroll") for (int k = 0; k < 2; ++k) dst[m][k] = *(const LAS bf16x8*)(lds + PG8_SA(b, h) + aoff + m * 2048 + k * 1024); } while (0)
; #define PG8_LDB(dst, b, h) do { _Pragma("unroll") for (int n = 0; n < 2; ++n) _Pragma("unroll") for (int k = 0; k < 2; ++k) dst[n][k] = *(const LAS bf16x8*)(lds + PG8_SB(b, h) + boff + n * 2048 + k * 1024); } while (0)
; #define PG8_MMA(ai, bj, At, Bt) do { __builtin_amdgcn_s_setprio(1); _Pragma("unroll") for (int m = 0; m < 4; ++m) _Pragma("unroll") for (int n = 0; n < 2; ++n) _Pragma("unroll") for (int k = 0; k < 2; ++k) \
;         acc[ai][bj][m][n] = __builtin_amdgcn_mfma_f32_16x16x32_bf16(Bt[n][k], At[m][k], acc[ai][bj][m][n], 0, 0, 0); __builtin_amdgcn_s_setprio(0); } while (0)
; #define PG8_WAIT_V(n) asm volatile("s_waitcnt vmcnt(" #n ")" ::: "memory")
; #define PG8_WAIT_L(n) asm volatile("s_waitcnt lgkmcnt(" #n ")" ::: "memory")
; #define PG8_BAR __builtin_amdgcn_s_barrier()
; #define PG8_SCHED __builtin_amdgcn_sched_barrier(0)
; template <class Epi, class Sched>
; DI void gemm_phase(LAS unsigned char* lds, const Gemm g, const Sched& S, const Epi& E) {
;     ...
;             PG8_WAIT_V(6); PG8_BAR; PG8_MMA(1, 1, At, B1); PG8_BAR;
;             PG8_LDB(B0, 1, 0); PG8_SCHED; PG8_LDA(At, 1, 0); PG8_STAGE(PG8_SA(0, 1), a2 + hstep, voffA);
;             PG8_WAIT_L(8); PG8_BAR; PG8_WAIT_L(0); PG8_MMA(0, 0, At, B0); PG8_BAR; PG8_SCHED;
;             PG8_LDB(B1, 1, 1); PG8_STAGE(PG8_SB(1, 0), b3, voffB);
;             PG8_BAR; PG8_WAIT_L(0); PG8_MMA(0, 1, At, B1); PG8_BAR;
;             PG8_LDA(At, 1, 1); PG8_STAGE(PG8_SA(1, 0), a3, voffA);
;             PG8_BAR; PG8_WAIT_L(0); PG8_MMA(1, 0, At, B0); PG8_BAR; PG8_SCHED;
;             PG8_STAGE(PG8_SB(1, 1), b3 + hstep, voffB);
;             PG8_WAIT_V(6); PG8_BAR; PG8_MMA(1, 1, At, B1); PG8_BAR;
	s_add_i32 s4, s87, s74
	s_mov_b32 m0, s4
	s_add_u32 s0, s10, 0x80000
	s_addc_u32 s1, s11, 0
	global_load_lds_dwordx4 v130, s[0:1]
	s_add_i32 m0, s4, 0x2000
	s_nop 0
	global_load_lds_dwordx4 v134, s[0:1]
	s_waitcnt vmcnt(6)
	s_barrier
	s_setprio 1
	v_mfma_f32_16x16x32_bf16 v[52:55], v[214:217], v[174:177], 0
	v_mfma_f32_16x16x32_bf16 v[48:51], v[222:225], v[174:177], 0
	v_mfma_f32_16x16x32_bf16 v[36:39], v[214:217], v[188:191], 0
	v_mfma_f32_16x16x32_bf16 v[32:35], v[222:225], v[188:191], 0
	v_mfma_f32_16x16x32_bf16 v[20:23], v[214:217], v[198:201], 0
	v_mfma_f32_16x16x32_bf16 v[16:19], v[222:225], v[198:201], 0
	v_mfma_f32_16x16x32_bf16 v[4:7], v[214:217], v[206:209], 0
	v_mfma_f32_16x16x32_bf16 v[0:3], v[222:225], v[206:209], 0
	v_mfma_f32_16x16x32_bf16 v[52:55], v[218:221], v[178:181], v[52:55]
	v_mfma_f32_16x16x32_bf16 v[48:51], v[226:229], v[178:181], v[48:51]
	v_mfma_f32_16x16x32_bf16 v[36:39], v[218:221], v[194:197], v[36:39]
	v_mfma_f32_16x16x32_bf16 v[32:35], v[226:229], v[194:197], v[32:35]
	v_mfma_f32_16x16x32_bf16 v[20:23], v[218:221], v[202:205], v[20:23]
	v_mfma_f32_16x16x32_bf16 v[16:19], v[226:229], v[202:205], v[16:19]
	v_mfma_f32_16x16x32_bf16 v[4:7], v[218:221], v[210:213], v[4:7]
	v_mfma_f32_16x16x32_bf16 v[0:3], v[226:229], v[210:213], v[0:3]
	s_setprio 0
	s_add_i32 s4, 0, 0x18000
	v_add_u32_e32 v158, s4, v163
	s_barrier
	ds_read_b128 v[146:149], v158
	ds_read_b128 v[150:153], v158 offset:1024
	ds_read_b128 v[154:157], v158 offset:2048
	ds_read_b128 v[170:173], v158 offset:3072
	s_add_u32 s0, s12, 0x80000
	s_addc_u32 s1, s13, 0
	s_mov_b32 m0, s76
	ds_read_b128 v[174:177], v165 offset:32768
	ds_read_b128 v[178:181], v165 offset:33792
	ds_read_b128 v[188:191], v165 offset:34816
	ds_read_b128 v[194:197], v165 offset:35840
	ds_read_b128 v[198:201], v165 offset:36864
	ds_read_b128 v[202:205], v165 offset:37888
	ds_read_b128 v[206:209], v165 offset:38912
	global_load_lds_dwordx4 v128, s[0:1]
	s_mov_b32 m0, s77
	ds_read_b128 v[210:213], v165 offset:39936
	global_load_lds_dwordx4 v132, s[0:1]
	s_waitcnt lgkmcnt(8)
	s_barrier
	s_waitcnt lgkmcnt(0)
	s_setprio 1
	v_mfma_f32_16x16x32_bf16 v[124:127], v[146:149], v[174:177], v[124:127]
	v_mfma_f32_16x16x32_bf16 v[120:123], v[154:157], v[174:177], v[120:123]
	v_mfma_f32_16x16x32_bf16 v[108:111], v[146:149], v[188:191], v[108:111]
	v_mfma_f32_16x16x32_bf16 v[104:107], v[154:157], v[188:191], v[104:107]
	v_mfma_f32_16x16x32_bf16 v[92:95], v[146:149], v[198:201], v[92:95]
	v_mfma_f32_16x16x32_bf16 v[88:91], v[154:157], v[198:201], v[88:91]
	v_mfma_f32_16x16x32_bf16 v[76:79], v[146:149], v[206:209], v[76:79]
	v_mfma_f32_16x16x32_bf16 v[72:75], v[154:157], v[206:209], v[72:75]
	v_mfma_f32_16x16x32_bf16 v[124:127], v[150:153], v[178:181], v[124:127]
	v_mfma_f32_16x16x32_bf16 v[120:123], v[170:173], v[178:181], v[120:123]
	v_mfma_f32_16x16x32_bf16 v[108:111], v[150:153], v[194:197], v[108:111]
	v_mfma_f32_16x16x32_bf16 v[104:107], v[170:173], v[194:197], v[104:107]
	v_mfma_f32_16x16x32_bf16 v[92:95], v[150:153], v[202:205], v[92:95]
	v_mfma_f32_16x16x32_bf16 v[88:91], v[170:173], v[202:205], v[88:91]
	v_mfma_f32_16x16x32_bf16 v[76:79], v[150:153], v[210:213], v[76:79]
	v_mfma_f32_16x16x32_bf16 v[72:75], v[170:173], v[210:213], v[72:75]
	s_setprio 0
	s_barrier
	s_add_i32 s5, 0, 0x1c000
	s_add_i32 s0, s4, s74
	v_add_u32_e32 v159, s5, v163
	s_add_i32 m0, s0, 0xffffff80
	ds_read_b128 v[214:217], v159
	ds_read_b128 v[218:221], v159 offset:1024
	ds_read_b128 v[222:225], v159 offset:2048
	global_load_lds_dwordx4 v130, s[10:11] offset:128
	s_add_i32 m0, s0, 0x1f80
	ds_read_b128 v[226:229], v159 offset:3072
	global_load_lds_dwordx4 v134, s[10:11] offset:128
	s_barrier
	s_waitcnt lgkmcnt(0)
	s_setprio 1
	v_mfma_f32_16x16x32_bf16 v[116:119], v[214:217], v[174:177], v[116:119]
	v_mfma_f32_16x16x32_bf16 v[112:115], v[222:225], v[174:177], v[112:115]
	v_mfma_f32_16x16x32_bf16 v[100:103], v[214:217], v[188:191], v[100:103]
	v_mfma_f32_16x16x32_bf16 v[96:99], v[222:225], v[188:191], v[96:99]
	v_mfma_f32_16x16x32_bf16 v[84:87], v[214:217], v[198:201], v[84:87]
	v_mfma_f32_16x16x32_bf16 v[80:83], v[222:225], v[198:201], v[80:83]
	v_mfma_f32_16x16x32_bf16 v[68:71], v[214:217], v[206:209], v[68:71]
	v_mfma_f32_16x16x32_bf16 v[64:67], v[222:225], v[206:209], v[64:67]
	v_mfma_f32_16x16x32_bf16 v[116:119], v[218:221], v[178:181], v[116:119]
	v_mfma_f32_16x16x32_bf16 v[112:115], v[226:229], v[178:181], v[112:115]
	v_mfma_f32_16x16x32_bf16 v[100:103], v[218:221], v[194:197], v[100:103]
	v_mfma_f32_16x16x32_bf16 v[96:99], v[226:229], v[194:197], v[96:99]
	v_mfma_f32_16x16x32_bf16 v[84:87], v[218:221], v[202:205], v[84:87]
	v_mfma_f32_16x16x32_bf16 v[80:83], v[226:229], v[202:205], v[80:83]
	v_mfma_f32_16x16x32_bf16 v[68:71], v[218:221], v[210:213], v[68:71]
	v_mfma_f32_16x16x32_bf16 v[64:67], v[226:229], v[210:213], v[64:67]
	s_setprio 0
	s_add_i32 m0, s97, 0xffffff80
	s_barrier
	ds_read_b128 v[174:177], v165 offset:49152
	ds_read_b128 v[178:181], v165 offset:50176
	ds_read_b128 v[188:191], v165 offset:51200
	ds_read_b128 v[194:197], v165 offset:52224
	ds_read_b128 v[198:201], v165 offset:53248
	ds_read_b128 v[202:205], v165 offset:54272
	ds_read_b128 v[206:209], v165 offset:55296
	global_load_lds_dwordx4 v128, s[12:13] offset:128
	s_add_i32 m0, s84, 0xffffff80
	ds_read_b128 v[210:213], v165 offset:56320
	global_load_lds_dwordx4 v132, s[12:13] offset:128
	s_barrier
; #define PG8_STAGE(bufoff, gbase, voff) do { _Pragma("unroll") for (int _i = 0; _i < 2; ++_i) \
;         __builtin_amdgcn_global_load_lds((const unsigned*)((const char*)(gbase) + (voff)[_i]), (LAS unsigned*)(lds + (bufoff) + ldsw + _i * 8192), 16, 0, 0); } while (0)
; #define PG8_LDA(dst, b, h) do { _Pragma("unroll") for (int m = 0; m < 4; ++m) _Pragma("unroll") for (int k = 0; k < 2; ++k) dst[m][k] = *(const LAS bf16x8*)(lds + PG8_SA(b, h) + aoff + m * 2048 + k * 1024); } while (0)
; #define PG8_LDB(dst, b, h) do { _Pragma("unroll") for (int n = 0; n < 2; ++n) _Pragma("unroll") for (int k = 0; k < 2; ++k) dst[n][k] = *(const LAS bf16x8*)(lds + PG8_SB(b, h) + boff + n * 2048 + k * 1024); } while (0)
; #define PG8_MMA(ai, bj, At, Bt) do { __builtin_amdgcn_s_setprio(1); _Pragma("unroll") for (int m = 0; m < 4; ++m) _Pragma("unroll") for (int n = 0; n < 2; ++n) _Pragma("unroll") for (int k = 0; k < 2; ++k) \
;         acc[ai][bj][m][n] = __builtin_amdgcn_mfma_f32_16x16x32_bf16(Bt[n][k], At[m][k], acc[ai][bj][m][n], 0, 0, 0); __builtin_amdgcn_s_setprio(0); } while (0)
; #define PG8_WAIT_V(n) asm volatile("s_waitcnt vmcnt(" #n ")" ::: "memory")
; #define PG8_WAIT_L(n) asm volatile("s_waitcnt lgkmcnt(" #n ")" ::: "memory")
; #define PG8_BAR __builtin_amdgcn_s_barrier()
; #define PG8_SCHED __builtin_amdgcn_sched_barrier(0)
; template <class Epi, class Sched>
; DI void gemm_phase(LAS unsigned char* lds, const Gemm g, const Sched& S, const Epi& E) {
;     ...
;             PG8_LDB(B0, 0, 0); PG8_SCHED; PG8_LDA(At, 0, 0); PG8_STAGE(PG8_SA(1, 1), a1 + hstep, voffA);
;             PG8_WAIT_L(8); PG8_BAR; PG8_WAIT_L(0); PG8_MMA(0, 0, At, B0); PG8_BAR; PG8_SCHED;
;             PG8_LDB(B1, 0, 1); PG8_STAGE(PG8_SB(0, 0), b2, voffB);
;     ...
;             PG8_BAR; PG8_WAIT_L(0); PG8_MMA(0, 1, At, B1); PG8_BAR;
;             PG8_LDA(At, 1, 1); PG8_STAGE(PG8_SA(1, 0), a3, voffA);
;             PG8_BAR; PG8_WAIT_L(0); PG8_MMA(1, 0, At, B0); PG8_BAR; PG8_SCHED;
;             PG8_STAGE(PG8_SB(1, 1), b3 + hstep, voffB);
;             PG8_WAIT_V(6); PG8_BAR; PG8_MMA(1, 1, At, B1); PG8_BAR;
	s_waitcnt lgkmcnt(0)
	s_setprio 1
	v_mfma_f32_16x16x32_bf16 v[60:63], v[146:149], v[174:177], v[60:63]
	v_mfma_f32_16x16x32_bf16 v[56:59], v[154:157], v[174:177], v[56:59]
	v_mfma_f32_16x16x32_bf16 v[44:47], v[146:149], v[188:191], v[44:47]
	v_mfma_f32_16x16x32_bf16 v[40:43], v[154:157], v[188:191], v[40:43]
	v_mfma_f32_16x16x32_bf16 v[28:31], v[146:149], v[198:201], v[28:31]
	v_mfma_f32_16x16x32_bf16 v[24:27], v[154:157], v[198:201], v[24:27]
	v_mfma_f32_16x16x32_bf16 v[12:15], v[146:149], v[206:209], v[12:15]
	v_mfma_f32_16x16x32_bf16 v[8:11], v[154:157], v[206:209], v[8:11]
	v_mfma_f32_16x16x32_bf16 v[60:63], v[150:153], v[178:181], v[60:63]
	v_mfma_f32_16x16x32_bf16 v[56:59], v[170:173], v[178:181], v[56:59]
	v_mfma_f32_16x16x32_bf16 v[44:47], v[150:153], v[194:197], v[44:47]
	v_mfma_f32_16x16x32_bf16 v[40:43], v[170:173], v[194:197], v[40:43]
	v_mfma_f32_16x16x32_bf16 v[28:31], v[150:153], v[202:205], v[28:31]
	v_mfma_f32_16x16x32_bf16 v[24:27], v[170:173], v[202:205], v[24:27]
	v_mfma_f32_16x16x32_bf16 v[12:15], v[150:153], v[210:213], v[12:15]
	v_mfma_f32_16x16x32_bf16 v[8:11], v[170:173], v[210:213], v[8:11]
	s_setprio 0
	s_barrier
	s_add_i32 s4, s5, s74
	s_mov_b32 m0, s4
	s_add_u32 s0, s10, 0x80080
	s_addc_u32 s1, s11, 0
	global_load_lds_dwordx4 v130, s[0:1]
	v_lshl_add_u64 v[146:147], s[0:1], 0, v[134:135]
	s_add_i32 m0, s4, 0x2000
	s_nop 0
	global_load_lds_dwordx4 v134, s[0:1]
	s_add_i32 s35, s35, 2
	s_add_u32 s8, s8, 0x100
	s_addc_u32 s9, s9, 0
	s_add_u32 s28, s28, 0x100
	s_addc_u32 s34, s34, 0
	s_cmp_gt_u32 s35, 29
	s_waitcnt vmcnt(6)
	s_barrier
	s_setprio 1
	v_mfma_f32_16x16x32_bf16 v[52:55], v[214:217], v[174:177], v[52:55]
	v_mfma_f32_16x16x32_bf16 v[48:51], v[222:225], v[174:177], v[48:51]
	v_mfma_f32_16x16x32_bf16 v[36:39], v[214:217], v[188:191], v[36:39]
	v_mfma_f32_16x16x32_bf16 v[32:35], v[222:225], v[188:191], v[32:35]
	v_mfma_f32_16x16x32_bf16 v[20:23], v[214:217], v[198:201], v[20:23]
	v_mfma_f32_16x16x32_bf16 v[16:19], v[222:225], v[198:201], v[16:19]
	v_mfma_f32_16x16x32_bf16 v[4:7], v[214:217], v[206:209], v[4:7]
	v_mfma_f32_16x16x32_bf16 v[0:3], v[222:225], v[206:209], v[0:3]
	v_mfma_f32_16x16x32_bf16 v[52:55], v[218:221], v[178:181], v[52:55]
	v_mfma_f32_16x16x32_bf16 v[48:51], v[226:229], v[178:181], v[48:51]
	v_mfma_f32_16x16x32_bf16 v[36:39], v[218:221], v[194:197], v[36:39]
	v_mfma_f32_16x16x32_bf16 v[32:35], v[226:229], v[194:197], v[32:35]
	v_mfma_f32_16x16x32_bf16 v[20:23], v[218:221], v[202:205], v[20:23]
	v_mfma_f32_16x16x32_bf16 v[16:19], v[226:229], v[202:205], v[16:19]
	v_mfma_f32_16x16x32_bf16 v[4:7], v[218:221], v[210:213], v[4:7]
	v_mfma_f32_16x16x32_bf16 v[0:3], v[226:229], v[210:213], v[0:3]
	s_setprio 0
	s_barrier
	s_cbranch_scc0 .LBB0_527
	s_branch .Lpeel_done_527
.LBB0_527:
	ds_read_b128 v[146:149], v164
	ds_read_b128 v[150:153], v164 offset:1024
	ds_read_b128 v[154:157], v164 offset:2048
	ds_read_b128 v[170:173], v164 offset:3072
	s_add_i32 m0, s59, 0xc000
	ds_read_b128 v[174:177], v165
	ds_read_b128 v[178:181], v165 offset:1024
	ds_read_b128 v[188:191], v165 offset:2048
	ds_read_b128 v[194:197], v165 offset:3072
	ds_read_b128 v[198:201], v165 offset:4096
	ds_read_b128 v[202:205], v165 offset:5120
	ds_read_b128 v[206:209], v165 offset:6144
	global_load_lds_dwordx4 v138, s[8:9]
	s_add_i32 m0, s59, 0xe000
	ds_read_b128 v[210:213], v165 offset:7168
	global_load_lds_dwordx4 v140, s[8:9]
	s_add_u32 s0, s8, 0xfff80080
	s_addc_u32 s1, s9, -1
	s_cmp_eq_u32 s35, 28
	s_cselect_b32 s13, s14, s1
	s_cselect_b32 s12, s15, s0
	s_cselect_b32 s11, s16, s34
	s_cselect_b32 s10, s17, s28
	s_waitcnt lgkmcnt(8)
	s_barrier
	s_waitcnt lgkmcnt(0)
	s_setprio 1
	v_mfma_f32_16x16x32_bf16 v[124:127], v[146:149], v[174:177], v[124:127]
	v_mfma_f32_16x16x32_bf16 v[120:123], v[154:157], v[174:177], v[120:123]
	v_mfma_f32_16x16x32_bf16 v[108:111], v[146:149], v[188:191], v[108:111]
	v_mfma_f32_16x16x32_bf16 v[104:107], v[154:157], v[188:191], v[104:107]
	v_mfma_f32_16x16x32_bf16 v[92:95], v[146:149], v[198:201], v[92:95]
	v_mfma_f32_16x16x32_bf16 v[88:91], v[154:157], v[198:201], v[88:91]
	v_mfma_f32_16x16x32_bf16 v[76:79], v[146:149], v[206:209], v[76:79]
	v_mfma_f32_16x16x32_bf16 v[72:75], v[154:157], v[206:209], v[72:75]
	v_mfma_f32_16x16x32_bf16 v[124:127], v[150:153], v[178:181], v[124:127]
	v_mfma_f32_16x16x32_bf16 v[120:123], v[170:173], v[178:181], v[120:123]
	v_mfma_f32_16x16x32_bf16 v[108:111], v[150:153], v[194:197], v[108:111]
	v_mfma_f32_16x16x32_bf16 v[104:107], v[170:173], v[194:197], v[104:107]
	v_mfma_f32_16x16x32_bf16 v[92:95], v[150:153], v[202:205], v[92:95]
	v_mfma_f32_16x16x32_bf16 v[88:91], v[170:173], v[202:205], v[88:91]
	v_mfma_f32_16x16x32_bf16 v[76:79], v[150:153], v[210:213], v[76:79]
	v_mfma_f32_16x16x32_bf16 v[72:75], v[170:173], v[210:213], v[72:75]
	s_setprio 0
	s_barrier
	s_add_i32 s0, s47, s74
	s_mov_b32 m0, s0
	ds_read_b128 v[214:217], v166
	ds_read_b128 v[218:221], v166 offset:1024
	ds_read_b128 v[222:225], v166 offset:2048
	global_load_lds_dwordx4 v130, s[10:11]
	s_add_i32 m0, s0, 0x2000
	ds_read_b128 v[226:229], v166 offset:3072
	global_load_lds_dwordx4 v134, s[10:11]
	s_barrier
; #define PG8_STAGE(bufoff, gbase, voff) do { _Pragma("unroll") for (int _i = 0; _i < 2; ++_i) \
;         __builtin_amdgcn_global_load_lds((const unsigned*)((const char*)(gbase) + (voff)[_i]), (LAS unsigned*)(lds + (bufoff) + ldsw + _i * 8192), 16, 0, 0); } while (0)
; #define PG8_LDA(dst, b, h) do { _Pragma("unroll") for (int m = 0; m < 4; ++m) _Pragma("unroll") for (int k = 0; k < 2; ++k) dst[m][k] = *(const LAS bf16x8*)(lds + PG8_SA(b, h) + aoff + m * 2048 + k * 1024); } while (0)
; #define PG8_LDB(dst, b, h) do { _Pragma("unroll") for (int n = 0; n < 2; ++n) _Pragma("unroll") for (int k = 0; k < 2; ++k) dst[n][k] = *(const LAS bf16x8*)(lds + PG8_SB(b, h) + boff + n * 2048 + k * 1024); } while (0)
; #define PG8_MMA(ai, bj, At, Bt) do { __builtin_amdgcn_s_setprio(1); _Pragma("unroll") for (int m = 0; m < 4; ++m) _Pragma("unroll") for (int n = 0; n < 2; ++n) _Pragma("unroll") for (int k = 0; k < 2; ++k) \
;         acc[ai][bj][m][n] = __builtin_amdgcn_mfma_f32_16x16x32_bf16(Bt[n][k], At[m][k], acc[ai][bj][m][n], 0, 0, 0); __builtin_amdgcn_s_setprio(0); } while (0)
; #define PG8_WAIT_V(n) asm volatile("s_waitcnt vmcnt(" #n ")" ::: "memory")
; #define PG8_WAIT_L(n) asm volatile("s_waitcnt lgkmcnt(" #n ")" ::: "memory")
; #define PG8_BAR __builtin_amdgcn_s_barrier()
; #define PG8_SCHED __builtin_amdgcn_sched_barrier(0)
; template <class Epi, class Sched>
; DI void gemm_phase(LAS unsigned char* lds, const Gemm g, const Sched& S, const Epi& E) {
;     ...
;             PG8_BAR; PG8_WAIT_L(0); PG8_MMA(0, 1, At, B1); PG8_BAR;
;             PG8_LDA(At, 0, 1); PG8_STAGE(PG8_SA(0, 0), a2, voffA);
;             PG8_BAR; PG8_WAIT_L(0); PG8_MMA(1, 0, At, B0); PG8_BAR; PG8_SCHED;
;             PG8_STAGE(PG8_SB(0, 1), b2 + hstep, voffB);
;             PG8_WAIT_V(6); PG8_BAR; PG8_MMA(1, 1, At, B1); PG8_BAR;
;             PG8_LDB(B0, 1, 0); PG8_SCHED; PG8_LDA(At, 1, 0); PG8_STAGE(PG8_SA(0, 1), a2 + hstep, voffA);
;             PG8_WAIT_L(8); PG8_BAR; PG8_WAIT_L(0); PG8_MMA(0, 0, At, B0); PG8_BAR; PG8_SCHED;
	s_waitcnt lgkmcnt(0)
	s_setprio 1
	v_mfma_f32_16x16x32_bf16 v[116:119], v[214:217], v[174:177], v[116:119]
	v_mfma_f32_16x16x32_bf16 v[112:115], v[222:225], v[174:177], v[112:115]
	v_mfma_f32_16x16x32_bf16 v[100:103], v[214:217], v[188:191], v[100:103]
	v_mfma_f32_16x16x32_bf16 v[96:99], v[222:225], v[188:191], v[96:99]
	v_mfma_f32_16x16x32_bf16 v[84:87], v[214:217], v[198:201], v[84:87]
	v_mfma_f32_16x16x32_bf16 v[80:83], v[222:225], v[198:201], v[80:83]
	v_mfma_f32_16x16x32_bf16 v[68:71], v[214:217], v[206:209], v[68:71]
	v_mfma_f32_16x16x32_bf16 v[64:67], v[222:225], v[206:209], v[64:67]
	v_mfma_f32_16x16x32_bf16 v[116:119], v[218:221], v[178:181], v[116:119]
	v_mfma_f32_16x16x32_bf16 v[112:115], v[226:229], v[178:181], v[112:115]
	v_mfma_f32_16x16x32_bf16 v[100:103], v[218:221], v[194:197], v[100:103]
	v_mfma_f32_16x16x32_bf16 v[96:99], v[226:229], v[194:197], v[96:99]
	v_mfma_f32_16x16x32_bf16 v[84:87], v[218:221], v[202:205], v[84:87]
	v_mfma_f32_16x16x32_bf16 v[80:83], v[226:229], v[202:205], v[80:83]
	v_mfma_f32_16x16x32_bf16 v[68:71], v[218:221], v[210:213], v[68:71]
	v_mfma_f32_16x16x32_bf16 v[64:67], v[226:229], v[210:213], v[64:67]
	s_setprio 0
	s_mov_b32 m0, s59
	s_barrier
	ds_read_b128 v[174:177], v165 offset:16384
	ds_read_b128 v[178:181], v165 offset:17408
	ds_read_b128 v[188:191], v165 offset:18432
	ds_read_b128 v[194:197], v165 offset:19456
	ds_read_b128 v[198:201], v165 offset:20480
	ds_read_b128 v[202:205], v165 offset:21504
	ds_read_b128 v[206:209], v165 offset:22528
	global_load_lds_dwordx4 v128, s[12:13]
	s_mov_b32 m0, s75
	ds_read_b128 v[210:213], v165 offset:23552
	global_load_lds_dwordx4 v132, s[12:13]
	s_barrier
	s_waitcnt lgkmcnt(0)
	s_setprio 1
	v_mfma_f32_16x16x32_bf16 v[60:63], v[146:149], v[174:177], v[60:63]
	v_mfma_f32_16x16x32_bf16 v[56:59], v[154:157], v[174:177], v[56:59]
	v_mfma_f32_16x16x32_bf16 v[44:47], v[146:149], v[188:191], v[44:47]
	v_mfma_f32_16x16x32_bf16 v[40:43], v[154:157], v[188:191], v[40:43]
	v_mfma_f32_16x16x32_bf16 v[28:31], v[146:149], v[198:201], v[28:31]
	v_mfma_f32_16x16x32_bf16 v[24:27], v[154:157], v[198:201], v[24:27]
	v_mfma_f32_16x16x32_bf16 v[12:15], v[146:149], v[206:209], v[12:15]
	v_mfma_f32_16x16x32_bf16 v[8:11], v[154:157], v[206:209], v[8:11]
	v_mfma_f32_16x16x32_bf16 v[60:63], v[150:153], v[178:181], v[60:63]
	v_mfma_f32_16x16x32_bf16 v[56:59], v[170:173], v[178:181], v[56:59]
	v_mfma_f32_16x16x32_bf16 v[44:47], v[150:153], v[194:197], v[44:47]
	v_mfma_f32_16x16x32_bf16 v[40:43], v[170:173], v[194:197], v[40:43]
	v_mfma_f32_16x16x32_bf16 v[28:31], v[150:153], v[202:205], v[28:31]
	v_mfma_f32_16x16x32_bf16 v[24:27], v[170:173], v[202:205], v[24:27]
	v_mfma_f32_16x16x32_bf16 v[12:15], v[150:153], v[210:213], v[12:15]
	v_mfma_f32_16x16x32_bf16 v[8:11], v[170:173], v[210:213], v[8:11]
	s_setprio 0
	s_barrier
	s_add_i32 s4, s87, s74
	s_mov_b32 m0, s4
	s_add_u32 s0, s10, 0x80000
	s_addc_u32 s1, s11, 0
	global_load_lds_dwordx4 v130, s[0:1]
	s_add_i32 m0, s4, 0x2000
	s_nop 0
	global_load_lds_dwordx4 v134, s[0:1]
	s_waitcnt vmcnt(6)
	s_barrier
	s_setprio 1
	v_mfma_f32_16x16x32_bf16 v[52:55], v[214:217], v[174:177], v[52:55]
	v_mfma_f32_16x16x32_bf16 v[48:51], v[222:225], v[174:177], v[48:51]
	v_mfma_f32_16x16x32_bf16 v[36:39], v[214:217], v[188:191], v[36:39]
	v_mfma_f32_16x16x32_bf16 v[32:35], v[222:225], v[188:191], v[32:35]
	v_mfma_f32_16x16x32_bf16 v[20:23], v[214:217], v[198:201], v[20:23]
	v_mfma_f32_16x16x32_bf16 v[16:19], v[222:225], v[198:201], v[16:19]
	v_mfma_f32_16x16x32_bf16 v[4:7], v[214:217], v[206:209], v[4:7]
	v_mfma_f32_16x16x32_bf16 v[0:3], v[222:225], v[206:209], v[0:3]
	v_mfma_f32_16x16x32_bf16 v[52:55], v[218:221], v[178:181], v[52:55]
	v_mfma_f32_16x16x32_bf16 v[48:51], v[226:229], v[178:181], v[48:51]
	v_mfma_f32_16x16x32_bf16 v[36:39], v[218:221], v[194:197], v[36:39]
	v_mfma_f32_16x16x32_bf16 v[32:35], v[226:229], v[194:197], v[32:35]
	v_mfma_f32_16x16x32_bf16 v[20:23], v[218:221], v[202:205], v[20:23]
	v_mfma_f32_16x16x32_bf16 v[16:19], v[226:229], v[202:205], v[16:19]
	v_mfma_f32_16x16x32_bf16 v[4:7], v[218:221], v[210:213], v[4:7]
	v_mfma_f32_16x16x32_bf16 v[0:3], v[226:229], v[210:213], v[0:3]
	s_setprio 0
	s_add_i32 s4, 0, 0x18000
	s_barrier
	ds_read_b128 v[146:149], v158
	ds_read_b128 v[150:153], v158 offset:1024
	ds_read_b128 v[154:157], v158 offset:2048
	ds_read_b128 v[170:173], v158 offset:3072
	s_add_u32 s0, s12, 0x80000
	s_addc_u32 s1, s13, 0
	s_mov_b32 m0, s76
	ds_read_b128 v[174:177], v165 offset:32768
	ds_read_b128 v[178:181], v165 offset:33792
	ds_read_b128 v[188:191], v165 offset:34816
	ds_read_b128 v[194:197], v165 offset:35840
	ds_read_b128 v[198:201], v165 offset:36864
	ds_read_b128 v[202:205], v165 offset:37888
	ds_read_b128 v[206:209], v165 offset:38912
	global_load_lds_dwordx4 v128, s[0:1]
	s_mov_b32 m0, s77
	ds_read_b128 v[210:213], v165 offset:39936
	global_load_lds_dwordx4 v132, s[0:1]
	s_waitcnt lgkmcnt(8)
	s_barrier
; #define PG8_STAGE(bufoff, gbase, voff) do { _Pragma("unroll") for (int _i = 0; _i < 2; ++_i) \
;         __builtin_amdgcn_global_load_lds((const unsigned*)((const char*)(gbase) + (voff)[_i]), (LAS unsigned*)(lds + (bufoff) + ldsw + _i * 8192), 16, 0, 0); } while (0)
; #define PG8_LDA(dst, b, h) do { _Pragma("unroll") for (int m = 0; m < 4; ++m) _Pragma("unroll") for (int k = 0; k < 2; ++k) dst[m][k] = *(const LAS bf16x8*)(lds + PG8_SA(b, h) + aoff + m * 2048 + k * 1024); } while (0)
; #define PG8_LDB(dst, b, h) do { _Pragma("unroll") for (int n = 0; n < 2; ++n) _Pragma("unroll") for (int k = 0; k < 2; ++k) dst[n][k] = *(const LAS bf16x8*)(lds + PG8_SB(b, h) + boff + n * 2048 + k * 1024); } while (0)
; #define PG8_MMA(ai, bj, At, Bt) do { __builtin_amdgcn_s_setprio(1); _Pragma("unroll") for (int m = 0; m < 4; ++m) _Pragma("unroll") for (int n = 0; n < 2; ++n) _Pragma("unroll") for (int k = 0; k < 2; ++k) \
;         acc[ai][bj][m][n] = __builtin_amdgcn_mfma_f32_16x16x32_bf16(Bt[n][k], At[m][k], acc[ai][bj][m][n], 0, 0, 0); __builtin_amdgcn_s_setprio(0); } while (0)
; #define PG8_WAIT_V(n) asm volatile("s_waitcnt vmcnt(" #n ")" ::: "memory")
; #define PG8_WAIT_L(n) asm volatile("s_waitcnt lgkmcnt(" #n ")" ::: "memory")
; #define PG8_BAR __builtin_amdgcn_s_barrier()
; #define PG8_SCHED __builtin_amdgcn_sched_barrier(0)
; template <class Epi, class Sched>
; DI void gemm_phase(LAS unsigned char* lds, const Gemm g, const Sched& S, const Epi& E) {
;     ...
;             PG8_WAIT_L(8); PG8_BAR; PG8_WAIT_L(0); PG8_MMA(0, 0, At, B0); PG8_BAR; PG8_SCHED;
;             PG8_LDB(B1, 1, 1); PG8_STAGE(PG8_SB(1, 0), b3, voffB);
;             PG8_BAR; PG8_WAIT_L(0); PG8_MMA(0, 1, At, B1); PG8_BAR;
;             PG8_LDA(At, 1, 1); PG8_STAGE(PG8_SA(1, 0), a3, voffA);
;             PG8_BAR; PG8_WAIT_L(0); PG8_MMA(1, 0, At, B0); PG8_BAR; PG8_SCHED;
;             PG8_STAGE(PG8_SB(1, 1), b3 + hstep, voffB);
;             PG8_WAIT_V(6); PG8_BAR; PG8_MMA(1, 1, At, B1); PG8_BAR;
	s_waitcnt lgkmcnt(0)
	s_setprio 1
	v_mfma_f32_16x16x32_bf16 v[124:127], v[146:149], v[174:177], v[124:127]
	v_mfma_f32_16x16x32_bf16 v[120:123], v[154:157], v[174:177], v[120:123]
	v_mfma_f32_16x16x32_bf16 v[108:111], v[146:149], v[188:191], v[108:111]
	v_mfma_f32_16x16x32_bf16 v[104:107], v[154:157], v[188:191], v[104:107]
	v_mfma_f32_16x16x32_bf16 v[92:95], v[146:149], v[198:201], v[92:95]
	v_mfma_f32_16x16x32_bf16 v[88:91], v[154:157], v[198:201], v[88:91]
	v_mfma_f32_16x16x32_bf16 v[76:79], v[146:149], v[206:209], v[76:79]
	v_mfma_f32_16x16x32_bf16 v[72:75], v[154:157], v[206:209], v[72:75]
	v_mfma_f32_16x16x32_bf16 v[124:127], v[150:153], v[178:181], v[124:127]
	v_mfma_f32_16x16x32_bf16 v[120:123], v[170:173], v[178:181], v[120:123]
	v_mfma_f32_16x16x32_bf16 v[108:111], v[150:153], v[194:197], v[108:111]
	v_mfma_f32_16x16x32_bf16 v[104:107], v[170:173], v[194:197], v[104:107]
	v_mfma_f32_16x16x32_bf16 v[92:95], v[150:153], v[202:205], v[92:95]
	v_mfma_f32_16x16x32_bf16 v[88:91], v[170:173], v[202:205], v[88:91]
	v_mfma_f32_16x16x32_bf16 v[76:79], v[150:153], v[210:213], v[76:79]
	v_mfma_f32_16x16x32_bf16 v[72:75], v[170:173], v[210:213], v[72:75]
	s_setprio 0
	s_barrier
	s_add_i32 s5, 0, 0x1c000
	s_add_i32 s0, s4, s74
	s_add_i32 m0, s0, 0xffffff80
	ds_read_b128 v[214:217], v159
	ds_read_b128 v[218:221], v159 offset:1024
	ds_read_b128 v[222:225], v159 offset:2048
	global_load_lds_dwordx4 v130, s[10:11] offset:128
	s_add_i32 m0, s0, 0x1f80
	ds_read_b128 v[226:229], v159 offset:3072
	global_load_lds_dwordx4 v134, s[10:11] offset:128
	s_barrier
	s_waitcnt lgkmcnt(0)
	s_setprio 1
	v_mfma_f32_16x16x32_bf16 v[116:119], v[214:217], v[174:177], v[116:119]
	v_mfma_f32_16x16x32_bf16 v[112:115], v[222:225], v[174:177], v[112:115]
	v_mfma_f32_16x16x32_bf16 v[100:103], v[214:217], v[188:191], v[100:103]
	v_mfma_f32_16x16x32_bf16 v[96:99], v[222:225], v[188:191], v[96:99]
	v_mfma_f32_16x16x32_bf16 v[84:87], v[214:217], v[198:201], v[84:87]
	v_mfma_f32_16x16x32_bf16 v[80:83], v[222:225], v[198:201], v[80:83]
	v_mfma_f32_16x16x32_bf16 v[68:71], v[214:217], v[206:209], v[68:71]
	v_mfma_f32_16x16x32_bf16 v[64:67], v[222:225], v[206:209], v[64:67]
	v_mfma_f32_16x16x32_bf16 v[116:119], v[218:221], v[178:181], v[116:119]
	v_mfma_f32_16x16x32_bf16 v[112:115], v[226:229], v[178:181], v[112:115]
	v_mfma_f32_16x16x32_bf16 v[100:103], v[218:221], v[194:197], v[100:103]
	v_mfma_f32_16x16x32_bf16 v[96:99], v[226:229], v[194:197], v[96:99]
	v_mfma_f32_16x16x32_bf16 v[84:87], v[218:221], v[202:205], v[84:87]
	v_mfma_f32_16x16x32_bf16 v[80:83], v[226:229], v[202:205], v[80:83]
	v_mfma_f32_16x16x32_bf16 v[68:71], v[218:221], v[210:213], v[68:71]
	v_mfma_f32_16x16x32_bf16 v[64:67], v[226:229], v[210:213], v[64:67]
	s_setprio 0
	s_add_i32 m0, s97, 0xffffff80
	s_barrier
	ds_read_b128 v[174:177], v165 offset:49152
	ds_read_b128 v[178:181], v165 offset:50176
	ds_read_b128 v[188:191], v165 offset:51200
	ds_read_b128 v[194:197], v165 offset:52224
	ds_read_b128 v[198:201], v165 offset:53248
	ds_read_b128 v[202:205], v165 offset:54272
	ds_read_b128 v[206:209], v165 offset:55296
	global_load_lds_dwordx4 v128, s[12:13] offset:128
	s_add_i32 m0, s84, 0xffffff80
	ds_read_b128 v[210:213], v165 offset:56320
	global_load_lds_dwordx4 v132, s[12:13] offset:128
	s_barrier
	s_waitcnt lgkmcnt(0)
	s_setprio 1
	v_mfma_f32_16x16x32_bf16 v[60:63], v[146:149], v[174:177], v[60:63]
	v_mfma_f32_16x16x32_bf16 v[56:59], v[154:157], v[174:177], v[56:59]
	v_mfma_f32_16x16x32_bf16 v[44:47], v[146:149], v[188:191], v[44:47]
	v_mfma_f32_16x16x32_bf16 v[40:43], v[154:157], v[188:191], v[40:43]
	v_mfma_f32_16x16x32_bf16 v[28:31], v[146:149], v[198:201], v[28:31]
	v_mfma_f32_16x16x32_bf16 v[24:27], v[154:157], v[198:201], v[24:27]
	v_mfma_f32_16x16x32_bf16 v[12:15], v[146:149], v[206:209], v[12:15]
	v_mfma_f32_16x16x32_bf16 v[8:11], v[154:157], v[206:209], v[8:11]
	v_mfma_f32_16x16x32_bf16 v[60:63], v[150:153], v[178:181], v[60:63]
	v_mfma_f32_16x16x32_bf16 v[56:59], v[170:173], v[178:181], v[56:59]
	v_mfma_f32_16x16x32_bf16 v[44:47], v[150:153], v[194:197], v[44:47]
	v_mfma_f32_16x16x32_bf16 v[40:43], v[170:173], v[194:197], v[40:43]
	v_mfma_f32_16x16x32_bf16 v[28:31], v[150:153], v[202:205], v[28:31]
	v_mfma_f32_16x16x32_bf16 v[24:27], v[170:173], v[202:205], v[24:27]
	v_mfma_f32_16x16x32_bf16 v[12:15], v[150:153], v[210:213], v[12:15]
	v_mfma_f32_16x16x32_bf16 v[8:11], v[170:173], v[210:213], v[8:11]
	s_setprio 0
	s_barrier
	s_add_i32 s4, s5, s74
	s_mov_b32 m0, s4
	s_add_u32 s0, s10, 0x80080
	s_addc_u32 s1, s11, 0
	global_load_lds_dwordx4 v130, s[0:1]
	v_lshl_add_u64 v[146:147], s[0:1], 0, v[134:135]
	s_add_i32 m0, s4, 0x2000
	s_nop 0
	global_load_lds_dwordx4 v134, s[0:1]
	s_add_i32 s35, s35, 2
	s_add_u32 s8, s8, 0x100
	s_addc_u32 s9, s9, 0
	s_add_u32 s28, s28, 0x100
	s_addc_u32 s34, s34, 0
	s_cmp_gt_u32 s35, 29
	s_waitcnt vmcnt(6)
	s_barrier
	s_setprio 1
	v_mfma_f32_16x16x32_bf16 v[52:55], v[214:217], v[174:177], v[52:55]
	v_mfma_f32_16x16x32_bf16 v[48:51], v[222:225], v[174:177], v[48:51]
	v_mfma_f32_16x16x32_bf16 v[36:39], v[214:217], v[188:191], v[36:39]
	v_mfma_f32_16x16x32_bf16 v[32:35], v[222:225], v[188:191], v[32:35]
	v_mfma_f32_16x16x32_bf16 v[20:23], v[214:217], v[198:201], v[20:23]
	v_mfma_f32_16x16x32_bf16 v[16:19], v[222:225], v[198:201], v[16:19]
	v_mfma_f32_16x16x32_bf16 v[4:7], v[214:217], v[206:209], v[4:7]
	v_mfma_f32_16x16x32_bf16 v[0:3], v[222:225], v[206:209], v[0:3]
	v_mfma_f32_16x16x32_bf16 v[52:55], v[218:221], v[178:181], v[52:55]
	v_mfma_f32_16x16x32_bf16 v[48:51], v[226:229], v[178:181], v[48:51]
	v_mfma_f32_16x16x32_bf16 v[36:39], v[218:221], v[194:197], v[36:39]
	v_mfma_f32_16x16x32_bf16 v[32:35], v[226:229], v[194:197], v[32:35]
	v_mfma_f32_16x16x32_bf16 v[20:23], v[218:221], v[202:205], v[20:23]
	v_mfma_f32_16x16x32_bf16 v[16:19], v[226:229], v[202:205], v[16:19]
	v_mfma_f32_16x16x32_bf16 v[4:7], v[218:221], v[210:213], v[4:7]
	v_mfma_f32_16x16x32_bf16 v[0:3], v[226:229], v[210:213], v[0:3]
	s_setprio 0
	s_barrier
	s_cbranch_scc0 .LBB0_527

;     DI size_t aoff(const Unit& u, size_t tstep) const { return (size_t)u.pm * tstep; }
;     DI size_t boff(const Unit& u, size_t tstep) const { return (size_t)u.pn * tstep; }
;     DI size_t aoff(const Unit& u, size_t) const { return (size_t)u.ks * kbytes; }
; template <class Epi, class Sched>
; DI void gemm_phase(LAS unsigned char* lds, const Gemm g, const Sched& S, const Epi& E) {
;     ...
;         const bool has_next = S.next(ui + 1, nxt);
;         const char* nA = has_next ? (const char*)g.A + S.aoff(nxt, tstep) : cA; const char* nB = has_next ? (const char*)g.Bt + S.boff(nxt, tstep) : cB;
;         for (int t = 0; t < nt; t += 2) {
;             if constexpr (Epi::HAS_MID) { if (t == E.mid_t(nt)) { int fr3 = fr, fq3 = fq; asm volatile("" : "+v"(fr3), "+v"(fq3)); E.mid(acc, cur, wr, wc, fr3, fq3); } }
;             const bool last = (t == nt - 2);
;             const char* a1 = cA + (size_t)(t + 1) * kstep;
;             const char* a2 = last ? nA : cA + (size_t)(t + 2) * kstep; const char* b2 = last ? nB : cB + (size_t)(t + 2) * kstep;
;             const char* a3 = a2 + kstep; const char* b3 = b2 + kstep;
;             PG8_LDB(B0, 0, 0); PG8_SCHED; PG8_LDA(At, 0, 0); PG8_STAGE(PG8_SA(1, 1), a1 + hstep, voffA);
;             PG8_WAIT_L(8); PG8_BAR; PG8_WAIT_L(0); PG8_MMA(0, 0, At, B0); PG8_BAR; PG8_SCHED;
;             PG8_LDB(B1, 0, 1); PG8_STAGE(PG8_SB(0, 0), b2, voffB);
;             PG8_BAR; PG8_WAIT_L(0); PG8_MMA(0, 1, At, B1); PG8_BAR;
;             PG8_LDA(At, 0, 1); PG8_STAGE(PG8_SA(0, 0), a2, voffA);
;             PG8_BAR; PG8_WAIT_L(0); PG8_MMA(1, 0, At, B0); PG8_BAR; PG8_SCHED;
;             PG8_STAGE(PG8_SB(0, 1), b2 + hstep, voffB);
;             PG8_WAIT_V(6); PG8_BAR; PG8_MMA(1, 1, At, B1); PG8_BAR;
;             PG8_LDB(B0, 1, 0); PG8_SCHED; PG8_LDA(At, 1, 0); PG8_STAGE(PG8_SA(0, 1), a2 + hstep, voffA);
;             PG8_WAIT_L(8); PG8_BAR; PG8_WAIT_L(0); PG8_MMA(0, 0, At, B0); PG8_BAR; PG8_SCHED;
;             PG8_LDB(B1, 1, 1); PG8_STAGE(PG8_SB(1, 0), b3, voffB);
;             PG8_BAR; PG8_WAIT_L(0); PG8_MMA(0, 1, At, B1); PG8_BAR;
;             PG8_LDA(At, 1, 1); PG8_STAGE(PG8_SA(1, 0), a3, voffA);
;             PG8_BAR; PG8_WAIT_L(0); PG8_MMA(1, 0, At, B0); PG8_BAR; PG8_SCHED;
;             PG8_STAGE(PG8_SB(1, 1), b3 + hstep, voffB);
;             PG8_WAIT_V(6); PG8_BAR; PG8_MMA(1, 1, At, B1); PG8_BAR;
.LBB0_937:
	s_add_u32 s8, s38, 0x30080
	s_addc_u32 s9, s39, 0
	s_add_u32 s35, s36, 0x100
	v_mov_b32_e32 v0, 0
	s_addc_u32 s40, s37, 0
	s_mov_b32 s41, -2
	ds_read_b128 v[144:147], v165
	ds_read_b128 v[168:171], v165 offset:1024
	ds_read_b128 v[172:175], v165 offset:2048
	ds_read_b128 v[176:179], v165 offset:3072
	s_add_i32 m0, s51, 0xc000
	ds_read_b128 v[180:183], v166
	ds_read_b128 v[188:191], v166 offset:1024
	ds_read_b128 v[194:197], v166 offset:2048
	ds_read_b128 v[198:201], v166 offset:3072
	ds_read_b128 v[202:205], v166 offset:4096
	ds_read_b128 v[206:209], v166 offset:5120
	ds_read_b128 v[210:213], v166 offset:6144
	global_load_lds_dwordx4 v136, s[8:9]
	s_add_i32 m0, s51, 0xe000
	ds_read_b128 v[214:217], v166 offset:7168
	global_load_lds_dwordx4 v138, s[8:9]
	s_add_u32 s0, s8, 0xfffd0080
	s_addc_u32 s1, s9, -1
	s_cmp_eq_u32 s41, 8
	s_cselect_b32 s39, s31, s1
	s_cselect_b32 s38, s30, s0
	s_cselect_b32 s37, s11, s40
	s_cselect_b32 s36, s10, s35
	s_waitcnt lgkmcnt(8)
	s_barrier
	s_waitcnt lgkmcnt(0)
	s_setprio 1
	v_mfma_f32_16x16x32_bf16 v[124:127], v[144:147], v[180:183], 0
	v_mfma_f32_16x16x32_bf16 v[120:123], v[172:175], v[180:183], 0
	v_mfma_f32_16x16x32_bf16 v[108:111], v[144:147], v[194:197], 0
	v_mfma_f32_16x16x32_bf16 v[104:107], v[172:175], v[194:197], 0
	v_mfma_f32_16x16x32_bf16 v[92:95], v[144:147], v[202:205], 0
	v_mfma_f32_16x16x32_bf16 v[88:91], v[172:175], v[202:205], 0
	v_mfma_f32_16x16x32_bf16 v[76:79], v[144:147], v[210:213], 0
	v_mfma_f32_16x16x32_bf16 v[72:75], v[172:175], v[210:213], 0
	v_mfma_f32_16x16x32_bf16 v[124:127], v[168:171], v[188:191], v[124:127]
	v_mfma_f32_16x16x32_bf16 v[120:123], v[176:179], v[188:191], v[120:123]
	v_mfma_f32_16x16x32_bf16 v[108:111], v[168:171], v[198:201], v[108:111]
	v_mfma_f32_16x16x32_bf16 v[104:107], v[176:179], v[198:201], v[104:107]
	v_mfma_f32_16x16x32_bf16 v[92:95], v[168:171], v[206:209], v[92:95]
	v_mfma_f32_16x16x32_bf16 v[88:91], v[176:179], v[206:209], v[88:91]
	v_mfma_f32_16x16x32_bf16 v[76:79], v[168:171], v[214:217], v[76:79]
	v_mfma_f32_16x16x32_bf16 v[72:75], v[176:179], v[214:217], v[72:75]
	s_setprio 0
	s_barrier
	s_add_i32 s0, s61, s50
	s_mov_b32 m0, s0
	ds_read_b128 v[218:221], v167
	ds_read_b128 v[222:225], v167 offset:1024
	ds_read_b128 v[226:229], v167 offset:2048
	global_load_lds_dwordx4 v130, s[36:37]
	s_add_i32 m0, s0, 0x2000
	ds_read_b128 v[230:233], v167 offset:3072
	global_load_lds_dwordx4 v134, s[36:37]
	s_barrier
	s_waitcnt lgkmcnt(0)
	s_setprio 1
	v_mfma_f32_16x16x32_bf16 v[116:119], v[218:221], v[180:183], 0
	v_mfma_f32_16x16x32_bf16 v[112:115], v[226:229], v[180:183], 0
	v_mfma_f32_16x16x32_bf16 v[100:103], v[218:221], v[194:197], 0
	v_mfma_f32_16x16x32_bf16 v[96:99], v[226:229], v[194:197], 0
	v_mfma_f32_16x16x32_bf16 v[84:87], v[218:221], v[202:205], 0
	v_mfma_f32_16x16x32_bf16 v[80:83], v[226:229], v[202:205], 0
	v_mfma_f32_16x16x32_bf16 v[68:71], v[218:221], v[210:213], 0
	v_mfma_f32_16x16x32_bf16 v[64:67], v[226:229], v[210:213], 0
	v_mfma_f32_16x16x32_bf16 v[116:119], v[222:225], v[188:191], v[116:119]
	v_mfma_f32_16x16x32_bf16 v[112:115], v[230:233], v[188:191], v[112:115]
	v_mfma_f32_16x16x32_bf16 v[100:103], v[222:225], v[198:201], v[100:103]
	v_mfma_f32_16x16x32_bf16 v[96:99], v[230:233], v[198:201], v[96:99]
	v_mfma_f32_16x16x32_bf16 v[84:87], v[222:225], v[206:209], v[84:87]
	v_mfma_f32_16x16x32_bf16 v[80:83], v[230:233], v[206:209], v[80:83]
	v_mfma_f32_16x16x32_bf16 v[68:71], v[222:225], v[214:217], v[68:71]
	v_mfma_f32_16x16x32_bf16 v[64:67], v[230:233], v[214:217], v[64:67]
	s_setprio 0
	s_mov_b32 m0, s51
	s_barrier
	ds_read_b128 v[180:183], v166 offset:16384
	ds_read_b128 v[188:191], v166 offset:17408
	ds_read_b128 v[194:197], v166 offset:18432
	ds_read_b128 v[198:201], v166 offset:19456
	ds_read_b128 v[202:205], v166 offset:20480
	ds_read_b128 v[206:209], v166 offset:21504
	ds_read_b128 v[210:213], v166 offset:22528
	global_load_lds_dwordx4 v128, s[38:39]
	s_mov_b32 m0, s52
	ds_read_b128 v[214:217], v166 offset:23552
	global_load_lds_dwordx4 v132, s[38:39]
	s_barrier
	s_waitcnt lgkmcnt(0)
	s_setprio 1
	v_mfma_f32_16x16x32_bf16 v[60:63], v[144:147], v[180:183], 0
	v_mfma_f32_16x16x32_bf16 v[56:59], v[172:175], v[180:183], 0
	v_mfma_f32_16x16x32_bf16 v[44:47], v[144:147], v[194:197], 0
	v_mfma_f32_16x16x32_bf16 v[40:43], v[172:175], v[194:197], 0
	v_mfma_f32_16x16x32_bf16 v[28:31], v[144:147], v[202:205], 0
	v_mfma_f32_16x16x32_bf16 v[24:27], v[172:175], v[202:205], 0
	v_mfma_f32_16x16x32_bf16 v[12:15], v[144:147], v[210:213], 0
	v_mfma_f32_16x16x32_bf16 v[8:11], v[172:175], v[210:213], 0
	v_mfma_f32_16x16x32_bf16 v[60:63], v[168:171], v[188:191], v[60:63]
	v_mfma_f32_16x16x32_bf16 v[56:59], v[176:179], v[188:191], v[56:59]
	v_mfma_f32_16x16x32_bf16 v[44:47], v[168:171], v[198:201], v[44:47]
	v_mfma_f32_16x16x32_bf16 v[40:43], v[176:179], v[198:201], v[40:43]
	v_mfma_f32_16x16x32_bf16 v[28:31], v[168:171], v[206:209], v[28:31]
	v_mfma_f32_16x16x32_bf16 v[24:27], v[176:179], v[206:209], v[24:27]
	v_mfma_f32_16x16x32_bf16 v[12:15], v[168:171], v[214:217], v[12:15]
	v_mfma_f32_16x16x32_bf16 v[8:11], v[176:179], v[214:217], v[8:11]
	s_setprio 0
	s_barrier
	s_add_i32 s4, s62, s50
	s_mov_b32 m0, s4
	s_add_u32 s0, s36, 0x30000
	s_addc_u32 s1, s37, 0
	global_load_lds_dwordx4 v130, s[0:1]
	s_add_i32 m0, s4, 0x2000
	s_nop 0
	global_load_lds_dwordx4 v134, s[0:1]
	s_waitcnt vmcnt(6)
	s_barrier
; #define PG8_STAGE(bufoff, gbase, voff) do { _Pragma("unroll") for (int _i = 0; _i < 2; ++_i) \
;         __builtin_amdgcn_global_load_lds((const unsigned*)((const char*)(gbase) + (voff)[_i]), (LAS unsigned*)(lds + (bufoff) + ldsw + _i * 8192), 16, 0, 0); } while (0)
; #define PG8_LDA(dst, b, h) do { _Pragma("unroll") for (int m = 0; m < 4; ++m) _Pragma("unroll") for (int k = 0; k < 2; ++k) dst[m][k] = *(const LAS bf16x8*)(lds + PG8_SA(b, h) + aoff + m * 2048 + k * 1024); } while (0)
; #define PG8_LDB(dst, b, h) do { _Pragma("unroll") for (int n = 0; n < 2; ++n) _Pragma("unroll") for (int k = 0; k < 2; ++k) dst[n][k] = *(const LAS bf16x8*)(lds + PG8_SB(b, h) + boff + n * 2048 + k * 1024); } while (0)
; #define PG8_MMA(ai, bj, At, Bt) do { __builtin_amdgcn_s_setprio(1); _Pragma("unroll") for (int m = 0; m < 4; ++m) _Pragma("unroll") for (int n = 0; n < 2; ++n) _Pragma("unroll") for (int k = 0; k < 2; ++k) \
;         acc[ai][bj][m][n] = __builtin_amdgcn_mfma_f32_16x16x32_bf16(Bt[n][k], At[m][k], acc[ai][bj][m][n], 0, 0, 0); __builtin_amdgcn_s_setprio(0); } while (0)
; #define PG8_WAIT_V(n) asm volatile("s_waitcnt vmcnt(" #n ")" ::: "memory")
; #define PG8_WAIT_L(n) asm volatile("s_waitcnt lgkmcnt(" #n ")" ::: "memory")
; #define PG8_BAR __builtin_amdgcn_s_barrier()
; #define PG8_SCHED __builtin_amdgcn_sched_barrier(0)
; template <class Epi, class Sched>
; DI void gemm_phase(LAS unsigned char* lds, const Gemm g, const Sched& S, const Epi& E) {
;     ...
;             PG8_WAIT_V(6); PG8_BAR; PG8_MMA(1, 1, At, B1); PG8_BAR;
;             PG8_LDB(B0, 1, 0); PG8_SCHED; PG8_LDA(At, 1, 0); PG8_STAGE(PG8_SA(0, 1), a2 + hstep, voffA);
;             PG8_WAIT_L(8); PG8_BAR; PG8_WAIT_L(0); PG8_MMA(0, 0, At, B0); PG8_BAR; PG8_SCHED;
;             PG8_LDB(B1, 1, 1); PG8_STAGE(PG8_SB(1, 0), b3, voffB);
;             PG8_BAR; PG8_WAIT_L(0); PG8_MMA(0, 1, At, B1); PG8_BAR;
;             PG8_LDA(At, 1, 1); PG8_STAGE(PG8_SA(1, 0), a3, voffA);
;             PG8_BAR; PG8_WAIT_L(0); PG8_MMA(1, 0, At, B0); PG8_BAR; PG8_SCHED;
;             PG8_STAGE(PG8_SB(1, 1), b3 + hstep, voffB);
;             PG8_WAIT_V(6); PG8_BAR; PG8_MMA(1, 1, At, B1); PG8_BAR;
	s_setprio 1
	v_mfma_f32_16x16x32_bf16 v[52:55], v[218:221], v[180:183], 0
	v_mfma_f32_16x16x32_bf16 v[48:51], v[226:229], v[180:183], 0
	v_mfma_f32_16x16x32_bf16 v[36:39], v[218:221], v[194:197], 0
	v_mfma_f32_16x16x32_bf16 v[32:35], v[226:229], v[194:197], 0
	v_mfma_f32_16x16x32_bf16 v[20:23], v[218:221], v[202:205], 0
	v_mfma_f32_16x16x32_bf16 v[16:19], v[226:229], v[202:205], 0
	v_mfma_f32_16x16x32_bf16 v[4:7], v[218:221], v[210:213], 0
	v_mfma_f32_16x16x32_bf16 v[0:3], v[226:229], v[210:213], 0
	v_mfma_f32_16x16x32_bf16 v[52:55], v[222:225], v[188:191], v[52:55]
	v_mfma_f32_16x16x32_bf16 v[48:51], v[230:233], v[188:191], v[48:51]
	v_mfma_f32_16x16x32_bf16 v[36:39], v[222:225], v[198:201], v[36:39]
	v_mfma_f32_16x16x32_bf16 v[32:35], v[230:233], v[198:201], v[32:35]
	v_mfma_f32_16x16x32_bf16 v[20:23], v[222:225], v[206:209], v[20:23]
	v_mfma_f32_16x16x32_bf16 v[16:19], v[230:233], v[206:209], v[16:19]
	v_mfma_f32_16x16x32_bf16 v[4:7], v[222:225], v[214:217], v[4:7]
	v_mfma_f32_16x16x32_bf16 v[0:3], v[230:233], v[214:217], v[0:3]
	s_setprio 0
	s_add_i32 s4, 0, 0x18000
	v_add_u32_e32 v148, s4, v164
	s_barrier
	ds_read_b128 v[144:147], v148
	ds_read_b128 v[168:171], v148 offset:1024
	ds_read_b128 v[172:175], v148 offset:2048
	ds_read_b128 v[176:179], v148 offset:3072
	s_add_u32 s0, s38, 0x30000
	s_addc_u32 s1, s39, 0
	s_mov_b32 m0, s53
	ds_read_b128 v[180:183], v166 offset:32768
	ds_read_b128 v[188:191], v166 offset:33792
	ds_read_b128 v[194:197], v166 offset:34816
	ds_read_b128 v[198:201], v166 offset:35840
	ds_read_b128 v[202:205], v166 offset:36864
	ds_read_b128 v[206:209], v166 offset:37888
	ds_read_b128 v[210:213], v166 offset:38912
	global_load_lds_dwordx4 v128, s[0:1]
	s_mov_b32 m0, s54
	ds_read_b128 v[214:217], v166 offset:39936
	global_load_lds_dwordx4 v132, s[0:1]
	s_waitcnt lgkmcnt(8)
	s_barrier
	s_waitcnt lgkmcnt(0)
	s_setprio 1
	v_mfma_f32_16x16x32_bf16 v[124:127], v[144:147], v[180:183], v[124:127]
	v_mfma_f32_16x16x32_bf16 v[120:123], v[172:175], v[180:183], v[120:123]
	v_mfma_f32_16x16x32_bf16 v[108:111], v[144:147], v[194:197], v[108:111]
	v_mfma_f32_16x16x32_bf16 v[104:107], v[172:175], v[194:197], v[104:107]
	v_mfma_f32_16x16x32_bf16 v[92:95], v[144:147], v[202:205], v[92:95]
	v_mfma_f32_16x16x32_bf16 v[88:91], v[172:175], v[202:205], v[88:91]
	v_mfma_f32_16x16x32_bf16 v[76:79], v[144:147], v[210:213], v[76:79]
	v_mfma_f32_16x16x32_bf16 v[72:75], v[172:175], v[210:213], v[72:75]
	v_mfma_f32_16x16x32_bf16 v[124:127], v[168:171], v[188:191], v[124:127]
	v_mfma_f32_16x16x32_bf16 v[120:123], v[176:179], v[188:191], v[120:123]
	v_mfma_f32_16x16x32_bf16 v[108:111], v[168:171], v[198:201], v[108:111]
	v_mfma_f32_16x16x32_bf16 v[104:107], v[176:179], v[198:201], v[104:107]
	v_mfma_f32_16x16x32_bf16 v[92:95], v[168:171], v[206:209], v[92:95]
	v_mfma_f32_16x16x32_bf16 v[88:91], v[176:179], v[206:209], v[88:91]
	v_mfma_f32_16x16x32_bf16 v[76:79], v[168:171], v[214:217], v[76:79]
	v_mfma_f32_16x16x32_bf16 v[72:75], v[176:179], v[214:217], v[72:75]
	s_setprio 0
	s_barrier
	s_add_i32 s5, 0, 0x1c000
	s_add_i32 s0, s4, s50
	v_add_u32_e32 v149, s5, v164
	s_add_i32 m0, s0, 0xffffff80
	ds_read_b128 v[218:221], v149
	ds_read_b128 v[222:225], v149 offset:1024
	ds_read_b128 v[226:229], v149 offset:2048
	global_load_lds_dwordx4 v130, s[36:37] offset:128
	s_add_i32 m0, s0, 0x1f80
	ds_read_b128 v[230:233], v149 offset:3072
	global_load_lds_dwordx4 v134, s[36:37] offset:128
	s_barrier
	s_waitcnt lgkmcnt(0)
	s_setprio 1
	v_mfma_f32_16x16x32_bf16 v[116:119], v[218:221], v[180:183], v[116:119]
	v_mfma_f32_16x16x32_bf16 v[112:115], v[226:229], v[180:183], v[112:115]
	v_mfma_f32_16x16x32_bf16 v[100:103], v[218:221], v[194:197], v[100:103]
	v_mfma_f32_16x16x32_bf16 v[96:99], v[226:229], v[194:197], v[96:99]
	v_mfma_f32_16x16x32_bf16 v[84:87], v[218:221], v[202:205], v[84:87]
	v_mfma_f32_16x16x32_bf16 v[80:83], v[226:229], v[202:205], v[80:83]
	v_mfma_f32_16x16x32_bf16 v[68:71], v[218:221], v[210:213], v[68:71]
	v_mfma_f32_16x16x32_bf16 v[64:67], v[226:229], v[210:213], v[64:67]
	v_mfma_f32_16x16x32_bf16 v[116:119], v[222:225], v[188:191], v[116:119]
	v_mfma_f32_16x16x32_bf16 v[112:115], v[230:233], v[188:191], v[112:115]
	v_mfma_f32_16x16x32_bf16 v[100:103], v[222:225], v[198:201], v[100:103]
	v_mfma_f32_16x16x32_bf16 v[96:99], v[230:233], v[198:201], v[96:99]
	v_mfma_f32_16x16x32_bf16 v[84:87], v[222:225], v[206:209], v[84:87]
	v_mfma_f32_16x16x32_bf16 v[80:83], v[230:233], v[206:209], v[80:83]
	v_mfma_f32_16x16x32_bf16 v[68:71], v[222:225], v[214:217], v[68:71]
	v_mfma_f32_16x16x32_bf16 v[64:67], v[230:233], v[214:217], v[64:67]
	s_setprio 0
	s_add_i32 m0, s57, 0xffffff80
	s_barrier
	ds_read_b128 v[180:183], v166 offset:49152
	ds_read_b128 v[188:191], v166 offset:50176
	ds_read_b128 v[194:197], v166 offset:51200
	ds_read_b128 v[198:201], v166 offset:52224
	ds_read_b128 v[202:205], v166 offset:53248
	ds_read_b128 v[206:209], v166 offset:54272
	ds_read_b128 v[210:213], v166 offset:55296
	global_load_lds_dwordx4 v128, s[38:39] offset:128
	s_add_i32 m0, s58, 0xffffff80
	ds_read_b128 v[214:217], v166 offset:56320
	global_load_lds_dwordx4 v132, s[38:39] offset:128
	s_barrier
; #define PG8_STAGE(bufoff, gbase, voff) do { _Pragma("unroll") for (int _i = 0; _i < 2; ++_i) \
;         __builtin_amdgcn_global_load_lds((const unsigned*)((const char*)(gbase) + (voff)[_i]), (LAS unsigned*)(lds + (bufoff) + ldsw + _i * 8192), 16, 0, 0); } while (0)
; #define PG8_LDA(dst, b, h) do { _Pragma("unroll") for (int m = 0; m < 4; ++m) _Pragma("unroll") for (int k = 0; k < 2; ++k) dst[m][k] = *(const LAS bf16x8*)(lds + PG8_SA(b, h) + aoff + m * 2048 + k * 1024); } while (0)
; #define PG8_LDB(dst, b, h) do { _Pragma("unroll") for (int n = 0; n < 2; ++n) _Pragma("unroll") for (int k = 0; k < 2; ++k) dst[n][k] = *(const LAS bf16x8*)(lds + PG8_SB(b, h) + boff + n * 2048 + k * 1024); } while (0)
; #define PG8_MMA(ai, bj, At, Bt) do { __builtin_amdgcn_s_setprio(1); _Pragma("unroll") for (int m = 0; m < 4; ++m) _Pragma("unroll") for (int n = 0; n < 2; ++n) _Pragma("unroll") for (int k = 0; k < 2; ++k) \
;         acc[ai][bj][m][n] = __builtin_amdgcn_mfma_f32_16x16x32_bf16(Bt[n][k], At[m][k], acc[ai][bj][m][n], 0, 0, 0); __builtin_amdgcn_s_setprio(0); } while (0)
; #define PG8_WAIT_V(n) asm volatile("s_waitcnt vmcnt(" #n ")" ::: "memory")
; #define PG8_WAIT_L(n) asm volatile("s_waitcnt lgkmcnt(" #n ")" ::: "memory")
; #define PG8_BAR __builtin_amdgcn_s_barrier()
; #define PG8_SCHED __builtin_amdgcn_sched_barrier(0)
; template <class Epi, class Sched>
; DI void gemm_phase(LAS unsigned char* lds, const Gemm g, const Sched& S, const Epi& E) {
;     ...
;             PG8_LDB(B0, 0, 0); PG8_SCHED; PG8_LDA(At, 0, 0); PG8_STAGE(PG8_SA(1, 1), a1 + hstep, voffA);
;             PG8_WAIT_L(8); PG8_BAR; PG8_WAIT_L(0); PG8_MMA(0, 0, At, B0); PG8_BAR; PG8_SCHED;
;             PG8_LDB(B1, 0, 1); PG8_STAGE(PG8_SB(0, 0), b2, voffB);
;     ...
;             PG8_BAR; PG8_WAIT_L(0); PG8_MMA(0, 1, At, B1); PG8_BAR;
;             PG8_LDA(At, 1, 1); PG8_STAGE(PG8_SA(1, 0), a3, voffA);
;             PG8_BAR; PG8_WAIT_L(0); PG8_MMA(1, 0, At, B0); PG8_BAR; PG8_SCHED;
;             PG8_STAGE(PG8_SB(1, 1), b3 + hstep, voffB);
;             PG8_WAIT_V(6); PG8_BAR; PG8_MMA(1, 1, At, B1); PG8_BAR;
	s_waitcnt lgkmcnt(0)
	s_setprio 1
	v_mfma_f32_16x16x32_bf16 v[60:63], v[144:147], v[180:183], v[60:63]
	v_mfma_f32_16x16x32_bf16 v[56:59], v[172:175], v[180:183], v[56:59]
	v_mfma_f32_16x16x32_bf16 v[44:47], v[144:147], v[194:197], v[44:47]
	v_mfma_f32_16x16x32_bf16 v[40:43], v[172:175], v[194:197], v[40:43]
	v_mfma_f32_16x16x32_bf16 v[28:31], v[144:147], v[202:205], v[28:31]
	v_mfma_f32_16x16x32_bf16 v[24:27], v[172:175], v[202:205], v[24:27]
	v_mfma_f32_16x16x32_bf16 v[12:15], v[144:147], v[210:213], v[12:15]
	v_mfma_f32_16x16x32_bf16 v[8:11], v[172:175], v[210:213], v[8:11]
	v_mfma_f32_16x16x32_bf16 v[60:63], v[168:171], v[188:191], v[60:63]
	v_mfma_f32_16x16x32_bf16 v[56:59], v[176:179], v[188:191], v[56:59]
	v_mfma_f32_16x16x32_bf16 v[44:47], v[168:171], v[198:201], v[44:47]
	v_mfma_f32_16x16x32_bf16 v[40:43], v[176:179], v[198:201], v[40:43]
	v_mfma_f32_16x16x32_bf16 v[28:31], v[168:171], v[206:209], v[28:31]
	v_mfma_f32_16x16x32_bf16 v[24:27], v[176:179], v[206:209], v[24:27]
	v_mfma_f32_16x16x32_bf16 v[12:15], v[168:171], v[214:217], v[12:15]
	v_mfma_f32_16x16x32_bf16 v[8:11], v[176:179], v[214:217], v[8:11]
	s_setprio 0
	s_barrier
	s_add_i32 s4, s5, s50
	s_mov_b32 m0, s4
	s_add_u32 s0, s36, 0x30080
	s_addc_u32 s1, s37, 0
	global_load_lds_dwordx4 v130, s[0:1]
	s_add_i32 m0, s4, 0x2000
	s_nop 0
	global_load_lds_dwordx4 v134, s[0:1]
	s_add_i32 s41, s41, 2
	s_add_u32 s8, s8, 0x100
	s_addc_u32 s9, s9, 0
	s_add_u32 s35, s35, 0x100
	s_addc_u32 s40, s40, 0
	s_cmp_gt_u32 s41, 9
	s_waitcnt vmcnt(6)
	s_barrier
	s_setprio 1
	v_mfma_f32_16x16x32_bf16 v[52:55], v[218:221], v[180:183], v[52:55]
	v_mfma_f32_16x16x32_bf16 v[48:51], v[226:229], v[180:183], v[48:51]
	v_mfma_f32_16x16x32_bf16 v[36:39], v[218:221], v[194:197], v[36:39]
	v_mfma_f32_16x16x32_bf16 v[32:35], v[226:229], v[194:197], v[32:35]
	v_mfma_f32_16x16x32_bf16 v[20:23], v[218:221], v[202:205], v[20:23]
	v_mfma_f32_16x16x32_bf16 v[16:19], v[226:229], v[202:205], v[16:19]
	v_mfma_f32_16x16x32_bf16 v[4:7], v[218:221], v[210:213], v[4:7]
	v_mfma_f32_16x16x32_bf16 v[0:3], v[226:229], v[210:213], v[0:3]
	v_mfma_f32_16x16x32_bf16 v[52:55], v[222:225], v[188:191], v[52:55]
	v_mfma_f32_16x16x32_bf16 v[48:51], v[230:233], v[188:191], v[48:51]
	v_mfma_f32_16x16x32_bf16 v[36:39], v[222:225], v[198:201], v[36:39]
	v_mfma_f32_16x16x32_bf16 v[32:35], v[230:233], v[198:201], v[32:35]
	v_mfma_f32_16x16x32_bf16 v[20:23], v[222:225], v[206:209], v[20:23]
	v_mfma_f32_16x16x32_bf16 v[16:19], v[230:233], v[206:209], v[16:19]
	v_mfma_f32_16x16x32_bf16 v[4:7], v[222:225], v[214:217], v[4:7]
	v_mfma_f32_16x16x32_bf16 v[0:3], v[230:233], v[214:217], v[0:3]
	s_setprio 0
	s_barrier
	s_cbranch_scc0 .LBB0_938
	s_branch .Lpeel_done_938
.LBB0_938:
	ds_read_b128 v[144:147], v165
	ds_read_b128 v[168:171], v165 offset:1024
	ds_read_b128 v[172:175], v165 offset:2048
	ds_read_b128 v[176:179], v165 offset:3072
	s_add_i32 m0, s51, 0xc000
	ds_read_b128 v[180:183], v166
	ds_read_b128 v[188:191], v166 offset:1024
	ds_read_b128 v[194:197], v166 offset:2048
	ds_read_b128 v[198:201], v166 offset:3072
	ds_read_b128 v[202:205], v166 offset:4096
	ds_read_b128 v[206:209], v166 offset:5120
	ds_read_b128 v[210:213], v166 offset:6144
	global_load_lds_dwordx4 v136, s[8:9]
	s_add_i32 m0, s51, 0xe000
	ds_read_b128 v[214:217], v166 offset:7168
	global_load_lds_dwordx4 v138, s[8:9]
	s_add_u32 s0, s8, 0xfffd0080
	s_addc_u32 s1, s9, -1
	s_cmp_eq_u32 s41, 8
	s_cselect_b32 s39, s31, s1
	s_cselect_b32 s38, s30, s0
	s_cselect_b32 s37, s11, s40
	s_cselect_b32 s36, s10, s35
	s_waitcnt lgkmcnt(8)
	s_barrier
	s_waitcnt lgkmcnt(0)
	s_setprio 1
	v_mfma_f32_16x16x32_bf16 v[124:127], v[144:147], v[180:183], v[124:127]
	v_mfma_f32_16x16x32_bf16 v[120:123], v[172:175], v[180:183], v[120:123]
	v_mfma_f32_16x16x32_bf16 v[108:111], v[144:147], v[194:197], v[108:111]
	v_mfma_f32_16x16x32_bf16 v[104:107], v[172:175], v[194:197], v[104:107]
	v_mfma_f32_16x16x32_bf16 v[92:95], v[144:147], v[202:205], v[92:95]
	v_mfma_f32_16x16x32_bf16 v[88:91], v[172:175], v[202:205], v[88:91]
	v_mfma_f32_16x16x32_bf16 v[76:79], v[144:147], v[210:213], v[76:79]
	v_mfma_f32_16x16x32_bf16 v[72:75], v[172:175], v[210:213], v[72:75]
	v_mfma_f32_16x16x32_bf16 v[124:127], v[168:171], v[188:191], v[124:127]
	v_mfma_f32_16x16x32_bf16 v[120:123], v[176:179], v[188:191], v[120:123]
	v_mfma_f32_16x16x32_bf16 v[108:111], v[168:171], v[198:201], v[108:111]
	v_mfma_f32_16x16x32_bf16 v[104:107], v[176:179], v[198:201], v[104:107]
	v_mfma_f32_16x16x32_bf16 v[92:95], v[168:171], v[206:209], v[92:95]
	v_mfma_f32_16x16x32_bf16 v[88:91], v[176:179], v[206:209], v[88:91]
	v_mfma_f32_16x16x32_bf16 v[76:79], v[168:171], v[214:217], v[76:79]
	v_mfma_f32_16x16x32_bf16 v[72:75], v[176:179], v[214:217], v[72:75]
	s_setprio 0
	s_barrier
	s_add_i32 s0, s61, s50
	s_mov_b32 m0, s0
	ds_read_b128 v[218:221], v167
	ds_read_b128 v[222:225], v167 offset:1024
	ds_read_b128 v[226:229], v167 offset:2048
	global_load_lds_dwordx4 v130, s[36:37]
	s_add_i32 m0, s0, 0x2000
	ds_read_b128 v[230:233], v167 offset:3072
	global_load_lds_dwordx4 v134, s[36:37]
	s_barrier
; #define PG8_STAGE(bufoff, gbase, voff) do { _Pragma("unroll") for (int _i = 0; _i < 2; ++_i) \
;         __builtin_amdgcn_global_load_lds((const unsigned*)((const char*)(gbase) + (voff)[_i]), (LAS unsigned*)(lds + (bufoff) + ldsw + _i * 8192), 16, 0, 0); } while (0)
; #define PG8_LDA(dst, b, h) do { _Pragma("unroll") for (int m = 0; m < 4; ++m) _Pragma("unroll") for (int k = 0; k < 2; ++k) dst[m][k] = *(const LAS bf16x8*)(lds + PG8_SA(b, h) + aoff + m * 2048 + k * 1024); } while (0)
; #define PG8_LDB(dst, b, h) do { _Pragma("unroll") for (int n = 0; n < 2; ++n) _Pragma("unroll") for (int k = 0; k < 2; ++k) dst[n][k] = *(const LAS bf16x8*)(lds + PG8_SB(b, h) + boff + n * 2048 + k * 1024); } while (0)
; #define PG8_MMA(ai, bj, At, Bt) do { __builtin_amdgcn_s_setprio(1); _Pragma("unroll") for (int m = 0; m < 4; ++m) _Pragma("unroll") for (int n = 0; n < 2; ++n) _Pragma("unroll") for (int k = 0; k < 2; ++k) \
;         acc[ai][bj][m][n] = __builtin_amdgcn_mfma_f32_16x16x32_bf16(Bt[n][k], At[m][k], acc[ai][bj][m][n], 0, 0, 0); __builtin_amdgcn_s_setprio(0); } while (0)
; #define PG8_WAIT_V(n) asm volatile("s_waitcnt vmcnt(" #n ")" ::: "memory")
; #define PG8_WAIT_L(n) asm volatile("s_waitcnt lgkmcnt(" #n ")" ::: "memory")
; #define PG8_BAR __builtin_amdgcn_s_barrier()
; #define PG8_SCHED __builtin_amdgcn_sched_barrier(0)
; template <class Epi, class Sched>
; DI void gemm_phase(LAS unsigned char* lds, const Gemm g, const Sched& S, const Epi& E) {
;     ...
;             PG8_BAR; PG8_WAIT_L(0); PG8_MMA(0, 1, At, B1); PG8_BAR;
;             PG8_LDA(At, 0, 1); PG8_STAGE(PG8_SA(0, 0), a2, voffA);
;             PG8_BAR; PG8_WAIT_L(0); PG8_MMA(1, 0, At, B0); PG8_BAR; PG8_SCHED;
;             PG8_STAGE(PG8_SB(0, 1), b2 + hstep, voffB);
;             PG8_WAIT_V(6); PG8_BAR; PG8_MMA(1, 1, At, B1); PG8_BAR;
;             PG8_LDB(B0, 1, 0); PG8_SCHED; PG8_LDA(At, 1, 0); PG8_STAGE(PG8_SA(0, 1), a2 + hstep, voffA);
;             PG8_WAIT_L(8); PG8_BAR; PG8_WAIT_L(0); PG8_MMA(0, 0, At, B0); PG8_BAR; PG8_SCHED;
	s_waitcnt lgkmcnt(0)
	s_setprio 1
	v_mfma_f32_16x16x32_bf16 v[116:119], v[218:221], v[180:183], v[116:119]
	v_mfma_f32_16x16x32_bf16 v[112:115], v[226:229], v[180:183], v[112:115]
	v_mfma_f32_16x16x32_bf16 v[100:103], v[218:221], v[194:197], v[100:103]
	v_mfma_f32_16x16x32_bf16 v[96:99], v[226:229], v[194:197], v[96:99]
	v_mfma_f32_16x16x32_bf16 v[84:87], v[218:221], v[202:205], v[84:87]
	v_mfma_f32_16x16x32_bf16 v[80:83], v[226:229], v[202:205], v[80:83]
	v_mfma_f32_16x16x32_bf16 v[68:71], v[218:221], v[210:213], v[68:71]
	v_mfma_f32_16x16x32_bf16 v[64:67], v[226:229], v[210:213], v[64:67]
	v_mfma_f32_16x16x32_bf16 v[116:119], v[222:225], v[188:191], v[116:119]
	v_mfma_f32_16x16x32_bf16 v[112:115], v[230:233], v[188:191], v[112:115]
	v_mfma_f32_16x16x32_bf16 v[100:103], v[222:225], v[198:201], v[100:103]
	v_mfma_f32_16x16x32_bf16 v[96:99], v[230:233], v[198:201], v[96:99]
	v_mfma_f32_16x16x32_bf16 v[84:87], v[222:225], v[206:209], v[84:87]
	v_mfma_f32_16x16x32_bf16 v[80:83], v[230:233], v[206:209], v[80:83]
	v_mfma_f32_16x16x32_bf16 v[68:71], v[222:225], v[214:217], v[68:71]
	v_mfma_f32_16x16x32_bf16 v[64:67], v[230:233], v[214:217], v[64:67]
	s_setprio 0
	s_mov_b32 m0, s51
	s_barrier
	ds_read_b128 v[180:183], v166 offset:16384
	ds_read_b128 v[188:191], v166 offset:17408
	ds_read_b128 v[194:197], v166 offset:18432
	ds_read_b128 v[198:201], v166 offset:19456
	ds_read_b128 v[202:205], v166 offset:20480
	ds_read_b128 v[206:209], v166 offset:21504
	ds_read_b128 v[210:213], v166 offset:22528
	global_load_lds_dwordx4 v128, s[38:39]
	s_mov_b32 m0, s52
	ds_read_b128 v[214:217], v166 offset:23552
	global_load_lds_dwordx4 v132, s[38:39]
	s_barrier
	s_waitcnt lgkmcnt(0)
	s_setprio 1
	v_mfma_f32_16x16x32_bf16 v[60:63], v[144:147], v[180:183], v[60:63]
	v_mfma_f32_16x16x32_bf16 v[56:59], v[172:175], v[180:183], v[56:59]
	v_mfma_f32_16x16x32_bf16 v[44:47], v[144:147], v[194:197], v[44:47]
	v_mfma_f32_16x16x32_bf16 v[40:43], v[172:175], v[194:197], v[40:43]
	v_mfma_f32_16x16x32_bf16 v[28:31], v[144:147], v[202:205], v[28:31]
	v_mfma_f32_16x16x32_bf16 v[24:27], v[172:175], v[202:205], v[24:27]
	v_mfma_f32_16x16x32_bf16 v[12:15], v[144:147], v[210:213], v[12:15]
	v_mfma_f32_16x16x32_bf16 v[8:11], v[172:175], v[210:213], v[8:11]
	v_mfma_f32_16x16x32_bf16 v[60:63], v[168:171], v[188:191], v[60:63]
	v_mfma_f32_16x16x32_bf16 v[56:59], v[176:179], v[188:191], v[56:59]
	v_mfma_f32_16x16x32_bf16 v[44:47], v[168:171], v[198:201], v[44:47]
	v_mfma_f32_16x16x32_bf16 v[40:43], v[176:179], v[198:201], v[40:43]
	v_mfma_f32_16x16x32_bf16 v[28:31], v[168:171], v[206:209], v[28:31]
	v_mfma_f32_16x16x32_bf16 v[24:27], v[176:179], v[206:209], v[24:27]
	v_mfma_f32_16x16x32_bf16 v[12:15], v[168:171], v[214:217], v[12:15]
	v_mfma_f32_16x16x32_bf16 v[8:11], v[176:179], v[214:217], v[8:11]
	s_setprio 0
	s_barrier
	s_add_i32 s4, s62, s50
	s_mov_b32 m0, s4
	s_add_u32 s0, s36, 0x30000
	s_addc_u32 s1, s37, 0
	global_load_lds_dwordx4 v130, s[0:1]
	s_add_i32 m0, s4, 0x2000
	s_nop 0
	global_load_lds_dwordx4 v134, s[0:1]
	s_waitcnt vmcnt(6)
	s_barrier
	s_setprio 1
	v_mfma_f32_16x16x32_bf16 v[52:55], v[218:221], v[180:183], v[52:55]
	v_mfma_f32_16x16x32_bf16 v[48:51], v[226:229], v[180:183], v[48:51]
	v_mfma_f32_16x16x32_bf16 v[36:39], v[218:221], v[194:197], v[36:39]
	v_mfma_f32_16x16x32_bf16 v[32:35], v[226:229], v[194:197], v[32:35]
	v_mfma_f32_16x16x32_bf16 v[20:23], v[218:221], v[202:205], v[20:23]
	v_mfma_f32_16x16x32_bf16 v[16:19], v[226:229], v[202:205], v[16:19]
	v_mfma_f32_16x16x32_bf16 v[4:7], v[218:221], v[210:213], v[4:7]
	v_mfma_f32_16x16x32_bf16 v[0:3], v[226:229], v[210:213], v[0:3]
	v_mfma_f32_16x16x32_bf16 v[52:55], v[222:225], v[188:191], v[52:55]
	v_mfma_f32_16x16x32_bf16 v[48:51], v[230:233], v[188:191], v[48:51]
	v_mfma_f32_16x16x32_bf16 v[36:39], v[222:225], v[198:201], v[36:39]
	v_mfma_f32_16x16x32_bf16 v[32:35], v[230:233], v[198:201], v[32:35]
	v_mfma_f32_16x16x32_bf16 v[20:23], v[222:225], v[206:209], v[20:23]
	v_mfma_f32_16x16x32_bf16 v[16:19], v[230:233], v[206:209], v[16:19]
	v_mfma_f32_16x16x32_bf16 v[4:7], v[222:225], v[214:217], v[4:7]
	v_mfma_f32_16x16x32_bf16 v[0:3], v[230:233], v[214:217], v[0:3]
	s_setprio 0
	s_add_i32 s4, 0, 0x18000
	s_barrier
	ds_read_b128 v[144:147], v148
	ds_read_b128 v[168:171], v148 offset:1024
	ds_read_b128 v[172:175], v148 offset:2048
	ds_read_b128 v[176:179], v148 offset:3072
	s_add_u32 s0, s38, 0x30000
	s_addc_u32 s1, s39, 0
	s_mov_b32 m0, s53
	ds_read_b128 v[180:183], v166 offset:32768
	ds_read_b128 v[188:191], v166 offset:33792
	ds_read_b128 v[194:197], v166 offset:34816
	ds_read_b128 v[198:201], v166 offset:35840
	ds_read_b128 v[202:205], v166 offset:36864
	ds_read_b128 v[206:209], v166 offset:37888
	ds_read_b128 v[210:213], v166 offset:38912
	global_load_lds_dwordx4 v128, s[0:1]
	s_mov_b32 m0, s54
	ds_read_b128 v[214:217], v166 offset:39936
	global_load_lds_dwordx4 v132, s[0:1]
	s_waitcnt lgkmcnt(8)
	s_barrier
; #define PG8_STAGE(bufoff, gbase, voff) do { _Pragma("unroll") for (int _i = 0; _i < 2; ++_i) \
;         __builtin_amdgcn_global_load_lds((const unsigned*)((const char*)(gbase) + (voff)[_i]), (LAS unsigned*)(lds + (bufoff) + ldsw + _i * 8192), 16, 0, 0); } while (0)
; #define PG8_LDA(dst, b, h) do { _Pragma("unroll") for (int m = 0; m < 4; ++m) _Pragma("unroll") for (int k = 0; k < 2; ++k) dst[m][k] = *(const LAS bf16x8*)(lds + PG8_SA(b, h) + aoff + m * 2048 + k * 1024); } while (0)
; #define PG8_LDB(dst, b, h) do { _Pragma("unroll") for (int n = 0; n < 2; ++n) _Pragma("unroll") for (int k = 0; k < 2; ++k) dst[n][k] = *(const LAS bf16x8*)(lds + PG8_SB(b, h) + boff + n * 2048 + k * 1024); } while (0)
; #define PG8_MMA(ai, bj, At, Bt) do { __builtin_amdgcn_s_setprio(1); _Pragma("unroll") for (int m = 0; m < 4; ++m) _Pragma("unroll") for (int n = 0; n < 2; ++n) _Pragma("unroll") for (int k = 0; k < 2; ++k) \
;         acc[ai][bj][m][n] = __builtin_amdgcn_mfma_f32_16x16x32_bf16(Bt[n][k], At[m][k], acc[ai][bj][m][n], 0, 0, 0); __builtin_amdgcn_s_setprio(0); } while (0)
; #define PG8_WAIT_V(n) asm volatile("s_waitcnt vmcnt(" #n ")" ::: "memory")
; #define PG8_WAIT_L(n) asm volatile("s_waitcnt lgkmcnt(" #n ")" ::: "memory")
; #define PG8_BAR __builtin_amdgcn_s_barrier()
; #define PG8_SCHED __builtin_amdgcn_sched_barrier(0)
; template <class Epi, class Sched>
; DI void gemm_phase(LAS unsigned char* lds, const Gemm g, const Sched& S, const Epi& E) {
;     ...
;             PG8_WAIT_L(8); PG8_BAR; PG8_WAIT_L(0); PG8_MMA(0, 0, At, B0); PG8_BAR; PG8_SCHED;
;             PG8_LDB(B1, 1, 1); PG8_STAGE(PG8_SB(1, 0), b3, voffB);
;             PG8_BAR; PG8_WAIT_L(0); PG8_MMA(0, 1, At, B1); PG8_BAR;
;             PG8_LDA(At, 1, 1); PG8_STAGE(PG8_SA(1, 0), a3, voffA);
;             PG8_BAR; PG8_WAIT_L(0); PG8_MMA(1, 0, At, B0); PG8_BAR; PG8_SCHED;
;             PG8_STAGE(PG8_SB(1, 1), b3 + hstep, voffB);
;             PG8_WAIT_V(6); PG8_BAR; PG8_MMA(1, 1, At, B1); PG8_BAR;
	s_waitcnt lgkmcnt(0)
	s_setprio 1
	v_mfma_f32_16x16x32_bf16 v[124:127], v[144:147], v[180:183], v[124:127]
	v_mfma_f32_16x16x32_bf16 v[120:123], v[172:175], v[180:183], v[120:123]
	v_mfma_f32_16x16x32_bf16 v[108:111], v[144:147], v[194:197], v[108:111]
	v_mfma_f32_16x16x32_bf16 v[104:107], v[172:175], v[194:197], v[104:107]
	v_mfma_f32_16x16x32_bf16 v[92:95], v[144:147], v[202:205], v[92:95]
	v_mfma_f32_16x16x32_bf16 v[88:91], v[172:175], v[202:205], v[88:91]
	v_mfma_f32_16x16x32_bf16 v[76:79], v[144:147], v[210:213], v[76:79]
	v_mfma_f32_16x16x32_bf16 v[72:75], v[172:175], v[210:213], v[72:75]
	v_mfma_f32_16x16x32_bf16 v[124:127], v[168:171], v[188:191], v[124:127]
	v_mfma_f32_16x16x32_bf16 v[120:123], v[176:179], v[188:191], v[120:123]
	v_mfma_f32_16x16x32_bf16 v[108:111], v[168:171], v[198:201], v[108:111]
	v_mfma_f32_16x16x32_bf16 v[104:107], v[176:179], v[198:201], v[104:107]
	v_mfma_f32_16x16x32_bf16 v[92:95], v[168:171], v[206:209], v[92:95]
	v_mfma_f32_16x16x32_bf16 v[88:91], v[176:179], v[206:209], v[88:91]
	v_mfma_f32_16x16x32_bf16 v[76:79], v[168:171], v[214:217], v[76:79]
	v_mfma_f32_16x16x32_bf16 v[72:75], v[176:179], v[214:217], v[72:75]
	s_setprio 0
	s_barrier
	s_add_i32 s5, 0, 0x1c000
	s_add_i32 s0, s4, s50
	s_add_i32 m0, s0, 0xffffff80
	ds_read_b128 v[218:221], v149
	ds_read_b128 v[222:225], v149 offset:1024
	ds_read_b128 v[226:229], v149 offset:2048
	global_load_lds_dwordx4 v130, s[36:37] offset:128
	s_add_i32 m0, s0, 0x1f80
	ds_read_b128 v[230:233], v149 offset:3072
	global_load_lds_dwordx4 v134, s[36:37] offset:128
	s_barrier
	s_waitcnt lgkmcnt(0)
	s_setprio 1
	v_mfma_f32_16x16x32_bf16 v[116:119], v[218:221], v[180:183], v[116:119]
	v_mfma_f32_16x16x32_bf16 v[112:115], v[226:229], v[180:183], v[112:115]
	v_mfma_f32_16x16x32_bf16 v[100:103], v[218:221], v[194:197], v[100:103]
	v_mfma_f32_16x16x32_bf16 v[96:99], v[226:229], v[194:197], v[96:99]
	v_mfma_f32_16x16x32_bf16 v[84:87], v[218:221], v[202:205], v[84:87]
	v_mfma_f32_16x16x32_bf16 v[80:83], v[226:229], v[202:205], v[80:83]
	v_mfma_f32_16x16x32_bf16 v[68:71], v[218:221], v[210:213], v[68:71]
	v_mfma_f32_16x16x32_bf16 v[64:67], v[226:229], v[210:213], v[64:67]
	v_mfma_f32_16x16x32_bf16 v[116:119], v[222:225], v[188:191], v[116:119]
	v_mfma_f32_16x16x32_bf16 v[112:115], v[230:233], v[188:191], v[112:115]
	v_mfma_f32_16x16x32_bf16 v[100:103], v[222:225], v[198:201], v[100:103]
	v_mfma_f32_16x16x32_bf16 v[96:99], v[230:233], v[198:201], v[96:99]
	v_mfma_f32_16x16x32_bf16 v[84:87], v[222:225], v[206:209], v[84:87]
	v_mfma_f32_16x16x32_bf16 v[80:83], v[230:233], v[206:209], v[80:83]
	v_mfma_f32_16x16x32_bf16 v[68:71], v[222:225], v[214:217], v[68:71]
	v_mfma_f32_16x16x32_bf16 v[64:67], v[230:233], v[214:217], v[64:67]
	s_setprio 0
	s_add_i32 m0, s57, 0xffffff80
	s_barrier
	ds_read_b128 v[180:183], v166 offset:49152
	ds_read_b128 v[188:191], v166 offset:50176
	ds_read_b128 v[194:197], v166 offset:51200
	ds_read_b128 v[198:201], v166 offset:52224
	ds_read_b128 v[202:205], v166 offset:53248
	ds_read_b128 v[206:209], v166 offset:54272
	ds_read_b128 v[210:213], v166 offset:55296
	global_load_lds_dwordx4 v128, s[38:39] offset:128
	s_add_i32 m0, s58, 0xffffff80
	ds_read_b128 v[214:217], v166 offset:56320
	global_load_lds_dwordx4 v132, s[38:39] offset:128
	s_barrier
	s_waitcnt lgkmcnt(0)
	s_setprio 1
	v_mfma_f32_16x16x32_bf16 v[60:63], v[144:147], v[180:183], v[60:63]
	v_mfma_f32_16x16x32_bf16 v[56:59], v[172:175], v[180:183], v[56:59]
	v_mfma_f32_16x16x32_bf16 v[44:47], v[144:147], v[194:197], v[44:47]
	v_mfma_f32_16x16x32_bf16 v[40:43], v[172:175], v[194:197], v[40:43]
	v_mfma_f32_16x16x32_bf16 v[28:31], v[144:147], v[202:205], v[28:31]
	v_mfma_f32_16x16x32_bf16 v[24:27], v[172:175], v[202:205], v[24:27]
	v_mfma_f32_16x16x32_bf16 v[12:15], v[144:147], v[210:213], v[12:15]
	v_mfma_f32_16x16x32_bf16 v[8:11], v[172:175], v[210:213], v[8:11]
	v_mfma_f32_16x16x32_bf16 v[60:63], v[168:171], v[188:191], v[60:63]
	v_mfma_f32_16x16x32_bf16 v[56:59], v[176:179], v[188:191], v[56:59]
	v_mfma_f32_16x16x32_bf16 v[44:47], v[168:171], v[198:201], v[44:47]
	v_mfma_f32_16x16x32_bf16 v[40:43], v[176:179], v[198:201], v[40:43]
	v_mfma_f32_16x16x32_bf16 v[28:31], v[168:171], v[206:209], v[28:31]
	v_mfma_f32_16x16x32_bf16 v[24:27], v[176:179], v[206:209], v[24:27]
	v_mfma_f32_16x16x32_bf16 v[12:15], v[168:171], v[214:217], v[12:15]
	v_mfma_f32_16x16x32_bf16 v[8:11], v[176:179], v[214:217], v[8:11]
	s_setprio 0
	s_barrier
	s_add_i32 s4, s5, s50
	s_mov_b32 m0, s4
	s_add_u32 s0, s36, 0x30080
	s_addc_u32 s1, s37, 0
	global_load_lds_dwordx4 v130, s[0:1]
	s_add_i32 m0, s4, 0x2000
	s_nop 0
	global_load_lds_dwordx4 v134, s[0:1]
	s_add_i32 s41, s41, 2
	s_add_u32 s8, s8, 0x100
	s_addc_u32 s9, s9, 0
	s_add_u32 s35, s35, 0x100
	s_addc_u32 s40, s40, 0
	s_cmp_gt_u32 s41, 9
	s_waitcnt vmcnt(6)
	s_barrier
	s_setprio 1
	v_mfma_f32_16x16x32_bf16 v[52:55], v[218:221], v[180:183], v[52:55]
	v_mfma_f32_16x16x32_bf16 v[48:51], v[226:229], v[180:183], v[48:51]
	v_mfma_f32_16x16x32_bf16 v[36:39], v[218:221], v[194:197], v[36:39]
	v_mfma_f32_16x16x32_bf16 v[32:35], v[226:229], v[194:197], v[32:35]
	v_mfma_f32_16x16x32_bf16 v[20:23], v[218:221], v[202:205], v[20:23]
	v_mfma_f32_16x16x32_bf16 v[16:19], v[226:229], v[202:205], v[16:19]
	v_mfma_f32_16x16x32_bf16 v[4:7], v[218:221], v[210:213], v[4:7]
	v_mfma_f32_16x16x32_bf16 v[0:3], v[226:229], v[210:213], v[0:3]
	v_mfma_f32_16x16x32_bf16 v[52:55], v[222:225], v[188:191], v[52:55]
	v_mfma_f32_16x16x32_bf16 v[48:51], v[230:233], v[188:191], v[48:51]
	v_mfma_f32_16x16x32_bf16 v[36:39], v[222:225], v[198:201], v[36:39]
	v_mfma_f32_16x16x32_bf16 v[32:35], v[230:233], v[198:201], v[32:35]
	v_mfma_f32_16x16x32_bf16 v[20:23], v[222:225], v[206:209], v[20:23]
	v_mfma_f32_16x16x32_bf16 v[16:19], v[230:233], v[206:209], v[16:19]
	v_mfma_f32_16x16x32_bf16 v[4:7], v[222:225], v[214:217], v[4:7]
	v_mfma_f32_16x16x32_bf16 v[0:3], v[230:233], v[214:217], v[0:3]
	s_setprio 0
	s_barrier
	s_cbranch_scc0 .LBB0_938

;     DI size_t aoff(const Unit& u, size_t tstep) const { return (size_t)u.pm * tstep; }
;     DI size_t boff(const Unit& u, size_t tstep) const { return (size_t)u.pn * tstep; }
;     DI bool next(int i, Unit& u) const { const long L = (long)i * G + c; if (L >= np) return false; u.pm = pmv; u.pn = (int)(L % nN); u.ks = (int)(L / nN); return true; }
;     DI size_t aoff(const Unit& u, size_t) const { return (size_t)u.ks * kbytes; }
;     DI size_t boff(const Unit& u, size_t tstep) const { return (size_t)u.pn * tstep + (size_t)u.ks * kbytes; }
;     DI bool next(int i, Unit& u) const { Unit t; if (!S.next(i / 3, t)) return false; u.pm = t.pm; u.pn = t.pn; u.ks = i % 3; return true; }
; template <class Epi, class Sched>
; DI void gemm_phase(LAS unsigned char* lds, const Gemm g, const Sched& S, const Epi& E) {
;     ...
;         const bool has_next = S.next(ui + 1, nxt);
;         const char* nA = has_next ? (const char*)g.A + S.aoff(nxt, tstep) : cA; const char* nB = has_next ? (const char*)g.Bt + S.boff(nxt, tstep) : cB;
;         for (int t = 0; t < nt; t += 2) {
;             if constexpr (Epi::HAS_MID) { if (t == E.mid_t(nt)) { int fr3 = fr, fq3 = fq; asm volatile("" : "+v"(fr3), "+v"(fq3)); E.mid(acc, cur, wr, wc, fr3, fq3); } }
;             const bool last = (t == nt - 2);
;             const char* a1 = cA + (size_t)(t + 1) * kstep;
;             const char* a2 = last ? nA : cA + (size_t)(t + 2) * kstep; const char* b2 = last ? nB : cB + (size_t)(t + 2) * kstep;
;             const char* a3 = a2 + kstep; const char* b3 = b2 + kstep;
;             PG8_LDB(B0, 0, 0); PG8_SCHED; PG8_LDA(At, 0, 0); PG8_STAGE(PG8_SA(1, 1), a1 + hstep, voffA);
;             PG8_WAIT_L(8); PG8_BAR; PG8_WAIT_L(0); PG8_MMA(0, 0, At, B0); PG8_BAR; PG8_SCHED;
;             PG8_LDB(B1, 0, 1); PG8_STAGE(PG8_SB(0, 0), b2, voffB);
;             PG8_BAR; PG8_WAIT_L(0); PG8_MMA(0, 1, At, B1); PG8_BAR;
;             PG8_LDA(At, 0, 1); PG8_STAGE(PG8_SA(0, 0), a2, voffA);
;             PG8_BAR; PG8_WAIT_L(0); PG8_MMA(1, 0, At, B0); PG8_BAR; PG8_SCHED;
;             PG8_STAGE(PG8_SB(0, 1), b2 + hstep, voffB);
;             PG8_WAIT_V(6); PG8_BAR; PG8_MMA(1, 1, At, B1); PG8_BAR;
;             PG8_LDB(B0, 1, 0); PG8_SCHED; PG8_LDA(At, 1, 0); PG8_STAGE(PG8_SA(0, 1), a2 + hstep, voffA);
;             PG8_WAIT_L(8); PG8_BAR; PG8_WAIT_L(0); PG8_MMA(0, 0, At, B0); PG8_BAR; PG8_SCHED;
.LBB0_983:
	s_ashr_i32 s31, s30, 31
	s_lshl_b64 s[0:1], s[30:31], 18
	v_cmp_lt_i64_e32 vcc, s[36:37], v[142:143]
	s_add_u32 s36, s51, s0
	s_addc_u32 s37, s52, s1
	s_and_b64 s[0:1], vcc, exec
	s_cselect_b32 s9, s37, s43
	s_cselect_b32 s31, s36, s42
	s_ashr_i32 s29, s28, 31
	s_lshl_b64 s[0:1], s[28:29], 18
	s_add_u32 s38, s53, s0
	s_addc_u32 s39, s54, s1
	s_and_b64 s[0:1], vcc, exec
	s_cselect_b32 s29, s39, s45
	s_cselect_b32 s34, s38, s44
	s_add_u32 s42, s42, 0x20080
	s_addc_u32 s43, s43, 0
	s_add_u32 s35, s44, 0x100
	v_mov_b32_e32 v0, 0
	s_addc_u32 s41, s45, 0
	s_mov_b32 s79, -2
	ds_read_b128 v[146:149], v156
	ds_read_b128 v[150:153], v156 offset:1024
	ds_read_b128 v[160:163], v156 offset:2048
	ds_read_b128 v[164:167], v156 offset:3072
	s_add_i32 m0, s55, 0xc000
	ds_read_b128 v[168:171], v158
	ds_read_b128 v[172:175], v158 offset:1024
	ds_read_b128 v[176:179], v158 offset:2048
	ds_read_b128 v[180:183], v158 offset:3072
	ds_read_b128 v[188:191], v158 offset:4096
	ds_read_b128 v[194:197], v158 offset:5120
	ds_read_b128 v[198:201], v158 offset:6144
	global_load_lds_dwordx4 v138, s[42:43]
	s_add_i32 m0, s55, 0xe000
	ds_read_b128 v[202:205], v158 offset:7168
	global_load_lds_dwordx4 v140, s[42:43]
	s_add_u32 s0, s42, 0xfffe0080
	s_addc_u32 s1, s43, -1
	s_cmp_eq_u32 s79, 4
	s_cselect_b32 s47, s9, s1
	s_cselect_b32 s46, s31, s0
	s_cselect_b32 s45, s29, s41
	s_cselect_b32 s44, s34, s35
	s_waitcnt lgkmcnt(8)
	s_barrier
	s_waitcnt lgkmcnt(0)
	s_setprio 1
	v_mfma_f32_16x16x32_bf16 v[124:127], v[146:149], v[168:171], 0
	v_mfma_f32_16x16x32_bf16 v[120:123], v[160:163], v[168:171], 0
	v_mfma_f32_16x16x32_bf16 v[108:111], v[146:149], v[176:179], 0
	v_mfma_f32_16x16x32_bf16 v[104:107], v[160:163], v[176:179], 0
	v_mfma_f32_16x16x32_bf16 v[92:95], v[146:149], v[188:191], 0
	v_mfma_f32_16x16x32_bf16 v[88:91], v[160:163], v[188:191], 0
	v_mfma_f32_16x16x32_bf16 v[76:79], v[146:149], v[198:201], 0
	v_mfma_f32_16x16x32_bf16 v[72:75], v[160:163], v[198:201], 0
	v_mfma_f32_16x16x32_bf16 v[124:127], v[150:153], v[172:175], v[124:127]
	v_mfma_f32_16x16x32_bf16 v[120:123], v[164:167], v[172:175], v[120:123]
	v_mfma_f32_16x16x32_bf16 v[108:111], v[150:153], v[180:183], v[108:111]
	v_mfma_f32_16x16x32_bf16 v[104:107], v[164:167], v[180:183], v[104:107]
	v_mfma_f32_16x16x32_bf16 v[92:95], v[150:153], v[194:197], v[92:95]
	v_mfma_f32_16x16x32_bf16 v[88:91], v[164:167], v[194:197], v[88:91]
	v_mfma_f32_16x16x32_bf16 v[76:79], v[150:153], v[202:205], v[76:79]
	v_mfma_f32_16x16x32_bf16 v[72:75], v[164:167], v[202:205], v[72:75]
	s_setprio 0
	s_barrier
	s_add_i32 s0, s66, s50
	s_mov_b32 m0, s0
	ds_read_b128 v[206:209], v159
	ds_read_b128 v[210:213], v159 offset:1024
	ds_read_b128 v[214:217], v159 offset:2048
	global_load_lds_dwordx4 v130, s[44:45]
	s_add_i32 m0, s0, 0x2000
	ds_read_b128 v[218:221], v159 offset:3072
	global_load_lds_dwordx4 v134, s[44:45]
	s_barrier
	s_waitcnt lgkmcnt(0)
	s_setprio 1
	v_mfma_f32_16x16x32_bf16 v[116:119], v[206:209], v[168:171], 0
	v_mfma_f32_16x16x32_bf16 v[112:115], v[214:217], v[168:171], 0
	v_mfma_f32_16x16x32_bf16 v[100:103], v[206:209], v[176:179], 0
	v_mfma_f32_16x16x32_bf16 v[96:99], v[214:217], v[176:179], 0
	v_mfma_f32_16x16x32_bf16 v[84:87], v[206:209], v[188:191], 0
	v_mfma_f32_16x16x32_bf16 v[80:83], v[214:217], v[188:191], 0
	v_mfma_f32_16x16x32_bf16 v[68:71], v[206:209], v[198:201], 0
	v_mfma_f32_16x16x32_bf16 v[64:67], v[214:217], v[198:201], 0
	v_mfma_f32_16x16x32_bf16 v[116:119], v[210:213], v[172:175], v[116:119]
	v_mfma_f32_16x16x32_bf16 v[112:115], v[218:221], v[172:175], v[112:115]
	v_mfma_f32_16x16x32_bf16 v[100:103], v[210:213], v[180:183], v[100:103]
	v_mfma_f32_16x16x32_bf16 v[96:99], v[218:221], v[180:183], v[96:99]
	v_mfma_f32_16x16x32_bf16 v[84:87], v[210:213], v[194:197], v[84:87]
	v_mfma_f32_16x16x32_bf16 v[80:83], v[218:221], v[194:197], v[80:83]
	v_mfma_f32_16x16x32_bf16 v[68:71], v[210:213], v[202:205], v[68:71]
	v_mfma_f32_16x16x32_bf16 v[64:67], v[218:221], v[202:205], v[64:67]
	s_setprio 0
	s_mov_b32 m0, s55
	s_barrier
	ds_read_b128 v[168:171], v158 offset:16384
	ds_read_b128 v[172:175], v158 offset:17408
	ds_read_b128 v[176:179], v158 offset:18432
	ds_read_b128 v[180:183], v158 offset:19456
	ds_read_b128 v[188:191], v158 offset:20480
	ds_read_b128 v[194:197], v158 offset:21504
	ds_read_b128 v[198:201], v158 offset:22528
	global_load_lds_dwordx4 v128, s[46:47]
	s_mov_b32 m0, s56
	ds_read_b128 v[202:205], v158 offset:23552
	global_load_lds_dwordx4 v132, s[46:47]
	s_barrier
	s_waitcnt lgkmcnt(0)
	s_setprio 1
	v_mfma_f32_16x16x32_bf16 v[60:63], v[146:149], v[168:171], 0
	v_mfma_f32_16x16x32_bf16 v[56:59], v[160:163], v[168:171], 0
	v_mfma_f32_16x16x32_bf16 v[44:47], v[146:149], v[176:179], 0
	v_mfma_f32_16x16x32_bf16 v[40:43], v[160:163], v[176:179], 0
	v_mfma_f32_16x16x32_bf16 v[28:31], v[146:149], v[188:191], 0
	v_mfma_f32_16x16x32_bf16 v[24:27], v[160:163], v[188:191], 0
	v_mfma_f32_16x16x32_bf16 v[12:15], v[146:149], v[198:201], 0
	v_mfma_f32_16x16x32_bf16 v[8:11], v[160:163], v[198:201], 0
	v_mfma_f32_16x16x32_bf16 v[60:63], v[150:153], v[172:175], v[60:63]
	v_mfma_f32_16x16x32_bf16 v[56:59], v[164:167], v[172:175], v[56:59]
	v_mfma_f32_16x16x32_bf16 v[44:47], v[150:153], v[180:183], v[44:47]
	v_mfma_f32_16x16x32_bf16 v[40:43], v[164:167], v[180:183], v[40:43]
	v_mfma_f32_16x16x32_bf16 v[28:31], v[150:153], v[194:197], v[28:31]
	v_mfma_f32_16x16x32_bf16 v[24:27], v[164:167], v[194:197], v[24:27]
	v_mfma_f32_16x16x32_bf16 v[12:15], v[150:153], v[202:205], v[12:15]
	v_mfma_f32_16x16x32_bf16 v[8:11], v[164:167], v[202:205], v[8:11]
	s_setprio 0
	s_barrier
; #define PG8_STAGE(bufoff, gbase, voff) do { _Pragma("unroll") for (int _i = 0; _i < 2; ++_i) \
;         __builtin_amdgcn_global_load_lds((const unsigned*)((const char*)(gbase) + (voff)[_i]), (LAS unsigned*)(lds + (bufoff) + ldsw + _i * 8192), 16, 0, 0); } while (0)
; #define PG8_LDA(dst, b, h) do { _Pragma("unroll") for (int m = 0; m < 4; ++m) _Pragma("unroll") for (int k = 0; k < 2; ++k) dst[m][k] = *(const LAS bf16x8*)(lds + PG8_SA(b, h) + aoff + m * 2048 + k * 1024); } while (0)
; #define PG8_LDB(dst, b, h) do { _Pragma("unroll") for (int n = 0; n < 2; ++n) _Pragma("unroll") for (int k = 0; k < 2; ++k) dst[n][k] = *(const LAS bf16x8*)(lds + PG8_SB(b, h) + boff + n * 2048 + k * 1024); } while (0)
; #define PG8_MMA(ai, bj, At, Bt) do { __builtin_amdgcn_s_setprio(1); _Pragma("unroll") for (int m = 0; m < 4; ++m) _Pragma("unroll") for (int n = 0; n < 2; ++n) _Pragma("unroll") for (int k = 0; k < 2; ++k) \
;         acc[ai][bj][m][n] = __builtin_amdgcn_mfma_f32_16x16x32_bf16(Bt[n][k], At[m][k], acc[ai][bj][m][n], 0, 0, 0); __builtin_amdgcn_s_setprio(0); } while (0)
; #define PG8_WAIT_V(n) asm volatile("s_waitcnt vmcnt(" #n ")" ::: "memory")
; #define PG8_WAIT_L(n) asm volatile("s_waitcnt lgkmcnt(" #n ")" ::: "memory")
; #define PG8_BAR __builtin_amdgcn_s_barrier()
; #define PG8_SCHED __builtin_amdgcn_sched_barrier(0)
; template <class Epi, class Sched>
; DI void gemm_phase(LAS unsigned char* lds, const Gemm g, const Sched& S, const Epi& E) {
;     ...
;             PG8_WAIT_V(6); PG8_BAR; PG8_MMA(1, 1, At, B1); PG8_BAR;
;             PG8_LDB(B0, 1, 0); PG8_SCHED; PG8_LDA(At, 1, 0); PG8_STAGE(PG8_SA(0, 1), a2 + hstep, voffA);
;             PG8_WAIT_L(8); PG8_BAR; PG8_WAIT_L(0); PG8_MMA(0, 0, At, B0); PG8_BAR; PG8_SCHED;
;             PG8_LDB(B1, 1, 1); PG8_STAGE(PG8_SB(1, 0), b3, voffB);
;             PG8_BAR; PG8_WAIT_L(0); PG8_MMA(0, 1, At, B1); PG8_BAR;
;             PG8_LDA(At, 1, 1); PG8_STAGE(PG8_SA(1, 0), a3, voffA);
;             PG8_BAR; PG8_WAIT_L(0); PG8_MMA(1, 0, At, B0); PG8_BAR; PG8_SCHED;
;             PG8_STAGE(PG8_SB(1, 1), b3 + hstep, voffB);
;             PG8_WAIT_V(6); PG8_BAR; PG8_MMA(1, 1, At, B1); PG8_BAR;
	s_add_i32 s4, s67, s50
	s_mov_b32 m0, s4
	s_add_u32 s0, s44, 0x20000
	s_addc_u32 s1, s45, 0
	global_load_lds_dwordx4 v130, s[0:1]
	s_add_i32 m0, s4, 0x2000
	s_nop 0
	global_load_lds_dwordx4 v134, s[0:1]
	s_waitcnt vmcnt(6)
	s_barrier
	s_setprio 1
	v_mfma_f32_16x16x32_bf16 v[52:55], v[206:209], v[168:171], 0
	v_mfma_f32_16x16x32_bf16 v[48:51], v[214:217], v[168:171], 0
	v_mfma_f32_16x16x32_bf16 v[36:39], v[206:209], v[176:179], 0
	v_mfma_f32_16x16x32_bf16 v[32:35], v[214:217], v[176:179], 0
	v_mfma_f32_16x16x32_bf16 v[20:23], v[206:209], v[188:191], 0
	v_mfma_f32_16x16x32_bf16 v[16:19], v[214:217], v[188:191], 0
	v_mfma_f32_16x16x32_bf16 v[4:7], v[206:209], v[198:201], 0
	v_mfma_f32_16x16x32_bf16 v[0:3], v[214:217], v[198:201], 0
	v_mfma_f32_16x16x32_bf16 v[52:55], v[210:213], v[172:175], v[52:55]
	v_mfma_f32_16x16x32_bf16 v[48:51], v[218:221], v[172:175], v[48:51]
	v_mfma_f32_16x16x32_bf16 v[36:39], v[210:213], v[180:183], v[36:39]
	v_mfma_f32_16x16x32_bf16 v[32:35], v[218:221], v[180:183], v[32:35]
	v_mfma_f32_16x16x32_bf16 v[20:23], v[210:213], v[194:197], v[20:23]
	v_mfma_f32_16x16x32_bf16 v[16:19], v[218:221], v[194:197], v[16:19]
	v_mfma_f32_16x16x32_bf16 v[4:7], v[210:213], v[202:205], v[4:7]
	v_mfma_f32_16x16x32_bf16 v[0:3], v[218:221], v[202:205], v[0:3]
	s_setprio 0
	s_add_i32 s4, 0, 0x18000
	v_add_u32_e32 v222, s4, v157
	s_barrier
	ds_read_b128 v[146:149], v222
	ds_read_b128 v[150:153], v222 offset:1024
	ds_read_b128 v[160:163], v222 offset:2048
	ds_read_b128 v[164:167], v222 offset:3072
	s_add_u32 s0, s46, 0x20000
	s_addc_u32 s1, s47, 0
	s_mov_b32 m0, s57
	ds_read_b128 v[168:171], v158 offset:32768
	ds_read_b128 v[172:175], v158 offset:33792
	ds_read_b128 v[176:179], v158 offset:34816
	ds_read_b128 v[180:183], v158 offset:35840
	ds_read_b128 v[188:191], v158 offset:36864
	ds_read_b128 v[194:197], v158 offset:37888
	ds_read_b128 v[198:201], v158 offset:38912
	global_load_lds_dwordx4 v128, s[0:1]
	s_mov_b32 m0, s58
	ds_read_b128 v[202:205], v158 offset:39936
	global_load_lds_dwordx4 v132, s[0:1]
	s_waitcnt lgkmcnt(8)
	s_barrier
	s_waitcnt lgkmcnt(0)
	s_setprio 1
	v_mfma_f32_16x16x32_bf16 v[124:127], v[146:149], v[168:171], v[124:127]
	v_mfma_f32_16x16x32_bf16 v[120:123], v[160:163], v[168:171], v[120:123]
	v_mfma_f32_16x16x32_bf16 v[108:111], v[146:149], v[176:179], v[108:111]
	v_mfma_f32_16x16x32_bf16 v[104:107], v[160:163], v[176:179], v[104:107]
	v_mfma_f32_16x16x32_bf16 v[92:95], v[146:149], v[188:191], v[92:95]
	v_mfma_f32_16x16x32_bf16 v[88:91], v[160:163], v[188:191], v[88:91]
	v_mfma_f32_16x16x32_bf16 v[76:79], v[146:149], v[198:201], v[76:79]
	v_mfma_f32_16x16x32_bf16 v[72:75], v[160:163], v[198:201], v[72:75]
	v_mfma_f32_16x16x32_bf16 v[124:127], v[150:153], v[172:175], v[124:127]
	v_mfma_f32_16x16x32_bf16 v[120:123], v[164:167], v[172:175], v[120:123]
	v_mfma_f32_16x16x32_bf16 v[108:111], v[150:153], v[180:183], v[108:111]
	v_mfma_f32_16x16x32_bf16 v[104:107], v[164:167], v[180:183], v[104:107]
	v_mfma_f32_16x16x32_bf16 v[92:95], v[150:153], v[194:197], v[92:95]
	v_mfma_f32_16x16x32_bf16 v[88:91], v[164:167], v[194:197], v[88:91]
	v_mfma_f32_16x16x32_bf16 v[76:79], v[150:153], v[202:205], v[76:79]
	v_mfma_f32_16x16x32_bf16 v[72:75], v[164:167], v[202:205], v[72:75]
	s_setprio 0
	s_barrier
	s_add_i32 s5, 0, 0x1c000
	s_add_i32 s0, s4, s50
	v_add_u32_e32 v223, s5, v157
	s_add_i32 m0, s0, 0xffffff80
	ds_read_b128 v[206:209], v223
	ds_read_b128 v[210:213], v223 offset:1024
	ds_read_b128 v[214:217], v223 offset:2048
	global_load_lds_dwordx4 v130, s[44:45] offset:128
	s_add_i32 m0, s0, 0x1f80
	ds_read_b128 v[218:221], v223 offset:3072
	global_load_lds_dwordx4 v134, s[44:45] offset:128
	s_barrier
	s_waitcnt lgkmcnt(0)
	s_setprio 1
	v_mfma_f32_16x16x32_bf16 v[116:119], v[206:209], v[168:171], v[116:119]
	v_mfma_f32_16x16x32_bf16 v[112:115], v[214:217], v[168:171], v[112:115]
	v_mfma_f32_16x16x32_bf16 v[100:103], v[206:209], v[176:179], v[100:103]
	v_mfma_f32_16x16x32_bf16 v[96:99], v[214:217], v[176:179], v[96:99]
	v_mfma_f32_16x16x32_bf16 v[84:87], v[206:209], v[188:191], v[84:87]
	v_mfma_f32_16x16x32_bf16 v[80:83], v[214:217], v[188:191], v[80:83]
	v_mfma_f32_16x16x32_bf16 v[68:71], v[206:209], v[198:201], v[68:71]
	v_mfma_f32_16x16x32_bf16 v[64:67], v[214:217], v[198:201], v[64:67]
	v_mfma_f32_16x16x32_bf16 v[116:119], v[210:213], v[172:175], v[116:119]
	v_mfma_f32_16x16x32_bf16 v[112:115], v[218:221], v[172:175], v[112:115]
	v_mfma_f32_16x16x32_bf16 v[100:103], v[210:213], v[180:183], v[100:103]
	v_mfma_f32_16x16x32_bf16 v[96:99], v[218:221], v[180:183], v[96:99]
	v_mfma_f32_16x16x32_bf16 v[84:87], v[210:213], v[194:197], v[84:87]
	v_mfma_f32_16x16x32_bf16 v[80:83], v[218:221], v[194:197], v[80:83]
	v_mfma_f32_16x16x32_bf16 v[68:71], v[210:213], v[202:205], v[68:71]
	v_mfma_f32_16x16x32_bf16 v[64:67], v[218:221], v[202:205], v[64:67]
	s_setprio 0
	s_add_i32 m0, s62, 0xffffff80
	s_barrier
	ds_read_b128 v[168:171], v158 offset:49152
	ds_read_b128 v[172:175], v158 offset:50176
	ds_read_b128 v[176:179], v158 offset:51200
	ds_read_b128 v[180:183], v158 offset:52224
	ds_read_b128 v[188:191], v158 offset:53248
	ds_read_b128 v[194:197], v158 offset:54272
	ds_read_b128 v[198:201], v158 offset:55296
	global_load_lds_dwordx4 v128, s[46:47] offset:128
	s_add_i32 m0, s63, 0xffffff80
	ds_read_b128 v[202:205], v158 offset:56320
	global_load_lds_dwordx4 v132, s[46:47] offset:128
	s_barrier
; #define PG8_STAGE(bufoff, gbase, voff) do { _Pragma("unroll") for (int _i = 0; _i < 2; ++_i) \
;         __builtin_amdgcn_global_load_lds((const unsigned*)((const char*)(gbase) + (voff)[_i]), (LAS unsigned*)(lds + (bufoff) + ldsw + _i * 8192), 16, 0, 0); } while (0)
; #define PG8_LDA(dst, b, h) do { _Pragma("unroll") for (int m = 0; m < 4; ++m) _Pragma("unroll") for (int k = 0; k < 2; ++k) dst[m][k] = *(const LAS bf16x8*)(lds + PG8_SA(b, h) + aoff + m * 2048 + k * 1024); } while (0)
; #define PG8_LDB(dst, b, h) do { _Pragma("unroll") for (int n = 0; n < 2; ++n) _Pragma("unroll") for (int k = 0; k < 2; ++k) dst[n][k] = *(const LAS bf16x8*)(lds + PG8_SB(b, h) + boff + n * 2048 + k * 1024); } while (0)
; #define PG8_MMA(ai, bj, At, Bt) do { __builtin_amdgcn_s_setprio(1); _Pragma("unroll") for (int m = 0; m < 4; ++m) _Pragma("unroll") for (int n = 0; n < 2; ++n) _Pragma("unroll") for (int k = 0; k < 2; ++k) \
;         acc[ai][bj][m][n] = __builtin_amdgcn_mfma_f32_16x16x32_bf16(Bt[n][k], At[m][k], acc[ai][bj][m][n], 0, 0, 0); __builtin_amdgcn_s_setprio(0); } while (0)
; #define PG8_WAIT_V(n) asm volatile("s_waitcnt vmcnt(" #n ")" ::: "memory")
; #define PG8_WAIT_L(n) asm volatile("s_waitcnt lgkmcnt(" #n ")" ::: "memory")
; #define PG8_BAR __builtin_amdgcn_s_barrier()
; #define PG8_SCHED __builtin_amdgcn_sched_barrier(0)
; template <class Epi, class Sched>
; DI void gemm_phase(LAS unsigned char* lds, const Gemm g, const Sched& S, const Epi& E) {
;     ...
;             PG8_LDB(B0, 0, 0); PG8_SCHED; PG8_LDA(At, 0, 0); PG8_STAGE(PG8_SA(1, 1), a1 + hstep, voffA);
;             PG8_WAIT_L(8); PG8_BAR; PG8_WAIT_L(0); PG8_MMA(0, 0, At, B0); PG8_BAR; PG8_SCHED;
;             PG8_LDB(B1, 0, 1); PG8_STAGE(PG8_SB(0, 0), b2, voffB);
;     ...
;             PG8_BAR; PG8_WAIT_L(0); PG8_MMA(0, 1, At, B1); PG8_BAR;
;             PG8_LDA(At, 1, 1); PG8_STAGE(PG8_SA(1, 0), a3, voffA);
;             PG8_BAR; PG8_WAIT_L(0); PG8_MMA(1, 0, At, B0); PG8_BAR; PG8_SCHED;
;             PG8_STAGE(PG8_SB(1, 1), b3 + hstep, voffB);
;             PG8_WAIT_V(6); PG8_BAR; PG8_MMA(1, 1, At, B1); PG8_BAR;
	s_waitcnt lgkmcnt(0)
	s_setprio 1
	v_mfma_f32_16x16x32_bf16 v[60:63], v[146:149], v[168:171], v[60:63]
	v_mfma_f32_16x16x32_bf16 v[56:59], v[160:163], v[168:171], v[56:59]
	v_mfma_f32_16x16x32_bf16 v[44:47], v[146:149], v[176:179], v[44:47]
	v_mfma_f32_16x16x32_bf16 v[40:43], v[160:163], v[176:179], v[40:43]
	v_mfma_f32_16x16x32_bf16 v[28:31], v[146:149], v[188:191], v[28:31]
	v_mfma_f32_16x16x32_bf16 v[24:27], v[160:163], v[188:191], v[24:27]
	v_mfma_f32_16x16x32_bf16 v[12:15], v[146:149], v[198:201], v[12:15]
	v_mfma_f32_16x16x32_bf16 v[8:11], v[160:163], v[198:201], v[8:11]
	v_mfma_f32_16x16x32_bf16 v[60:63], v[150:153], v[172:175], v[60:63]
	v_mfma_f32_16x16x32_bf16 v[56:59], v[164:167], v[172:175], v[56:59]
	v_mfma_f32_16x16x32_bf16 v[44:47], v[150:153], v[180:183], v[44:47]
	v_mfma_f32_16x16x32_bf16 v[40:43], v[164:167], v[180:183], v[40:43]
	v_mfma_f32_16x16x32_bf16 v[28:31], v[150:153], v[194:197], v[28:31]
	v_mfma_f32_16x16x32_bf16 v[24:27], v[164:167], v[194:197], v[24:27]
	v_mfma_f32_16x16x32_bf16 v[12:15], v[150:153], v[202:205], v[12:15]
	v_mfma_f32_16x16x32_bf16 v[8:11], v[164:167], v[202:205], v[8:11]
	s_setprio 0
	s_barrier
	s_add_i32 s4, s5, s50
	s_mov_b32 m0, s4
	s_add_u32 s0, s44, 0x20080
	s_addc_u32 s1, s45, 0
	global_load_lds_dwordx4 v130, s[0:1]
	v_lshl_add_u64 v[146:147], s[0:1], 0, v[134:135]
	s_add_i32 m0, s4, 0x2000
	s_nop 0
	global_load_lds_dwordx4 v134, s[0:1]
	s_add_i32 s79, s79, 2
	s_add_u32 s42, s42, 0x100
	s_addc_u32 s43, s43, 0
	s_add_u32 s35, s35, 0x100
	s_addc_u32 s41, s41, 0
	s_cmp_gt_u32 s79, 5
	s_waitcnt vmcnt(6)
	s_barrier
	s_setprio 1
	v_mfma_f32_16x16x32_bf16 v[52:55], v[206:209], v[168:171], v[52:55]
	v_mfma_f32_16x16x32_bf16 v[48:51], v[214:217], v[168:171], v[48:51]
	v_mfma_f32_16x16x32_bf16 v[36:39], v[206:209], v[176:179], v[36:39]
	v_mfma_f32_16x16x32_bf16 v[32:35], v[214:217], v[176:179], v[32:35]
	v_mfma_f32_16x16x32_bf16 v[20:23], v[206:209], v[188:191], v[20:23]
	v_mfma_f32_16x16x32_bf16 v[16:19], v[214:217], v[188:191], v[16:19]
	v_mfma_f32_16x16x32_bf16 v[4:7], v[206:209], v[198:201], v[4:7]
	v_mfma_f32_16x16x32_bf16 v[0:3], v[214:217], v[198:201], v[0:3]
	v_mfma_f32_16x16x32_bf16 v[52:55], v[210:213], v[172:175], v[52:55]
	v_mfma_f32_16x16x32_bf16 v[48:51], v[218:221], v[172:175], v[48:51]
	v_mfma_f32_16x16x32_bf16 v[36:39], v[210:213], v[180:183], v[36:39]
	v_mfma_f32_16x16x32_bf16 v[32:35], v[218:221], v[180:183], v[32:35]
	v_mfma_f32_16x16x32_bf16 v[20:23], v[210:213], v[194:197], v[20:23]
	v_mfma_f32_16x16x32_bf16 v[16:19], v[218:221], v[194:197], v[16:19]
	v_mfma_f32_16x16x32_bf16 v[4:7], v[210:213], v[202:205], v[4:7]
	v_mfma_f32_16x16x32_bf16 v[0:3], v[218:221], v[202:205], v[0:3]
	s_setprio 0
	s_barrier
	s_cbranch_scc0 .LBB0_984
	s_branch .Lpeel_done_984
.LBB0_984:
	ds_read_b128 v[146:149], v156
	ds_read_b128 v[150:153], v156 offset:1024
	ds_read_b128 v[160:163], v156 offset:2048
	ds_read_b128 v[164:167], v156 offset:3072
	s_add_i32 m0, s55, 0xc000
	ds_read_b128 v[168:171], v158
	ds_read_b128 v[172:175], v158 offset:1024
	ds_read_b128 v[176:179], v158 offset:2048
	ds_read_b128 v[180:183], v158 offset:3072
	ds_read_b128 v[188:191], v158 offset:4096
	ds_read_b128 v[194:197], v158 offset:5120
	ds_read_b128 v[198:201], v158 offset:6144
	global_load_lds_dwordx4 v138, s[42:43]
	s_add_i32 m0, s55, 0xe000
	ds_read_b128 v[202:205], v158 offset:7168
	global_load_lds_dwordx4 v140, s[42:43]
	s_add_u32 s0, s42, 0xfffe0080
	s_addc_u32 s1, s43, -1
	s_cmp_eq_u32 s79, 4
	s_cselect_b32 s47, s9, s1
	s_cselect_b32 s46, s31, s0
	s_cselect_b32 s45, s29, s41
	s_cselect_b32 s44, s34, s35
	s_waitcnt lgkmcnt(8)
	s_barrier
	s_waitcnt lgkmcnt(0)
	s_setprio 1
	v_mfma_f32_16x16x32_bf16 v[124:127], v[146:149], v[168:171], v[124:127]
	v_mfma_f32_16x16x32_bf16 v[120:123], v[160:163], v[168:171], v[120:123]
	v_mfma_f32_16x16x32_bf16 v[108:111], v[146:149], v[176:179], v[108:111]
	v_mfma_f32_16x16x32_bf16 v[104:107], v[160:163], v[176:179], v[104:107]
	v_mfma_f32_16x16x32_bf16 v[92:95], v[146:149], v[188:191], v[92:95]
	v_mfma_f32_16x16x32_bf16 v[88:91], v[160:163], v[188:191], v[88:91]
	v_mfma_f32_16x16x32_bf16 v[76:79], v[146:149], v[198:201], v[76:79]
	v_mfma_f32_16x16x32_bf16 v[72:75], v[160:163], v[198:201], v[72:75]
	v_mfma_f32_16x16x32_bf16 v[124:127], v[150:153], v[172:175], v[124:127]
	v_mfma_f32_16x16x32_bf16 v[120:123], v[164:167], v[172:175], v[120:123]
	v_mfma_f32_16x16x32_bf16 v[108:111], v[150:153], v[180:183], v[108:111]
	v_mfma_f32_16x16x32_bf16 v[104:107], v[164:167], v[180:183], v[104:107]
	v_mfma_f32_16x16x32_bf16 v[92:95], v[150:153], v[194:197], v[92:95]
	v_mfma_f32_16x16x32_bf16 v[88:91], v[164:167], v[194:197], v[88:91]
	v_mfma_f32_16x16x32_bf16 v[76:79], v[150:153], v[202:205], v[76:79]
	v_mfma_f32_16x16x32_bf16 v[72:75], v[164:167], v[202:205], v[72:75]
	s_setprio 0
	s_barrier
	s_add_i32 s0, s66, s50
	s_mov_b32 m0, s0
	ds_read_b128 v[206:209], v159
	ds_read_b128 v[210:213], v159 offset:1024
	ds_read_b128 v[214:217], v159 offset:2048
	global_load_lds_dwordx4 v130, s[44:45]
	s_add_i32 m0, s0, 0x2000
	ds_read_b128 v[218:221], v159 offset:3072
	global_load_lds_dwordx4 v134, s[44:45]
	s_barrier
; #define PG8_STAGE(bufoff, gbase, voff) do { _Pragma("unroll") for (int _i = 0; _i < 2; ++_i) \
;         __builtin_amdgcn_global_load_lds((const unsigned*)((const char*)(gbase) + (voff)[_i]), (LAS unsigned*)(lds + (bufoff) + ldsw + _i * 8192), 16, 0, 0); } while (0)
; #define PG8_LDA(dst, b, h) do { _Pragma("unroll") for (int m = 0; m < 4; ++m) _Pragma("unroll") for (int k = 0; k < 2; ++k) dst[m][k] = *(const LAS bf16x8*)(lds + PG8_SA(b, h) + aoff + m * 2048 + k * 1024); } while (0)
; #define PG8_LDB(dst, b, h) do { _Pragma("unroll") for (int n = 0; n < 2; ++n) _Pragma("unroll") for (int k = 0; k < 2; ++k) dst[n][k] = *(const LAS bf16x8*)(lds + PG8_SB(b, h) + boff + n * 2048 + k * 1024); } while (0)
; #define PG8_MMA(ai, bj, At, Bt) do { __builtin_amdgcn_s_setprio(1); _Pragma("unroll") for (int m = 0; m < 4; ++m) _Pragma("unroll") for (int n = 0; n < 2; ++n) _Pragma("unroll") for (int k = 0; k < 2; ++k) \
;         acc[ai][bj][m][n] = __builtin_amdgcn_mfma_f32_16x16x32_bf16(Bt[n][k], At[m][k], acc[ai][bj][m][n], 0, 0, 0); __builtin_amdgcn_s_setprio(0); } while (0)
; #define PG8_WAIT_V(n) asm volatile("s_waitcnt vmcnt(" #n ")" ::: "memory")
; #define PG8_WAIT_L(n) asm volatile("s_waitcnt lgkmcnt(" #n ")" ::: "memory")
; #define PG8_BAR __builtin_amdgcn_s_barrier()
; #define PG8_SCHED __builtin_amdgcn_sched_barrier(0)
; template <class Epi, class Sched>
; DI void gemm_phase(LAS unsigned char* lds, const Gemm g, const Sched& S, const Epi& E) {
;     ...
;             PG8_BAR; PG8_WAIT_L(0); PG8_MMA(0, 1, At, B1); PG8_BAR;
;             PG8_LDA(At, 0, 1); PG8_STAGE(PG8_SA(0, 0), a2, voffA);
;             PG8_BAR; PG8_WAIT_L(0); PG8_MMA(1, 0, At, B0); PG8_BAR; PG8_SCHED;
;             PG8_STAGE(PG8_SB(0, 1), b2 + hstep, voffB);
;             PG8_WAIT_V(6); PG8_BAR; PG8_MMA(1, 1, At, B1); PG8_BAR;
;             PG8_LDB(B0, 1, 0); PG8_SCHED; PG8_LDA(At, 1, 0); PG8_STAGE(PG8_SA(0, 1), a2 + hstep, voffA);
;             PG8_WAIT_L(8); PG8_BAR; PG8_WAIT_L(0); PG8_MMA(0, 0, At, B0); PG8_BAR; PG8_SCHED;
	s_waitcnt lgkmcnt(0)
	s_setprio 1
	v_mfma_f32_16x16x32_bf16 v[116:119], v[206:209], v[168:171], v[116:119]
	v_mfma_f32_16x16x32_bf16 v[112:115], v[214:217], v[168:171], v[112:115]
	v_mfma_f32_16x16x32_bf16 v[100:103], v[206:209], v[176:179], v[100:103]
	v_mfma_f32_16x16x32_bf16 v[96:99], v[214:217], v[176:179], v[96:99]
	v_mfma_f32_16x16x32_bf16 v[84:87], v[206:209], v[188:191], v[84:87]
	v_mfma_f32_16x16x32_bf16 v[80:83], v[214:217], v[188:191], v[80:83]
	v_mfma_f32_16x16x32_bf16 v[68:71], v[206:209], v[198:201], v[68:71]
	v_mfma_f32_16x16x32_bf16 v[64:67], v[214:217], v[198:201], v[64:67]
	v_mfma_f32_16x16x32_bf16 v[116:119], v[210:213], v[172:175], v[116:119]
	v_mfma_f32_16x16x32_bf16 v[112:115], v[218:221], v[172:175], v[112:115]
	v_mfma_f32_16x16x32_bf16 v[100:103], v[210:213], v[180:183], v[100:103]
	v_mfma_f32_16x16x32_bf16 v[96:99], v[218:221], v[180:183], v[96:99]
	v_mfma_f32_16x16x32_bf16 v[84:87], v[210:213], v[194:197], v[84:87]
	v_mfma_f32_16x16x32_bf16 v[80:83], v[218:221], v[194:197], v[80:83]
	v_mfma_f32_16x16x32_bf16 v[68:71], v[210:213], v[202:205], v[68:71]
	v_mfma_f32_16x16x32_bf16 v[64:67], v[218:221], v[202:205], v[64:67]
	s_setprio 0
	s_mov_b32 m0, s55
	s_barrier
	ds_read_b128 v[168:171], v158 offset:16384
	ds_read_b128 v[172:175], v158 offset:17408
	ds_read_b128 v[176:179], v158 offset:18432
	ds_read_b128 v[180:183], v158 offset:19456
	ds_read_b128 v[188:191], v158 offset:20480
	ds_read_b128 v[194:197], v158 offset:21504
	ds_read_b128 v[198:201], v158 offset:22528
	global_load_lds_dwordx4 v128, s[46:47]
	s_mov_b32 m0, s56
	ds_read_b128 v[202:205], v158 offset:23552
	global_load_lds_dwordx4 v132, s[46:47]
	s_barrier
	s_waitcnt lgkmcnt(0)
	s_setprio 1
	v_mfma_f32_16x16x32_bf16 v[60:63], v[146:149], v[168:171], v[60:63]
	v_mfma_f32_16x16x32_bf16 v[56:59], v[160:163], v[168:171], v[56:59]
	v_mfma_f32_16x16x32_bf16 v[44:47], v[146:149], v[176:179], v[44:47]
	v_mfma_f32_16x16x32_bf16 v[40:43], v[160:163], v[176:179], v[40:43]
	v_mfma_f32_16x16x32_bf16 v[28:31], v[146:149], v[188:191], v[28:31]
	v_mfma_f32_16x16x32_bf16 v[24:27], v[160:163], v[188:191], v[24:27]
	v_mfma_f32_16x16x32_bf16 v[12:15], v[146:149], v[198:201], v[12:15]
	v_mfma_f32_16x16x32_bf16 v[8:11], v[160:163], v[198:201], v[8:11]
	v_mfma_f32_16x16x32_bf16 v[60:63], v[150:153], v[172:175], v[60:63]
	v_mfma_f32_16x16x32_bf16 v[56:59], v[164:167], v[172:175], v[56:59]
	v_mfma_f32_16x16x32_bf16 v[44:47], v[150:153], v[180:183], v[44:47]
	v_mfma_f32_16x16x32_bf16 v[40:43], v[164:167], v[180:183], v[40:43]
	v_mfma_f32_16x16x32_bf16 v[28:31], v[150:153], v[194:197], v[28:31]
	v_mfma_f32_16x16x32_bf16 v[24:27], v[164:167], v[194:197], v[24:27]
	v_mfma_f32_16x16x32_bf16 v[12:15], v[150:153], v[202:205], v[12:15]
	v_mfma_f32_16x16x32_bf16 v[8:11], v[164:167], v[202:205], v[8:11]
	s_setprio 0
	s_barrier
	s_add_i32 s4, s67, s50
	s_mov_b32 m0, s4
	s_add_u32 s0, s44, 0x20000
	s_addc_u32 s1, s45, 0
	global_load_lds_dwordx4 v130, s[0:1]
	s_add_i32 m0, s4, 0x2000
	s_nop 0
	global_load_lds_dwordx4 v134, s[0:1]
	s_waitcnt vmcnt(6)
	s_barrier
	s_setprio 1
	v_mfma_f32_16x16x32_bf16 v[52:55], v[206:209], v[168:171], v[52:55]
	v_mfma_f32_16x16x32_bf16 v[48:51], v[214:217], v[168:171], v[48:51]
	v_mfma_f32_16x16x32_bf16 v[36:39], v[206:209], v[176:179], v[36:39]
	v_mfma_f32_16x16x32_bf16 v[32:35], v[214:217], v[176:179], v[32:35]
	v_mfma_f32_16x16x32_bf16 v[20:23], v[206:209], v[188:191], v[20:23]
	v_mfma_f32_16x16x32_bf16 v[16:19], v[214:217], v[188:191], v[16:19]
	v_mfma_f32_16x16x32_bf16 v[4:7], v[206:209], v[198:201], v[4:7]
	v_mfma_f32_16x16x32_bf16 v[0:3], v[214:217], v[198:201], v[0:3]
	v_mfma_f32_16x16x32_bf16 v[52:55], v[210:213], v[172:175], v[52:55]
	v_mfma_f32_16x16x32_bf16 v[48:51], v[218:221], v[172:175], v[48:51]
	v_mfma_f32_16x16x32_bf16 v[36:39], v[210:213], v[180:183], v[36:39]
	v_mfma_f32_16x16x32_bf16 v[32:35], v[218:221], v[180:183], v[32:35]
	v_mfma_f32_16x16x32_bf16 v[20:23], v[210:213], v[194:197], v[20:23]
	v_mfma_f32_16x16x32_bf16 v[16:19], v[218:221], v[194:197], v[16:19]
	v_mfma_f32_16x16x32_bf16 v[4:7], v[210:213], v[202:205], v[4:7]
	v_mfma_f32_16x16x32_bf16 v[0:3], v[218:221], v[202:205], v[0:3]
	s_setprio 0
	s_add_i32 s4, 0, 0x18000
	s_barrier
	ds_read_b128 v[146:149], v222
	ds_read_b128 v[150:153], v222 offset:1024
	ds_read_b128 v[160:163], v222 offset:2048
	ds_read_b128 v[164:167], v222 offset:3072
	s_add_u32 s0, s46, 0x20000
	s_addc_u32 s1, s47, 0
	s_mov_b32 m0, s57
	ds_read_b128 v[168:171], v158 offset:32768
	ds_read_b128 v[172:175], v158 offset:33792
	ds_read_b128 v[176:179], v158 offset:34816
	ds_read_b128 v[180:183], v158 offset:35840
	ds_read_b128 v[188:191], v158 offset:36864
	ds_read_b128 v[194:197], v158 offset:37888
	ds_read_b128 v[198:201], v158 offset:38912
	global_load_lds_dwordx4 v128, s[0:1]
	s_mov_b32 m0, s58
	ds_read_b128 v[202:205], v158 offset:39936
	global_load_lds_dwordx4 v132, s[0:1]
	s_waitcnt lgkmcnt(8)
	s_barrier
; #define PG8_STAGE(bufoff, gbase, voff) do { _Pragma("unroll") for (int _i = 0; _i < 2; ++_i) \
;         __builtin_amdgcn_global_load_lds((const unsigned*)((const char*)(gbase) + (voff)[_i]), (LAS unsigned*)(lds + (bufoff) + ldsw + _i * 8192), 16, 0, 0); } while (0)
; #define PG8_LDA(dst, b, h) do { _Pragma("unroll") for (int m = 0; m < 4; ++m) _Pragma("unroll") for (int k = 0; k < 2; ++k) dst[m][k] = *(const LAS bf16x8*)(lds + PG8_SA(b, h) + aoff + m * 2048 + k * 1024); } while (0)
; #define PG8_LDB(dst, b, h) do { _Pragma("unroll") for (int n = 0; n < 2; ++n) _Pragma("unroll") for (int k = 0; k < 2; ++k) dst[n][k] = *(const LAS bf16x8*)(lds + PG8_SB(b, h) + boff + n * 2048 + k * 1024); } while (0)
; #define PG8_MMA(ai, bj, At, Bt) do { __builtin_amdgcn_s_setprio(1); _Pragma("unroll") for (int m = 0; m < 4; ++m) _Pragma("unroll") for (int n = 0; n < 2; ++n) _Pragma("unroll") for (int k = 0; k < 2; ++k) \
;         acc[ai][bj][m][n] = __builtin_amdgcn_mfma_f32_16x16x32_bf16(Bt[n][k], At[m][k], acc[ai][bj][m][n], 0, 0, 0); __builtin_amdgcn_s_setprio(0); } while (0)
; #define PG8_WAIT_V(n) asm volatile("s_waitcnt vmcnt(" #n ")" ::: "memory")
; #define PG8_WAIT_L(n) asm volatile("s_waitcnt lgkmcnt(" #n ")" ::: "memory")
; #define PG8_BAR __builtin_amdgcn_s_barrier()
; #define PG8_SCHED __builtin_amdgcn_sched_barrier(0)
; template <class Epi, class Sched>
; DI void gemm_phase(LAS unsigned char* lds, const Gemm g, const Sched& S, const Epi& E) {
;     ...
;             PG8_WAIT_L(8); PG8_BAR; PG8_WAIT_L(0); PG8_MMA(0, 0, At, B0); PG8_BAR; PG8_SCHED;
;             PG8_LDB(B1, 1, 1); PG8_STAGE(PG8_SB(1, 0), b3, voffB);
;             PG8_BAR; PG8_WAIT_L(0); PG8_MMA(0, 1, At, B1); PG8_BAR;
;             PG8_LDA(At, 1, 1); PG8_STAGE(PG8_SA(1, 0), a3, voffA);
;             PG8_BAR; PG8_WAIT_L(0); PG8_MMA(1, 0, At, B0); PG8_BAR; PG8_SCHED;
;             PG8_STAGE(PG8_SB(1, 1), b3 + hstep, voffB);
;             PG8_WAIT_V(6); PG8_BAR; PG8_MMA(1, 1, At, B1); PG8_BAR;
	s_waitcnt lgkmcnt(0)
	s_setprio 1
	v_mfma_f32_16x16x32_bf16 v[124:127], v[146:149], v[168:171], v[124:127]
	v_mfma_f32_16x16x32_bf16 v[120:123], v[160:163], v[168:171], v[120:123]
	v_mfma_f32_16x16x32_bf16 v[108:111], v[146:149], v[176:179], v[108:111]
	v_mfma_f32_16x16x32_bf16 v[104:107], v[160:163], v[176:179], v[104:107]
	v_mfma_f32_16x16x32_bf16 v[92:95], v[146:149], v[188:191], v[92:95]
	v_mfma_f32_16x16x32_bf16 v[88:91], v[160:163], v[188:191], v[88:91]
	v_mfma_f32_16x16x32_bf16 v[76:79], v[146:149], v[198:201], v[76:79]
	v_mfma_f32_16x16x32_bf16 v[72:75], v[160:163], v[198:201], v[72:75]
	v_mfma_f32_16x16x32_bf16 v[124:127], v[150:153], v[172:175], v[124:127]
	v_mfma_f32_16x16x32_bf16 v[120:123], v[164:167], v[172:175], v[120:123]
	v_mfma_f32_16x16x32_bf16 v[108:111], v[150:153], v[180:183], v[108:111]
	v_mfma_f32_16x16x32_bf16 v[104:107], v[164:167], v[180:183], v[104:107]
	v_mfma_f32_16x16x32_bf16 v[92:95], v[150:153], v[194:197], v[92:95]
	v_mfma_f32_16x16x32_bf16 v[88:91], v[164:167], v[194:197], v[88:91]
	v_mfma_f32_16x16x32_bf16 v[76:79], v[150:153], v[202:205], v[76:79]
	v_mfma_f32_16x16x32_bf16 v[72:75], v[164:167], v[202:205], v[72:75]
	s_setprio 0
	s_barrier
	s_add_i32 s5, 0, 0x1c000
	s_add_i32 s0, s4, s50
	s_add_i32 m0, s0, 0xffffff80
	ds_read_b128 v[206:209], v223
	ds_read_b128 v[210:213], v223 offset:1024
	ds_read_b128 v[214:217], v223 offset:2048
	global_load_lds_dwordx4 v130, s[44:45] offset:128
	s_add_i32 m0, s0, 0x1f80
	ds_read_b128 v[218:221], v223 offset:3072
	global_load_lds_dwordx4 v134, s[44:45] offset:128
	s_barrier
	s_waitcnt lgkmcnt(0)
	s_setprio 1
	v_mfma_f32_16x16x32_bf16 v[116:119], v[206:209], v[168:171], v[116:119]
	v_mfma_f32_16x16x32_bf16 v[112:115], v[214:217], v[168:171], v[112:115]
	v_mfma_f32_16x16x32_bf16 v[100:103], v[206:209], v[176:179], v[100:103]
	v_mfma_f32_16x16x32_bf16 v[96:99], v[214:217], v[176:179], v[96:99]
	v_mfma_f32_16x16x32_bf16 v[84:87], v[206:209], v[188:191], v[84:87]
	v_mfma_f32_16x16x32_bf16 v[80:83], v[214:217], v[188:191], v[80:83]
	v_mfma_f32_16x16x32_bf16 v[68:71], v[206:209], v[198:201], v[68:71]
	v_mfma_f32_16x16x32_bf16 v[64:67], v[214:217], v[198:201], v[64:67]
	v_mfma_f32_16x16x32_bf16 v[116:119], v[210:213], v[172:175], v[116:119]
	v_mfma_f32_16x16x32_bf16 v[112:115], v[218:221], v[172:175], v[112:115]
	v_mfma_f32_16x16x32_bf16 v[100:103], v[210:213], v[180:183], v[100:103]
	v_mfma_f32_16x16x32_bf16 v[96:99], v[218:221], v[180:183], v[96:99]
	v_mfma_f32_16x16x32_bf16 v[84:87], v[210:213], v[194:197], v[84:87]
	v_mfma_f32_16x16x32_bf16 v[80:83], v[218:221], v[194:197], v[80:83]
	v_mfma_f32_16x16x32_bf16 v[68:71], v[210:213], v[202:205], v[68:71]
	v_mfma_f32_16x16x32_bf16 v[64:67], v[218:221], v[202:205], v[64:67]
	s_setprio 0
	s_add_i32 m0, s62, 0xffffff80
	s_barrier
	ds_read_b128 v[168:171], v158 offset:49152
	ds_read_b128 v[172:175], v158 offset:50176
	ds_read_b128 v[176:179], v158 offset:51200
	ds_read_b128 v[180:183], v158 offset:52224
	ds_read_b128 v[188:191], v158 offset:53248
	ds_read_b128 v[194:197], v158 offset:54272
	ds_read_b128 v[198:201], v158 offset:55296
	global_load_lds_dwordx4 v128, s[46:47] offset:128
	s_add_i32 m0, s63, 0xffffff80
	ds_read_b128 v[202:205], v158 offset:56320
	global_load_lds_dwordx4 v132, s[46:47] offset:128
	s_barrier
	s_waitcnt lgkmcnt(0)
	s_setprio 1
	v_mfma_f32_16x16x32_bf16 v[60:63], v[146:149], v[168:171], v[60:63]
	v_mfma_f32_16x16x32_bf16 v[56:59], v[160:163], v[168:171], v[56:59]
	v_mfma_f32_16x16x32_bf16 v[44:47], v[146:149], v[176:179], v[44:47]
	v_mfma_f32_16x16x32_bf16 v[40:43], v[160:163], v[176:179], v[40:43]
	v_mfma_f32_16x16x32_bf16 v[28:31], v[146:149], v[188:191], v[28:31]
	v_mfma_f32_16x16x32_bf16 v[24:27], v[160:163], v[188:191], v[24:27]
	v_mfma_f32_16x16x32_bf16 v[12:15], v[146:149], v[198:201], v[12:15]
	v_mfma_f32_16x16x32_bf16 v[8:11], v[160:163], v[198:201], v[8:11]
	v_mfma_f32_16x16x32_bf16 v[60:63], v[150:153], v[172:175], v[60:63]
	v_mfma_f32_16x16x32_bf16 v[56:59], v[164:167], v[172:175], v[56:59]
	v_mfma_f32_16x16x32_bf16 v[44:47], v[150:153], v[180:183], v[44:47]
	v_mfma_f32_16x16x32_bf16 v[40:43], v[164:167], v[180:183], v[40:43]
	v_mfma_f32_16x16x32_bf16 v[28:31], v[150:153], v[194:197], v[28:31]
	v_mfma_f32_16x16x32_bf16 v[24:27], v[164:167], v[194:197], v[24:27]
	v_mfma_f32_16x16x32_bf16 v[12:15], v[150:153], v[202:205], v[12:15]
	v_mfma_f32_16x16x32_bf16 v[8:11], v[164:167], v[202:205], v[8:11]
	s_setprio 0
	s_barrier
	s_add_i32 s4, s5, s50
	s_mov_b32 m0, s4
	s_add_u32 s0, s44, 0x20080
	s_addc_u32 s1, s45, 0
	global_load_lds_dwordx4 v130, s[0:1]
	v_lshl_add_u64 v[146:147], s[0:1], 0, v[134:135]
	s_add_i32 m0, s4, 0x2000
	s_nop 0
	global_load_lds_dwordx4 v134, s[0:1]
	s_add_i32 s79, s79, 2
	s_add_u32 s42, s42, 0x100
	s_addc_u32 s43, s43, 0
	s_add_u32 s35, s35, 0x100
	s_addc_u32 s41, s41, 0
	s_cmp_gt_u32 s79, 5
	s_waitcnt vmcnt(6)
	s_barrier
	s_setprio 1
	v_mfma_f32_16x16x32_bf16 v[52:55], v[206:209], v[168:171], v[52:55]
	v_mfma_f32_16x16x32_bf16 v[48:51], v[214:217], v[168:171], v[48:51]
	v_mfma_f32_16x16x32_bf16 v[36:39], v[206:209], v[176:179], v[36:39]
	v_mfma_f32_16x16x32_bf16 v[32:35], v[214:217], v[176:179], v[32:35]
	v_mfma_f32_16x16x32_bf16 v[20:23], v[206:209], v[188:191], v[20:23]
	v_mfma_f32_16x16x32_bf16 v[16:19], v[214:217], v[188:191], v[16:19]
	v_mfma_f32_16x16x32_bf16 v[4:7], v[206:209], v[198:201], v[4:7]
	v_mfma_f32_16x16x32_bf16 v[0:3], v[214:217], v[198:201], v[0:3]
	v_mfma_f32_16x16x32_bf16 v[52:55], v[210:213], v[172:175], v[52:55]
	v_mfma_f32_16x16x32_bf16 v[48:51], v[218:221], v[172:175], v[48:51]
	v_mfma_f32_16x16x32_bf16 v[36:39], v[210:213], v[180:183], v[36:39]
	v_mfma_f32_16x16x32_bf16 v[32:35], v[218:221], v[180:183], v[32:35]
	v_mfma_f32_16x16x32_bf16 v[20:23], v[210:213], v[194:197], v[20:23]
	v_mfma_f32_16x16x32_bf16 v[16:19], v[218:221], v[194:197], v[16:19]
	v_mfma_f32_16x16x32_bf16 v[4:7], v[210:213], v[202:205], v[4:7]
	v_mfma_f32_16x16x32_bf16 v[0:3], v[218:221], v[202:205], v[0:3]
	s_setprio 0
	s_barrier
	s_cbranch_scc0 .LBB0_984

;     DI size_t aoff(const Unit& u, size_t tstep) const { return (size_t)u.pm * tstep; }
;     DI size_t boff(const Unit& u, size_t tstep) const { return (size_t)u.pn * tstep; }
;     DI bool next(int i, Unit& u) const { const long L = (long)i * G + c; if (L >= np) return false; u.pm = pmv; u.pn = (int)(L % nN); u.ks = (int)(L / nN); return true; }
;     DI size_t aoff(const Unit& u, size_t) const { return (size_t)u.ks * kbytes; }
;     DI size_t boff(const Unit& u, size_t tstep) const { return (size_t)u.pn * tstep + (size_t)u.ks * kbytes; }
;     DI bool next(int i, Unit& u) const { Unit t; if (!S.next(i / 3, t)) return false; u.pm = t.pm; u.pn = t.pn; u.ks = i % 3; return true; }
; template <class Epi, class Sched>
; DI void gemm_phase(LAS unsigned char* lds, const Gemm g, const Sched& S, const Epi& E) {
;     ...
;         const bool has_next = S.next(ui + 1, nxt);
;         const char* nA = has_next ? (const char*)g.A + S.aoff(nxt, tstep) : cA; const char* nB = has_next ? (const char*)g.Bt + S.boff(nxt, tstep) : cB;
;         for (int t = 0; t < nt; t += 2) {
;             if constexpr (Epi::HAS_MID) { if (t == E.mid_t(nt)) { int fr3 = fr, fq3 = fq; asm volatile("" : "+v"(fr3), "+v"(fq3)); E.mid(acc, cur, wr, wc, fr3, fq3); } }
;             const bool last = (t == nt - 2);
;             const char* a1 = cA + (size_t)(t + 1) * kstep;
;             const char* a2 = last ? nA : cA + (size_t)(t + 2) * kstep; const char* b2 = last ? nB : cB + (size_t)(t + 2) * kstep;
;             const char* a3 = a2 + kstep; const char* b3 = b2 + kstep;
;             PG8_LDB(B0, 0, 0); PG8_SCHED; PG8_LDA(At, 0, 0); PG8_STAGE(PG8_SA(1, 1), a1 + hstep, voffA);
;             PG8_WAIT_L(8); PG8_BAR; PG8_WAIT_L(0); PG8_MMA(0, 0, At, B0); PG8_BAR; PG8_SCHED;
;             PG8_LDB(B1, 0, 1); PG8_STAGE(PG8_SB(0, 0), b2, voffB);
;             PG8_BAR; PG8_WAIT_L(0); PG8_MMA(0, 1, At, B1); PG8_BAR;
;             PG8_LDA(At, 0, 1); PG8_STAGE(PG8_SA(0, 0), a2, voffA);
;             PG8_BAR; PG8_WAIT_L(0); PG8_MMA(1, 0, At, B0); PG8_BAR; PG8_SCHED;
;             PG8_STAGE(PG8_SB(0, 1), b2 + hstep, voffB);
;             PG8_WAIT_V(6); PG8_BAR; PG8_MMA(1, 1, At, B1); PG8_BAR;
;             PG8_LDB(B0, 1, 0); PG8_SCHED; PG8_LDA(At, 1, 0); PG8_STAGE(PG8_SA(0, 1), a2 + hstep, voffA);
;             PG8_WAIT_L(8); PG8_BAR; PG8_WAIT_L(0); PG8_MMA(0, 0, At, B0); PG8_BAR; PG8_SCHED;
.LBB0_1507:
	s_ashr_i32 s37, s36, 31
	s_lshl_b64 s[0:1], s[36:37], 20
	v_cmp_lt_i64_e32 vcc, s[38:39], v[140:141]
	s_add_u32 s38, s13, s0
	s_addc_u32 s39, s50, s1
	s_and_b64 s[0:1], vcc, exec
	s_cselect_b32 s34, s39, s45
	s_cselect_b32 s35, s38, s44
	s_ashr_i32 s31, s30, 31
	s_lshl_b64 s[0:1], s[30:31], 20
	s_add_u32 s40, s55, s0
	s_addc_u32 s41, s56, s1
	s_and_b64 s[0:1], vcc, exec
	s_cselect_b32 s31, s41, s47
	s_cselect_b32 s37, s40, s46
	s_add_u32 s44, s44, 0x80080
	s_addc_u32 s45, s45, 0
	s_add_u32 s43, s46, 0x100
	v_mov_b32_e32 v0, 0
	s_addc_u32 s68, s47, 0
	s_mov_b32 s69, -2
	s_waitcnt lgkmcnt(0)
	ds_read_b128 v[144:147], v150
	ds_read_b128 v[154:157], v150 offset:1024
	ds_read_b128 v[158:161], v150 offset:2048
	ds_read_b128 v[162:165], v150 offset:3072
	s_add_i32 m0, s52, 0xc000
	ds_read_b128 v[166:169], v151
	ds_read_b128 v[170:173], v151 offset:1024
	ds_read_b128 v[174:177], v151 offset:2048
	ds_read_b128 v[178:181], v151 offset:3072
	ds_read_b128 v[188:191], v151 offset:4096
	ds_read_b128 v[206:209], v151 offset:5120
	ds_read_b128 v[210:213], v151 offset:6144
	global_load_lds_dwordx4 v136, s[44:45]
	s_add_i32 m0, s52, 0xe000
	ds_read_b128 v[214:217], v151 offset:7168
	global_load_lds_dwordx4 v138, s[44:45]
	s_add_u32 s0, s44, 0xfff80080
	s_addc_u32 s1, s45, -1
	s_cmp_eq_u32 s69, 28
	s_cselect_b32 s49, s34, s1
	s_cselect_b32 s48, s35, s0
	s_cselect_b32 s47, s31, s68
	s_cselect_b32 s46, s37, s43
	s_waitcnt lgkmcnt(8)
	s_barrier
	s_waitcnt lgkmcnt(0)
	s_setprio 1
	v_mfma_f32_16x16x32_bf16 v[124:127], v[144:147], v[166:169], 0
	v_mfma_f32_16x16x32_bf16 v[120:123], v[158:161], v[166:169], 0
	v_mfma_f32_16x16x32_bf16 v[108:111], v[144:147], v[174:177], 0
	v_mfma_f32_16x16x32_bf16 v[104:107], v[158:161], v[174:177], 0
	v_mfma_f32_16x16x32_bf16 v[92:95], v[144:147], v[188:191], 0
	v_mfma_f32_16x16x32_bf16 v[88:91], v[158:161], v[188:191], 0
	v_mfma_f32_16x16x32_bf16 v[76:79], v[144:147], v[210:213], 0
	v_mfma_f32_16x16x32_bf16 v[72:75], v[158:161], v[210:213], 0
	v_mfma_f32_16x16x32_bf16 v[124:127], v[154:157], v[170:173], v[124:127]
	v_mfma_f32_16x16x32_bf16 v[120:123], v[162:165], v[170:173], v[120:123]
	v_mfma_f32_16x16x32_bf16 v[108:111], v[154:157], v[178:181], v[108:111]
	v_mfma_f32_16x16x32_bf16 v[104:107], v[162:165], v[178:181], v[104:107]
	v_mfma_f32_16x16x32_bf16 v[92:95], v[154:157], v[206:209], v[92:95]
	v_mfma_f32_16x16x32_bf16 v[88:91], v[162:165], v[206:209], v[88:91]
	v_mfma_f32_16x16x32_bf16 v[76:79], v[154:157], v[214:217], v[76:79]
	v_mfma_f32_16x16x32_bf16 v[72:75], v[162:165], v[214:217], v[72:75]
	s_setprio 0
	s_barrier
	s_add_i32 s0, s65, s51
	s_mov_b32 m0, s0
	ds_read_b128 v[218:221], v152
	ds_read_b128 v[222:225], v152 offset:1024
	ds_read_b128 v[226:229], v152 offset:2048
	global_load_lds_dwordx4 v132, s[46:47]
	s_add_i32 m0, s0, 0x2000
	ds_read_b128 v[230:233], v152 offset:3072
	global_load_lds_dwordx4 v134, s[46:47]
	s_barrier
	s_waitcnt lgkmcnt(0)
	s_setprio 1
	v_mfma_f32_16x16x32_bf16 v[116:119], v[218:221], v[166:169], 0
	v_mfma_f32_16x16x32_bf16 v[112:115], v[226:229], v[166:169], 0
	v_mfma_f32_16x16x32_bf16 v[100:103], v[218:221], v[174:177], 0
	v_mfma_f32_16x16x32_bf16 v[96:99], v[226:229], v[174:177], 0
	v_mfma_f32_16x16x32_bf16 v[84:87], v[218:221], v[188:191], 0
	v_mfma_f32_16x16x32_bf16 v[80:83], v[226:229], v[188:191], 0
	v_mfma_f32_16x16x32_bf16 v[68:71], v[218:221], v[210:213], 0
	v_mfma_f32_16x16x32_bf16 v[64:67], v[226:229], v[210:213], 0
	v_mfma_f32_16x16x32_bf16 v[116:119], v[222:225], v[170:173], v[116:119]
	v_mfma_f32_16x16x32_bf16 v[112:115], v[230:233], v[170:173], v[112:115]
	v_mfma_f32_16x16x32_bf16 v[100:103], v[222:225], v[178:181], v[100:103]
	v_mfma_f32_16x16x32_bf16 v[96:99], v[230:233], v[178:181], v[96:99]
	v_mfma_f32_16x16x32_bf16 v[84:87], v[222:225], v[206:209], v[84:87]
	v_mfma_f32_16x16x32_bf16 v[80:83], v[230:233], v[206:209], v[80:83]
	v_mfma_f32_16x16x32_bf16 v[68:71], v[222:225], v[214:217], v[68:71]
	v_mfma_f32_16x16x32_bf16 v[64:67], v[230:233], v[214:217], v[64:67]
	s_setprio 0
	s_mov_b32 m0, s52
	s_barrier
	ds_read_b128 v[166:169], v151 offset:16384
	ds_read_b128 v[170:173], v151 offset:17408
	ds_read_b128 v[174:177], v151 offset:18432
	ds_read_b128 v[178:181], v151 offset:19456
	ds_read_b128 v[188:191], v151 offset:20480
	ds_read_b128 v[206:209], v151 offset:21504
	ds_read_b128 v[210:213], v151 offset:22528
	global_load_lds_dwordx4 v128, s[48:49]
	s_mov_b32 m0, s53
	ds_read_b128 v[214:217], v151 offset:23552
	global_load_lds_dwordx4 v130, s[48:49]
	s_barrier
	s_waitcnt lgkmcnt(0)
	s_setprio 1
	v_mfma_f32_16x16x32_bf16 v[60:63], v[144:147], v[166:169], 0
	v_mfma_f32_16x16x32_bf16 v[56:59], v[158:161], v[166:169], 0
	v_mfma_f32_16x16x32_bf16 v[44:47], v[144:147], v[174:177], 0
	v_mfma_f32_16x16x32_bf16 v[40:43], v[158:161], v[174:177], 0
	v_mfma_f32_16x16x32_bf16 v[28:31], v[144:147], v[188:191], 0
	v_mfma_f32_16x16x32_bf16 v[24:27], v[158:161], v[188:191], 0
	v_mfma_f32_16x16x32_bf16 v[12:15], v[144:147], v[210:213], 0
	v_mfma_f32_16x16x32_bf16 v[8:11], v[158:161], v[210:213], 0
	v_mfma_f32_16x16x32_bf16 v[60:63], v[154:157], v[170:173], v[60:63]
	v_mfma_f32_16x16x32_bf16 v[56:59], v[162:165], v[170:173], v[56:59]
	v_mfma_f32_16x16x32_bf16 v[44:47], v[154:157], v[178:181], v[44:47]
	v_mfma_f32_16x16x32_bf16 v[40:43], v[162:165], v[178:181], v[40:43]
	v_mfma_f32_16x16x32_bf16 v[28:31], v[154:157], v[206:209], v[28:31]
	v_mfma_f32_16x16x32_bf16 v[24:27], v[162:165], v[206:209], v[24:27]
	v_mfma_f32_16x16x32_bf16 v[12:15], v[154:157], v[214:217], v[12:15]
	v_mfma_f32_16x16x32_bf16 v[8:11], v[162:165], v[214:217], v[8:11]
	s_setprio 0
	s_barrier
; #define PG8_STAGE(bufoff, gbase, voff) do { _Pragma("unroll") for (int _i = 0; _i < 2; ++_i) \
;         __builtin_amdgcn_global_load_lds((const unsigned*)((const char*)(gbase) + (voff)[_i]), (LAS unsigned*)(lds + (bufoff) + ldsw + _i * 8192), 16, 0, 0); } while (0)
; #define PG8_LDA(dst, b, h) do { _Pragma("unroll") for (int m = 0; m < 4; ++m) _Pragma("unroll") for (int k = 0; k < 2; ++k) dst[m][k] = *(const LAS bf16x8*)(lds + PG8_SA(b, h) + aoff + m * 2048 + k * 1024); } while (0)
; #define PG8_LDB(dst, b, h) do { _Pragma("unroll") for (int n = 0; n < 2; ++n) _Pragma("unroll") for (int k = 0; k < 2; ++k) dst[n][k] = *(const LAS bf16x8*)(lds + PG8_SB(b, h) + boff + n * 2048 + k * 1024); } while (0)
; #define PG8_MMA(ai, bj, At, Bt) do { __builtin_amdgcn_s_setprio(1); _Pragma("unroll") for (int m = 0; m < 4; ++m) _Pragma("unroll") for (int n = 0; n < 2; ++n) _Pragma("unroll") for (int k = 0; k < 2; ++k) \
;         acc[ai][bj][m][n] = __builtin_amdgcn_mfma_f32_16x16x32_bf16(Bt[n][k], At[m][k], acc[ai][bj][m][n], 0, 0, 0); __builtin_amdgcn_s_setprio(0); } while (0)
; #define PG8_WAIT_V(n) asm volatile("s_waitcnt vmcnt(" #n ")" ::: "memory")
; #define PG8_WAIT_L(n) asm volatile("s_waitcnt lgkmcnt(" #n ")" ::: "memory")
; #define PG8_BAR __builtin_amdgcn_s_barrier()
; #define PG8_SCHED __builtin_amdgcn_sched_barrier(0)
; template <class Epi, class Sched>
; DI void gemm_phase(LAS unsigned char* lds, const Gemm g, const Sched& S, const Epi& E) {
;     ...
;             PG8_WAIT_V(6); PG8_BAR; PG8_MMA(1, 1, At, B1); PG8_BAR;
;             PG8_LDB(B0, 1, 0); PG8_SCHED; PG8_LDA(At, 1, 0); PG8_STAGE(PG8_SA(0, 1), a2 + hstep, voffA);
;             PG8_WAIT_L(8); PG8_BAR; PG8_WAIT_L(0); PG8_MMA(0, 0, At, B0); PG8_BAR; PG8_SCHED;
;             PG8_LDB(B1, 1, 1); PG8_STAGE(PG8_SB(1, 0), b3, voffB);
;             PG8_BAR; PG8_WAIT_L(0); PG8_MMA(0, 1, At, B1); PG8_BAR;
;             PG8_LDA(At, 1, 1); PG8_STAGE(PG8_SA(1, 0), a3, voffA);
;             PG8_BAR; PG8_WAIT_L(0); PG8_MMA(1, 0, At, B0); PG8_BAR; PG8_SCHED;
;             PG8_STAGE(PG8_SB(1, 1), b3 + hstep, voffB);
;             PG8_WAIT_V(6); PG8_BAR; PG8_MMA(1, 1, At, B1); PG8_BAR;
	s_add_i32 s4, s66, s51
	s_mov_b32 m0, s4
	s_add_u32 s0, s46, 0x80000
	s_addc_u32 s1, s47, 0
	global_load_lds_dwordx4 v132, s[0:1]
	s_add_i32 m0, s4, 0x2000
	s_nop 0
	global_load_lds_dwordx4 v134, s[0:1]
	s_waitcnt vmcnt(6)
	s_barrier
	s_setprio 1
	v_mfma_f32_16x16x32_bf16 v[52:55], v[218:221], v[166:169], 0
	v_mfma_f32_16x16x32_bf16 v[48:51], v[226:229], v[166:169], 0
	v_mfma_f32_16x16x32_bf16 v[36:39], v[218:221], v[174:177], 0
	v_mfma_f32_16x16x32_bf16 v[32:35], v[226:229], v[174:177], 0
	v_mfma_f32_16x16x32_bf16 v[20:23], v[218:221], v[188:191], 0
	v_mfma_f32_16x16x32_bf16 v[16:19], v[226:229], v[188:191], 0
	v_mfma_f32_16x16x32_bf16 v[4:7], v[218:221], v[210:213], 0
	v_mfma_f32_16x16x32_bf16 v[0:3], v[226:229], v[210:213], 0
	v_mfma_f32_16x16x32_bf16 v[52:55], v[222:225], v[170:173], v[52:55]
	v_mfma_f32_16x16x32_bf16 v[48:51], v[230:233], v[170:173], v[48:51]
	v_mfma_f32_16x16x32_bf16 v[36:39], v[222:225], v[178:181], v[36:39]
	v_mfma_f32_16x16x32_bf16 v[32:35], v[230:233], v[178:181], v[32:35]
	v_mfma_f32_16x16x32_bf16 v[20:23], v[222:225], v[206:209], v[20:23]
	v_mfma_f32_16x16x32_bf16 v[16:19], v[230:233], v[206:209], v[16:19]
	v_mfma_f32_16x16x32_bf16 v[4:7], v[222:225], v[214:217], v[4:7]
	v_mfma_f32_16x16x32_bf16 v[0:3], v[230:233], v[214:217], v[0:3]
	s_setprio 0
	s_add_i32 s4, 0, 0x18000
	v_add_u32_e32 v162, s4, v149
	s_barrier
	ds_read_b128 v[144:147], v162
	ds_read_b128 v[154:157], v162 offset:1024
	ds_read_b128 v[158:161], v162 offset:2048
	ds_read_b128 v[162:165], v162 offset:3072
	s_add_u32 s0, s48, 0x80000
	s_addc_u32 s1, s49, 0
	s_mov_b32 m0, s58
	ds_read_b128 v[166:169], v151 offset:32768
	ds_read_b128 v[170:173], v151 offset:33792
	ds_read_b128 v[174:177], v151 offset:34816
	ds_read_b128 v[178:181], v151 offset:35840
	ds_read_b128 v[188:191], v151 offset:36864
	ds_read_b128 v[206:209], v151 offset:37888
	ds_read_b128 v[210:213], v151 offset:38912
	global_load_lds_dwordx4 v128, s[0:1]
	s_mov_b32 m0, s59
	ds_read_b128 v[214:217], v151 offset:39936
	global_load_lds_dwordx4 v130, s[0:1]
	s_waitcnt lgkmcnt(8)
	s_barrier
	s_waitcnt lgkmcnt(0)
	s_setprio 1
	v_mfma_f32_16x16x32_bf16 v[124:127], v[144:147], v[166:169], v[124:127]
	v_mfma_f32_16x16x32_bf16 v[120:123], v[158:161], v[166:169], v[120:123]
	v_mfma_f32_16x16x32_bf16 v[108:111], v[144:147], v[174:177], v[108:111]
	v_mfma_f32_16x16x32_bf16 v[104:107], v[158:161], v[174:177], v[104:107]
	v_mfma_f32_16x16x32_bf16 v[92:95], v[144:147], v[188:191], v[92:95]
	v_mfma_f32_16x16x32_bf16 v[88:91], v[158:161], v[188:191], v[88:91]
	v_mfma_f32_16x16x32_bf16 v[76:79], v[144:147], v[210:213], v[76:79]
	v_mfma_f32_16x16x32_bf16 v[72:75], v[158:161], v[210:213], v[72:75]
	v_mfma_f32_16x16x32_bf16 v[124:127], v[154:157], v[170:173], v[124:127]
	v_mfma_f32_16x16x32_bf16 v[120:123], v[162:165], v[170:173], v[120:123]
	v_mfma_f32_16x16x32_bf16 v[108:111], v[154:157], v[178:181], v[108:111]
	v_mfma_f32_16x16x32_bf16 v[104:107], v[162:165], v[178:181], v[104:107]
	v_mfma_f32_16x16x32_bf16 v[92:95], v[154:157], v[206:209], v[92:95]
	v_mfma_f32_16x16x32_bf16 v[88:91], v[162:165], v[206:209], v[88:91]
	v_mfma_f32_16x16x32_bf16 v[76:79], v[154:157], v[214:217], v[76:79]
	v_mfma_f32_16x16x32_bf16 v[72:75], v[162:165], v[214:217], v[72:75]
	s_setprio 0
	s_barrier
	s_add_i32 s5, 0, 0x1c000
	s_add_i32 s0, s4, s51
	v_add_u32_e32 v201, s5, v149
	s_add_i32 m0, s0, 0xffffff80
	ds_read_b128 v[218:221], v201
	ds_read_b128 v[222:225], v201 offset:1024
	ds_read_b128 v[226:229], v201 offset:2048
	global_load_lds_dwordx4 v132, s[46:47] offset:128
	s_add_i32 m0, s0, 0x1f80
	ds_read_b128 v[230:233], v201 offset:3072
	global_load_lds_dwordx4 v134, s[46:47] offset:128
	s_barrier
	s_waitcnt lgkmcnt(0)
	s_setprio 1
	v_mfma_f32_16x16x32_bf16 v[116:119], v[218:221], v[166:169], v[116:119]
	v_mfma_f32_16x16x32_bf16 v[112:115], v[226:229], v[166:169], v[112:115]
	v_mfma_f32_16x16x32_bf16 v[100:103], v[218:221], v[174:177], v[100:103]
	v_mfma_f32_16x16x32_bf16 v[96:99], v[226:229], v[174:177], v[96:99]
	v_mfma_f32_16x16x32_bf16 v[84:87], v[218:221], v[188:191], v[84:87]
	v_mfma_f32_16x16x32_bf16 v[80:83], v[226:229], v[188:191], v[80:83]
	v_mfma_f32_16x16x32_bf16 v[68:71], v[218:221], v[210:213], v[68:71]
	v_mfma_f32_16x16x32_bf16 v[64:67], v[226:229], v[210:213], v[64:67]
	v_mfma_f32_16x16x32_bf16 v[116:119], v[222:225], v[170:173], v[116:119]
	v_mfma_f32_16x16x32_bf16 v[112:115], v[230:233], v[170:173], v[112:115]
	v_mfma_f32_16x16x32_bf16 v[100:103], v[222:225], v[178:181], v[100:103]
	v_mfma_f32_16x16x32_bf16 v[96:99], v[230:233], v[178:181], v[96:99]
	v_mfma_f32_16x16x32_bf16 v[84:87], v[222:225], v[206:209], v[84:87]
	v_mfma_f32_16x16x32_bf16 v[80:83], v[230:233], v[206:209], v[80:83]
	v_mfma_f32_16x16x32_bf16 v[68:71], v[222:225], v[214:217], v[68:71]
	v_mfma_f32_16x16x32_bf16 v[64:67], v[230:233], v[214:217], v[64:67]
	s_setprio 0
	s_add_i32 m0, s63, 0xffffff80
	s_barrier
	ds_read_b128 v[166:169], v151 offset:49152
	ds_read_b128 v[170:173], v151 offset:50176
	ds_read_b128 v[174:177], v151 offset:51200
	ds_read_b128 v[178:181], v151 offset:52224
	ds_read_b128 v[188:191], v151 offset:53248
	ds_read_b128 v[206:209], v151 offset:54272
	ds_read_b128 v[210:213], v151 offset:55296
	global_load_lds_dwordx4 v128, s[48:49] offset:128
	s_add_i32 m0, s64, 0xffffff80
	ds_read_b128 v[214:217], v151 offset:56320
	global_load_lds_dwordx4 v130, s[48:49] offset:128
	s_barrier
; #define PG8_STAGE(bufoff, gbase, voff) do { _Pragma("unroll") for (int _i = 0; _i < 2; ++_i) \
;         __builtin_amdgcn_global_load_lds((const unsigned*)((const char*)(gbase) + (voff)[_i]), (LAS unsigned*)(lds + (bufoff) + ldsw + _i * 8192), 16, 0, 0); } while (0)
; #define PG8_LDA(dst, b, h) do { _Pragma("unroll") for (int m = 0; m < 4; ++m) _Pragma("unroll") for (int k = 0; k < 2; ++k) dst[m][k] = *(const LAS bf16x8*)(lds + PG8_SA(b, h) + aoff + m * 2048 + k * 1024); } while (0)
; #define PG8_LDB(dst, b, h) do { _Pragma("unroll") for (int n = 0; n < 2; ++n) _Pragma("unroll") for (int k = 0; k < 2; ++k) dst[n][k] = *(const LAS bf16x8*)(lds + PG8_SB(b, h) + boff + n * 2048 + k * 1024); } while (0)
; #define PG8_MMA(ai, bj, At, Bt) do { __builtin_amdgcn_s_setprio(1); _Pragma("unroll") for (int m = 0; m < 4; ++m) _Pragma("unroll") for (int n = 0; n < 2; ++n) _Pragma("unroll") for (int k = 0; k < 2; ++k) \
;         acc[ai][bj][m][n] = __builtin_amdgcn_mfma_f32_16x16x32_bf16(Bt[n][k], At[m][k], acc[ai][bj][m][n], 0, 0, 0); __builtin_amdgcn_s_setprio(0); } while (0)
; #define PG8_WAIT_V(n) asm volatile("s_waitcnt vmcnt(" #n ")" ::: "memory")
; #define PG8_WAIT_L(n) asm volatile("s_waitcnt lgkmcnt(" #n ")" ::: "memory")
; #define PG8_BAR __builtin_amdgcn_s_barrier()
; #define PG8_SCHED __builtin_amdgcn_sched_barrier(0)
; template <class Epi, class Sched>
; DI void gemm_phase(LAS unsigned char* lds, const Gemm g, const Sched& S, const Epi& E) {
;     ...
;             PG8_LDB(B0, 0, 0); PG8_SCHED; PG8_LDA(At, 0, 0); PG8_STAGE(PG8_SA(1, 1), a1 + hstep, voffA);
;             PG8_WAIT_L(8); PG8_BAR; PG8_WAIT_L(0); PG8_MMA(0, 0, At, B0); PG8_BAR; PG8_SCHED;
;             PG8_LDB(B1, 0, 1); PG8_STAGE(PG8_SB(0, 0), b2, voffB);
;     ...
;             PG8_BAR; PG8_WAIT_L(0); PG8_MMA(0, 1, At, B1); PG8_BAR;
;             PG8_LDA(At, 1, 1); PG8_STAGE(PG8_SA(1, 0), a3, voffA);
;             PG8_BAR; PG8_WAIT_L(0); PG8_MMA(1, 0, At, B0); PG8_BAR; PG8_SCHED;
;             PG8_STAGE(PG8_SB(1, 1), b3 + hstep, voffB);
;             PG8_WAIT_V(6); PG8_BAR; PG8_MMA(1, 1, At, B1); PG8_BAR;
	s_waitcnt lgkmcnt(0)
	s_setprio 1
	v_mfma_f32_16x16x32_bf16 v[60:63], v[144:147], v[166:169], v[60:63]
	v_mfma_f32_16x16x32_bf16 v[56:59], v[158:161], v[166:169], v[56:59]
	v_mfma_f32_16x16x32_bf16 v[44:47], v[144:147], v[174:177], v[44:47]
	v_mfma_f32_16x16x32_bf16 v[40:43], v[158:161], v[174:177], v[40:43]
	v_mfma_f32_16x16x32_bf16 v[28:31], v[144:147], v[188:191], v[28:31]
	v_mfma_f32_16x16x32_bf16 v[24:27], v[158:161], v[188:191], v[24:27]
	v_mfma_f32_16x16x32_bf16 v[12:15], v[144:147], v[210:213], v[12:15]
	v_mfma_f32_16x16x32_bf16 v[8:11], v[158:161], v[210:213], v[8:11]
	v_mfma_f32_16x16x32_bf16 v[60:63], v[154:157], v[170:173], v[60:63]
	v_mfma_f32_16x16x32_bf16 v[56:59], v[162:165], v[170:173], v[56:59]
	v_mfma_f32_16x16x32_bf16 v[44:47], v[154:157], v[178:181], v[44:47]
	v_mfma_f32_16x16x32_bf16 v[40:43], v[162:165], v[178:181], v[40:43]
	v_mfma_f32_16x16x32_bf16 v[28:31], v[154:157], v[206:209], v[28:31]
	v_mfma_f32_16x16x32_bf16 v[24:27], v[162:165], v[206:209], v[24:27]
	v_mfma_f32_16x16x32_bf16 v[12:15], v[154:157], v[214:217], v[12:15]
	v_mfma_f32_16x16x32_bf16 v[8:11], v[162:165], v[214:217], v[8:11]
	s_setprio 0
	s_barrier
	s_add_i32 s4, s5, s51
	s_mov_b32 m0, s4
	s_add_u32 s0, s46, 0x80080
	s_addc_u32 s1, s47, 0
	global_load_lds_dwordx4 v132, s[0:1]
	s_add_i32 m0, s4, 0x2000
	s_nop 0
	global_load_lds_dwordx4 v134, s[0:1]
	s_add_i32 s69, s69, 2
	s_add_u32 s44, s44, 0x100
	s_addc_u32 s45, s45, 0
	s_add_u32 s43, s43, 0x100
	s_addc_u32 s68, s68, 0
	s_cmp_gt_u32 s69, 29
	s_waitcnt vmcnt(6)
	s_barrier
	s_setprio 1
	v_mfma_f32_16x16x32_bf16 v[52:55], v[218:221], v[166:169], v[52:55]
	v_mfma_f32_16x16x32_bf16 v[48:51], v[226:229], v[166:169], v[48:51]
	v_mfma_f32_16x16x32_bf16 v[36:39], v[218:221], v[174:177], v[36:39]
	v_mfma_f32_16x16x32_bf16 v[32:35], v[226:229], v[174:177], v[32:35]
	v_mfma_f32_16x16x32_bf16 v[20:23], v[218:221], v[188:191], v[20:23]
	v_mfma_f32_16x16x32_bf16 v[16:19], v[226:229], v[188:191], v[16:19]
	v_mfma_f32_16x16x32_bf16 v[4:7], v[218:221], v[210:213], v[4:7]
	v_mfma_f32_16x16x32_bf16 v[0:3], v[226:229], v[210:213], v[0:3]
	v_mfma_f32_16x16x32_bf16 v[52:55], v[222:225], v[170:173], v[52:55]
	v_mfma_f32_16x16x32_bf16 v[48:51], v[230:233], v[170:173], v[48:51]
	v_mfma_f32_16x16x32_bf16 v[36:39], v[222:225], v[178:181], v[36:39]
	v_mfma_f32_16x16x32_bf16 v[32:35], v[230:233], v[178:181], v[32:35]
	v_mfma_f32_16x16x32_bf16 v[20:23], v[222:225], v[206:209], v[20:23]
	v_mfma_f32_16x16x32_bf16 v[16:19], v[230:233], v[206:209], v[16:19]
	v_mfma_f32_16x16x32_bf16 v[4:7], v[222:225], v[214:217], v[4:7]
	v_mfma_f32_16x16x32_bf16 v[0:3], v[230:233], v[214:217], v[0:3]
	s_setprio 0
	s_barrier
	s_cbranch_scc0 .LBB0_1508
	s_branch .Lpeel_done_1508
.LBB0_1508:
	ds_read_b128 v[144:147], v150
	ds_read_b128 v[154:157], v150 offset:1024
	ds_read_b128 v[158:161], v150 offset:2048
	ds_read_b128 v[162:165], v150 offset:3072
	s_add_i32 m0, s52, 0xc000
	ds_read_b128 v[166:169], v151
	ds_read_b128 v[170:173], v151 offset:1024
	ds_read_b128 v[174:177], v151 offset:2048
	ds_read_b128 v[178:181], v151 offset:3072
	ds_read_b128 v[188:191], v151 offset:4096
	ds_read_b128 v[206:209], v151 offset:5120
	ds_read_b128 v[210:213], v151 offset:6144
	global_load_lds_dwordx4 v136, s[44:45]
	s_add_i32 m0, s52, 0xe000
	ds_read_b128 v[214:217], v151 offset:7168
	global_load_lds_dwordx4 v138, s[44:45]
	s_add_u32 s0, s44, 0xfff80080
	s_addc_u32 s1, s45, -1
	s_cmp_eq_u32 s69, 28
	s_cselect_b32 s49, s34, s1
	s_cselect_b32 s48, s35, s0
	s_cselect_b32 s47, s31, s68
	s_cselect_b32 s46, s37, s43
	s_waitcnt lgkmcnt(8)
	s_barrier
	s_waitcnt lgkmcnt(0)
	s_setprio 1
	v_mfma_f32_16x16x32_bf16 v[124:127], v[144:147], v[166:169], v[124:127]
	v_mfma_f32_16x16x32_bf16 v[120:123], v[158:161], v[166:169], v[120:123]
	v_mfma_f32_16x16x32_bf16 v[108:111], v[144:147], v[174:177], v[108:111]
	v_mfma_f32_16x16x32_bf16 v[104:107], v[158:161], v[174:177], v[104:107]
	v_mfma_f32_16x16x32_bf16 v[92:95], v[144:147], v[188:191], v[92:95]
	v_mfma_f32_16x16x32_bf16 v[88:91], v[158:161], v[188:191], v[88:91]
	v_mfma_f32_16x16x32_bf16 v[76:79], v[144:147], v[210:213], v[76:79]
	v_mfma_f32_16x16x32_bf16 v[72:75], v[158:161], v[210:213], v[72:75]
	v_mfma_f32_16x16x32_bf16 v[124:127], v[154:157], v[170:173], v[124:127]
	v_mfma_f32_16x16x32_bf16 v[120:123], v[162:165], v[170:173], v[120:123]
	v_mfma_f32_16x16x32_bf16 v[108:111], v[154:157], v[178:181], v[108:111]
	v_mfma_f32_16x16x32_bf16 v[104:107], v[162:165], v[178:181], v[104:107]
	v_mfma_f32_16x16x32_bf16 v[92:95], v[154:157], v[206:209], v[92:95]
	v_mfma_f32_16x16x32_bf16 v[88:91], v[162:165], v[206:209], v[88:91]
	v_mfma_f32_16x16x32_bf16 v[76:79], v[154:157], v[214:217], v[76:79]
	v_mfma_f32_16x16x32_bf16 v[72:75], v[162:165], v[214:217], v[72:75]
	s_setprio 0
	s_barrier
	s_add_i32 s0, s65, s51
	s_mov_b32 m0, s0
	ds_read_b128 v[218:221], v152
	ds_read_b128 v[222:225], v152 offset:1024
	ds_read_b128 v[226:229], v152 offset:2048
	global_load_lds_dwordx4 v132, s[46:47]
	s_add_i32 m0, s0, 0x2000
	ds_read_b128 v[230:233], v152 offset:3072
	global_load_lds_dwordx4 v134, s[46:47]
	s_barrier
; #define PG8_STAGE(bufoff, gbase, voff) do { _Pragma("unroll") for (int _i = 0; _i < 2; ++_i) \
;         __builtin_amdgcn_global_load_lds((const unsigned*)((const char*)(gbase) + (voff)[_i]), (LAS unsigned*)(lds + (bufoff) + ldsw + _i * 8192), 16, 0, 0); } while (0)
; #define PG8_LDA(dst, b, h) do { _Pragma("unroll") for (int m = 0; m < 4; ++m) _Pragma("unroll") for (int k = 0; k < 2; ++k) dst[m][k] = *(const LAS bf16x8*)(lds + PG8_SA(b, h) + aoff + m * 2048 + k * 1024); } while (0)
; #define PG8_LDB(dst, b, h) do { _Pragma("unroll") for (int n = 0; n < 2; ++n) _Pragma("unroll") for (int k = 0; k < 2; ++k) dst[n][k] = *(const LAS bf16x8*)(lds + PG8_SB(b, h) + boff + n * 2048 + k * 1024); } while (0)
; #define PG8_MMA(ai, bj, At, Bt) do { __builtin_amdgcn_s_setprio(1); _Pragma("unroll") for (int m = 0; m < 4; ++m) _Pragma("unroll") for (int n = 0; n < 2; ++n) _Pragma("unroll") for (int k = 0; k < 2; ++k) \
;         acc[ai][bj][m][n] = __builtin_amdgcn_mfma_f32_16x16x32_bf16(Bt[n][k], At[m][k], acc[ai][bj][m][n], 0, 0, 0); __builtin_amdgcn_s_setprio(0); } while (0)
; #define PG8_WAIT_V(n) asm volatile("s_waitcnt vmcnt(" #n ")" ::: "memory")
; #define PG8_WAIT_L(n) asm volatile("s_waitcnt lgkmcnt(" #n ")" ::: "memory")
; #define PG8_BAR __builtin_amdgcn_s_barrier()
; #define PG8_SCHED __builtin_amdgcn_sched_barrier(0)
; template <class Epi, class Sched>
; DI void gemm_phase(LAS unsigned char* lds, const Gemm g, const Sched& S, const Epi& E) {
;     ...
;             PG8_BAR; PG8_WAIT_L(0); PG8_MMA(0, 1, At, B1); PG8_BAR;
;             PG8_LDA(At, 0, 1); PG8_STAGE(PG8_SA(0, 0), a2, voffA);
;             PG8_BAR; PG8_WAIT_L(0); PG8_MMA(1, 0, At, B0); PG8_BAR; PG8_SCHED;
;             PG8_STAGE(PG8_SB(0, 1), b2 + hstep, voffB);
;             PG8_WAIT_V(6); PG8_BAR; PG8_MMA(1, 1, At, B1); PG8_BAR;
;             PG8_LDB(B0, 1, 0); PG8_SCHED; PG8_LDA(At, 1, 0); PG8_STAGE(PG8_SA(0, 1), a2 + hstep, voffA);
;             PG8_WAIT_L(8); PG8_BAR; PG8_WAIT_L(0); PG8_MMA(0, 0, At, B0); PG8_BAR; PG8_SCHED;
	s_waitcnt lgkmcnt(0)
	s_setprio 1
	v_mfma_f32_16x16x32_bf16 v[116:119], v[218:221], v[166:169], v[116:119]
	v_mfma_f32_16x16x32_bf16 v[112:115], v[226:229], v[166:169], v[112:115]
	v_mfma_f32_16x16x32_bf16 v[100:103], v[218:221], v[174:177], v[100:103]
	v_mfma_f32_16x16x32_bf16 v[96:99], v[226:229], v[174:177], v[96:99]
	v_mfma_f32_16x16x32_bf16 v[84:87], v[218:221], v[188:191], v[84:87]
	v_mfma_f32_16x16x32_bf16 v[80:83], v[226:229], v[188:191], v[80:83]
	v_mfma_f32_16x16x32_bf16 v[68:71], v[218:221], v[210:213], v[68:71]
	v_mfma_f32_16x16x32_bf16 v[64:67], v[226:229], v[210:213], v[64:67]
	v_mfma_f32_16x16x32_bf16 v[116:119], v[222:225], v[170:173], v[116:119]
	v_mfma_f32_16x16x32_bf16 v[112:115], v[230:233], v[170:173], v[112:115]
	v_mfma_f32_16x16x32_bf16 v[100:103], v[222:225], v[178:181], v[100:103]
	v_mfma_f32_16x16x32_bf16 v[96:99], v[230:233], v[178:181], v[96:99]
	v_mfma_f32_16x16x32_bf16 v[84:87], v[222:225], v[206:209], v[84:87]
	v_mfma_f32_16x16x32_bf16 v[80:83], v[230:233], v[206:209], v[80:83]
	v_mfma_f32_16x16x32_bf16 v[68:71], v[222:225], v[214:217], v[68:71]
	v_mfma_f32_16x16x32_bf16 v[64:67], v[230:233], v[214:217], v[64:67]
	s_setprio 0
	s_mov_b32 m0, s52
	s_barrier
	ds_read_b128 v[166:169], v151 offset:16384
	ds_read_b128 v[170:173], v151 offset:17408
	ds_read_b128 v[174:177], v151 offset:18432
	ds_read_b128 v[178:181], v151 offset:19456
	ds_read_b128 v[188:191], v151 offset:20480
	ds_read_b128 v[206:209], v151 offset:21504
	ds_read_b128 v[210:213], v151 offset:22528
	global_load_lds_dwordx4 v128, s[48:49]
	s_mov_b32 m0, s53
	ds_read_b128 v[214:217], v151 offset:23552
	global_load_lds_dwordx4 v130, s[48:49]
	s_barrier
	s_waitcnt lgkmcnt(0)
	s_setprio 1
	v_mfma_f32_16x16x32_bf16 v[60:63], v[144:147], v[166:169], v[60:63]
	v_mfma_f32_16x16x32_bf16 v[56:59], v[158:161], v[166:169], v[56:59]
	v_mfma_f32_16x16x32_bf16 v[44:47], v[144:147], v[174:177], v[44:47]
	v_mfma_f32_16x16x32_bf16 v[40:43], v[158:161], v[174:177], v[40:43]
	v_mfma_f32_16x16x32_bf16 v[28:31], v[144:147], v[188:191], v[28:31]
	v_mfma_f32_16x16x32_bf16 v[24:27], v[158:161], v[188:191], v[24:27]
	v_mfma_f32_16x16x32_bf16 v[12:15], v[144:147], v[210:213], v[12:15]
	v_mfma_f32_16x16x32_bf16 v[8:11], v[158:161], v[210:213], v[8:11]
	v_mfma_f32_16x16x32_bf16 v[60:63], v[154:157], v[170:173], v[60:63]
	v_mfma_f32_16x16x32_bf16 v[56:59], v[162:165], v[170:173], v[56:59]
	v_mfma_f32_16x16x32_bf16 v[44:47], v[154:157], v[178:181], v[44:47]
	v_mfma_f32_16x16x32_bf16 v[40:43], v[162:165], v[178:181], v[40:43]
	v_mfma_f32_16x16x32_bf16 v[28:31], v[154:157], v[206:209], v[28:31]
	v_mfma_f32_16x16x32_bf16 v[24:27], v[162:165], v[206:209], v[24:27]
	v_mfma_f32_16x16x32_bf16 v[12:15], v[154:157], v[214:217], v[12:15]
	v_mfma_f32_16x16x32_bf16 v[8:11], v[162:165], v[214:217], v[8:11]
	s_setprio 0
	s_barrier
	s_add_i32 s4, s66, s51
	s_mov_b32 m0, s4
	s_add_u32 s0, s46, 0x80000
	s_addc_u32 s1, s47, 0
	global_load_lds_dwordx4 v132, s[0:1]
	s_add_i32 m0, s4, 0x2000
	s_nop 0
	global_load_lds_dwordx4 v134, s[0:1]
	s_waitcnt vmcnt(6)
	s_barrier
	s_setprio 1
	v_mfma_f32_16x16x32_bf16 v[52:55], v[218:221], v[166:169], v[52:55]
	v_mfma_f32_16x16x32_bf16 v[48:51], v[226:229], v[166:169], v[48:51]
	v_mfma_f32_16x16x32_bf16 v[36:39], v[218:221], v[174:177], v[36:39]
	v_mfma_f32_16x16x32_bf16 v[32:35], v[226:229], v[174:177], v[32:35]
	v_mfma_f32_16x16x32_bf16 v[20:23], v[218:221], v[188:191], v[20:23]
	v_mfma_f32_16x16x32_bf16 v[16:19], v[226:229], v[188:191], v[16:19]
	v_mfma_f32_16x16x32_bf16 v[4:7], v[218:221], v[210:213], v[4:7]
	v_mfma_f32_16x16x32_bf16 v[0:3], v[226:229], v[210:213], v[0:3]
	v_mfma_f32_16x16x32_bf16 v[52:55], v[222:225], v[170:173], v[52:55]
	v_mfma_f32_16x16x32_bf16 v[48:51], v[230:233], v[170:173], v[48:51]
	v_mfma_f32_16x16x32_bf16 v[36:39], v[222:225], v[178:181], v[36:39]
	v_mfma_f32_16x16x32_bf16 v[32:35], v[230:233], v[178:181], v[32:35]
	v_mfma_f32_16x16x32_bf16 v[20:23], v[222:225], v[206:209], v[20:23]
	v_mfma_f32_16x16x32_bf16 v[16:19], v[230:233], v[206:209], v[16:19]
	v_mfma_f32_16x16x32_bf16 v[4:7], v[222:225], v[214:217], v[4:7]
	v_mfma_f32_16x16x32_bf16 v[0:3], v[230:233], v[214:217], v[0:3]
	s_setprio 0
	s_add_i32 s4, 0, 0x18000
	v_add_u32_e32 v162, s4, v149
	s_barrier
	ds_read_b128 v[144:147], v162
	ds_read_b128 v[154:157], v162 offset:1024
	ds_read_b128 v[158:161], v162 offset:2048
	ds_read_b128 v[162:165], v162 offset:3072
	s_add_u32 s0, s48, 0x80000
	s_addc_u32 s1, s49, 0
	s_mov_b32 m0, s58
	ds_read_b128 v[166:169], v151 offset:32768
	ds_read_b128 v[170:173], v151 offset:33792
	ds_read_b128 v[174:177], v151 offset:34816
	ds_read_b128 v[178:181], v151 offset:35840
	ds_read_b128 v[188:191], v151 offset:36864
	ds_read_b128 v[206:209], v151 offset:37888
	ds_read_b128 v[210:213], v151 offset:38912
	global_load_lds_dwordx4 v128, s[0:1]
	s_mov_b32 m0, s59
	ds_read_b128 v[214:217], v151 offset:39936
	global_load_lds_dwordx4 v130, s[0:1]
	s_waitcnt lgkmcnt(8)
	s_barrier
; #define PG8_STAGE(bufoff, gbase, voff) do { _Pragma("unroll") for (int _i = 0; _i < 2; ++_i) \
;         __builtin_amdgcn_global_load_lds((const unsigned*)((const char*)(gbase) + (voff)[_i]), (LAS unsigned*)(lds + (bufoff) + ldsw + _i * 8192), 16, 0, 0); } while (0)
; #define PG8_LDA(dst, b, h) do { _Pragma("unroll") for (int m = 0; m < 4; ++m) _Pragma("unroll") for (int k = 0; k < 2; ++k) dst[m][k] = *(const LAS bf16x8*)(lds + PG8_SA(b, h) + aoff + m * 2048 + k * 1024); } while (0)
; #define PG8_LDB(dst, b, h) do { _Pragma("unroll") for (int n = 0; n < 2; ++n) _Pragma("unroll") for (int k = 0; k < 2; ++k) dst[n][k] = *(const LAS bf16x8*)(lds + PG8_SB(b, h) + boff + n * 2048 + k * 1024); } while (0)
; #define PG8_MMA(ai, bj, At, Bt) do { __builtin_amdgcn_s_setprio(1); _Pragma("unroll") for (int m = 0; m < 4; ++m) _Pragma("unroll") for (int n = 0; n < 2; ++n) _Pragma("unroll") for (int k = 0; k < 2; ++k) \
;         acc[ai][bj][m][n] = __builtin_amdgcn_mfma_f32_16x16x32_bf16(Bt[n][k], At[m][k], acc[ai][bj][m][n], 0, 0, 0); __builtin_amdgcn_s_setprio(0); } while (0)
; #define PG8_WAIT_V(n) asm volatile("s_waitcnt vmcnt(" #n ")" ::: "memory")
; #define PG8_WAIT_L(n) asm volatile("s_waitcnt lgkmcnt(" #n ")" ::: "memory")
; #define PG8_BAR __builtin_amdgcn_s_barrier()
; #define PG8_SCHED __builtin_amdgcn_sched_barrier(0)
; template <class Epi, class Sched>
; DI void gemm_phase(LAS unsigned char* lds, const Gemm g, const Sched& S, const Epi& E) {
;     ...
;             PG8_WAIT_L(8); PG8_BAR; PG8_WAIT_L(0); PG8_MMA(0, 0, At, B0); PG8_BAR; PG8_SCHED;
;             PG8_LDB(B1, 1, 1); PG8_STAGE(PG8_SB(1, 0), b3, voffB);
;             PG8_BAR; PG8_WAIT_L(0); PG8_MMA(0, 1, At, B1); PG8_BAR;
;             PG8_LDA(At, 1, 1); PG8_STAGE(PG8_SA(1, 0), a3, voffA);
;             PG8_BAR; PG8_WAIT_L(0); PG8_MMA(1, 0, At, B0); PG8_BAR; PG8_SCHED;
;             PG8_STAGE(PG8_SB(1, 1), b3 + hstep, voffB);
;             PG8_WAIT_V(6); PG8_BAR; PG8_MMA(1, 1, At, B1); PG8_BAR;
	s_waitcnt lgkmcnt(0)
	s_setprio 1
	v_mfma_f32_16x16x32_bf16 v[124:127], v[144:147], v[166:169], v[124:127]
	v_mfma_f32_16x16x32_bf16 v[120:123], v[158:161], v[166:169], v[120:123]
	v_mfma_f32_16x16x32_bf16 v[108:111], v[144:147], v[174:177], v[108:111]
	v_mfma_f32_16x16x32_bf16 v[104:107], v[158:161], v[174:177], v[104:107]
	v_mfma_f32_16x16x32_bf16 v[92:95], v[144:147], v[188:191], v[92:95]
	v_mfma_f32_16x16x32_bf16 v[88:91], v[158:161], v[188:191], v[88:91]
	v_mfma_f32_16x16x32_bf16 v[76:79], v[144:147], v[210:213], v[76:79]
	v_mfma_f32_16x16x32_bf16 v[72:75], v[158:161], v[210:213], v[72:75]
	v_mfma_f32_16x16x32_bf16 v[124:127], v[154:157], v[170:173], v[124:127]
	v_mfma_f32_16x16x32_bf16 v[120:123], v[162:165], v[170:173], v[120:123]
	v_mfma_f32_16x16x32_bf16 v[108:111], v[154:157], v[178:181], v[108:111]
	v_mfma_f32_16x16x32_bf16 v[104:107], v[162:165], v[178:181], v[104:107]
	v_mfma_f32_16x16x32_bf16 v[92:95], v[154:157], v[206:209], v[92:95]
	v_mfma_f32_16x16x32_bf16 v[88:91], v[162:165], v[206:209], v[88:91]
	v_mfma_f32_16x16x32_bf16 v[76:79], v[154:157], v[214:217], v[76:79]
	v_mfma_f32_16x16x32_bf16 v[72:75], v[162:165], v[214:217], v[72:75]
	s_setprio 0
	s_barrier
	s_add_i32 s5, 0, 0x1c000
	s_add_i32 s0, s4, s51
	v_add_u32_e32 v201, s5, v149
	s_add_i32 m0, s0, 0xffffff80
	ds_read_b128 v[218:221], v201
	ds_read_b128 v[222:225], v201 offset:1024
	ds_read_b128 v[226:229], v201 offset:2048
	global_load_lds_dwordx4 v132, s[46:47] offset:128
	s_add_i32 m0, s0, 0x1f80
	ds_read_b128 v[230:233], v201 offset:3072
	global_load_lds_dwordx4 v134, s[46:47] offset:128
	s_barrier
	s_waitcnt lgkmcnt(0)
	s_setprio 1
	v_mfma_f32_16x16x32_bf16 v[116:119], v[218:221], v[166:169], v[116:119]
	v_mfma_f32_16x16x32_bf16 v[112:115], v[226:229], v[166:169], v[112:115]
	v_mfma_f32_16x16x32_bf16 v[100:103], v[218:221], v[174:177], v[100:103]
	v_mfma_f32_16x16x32_bf16 v[96:99], v[226:229], v[174:177], v[96:99]
	v_mfma_f32_16x16x32_bf16 v[84:87], v[218:221], v[188:191], v[84:87]
	v_mfma_f32_16x16x32_bf16 v[80:83], v[226:229], v[188:191], v[80:83]
	v_mfma_f32_16x16x32_bf16 v[68:71], v[218:221], v[210:213], v[68:71]
	v_mfma_f32_16x16x32_bf16 v[64:67], v[226:229], v[210:213], v[64:67]
	v_mfma_f32_16x16x32_bf16 v[116:119], v[222:225], v[170:173], v[116:119]
	v_mfma_f32_16x16x32_bf16 v[112:115], v[230:233], v[170:173], v[112:115]
	v_mfma_f32_16x16x32_bf16 v[100:103], v[222:225], v[178:181], v[100:103]
	v_mfma_f32_16x16x32_bf16 v[96:99], v[230:233], v[178:181], v[96:99]
	v_mfma_f32_16x16x32_bf16 v[84:87], v[222:225], v[206:209], v[84:87]
	v_mfma_f32_16x16x32_bf16 v[80:83], v[230:233], v[206:209], v[80:83]
	v_mfma_f32_16x16x32_bf16 v[68:71], v[222:225], v[214:217], v[68:71]
	v_mfma_f32_16x16x32_bf16 v[64:67], v[230:233], v[214:217], v[64:67]
	s_setprio 0
	s_add_i32 m0, s63, 0xffffff80
	s_barrier
	ds_read_b128 v[166:169], v151 offset:49152
	ds_read_b128 v[170:173], v151 offset:50176
	ds_read_b128 v[174:177], v151 offset:51200
	ds_read_b128 v[178:181], v151 offset:52224
	ds_read_b128 v[188:191], v151 offset:53248
	ds_read_b128 v[206:209], v151 offset:54272
	ds_read_b128 v[210:213], v151 offset:55296
	global_load_lds_dwordx4 v128, s[48:49] offset:128
	s_add_i32 m0, s64, 0xffffff80
	ds_read_b128 v[214:217], v151 offset:56320
	global_load_lds_dwordx4 v130, s[48:49] offset:128
	s_barrier
	s_waitcnt lgkmcnt(0)
	s_setprio 1
	v_mfma_f32_16x16x32_bf16 v[60:63], v[144:147], v[166:169], v[60:63]
	v_mfma_f32_16x16x32_bf16 v[56:59], v[158:161], v[166:169], v[56:59]
	v_mfma_f32_16x16x32_bf16 v[44:47], v[144:147], v[174:177], v[44:47]
	v_mfma_f32_16x16x32_bf16 v[40:43], v[158:161], v[174:177], v[40:43]
	v_mfma_f32_16x16x32_bf16 v[28:31], v[144:147], v[188:191], v[28:31]
	v_mfma_f32_16x16x32_bf16 v[24:27], v[158:161], v[188:191], v[24:27]
	v_mfma_f32_16x16x32_bf16 v[12:15], v[144:147], v[210:213], v[12:15]
	v_mfma_f32_16x16x32_bf16 v[8:11], v[158:161], v[210:213], v[8:11]
	v_mfma_f32_16x16x32_bf16 v[60:63], v[154:157], v[170:173], v[60:63]
	v_mfma_f32_16x16x32_bf16 v[56:59], v[162:165], v[170:173], v[56:59]
	v_mfma_f32_16x16x32_bf16 v[44:47], v[154:157], v[178:181], v[44:47]
	v_mfma_f32_16x16x32_bf16 v[40:43], v[162:165], v[178:181], v[40:43]
	v_mfma_f32_16x16x32_bf16 v[28:31], v[154:157], v[206:209], v[28:31]
	v_mfma_f32_16x16x32_bf16 v[24:27], v[162:165], v[206:209], v[24:27]
	v_mfma_f32_16x16x32_bf16 v[12:15], v[154:157], v[214:217], v[12:15]
	v_mfma_f32_16x16x32_bf16 v[8:11], v[162:165], v[214:217], v[8:11]
	s_setprio 0
	s_barrier
	s_add_i32 s4, s5, s51
	s_mov_b32 m0, s4
	s_add_u32 s0, s46, 0x80080
	s_addc_u32 s1, s47, 0
	global_load_lds_dwordx4 v132, s[0:1]
	s_add_i32 m0, s4, 0x2000
	s_nop 0
	global_load_lds_dwordx4 v134, s[0:1]
	s_add_i32 s69, s69, 2
	s_add_u32 s44, s44, 0x100
	s_addc_u32 s45, s45, 0
	s_add_u32 s43, s43, 0x100
	s_addc_u32 s68, s68, 0
	s_cmp_gt_u32 s69, 29
	s_waitcnt vmcnt(6)
	s_barrier
	s_setprio 1
	v_mfma_f32_16x16x32_bf16 v[52:55], v[218:221], v[166:169], v[52:55]
	v_mfma_f32_16x16x32_bf16 v[48:51], v[226:229], v[166:169], v[48:51]
	v_mfma_f32_16x16x32_bf16 v[36:39], v[218:221], v[174:177], v[36:39]
	v_mfma_f32_16x16x32_bf16 v[32:35], v[226:229], v[174:177], v[32:35]
	v_mfma_f32_16x16x32_bf16 v[20:23], v[218:221], v[188:191], v[20:23]
	v_mfma_f32_16x16x32_bf16 v[16:19], v[226:229], v[188:191], v[16:19]
	v_mfma_f32_16x16x32_bf16 v[4:7], v[218:221], v[210:213], v[4:7]
	v_mfma_f32_16x16x32_bf16 v[0:3], v[226:229], v[210:213], v[0:3]
	v_mfma_f32_16x16x32_bf16 v[52:55], v[222:225], v[170:173], v[52:55]
	v_mfma_f32_16x16x32_bf16 v[48:51], v[230:233], v[170:173], v[48:51]
	v_mfma_f32_16x16x32_bf16 v[36:39], v[222:225], v[178:181], v[36:39]
	v_mfma_f32_16x16x32_bf16 v[32:35], v[230:233], v[178:181], v[32:35]
	v_mfma_f32_16x16x32_bf16 v[20:23], v[222:225], v[206:209], v[20:23]
	v_mfma_f32_16x16x32_bf16 v[16:19], v[230:233], v[206:209], v[16:19]
	v_mfma_f32_16x16x32_bf16 v[4:7], v[222:225], v[214:217], v[4:7]
	v_mfma_f32_16x16x32_bf16 v[0:3], v[230:233], v[214:217], v[0:3]
	s_setprio 0
	s_barrier
	s_cbranch_scc0 .LBB0_1508

;     DI size_t aoff(const Unit& u, size_t tstep) const { return (size_t)u.pm * tstep; }
;     DI size_t boff(const Unit& u, size_t tstep) const { return (size_t)u.pn * tstep; }
;     DI bool next(int i, Unit& u) const { const long L = (long)i * G + c; if (L >= np) return false; u.pm = pmv; u.pn = (int)(L % nN); u.ks = (int)(L / nN); return true; }
;     DI size_t aoff(const Unit& u, size_t) const { return (size_t)u.ks * kbytes; }
;     DI size_t boff(const Unit& u, size_t tstep) const { return (size_t)u.pn * tstep + (size_t)u.ks * kbytes; }
;     DI bool next(int i, Unit& u) const { Unit t; if (!S.next(i / 3, t)) return false; u.pm = t.pm; u.pn = t.pn; u.ks = i % 3; return true; }
;     DI size_t aoff(const Unit& u, size_t tstep) const { return (u.ks < 2 ? offU : offOA) + (size_t)u.pm * tstep; }
; #define PG8_LDA(dst, b, h) do { _Pragma("unroll") for (int m = 0; m < 4; ++m) _Pragma("unroll") for (int k = 0; k < 2; ++k) dst[m][k] = *(const LAS bf16x8*)(lds + PG8_SA(b, h) + aoff + m * 2048 + k * 1024); } while (0)
; template <class Epi, class Sched>
; DI void gemm_phase(LAS unsigned char* lds, const Gemm g, const Sched& S, const Epi& E) {
;     ...
;         const bool has_next = S.next(ui + 1, nxt);
;         const char* nA = has_next ? (const char*)g.A + S.aoff(nxt, tstep) : cA; const char* nB = has_next ? (const char*)g.Bt + S.boff(nxt, tstep) : cB;
;         for (int t = 0; t < nt; t += 2) {
;             if constexpr (Epi::HAS_MID) { if (t == E.mid_t(nt)) { int fr3 = fr, fq3 = fq; asm volatile("" : "+v"(fr3), "+v"(fq3)); E.mid(acc, cur, wr, wc, fr3, fq3); } }
;             const bool last = (t == nt - 2);
;             const char* a1 = cA + (size_t)(t + 1) * kstep;
;             const char* a2 = last ? nA : cA + (size_t)(t + 2) * kstep; const char* b2 = last ? nB : cB + (size_t)(t + 2) * kstep;
;             const char* a3 = a2 + kstep; const char* b3 = b2 + kstep;
;             PG8_LDB(B0, 0, 0); PG8_SCHED; PG8_LDA(At, 0, 0); PG8_STAGE(PG8_SA(1, 1), a1 + hstep, voffA);
;             PG8_WAIT_L(8); PG8_BAR; PG8_WAIT_L(0); PG8_MMA(0, 0, At, B0); PG8_BAR; PG8_SCHED;
;             PG8_LDB(B1, 0, 1); PG8_STAGE(PG8_SB(0, 0), b2, voffB);
;             PG8_BAR; PG8_WAIT_L(0); PG8_MMA(0, 1, At, B1); PG8_BAR;
;             PG8_LDA(At, 0, 1); PG8_STAGE(PG8_SA(0, 0), a2, voffA);
;             PG8_BAR; PG8_WAIT_L(0); PG8_MMA(1, 0, At, B0); PG8_BAR; PG8_SCHED;
.LBB0_1667:
	s_ashr_i32 s29, s28, 31
	s_lshl_b64 s[0:1], s[28:29], 20
	s_add_u32 s30, s45, s0
	v_cmp_lt_i64_e32 vcc, s[8:9], v[140:141]
	s_addc_u32 s31, s46, s1
	s_and_b64 s[0:1], vcc, exec
	s_cselect_b32 s29, s31, s43
	s_cselect_b32 s35, s30, s42
	s_ashr_i32 s19, s18, 31
	s_lshl_b64 s[0:1], s[18:19], 20
	s_add_u32 s36, s47, s0
	s_addc_u32 s37, s48, s1
	s_and_b64 s[0:1], vcc, exec
	s_cselect_b32 s19, s37, s41
	s_cselect_b32 s65, s36, s40
	s_add_u32 s8, s42, 0x80080
	s_addc_u32 s9, s43, 0
	s_add_u32 s66, s40, 0x100
	v_mov_b32_e32 v8, 0
	s_addc_u32 s67, s41, 0
	s_mov_b32 s68, -2
	ds_read_b128 v[144:147], v149
	ds_read_b128 v[156:159], v149 offset:1024
	ds_read_b128 v[160:163], v149 offset:2048
	ds_read_b128 v[164:167], v149 offset:3072
	s_add_i32 m0, s39, 0xc000
	ds_read_b128 v[168:171], v150
	ds_read_b128 v[172:175], v150 offset:1024
	ds_read_b128 v[176:179], v150 offset:2048
	ds_read_b128 v[180:183], v150 offset:3072
	ds_read_b128 v[188:191], v150 offset:4096
	ds_read_b128 v[206:209], v150 offset:5120
	ds_read_b128 v[210:213], v150 offset:6144
	global_load_lds_dwordx4 v136, s[8:9]
	s_add_i32 m0, s39, 0xe000
	ds_read_b128 v[214:217], v150 offset:7168
	global_load_lds_dwordx4 v138, s[8:9]
	s_add_u32 s0, s8, 0xfff80080
	s_addc_u32 s1, s9, -1
	s_cmp_eq_u32 s68, 28
	s_cselect_b32 s43, s29, s1
	s_cselect_b32 s42, s35, s0
	s_cselect_b32 s41, s19, s67
	s_cselect_b32 s40, s65, s66
	s_waitcnt lgkmcnt(8)
	s_barrier
	s_waitcnt lgkmcnt(0)
	s_setprio 1
	v_mfma_f32_16x16x32_bf16 v[116:119], v[144:147], v[168:171], 0
	v_mfma_f32_16x16x32_bf16 v[112:115], v[160:163], v[168:171], 0
	v_mfma_f32_16x16x32_bf16 v[100:103], v[144:147], v[176:179], 0
	v_mfma_f32_16x16x32_bf16 v[96:99], v[160:163], v[176:179], 0
	v_mfma_f32_16x16x32_bf16 v[84:87], v[144:147], v[188:191], 0
	v_mfma_f32_16x16x32_bf16 v[80:83], v[160:163], v[188:191], 0
	v_mfma_f32_16x16x32_bf16 v[68:71], v[144:147], v[210:213], 0
	v_mfma_f32_16x16x32_bf16 v[64:67], v[160:163], v[210:213], 0
	v_mfma_f32_16x16x32_bf16 v[116:119], v[156:159], v[172:175], v[116:119]
	v_mfma_f32_16x16x32_bf16 v[112:115], v[164:167], v[172:175], v[112:115]
	v_mfma_f32_16x16x32_bf16 v[100:103], v[156:159], v[180:183], v[100:103]
	v_mfma_f32_16x16x32_bf16 v[96:99], v[164:167], v[180:183], v[96:99]
	v_mfma_f32_16x16x32_bf16 v[84:87], v[156:159], v[206:209], v[84:87]
	v_mfma_f32_16x16x32_bf16 v[80:83], v[164:167], v[206:209], v[80:83]
	v_mfma_f32_16x16x32_bf16 v[68:71], v[156:159], v[214:217], v[68:71]
	v_mfma_f32_16x16x32_bf16 v[64:67], v[164:167], v[214:217], v[64:67]
	s_setprio 0
	s_barrier
	s_add_i32 s0, s61, s50
	s_mov_b32 m0, s0
	ds_read_b128 v[218:221], v151
	ds_read_b128 v[222:225], v151 offset:1024
	ds_read_b128 v[226:229], v151 offset:2048
	global_load_lds_dwordx4 v130, s[40:41]
	s_add_i32 m0, s0, 0x2000
	ds_read_b128 v[230:233], v151 offset:3072
	global_load_lds_dwordx4 v134, s[40:41]
	s_barrier
	s_waitcnt lgkmcnt(0)
	s_setprio 1
	v_mfma_f32_16x16x32_bf16 v[124:127], v[218:221], v[168:171], 0
	v_mfma_f32_16x16x32_bf16 v[120:123], v[226:229], v[168:171], 0
	v_mfma_f32_16x16x32_bf16 v[108:111], v[218:221], v[176:179], 0
	v_mfma_f32_16x16x32_bf16 v[104:107], v[226:229], v[176:179], 0
	v_mfma_f32_16x16x32_bf16 v[92:95], v[218:221], v[188:191], 0
	v_mfma_f32_16x16x32_bf16 v[88:91], v[226:229], v[188:191], 0
	v_mfma_f32_16x16x32_bf16 v[76:79], v[218:221], v[210:213], 0
	v_mfma_f32_16x16x32_bf16 v[72:75], v[226:229], v[210:213], 0
	v_mfma_f32_16x16x32_bf16 v[124:127], v[222:225], v[172:175], v[124:127]
	v_mfma_f32_16x16x32_bf16 v[120:123], v[230:233], v[172:175], v[120:123]
	v_mfma_f32_16x16x32_bf16 v[108:111], v[222:225], v[180:183], v[108:111]
	v_mfma_f32_16x16x32_bf16 v[104:107], v[230:233], v[180:183], v[104:107]
	v_mfma_f32_16x16x32_bf16 v[92:95], v[222:225], v[206:209], v[92:95]
	v_mfma_f32_16x16x32_bf16 v[88:91], v[230:233], v[206:209], v[88:91]
	v_mfma_f32_16x16x32_bf16 v[76:79], v[222:225], v[214:217], v[76:79]
	v_mfma_f32_16x16x32_bf16 v[72:75], v[230:233], v[214:217], v[72:75]
	s_setprio 0
	s_mov_b32 m0, s39
	s_barrier
	ds_read_b128 v[168:171], v150 offset:16384
	ds_read_b128 v[172:175], v150 offset:17408
	ds_read_b128 v[176:179], v150 offset:18432
	ds_read_b128 v[180:183], v150 offset:19456
	ds_read_b128 v[188:191], v150 offset:20480
	ds_read_b128 v[206:209], v150 offset:21504
	ds_read_b128 v[210:213], v150 offset:22528
	global_load_lds_dwordx4 v128, s[42:43]
	s_mov_b32 m0, s51
	ds_read_b128 v[214:217], v150 offset:23552
	global_load_lds_dwordx4 v132, s[42:43]
	s_barrier
	s_waitcnt lgkmcnt(0)
	s_setprio 1
	v_mfma_f32_16x16x32_bf16 v[52:55], v[144:147], v[168:171], 0
	v_mfma_f32_16x16x32_bf16 v[48:51], v[160:163], v[168:171], 0
	v_mfma_f32_16x16x32_bf16 v[36:39], v[144:147], v[176:179], 0
	v_mfma_f32_16x16x32_bf16 v[32:35], v[160:163], v[176:179], 0
	v_mfma_f32_16x16x32_bf16 v[20:23], v[144:147], v[188:191], 0
	v_mfma_f32_16x16x32_bf16 v[16:19], v[160:163], v[188:191], 0
	v_mfma_f32_16x16x32_bf16 v[4:7], v[144:147], v[210:213], 0
	v_mfma_f32_16x16x32_bf16 v[0:3], v[160:163], v[210:213], 0
	v_mfma_f32_16x16x32_bf16 v[52:55], v[156:159], v[172:175], v[52:55]
	v_mfma_f32_16x16x32_bf16 v[48:51], v[164:167], v[172:175], v[48:51]
	v_mfma_f32_16x16x32_bf16 v[36:39], v[156:159], v[180:183], v[36:39]
	v_mfma_f32_16x16x32_bf16 v[32:35], v[164:167], v[180:183], v[32:35]
	v_mfma_f32_16x16x32_bf16 v[20:23], v[156:159], v[206:209], v[20:23]
	v_mfma_f32_16x16x32_bf16 v[16:19], v[164:167], v[206:209], v[16:19]
	v_mfma_f32_16x16x32_bf16 v[4:7], v[156:159], v[214:217], v[4:7]
	v_mfma_f32_16x16x32_bf16 v[0:3], v[164:167], v[214:217], v[0:3]
	s_setprio 0
	s_barrier
; #define PG8_STAGE(bufoff, gbase, voff) do { _Pragma("unroll") for (int _i = 0; _i < 2; ++_i) \
;         __builtin_amdgcn_global_load_lds((const unsigned*)((const char*)(gbase) + (voff)[_i]), (LAS unsigned*)(lds + (bufoff) + ldsw + _i * 8192), 16, 0, 0); } while (0)
; #define PG8_LDA(dst, b, h) do { _Pragma("unroll") for (int m = 0; m < 4; ++m) _Pragma("unroll") for (int k = 0; k < 2; ++k) dst[m][k] = *(const LAS bf16x8*)(lds + PG8_SA(b, h) + aoff + m * 2048 + k * 1024); } while (0)
; #define PG8_LDB(dst, b, h) do { _Pragma("unroll") for (int n = 0; n < 2; ++n) _Pragma("unroll") for (int k = 0; k < 2; ++k) dst[n][k] = *(const LAS bf16x8*)(lds + PG8_SB(b, h) + boff + n * 2048 + k * 1024); } while (0)
; #define PG8_MMA(ai, bj, At, Bt) do { __builtin_amdgcn_s_setprio(1); _Pragma("unroll") for (int m = 0; m < 4; ++m) _Pragma("unroll") for (int n = 0; n < 2; ++n) _Pragma("unroll") for (int k = 0; k < 2; ++k) \
;         acc[ai][bj][m][n] = __builtin_amdgcn_mfma_f32_16x16x32_bf16(Bt[n][k], At[m][k], acc[ai][bj][m][n], 0, 0, 0); __builtin_amdgcn_s_setprio(0); } while (0)
; #define PG8_WAIT_V(n) asm volatile("s_waitcnt vmcnt(" #n ")" ::: "memory")
; #define PG8_WAIT_L(n) asm volatile("s_waitcnt lgkmcnt(" #n ")" ::: "memory")
; #define PG8_BAR __builtin_amdgcn_s_barrier()
; #define PG8_SCHED __builtin_amdgcn_sched_barrier(0)
; template <class Epi, class Sched>
; DI void gemm_phase(LAS unsigned char* lds, const Gemm g, const Sched& S, const Epi& E) {
;     ...
;             PG8_STAGE(PG8_SB(0, 1), b2 + hstep, voffB);
;             PG8_WAIT_V(6); PG8_BAR; PG8_MMA(1, 1, At, B1); PG8_BAR;
;             PG8_LDB(B0, 1, 0); PG8_SCHED; PG8_LDA(At, 1, 0); PG8_STAGE(PG8_SA(0, 1), a2 + hstep, voffA);
;             PG8_WAIT_L(8); PG8_BAR; PG8_WAIT_L(0); PG8_MMA(0, 0, At, B0); PG8_BAR; PG8_SCHED;
;             PG8_LDB(B1, 1, 1); PG8_STAGE(PG8_SB(1, 0), b3, voffB);
;             PG8_BAR; PG8_WAIT_L(0); PG8_MMA(0, 1, At, B1); PG8_BAR;
;             PG8_LDA(At, 1, 1); PG8_STAGE(PG8_SA(1, 0), a3, voffA);
	s_add_i32 s4, s62, s50
	s_mov_b32 m0, s4
	s_add_u32 s0, s40, 0x80000
	s_addc_u32 s1, s41, 0
	global_load_lds_dwordx4 v130, s[0:1]
	s_add_i32 m0, s4, 0x2000
	s_nop 0
	global_load_lds_dwordx4 v134, s[0:1]
	s_waitcnt vmcnt(6)
	s_barrier
	s_setprio 1
	v_mfma_f32_16x16x32_bf16 v[60:63], v[218:221], v[168:171], 0
	v_mfma_f32_16x16x32_bf16 v[56:59], v[226:229], v[168:171], 0
	v_mfma_f32_16x16x32_bf16 v[44:47], v[218:221], v[176:179], 0
	v_mfma_f32_16x16x32_bf16 v[40:43], v[226:229], v[176:179], 0
	v_mfma_f32_16x16x32_bf16 v[28:31], v[218:221], v[188:191], 0
	v_mfma_f32_16x16x32_bf16 v[24:27], v[226:229], v[188:191], 0
	v_mfma_f32_16x16x32_bf16 v[12:15], v[218:221], v[210:213], 0
	v_mfma_f32_16x16x32_bf16 v[8:11], v[226:229], v[210:213], 0
	v_mfma_f32_16x16x32_bf16 v[60:63], v[222:225], v[172:175], v[60:63]
	v_mfma_f32_16x16x32_bf16 v[56:59], v[230:233], v[172:175], v[56:59]
	v_mfma_f32_16x16x32_bf16 v[44:47], v[222:225], v[180:183], v[44:47]
	v_mfma_f32_16x16x32_bf16 v[40:43], v[230:233], v[180:183], v[40:43]
	v_mfma_f32_16x16x32_bf16 v[28:31], v[222:225], v[206:209], v[28:31]
	v_mfma_f32_16x16x32_bf16 v[24:27], v[230:233], v[206:209], v[24:27]
	v_mfma_f32_16x16x32_bf16 v[12:15], v[222:225], v[214:217], v[12:15]
	v_mfma_f32_16x16x32_bf16 v[8:11], v[230:233], v[214:217], v[8:11]
	s_setprio 0
	s_add_i32 s4, 0, 0x18000
	v_add_u32_e32 v202, s4, v148
	s_barrier
	ds_read_b128 v[144:147], v202
	ds_read_b128 v[156:159], v202 offset:1024
	ds_read_b128 v[160:163], v202 offset:2048
	ds_read_b128 v[164:167], v202 offset:3072
	s_add_u32 s0, s42, 0x80000
	s_addc_u32 s1, s43, 0
	s_mov_b32 m0, s52
	ds_read_b128 v[168:171], v150 offset:32768
	ds_read_b128 v[172:175], v150 offset:33792
	ds_read_b128 v[176:179], v150 offset:34816
	ds_read_b128 v[180:183], v150 offset:35840
	ds_read_b128 v[188:191], v150 offset:36864
	ds_read_b128 v[206:209], v150 offset:37888
	ds_read_b128 v[210:213], v150 offset:38912
	global_load_lds_dwordx4 v128, s[0:1]
	s_mov_b32 m0, s53
	ds_read_b128 v[214:217], v150 offset:39936
	global_load_lds_dwordx4 v132, s[0:1]
	s_waitcnt lgkmcnt(8)
	s_barrier
	s_waitcnt lgkmcnt(0)
	s_setprio 1
	v_mfma_f32_16x16x32_bf16 v[116:119], v[144:147], v[168:171], v[116:119]
	v_mfma_f32_16x16x32_bf16 v[112:115], v[160:163], v[168:171], v[112:115]
	v_mfma_f32_16x16x32_bf16 v[100:103], v[144:147], v[176:179], v[100:103]
	v_mfma_f32_16x16x32_bf16 v[96:99], v[160:163], v[176:179], v[96:99]
	v_mfma_f32_16x16x32_bf16 v[84:87], v[144:147], v[188:191], v[84:87]
	v_mfma_f32_16x16x32_bf16 v[80:83], v[160:163], v[188:191], v[80:83]
	v_mfma_f32_16x16x32_bf16 v[68:71], v[144:147], v[210:213], v[68:71]
	v_mfma_f32_16x16x32_bf16 v[64:67], v[160:163], v[210:213], v[64:67]
	v_mfma_f32_16x16x32_bf16 v[116:119], v[156:159], v[172:175], v[116:119]
	v_mfma_f32_16x16x32_bf16 v[112:115], v[164:167], v[172:175], v[112:115]
	v_mfma_f32_16x16x32_bf16 v[100:103], v[156:159], v[180:183], v[100:103]
	v_mfma_f32_16x16x32_bf16 v[96:99], v[164:167], v[180:183], v[96:99]
	v_mfma_f32_16x16x32_bf16 v[84:87], v[156:159], v[206:209], v[84:87]
	v_mfma_f32_16x16x32_bf16 v[80:83], v[164:167], v[206:209], v[80:83]
	v_mfma_f32_16x16x32_bf16 v[68:71], v[156:159], v[214:217], v[68:71]
	v_mfma_f32_16x16x32_bf16 v[64:67], v[164:167], v[214:217], v[64:67]
	s_setprio 0
	s_barrier
	s_add_i32 s5, 0, 0x1c000
	s_add_i32 s0, s4, s50
	v_add_u32_e32 v203, s5, v148
	s_add_i32 m0, s0, 0xffffff80
	ds_read_b128 v[218:221], v203
	ds_read_b128 v[222:225], v203 offset:1024
	ds_read_b128 v[226:229], v203 offset:2048
	global_load_lds_dwordx4 v130, s[40:41] offset:128
	s_add_i32 m0, s0, 0x1f80
	ds_read_b128 v[230:233], v203 offset:3072
	global_load_lds_dwordx4 v134, s[40:41] offset:128
	s_barrier
	s_waitcnt lgkmcnt(0)
	s_setprio 1
	v_mfma_f32_16x16x32_bf16 v[124:127], v[218:221], v[168:171], v[124:127]
	v_mfma_f32_16x16x32_bf16 v[120:123], v[226:229], v[168:171], v[120:123]
	v_mfma_f32_16x16x32_bf16 v[108:111], v[218:221], v[176:179], v[108:111]
	v_mfma_f32_16x16x32_bf16 v[104:107], v[226:229], v[176:179], v[104:107]
	v_mfma_f32_16x16x32_bf16 v[92:95], v[218:221], v[188:191], v[92:95]
	v_mfma_f32_16x16x32_bf16 v[88:91], v[226:229], v[188:191], v[88:91]
	v_mfma_f32_16x16x32_bf16 v[76:79], v[218:221], v[210:213], v[76:79]
	v_mfma_f32_16x16x32_bf16 v[72:75], v[226:229], v[210:213], v[72:75]
	v_mfma_f32_16x16x32_bf16 v[124:127], v[222:225], v[172:175], v[124:127]
	v_mfma_f32_16x16x32_bf16 v[120:123], v[230:233], v[172:175], v[120:123]
	v_mfma_f32_16x16x32_bf16 v[108:111], v[222:225], v[180:183], v[108:111]
	v_mfma_f32_16x16x32_bf16 v[104:107], v[230:233], v[180:183], v[104:107]
	v_mfma_f32_16x16x32_bf16 v[92:95], v[222:225], v[206:209], v[92:95]
	v_mfma_f32_16x16x32_bf16 v[88:91], v[230:233], v[206:209], v[88:91]
	v_mfma_f32_16x16x32_bf16 v[76:79], v[222:225], v[214:217], v[76:79]
	v_mfma_f32_16x16x32_bf16 v[72:75], v[230:233], v[214:217], v[72:75]
	s_setprio 0
	s_add_i32 m0, s57, 0xffffff80
	s_barrier
	ds_read_b128 v[168:171], v150 offset:49152
	ds_read_b128 v[172:175], v150 offset:50176
	ds_read_b128 v[176:179], v150 offset:51200
	ds_read_b128 v[180:183], v150 offset:52224
	ds_read_b128 v[188:191], v150 offset:53248
	ds_read_b128 v[206:209], v150 offset:54272
	ds_read_b128 v[210:213], v150 offset:55296
	global_load_lds_dwordx4 v128, s[42:43] offset:128
	s_add_i32 m0, s58, 0xffffff80
	ds_read_b128 v[214:217], v150 offset:56320
	global_load_lds_dwordx4 v132, s[42:43] offset:128
	s_barrier
; #define PG8_STAGE(bufoff, gbase, voff) do { _Pragma("unroll") for (int _i = 0; _i < 2; ++_i) \
;         __builtin_amdgcn_global_load_lds((const unsigned*)((const char*)(gbase) + (voff)[_i]), (LAS unsigned*)(lds + (bufoff) + ldsw + _i * 8192), 16, 0, 0); } while (0)
; #define PG8_LDA(dst, b, h) do { _Pragma("unroll") for (int m = 0; m < 4; ++m) _Pragma("unroll") for (int k = 0; k < 2; ++k) dst[m][k] = *(const LAS bf16x8*)(lds + PG8_SA(b, h) + aoff + m * 2048 + k * 1024); } while (0)
; #define PG8_LDB(dst, b, h) do { _Pragma("unroll") for (int n = 0; n < 2; ++n) _Pragma("unroll") for (int k = 0; k < 2; ++k) dst[n][k] = *(const LAS bf16x8*)(lds + PG8_SB(b, h) + boff + n * 2048 + k * 1024); } while (0)
; #define PG8_WAIT_V(n) asm volatile("s_waitcnt vmcnt(" #n ")" ::: "memory")
; #define PG8_WAIT_L(n) asm volatile("s_waitcnt lgkmcnt(" #n ")" ::: "memory")
; #define PG8_BAR __builtin_amdgcn_s_barrier()
; #define PG8_SCHED __builtin_amdgcn_sched_barrier(0)
; template <class Epi, class Sched>
; DI void gemm_phase(LAS unsigned char* lds, const Gemm g, const Sched& S, const Epi& E) {
;     ...
;             PG8_LDB(B0, 0, 0); PG8_SCHED; PG8_LDA(At, 0, 0); PG8_STAGE(PG8_SA(1, 1), a1 + hstep, voffA);
;             PG8_WAIT_L(8); PG8_BAR; PG8_WAIT_L(0); PG8_MMA(0, 0, At, B0); PG8_BAR; PG8_SCHED;
;             PG8_LDB(B1, 0, 1); PG8_STAGE(PG8_SB(0, 0), b2, voffB);
;             PG8_BAR; PG8_WAIT_L(0); PG8_MMA(0, 1, At, B1); PG8_BAR;
;             PG8_LDA(At, 0, 1); PG8_STAGE(PG8_SA(0, 0), a2, voffA);
;             PG8_BAR; PG8_WAIT_L(0); PG8_MMA(1, 0, At, B0); PG8_BAR; PG8_SCHED;
;             PG8_STAGE(PG8_SB(0, 1), b2 + hstep, voffB);
;             PG8_WAIT_V(6); PG8_BAR; PG8_MMA(1, 1, At, B1); PG8_BAR;
;             PG8_LDB(B0, 1, 0); PG8_SCHED; PG8_LDA(At, 1, 0); PG8_STAGE(PG8_SA(0, 1), a2 + hstep, voffA);
;             PG8_WAIT_L(8); PG8_BAR; PG8_WAIT_L(0); PG8_MMA(0, 0, At, B0); PG8_BAR; PG8_SCHED;
;             PG8_LDB(B1, 1, 1); PG8_STAGE(PG8_SB(1, 0), b3, voffB);
;             PG8_BAR; PG8_WAIT_L(0); PG8_MMA(0, 1, At, B1); PG8_BAR;
;             PG8_LDA(At, 1, 1); PG8_STAGE(PG8_SA(1, 0), a3, voffA);
;             PG8_BAR; PG8_WAIT_L(0); PG8_MMA(1, 0, At, B0); PG8_BAR; PG8_SCHED;
;             PG8_STAGE(PG8_SB(1, 1), b3 + hstep, voffB);
;             PG8_WAIT_V(6); PG8_BAR; PG8_MMA(1, 1, At, B1); PG8_BAR;
	s_waitcnt lgkmcnt(0)
	s_setprio 1
	v_mfma_f32_16x16x32_bf16 v[52:55], v[144:147], v[168:171], v[52:55]
	v_mfma_f32_16x16x32_bf16 v[48:51], v[160:163], v[168:171], v[48:51]
	v_mfma_f32_16x16x32_bf16 v[36:39], v[144:147], v[176:179], v[36:39]
	v_mfma_f32_16x16x32_bf16 v[32:35], v[160:163], v[176:179], v[32:35]
	v_mfma_f32_16x16x32_bf16 v[20:23], v[144:147], v[188:191], v[20:23]
	v_mfma_f32_16x16x32_bf16 v[16:19], v[160:163], v[188:191], v[16:19]
	v_mfma_f32_16x16x32_bf16 v[4:7], v[144:147], v[210:213], v[4:7]
	v_mfma_f32_16x16x32_bf16 v[0:3], v[160:163], v[210:213], v[0:3]
	v_mfma_f32_16x16x32_bf16 v[52:55], v[156:159], v[172:175], v[52:55]
	v_mfma_f32_16x16x32_bf16 v[48:51], v[164:167], v[172:175], v[48:51]
	v_mfma_f32_16x16x32_bf16 v[36:39], v[156:159], v[180:183], v[36:39]
	v_mfma_f32_16x16x32_bf16 v[32:35], v[164:167], v[180:183], v[32:35]
	v_mfma_f32_16x16x32_bf16 v[20:23], v[156:159], v[206:209], v[20:23]
	v_mfma_f32_16x16x32_bf16 v[16:19], v[164:167], v[206:209], v[16:19]
	v_mfma_f32_16x16x32_bf16 v[4:7], v[156:159], v[214:217], v[4:7]
	v_mfma_f32_16x16x32_bf16 v[0:3], v[164:167], v[214:217], v[0:3]
	s_setprio 0
	s_barrier
	s_add_i32 s4, s5, s50
	s_mov_b32 m0, s4
	s_add_u32 s0, s40, 0x80080
	s_addc_u32 s1, s41, 0
	global_load_lds_dwordx4 v130, s[0:1]
	s_add_i32 m0, s4, 0x2000
	s_nop 0
	global_load_lds_dwordx4 v134, s[0:1]
	s_add_i32 s68, s68, 2
	s_add_u32 s8, s8, 0x100
	s_addc_u32 s9, s9, 0
	s_add_u32 s66, s66, 0x100
	s_addc_u32 s67, s67, 0
	s_cmp_gt_u32 s68, 29
	s_waitcnt vmcnt(6)
	s_barrier
	s_setprio 1
	v_mfma_f32_16x16x32_bf16 v[60:63], v[218:221], v[168:171], v[60:63]
	v_mfma_f32_16x16x32_bf16 v[56:59], v[226:229], v[168:171], v[56:59]
	v_mfma_f32_16x16x32_bf16 v[44:47], v[218:221], v[176:179], v[44:47]
	v_mfma_f32_16x16x32_bf16 v[40:43], v[226:229], v[176:179], v[40:43]
	v_mfma_f32_16x16x32_bf16 v[28:31], v[218:221], v[188:191], v[28:31]
	v_mfma_f32_16x16x32_bf16 v[24:27], v[226:229], v[188:191], v[24:27]
	v_mfma_f32_16x16x32_bf16 v[12:15], v[218:221], v[210:213], v[12:15]
	v_mfma_f32_16x16x32_bf16 v[8:11], v[226:229], v[210:213], v[8:11]
	v_mfma_f32_16x16x32_bf16 v[60:63], v[222:225], v[172:175], v[60:63]
	v_mfma_f32_16x16x32_bf16 v[56:59], v[230:233], v[172:175], v[56:59]
	v_mfma_f32_16x16x32_bf16 v[44:47], v[222:225], v[180:183], v[44:47]
	v_mfma_f32_16x16x32_bf16 v[40:43], v[230:233], v[180:183], v[40:43]
	v_mfma_f32_16x16x32_bf16 v[28:31], v[222:225], v[206:209], v[28:31]
	v_mfma_f32_16x16x32_bf16 v[24:27], v[230:233], v[206:209], v[24:27]
	v_mfma_f32_16x16x32_bf16 v[12:15], v[222:225], v[214:217], v[12:15]
	v_mfma_f32_16x16x32_bf16 v[8:11], v[230:233], v[214:217], v[8:11]
	s_setprio 0
	s_barrier
	s_cbranch_scc0 .LBB0_1668
	s_branch .Lpeel_done_1668
.LBB0_1668:
	ds_read_b128 v[144:147], v149
	ds_read_b128 v[156:159], v149 offset:1024
	ds_read_b128 v[160:163], v149 offset:2048
	ds_read_b128 v[164:167], v149 offset:3072
	s_add_i32 m0, s39, 0xc000
	ds_read_b128 v[168:171], v150
	ds_read_b128 v[172:175], v150 offset:1024
	ds_read_b128 v[176:179], v150 offset:2048
	ds_read_b128 v[180:183], v150 offset:3072
	ds_read_b128 v[188:191], v150 offset:4096
	ds_read_b128 v[206:209], v150 offset:5120
	ds_read_b128 v[210:213], v150 offset:6144
	global_load_lds_dwordx4 v136, s[8:9]
	s_add_i32 m0, s39, 0xe000
	ds_read_b128 v[214:217], v150 offset:7168
	global_load_lds_dwordx4 v138, s[8:9]
	s_add_u32 s0, s8, 0xfff80080
	s_addc_u32 s1, s9, -1
	s_cmp_eq_u32 s68, 28
	s_cselect_b32 s43, s29, s1
	s_cselect_b32 s42, s35, s0
	s_cselect_b32 s41, s19, s67
	s_cselect_b32 s40, s65, s66
	s_waitcnt lgkmcnt(8)
	s_barrier
	s_waitcnt lgkmcnt(0)
	s_setprio 1
	v_mfma_f32_16x16x32_bf16 v[116:119], v[144:147], v[168:171], v[116:119]
	v_mfma_f32_16x16x32_bf16 v[112:115], v[160:163], v[168:171], v[112:115]
	v_mfma_f32_16x16x32_bf16 v[100:103], v[144:147], v[176:179], v[100:103]
	v_mfma_f32_16x16x32_bf16 v[96:99], v[160:163], v[176:179], v[96:99]
	v_mfma_f32_16x16x32_bf16 v[84:87], v[144:147], v[188:191], v[84:87]
	v_mfma_f32_16x16x32_bf16 v[80:83], v[160:163], v[188:191], v[80:83]
	v_mfma_f32_16x16x32_bf16 v[68:71], v[144:147], v[210:213], v[68:71]
	v_mfma_f32_16x16x32_bf16 v[64:67], v[160:163], v[210:213], v[64:67]
	v_mfma_f32_16x16x32_bf16 v[116:119], v[156:159], v[172:175], v[116:119]
	v_mfma_f32_16x16x32_bf16 v[112:115], v[164:167], v[172:175], v[112:115]
	v_mfma_f32_16x16x32_bf16 v[100:103], v[156:159], v[180:183], v[100:103]
	v_mfma_f32_16x16x32_bf16 v[96:99], v[164:167], v[180:183], v[96:99]
	v_mfma_f32_16x16x32_bf16 v[84:87], v[156:159], v[206:209], v[84:87]
	v_mfma_f32_16x16x32_bf16 v[80:83], v[164:167], v[206:209], v[80:83]
	v_mfma_f32_16x16x32_bf16 v[68:71], v[156:159], v[214:217], v[68:71]
	v_mfma_f32_16x16x32_bf16 v[64:67], v[164:167], v[214:217], v[64:67]
	s_setprio 0
	s_barrier
	s_add_i32 s0, s61, s50
	s_mov_b32 m0, s0
	ds_read_b128 v[218:221], v151
	ds_read_b128 v[222:225], v151 offset:1024
	ds_read_b128 v[226:229], v151 offset:2048
	global_load_lds_dwordx4 v130, s[40:41]
	s_add_i32 m0, s0, 0x2000
	ds_read_b128 v[230:233], v151 offset:3072
	global_load_lds_dwordx4 v134, s[40:41]
	s_barrier
; #define PG8_STAGE(bufoff, gbase, voff) do { _Pragma("unroll") for (int _i = 0; _i < 2; ++_i) \
;         __builtin_amdgcn_global_load_lds((const unsigned*)((const char*)(gbase) + (voff)[_i]), (LAS unsigned*)(lds + (bufoff) + ldsw + _i * 8192), 16, 0, 0); } while (0)
; #define PG8_LDA(dst, b, h) do { _Pragma("unroll") for (int m = 0; m < 4; ++m) _Pragma("unroll") for (int k = 0; k < 2; ++k) dst[m][k] = *(const LAS bf16x8*)(lds + PG8_SA(b, h) + aoff + m * 2048 + k * 1024); } while (0)
; #define PG8_LDB(dst, b, h) do { _Pragma("unroll") for (int n = 0; n < 2; ++n) _Pragma("unroll") for (int k = 0; k < 2; ++k) dst[n][k] = *(const LAS bf16x8*)(lds + PG8_SB(b, h) + boff + n * 2048 + k * 1024); } while (0)
; #define PG8_MMA(ai, bj, At, Bt) do { __builtin_amdgcn_s_setprio(1); _Pragma("unroll") for (int m = 0; m < 4; ++m) _Pragma("unroll") for (int n = 0; n < 2; ++n) _Pragma("unroll") for (int k = 0; k < 2; ++k) \
;         acc[ai][bj][m][n] = __builtin_amdgcn_mfma_f32_16x16x32_bf16(Bt[n][k], At[m][k], acc[ai][bj][m][n], 0, 0, 0); __builtin_amdgcn_s_setprio(0); } while (0)
; #define PG8_WAIT_V(n) asm volatile("s_waitcnt vmcnt(" #n ")" ::: "memory")
; #define PG8_WAIT_L(n) asm volatile("s_waitcnt lgkmcnt(" #n ")" ::: "memory")
; #define PG8_BAR __builtin_amdgcn_s_barrier()
; #define PG8_SCHED __builtin_amdgcn_sched_barrier(0)
; template <class Epi, class Sched>
; DI void gemm_phase(LAS unsigned char* lds, const Gemm g, const Sched& S, const Epi& E) {
;     ...
;             PG8_BAR; PG8_WAIT_L(0); PG8_MMA(0, 1, At, B1); PG8_BAR;
;             PG8_LDA(At, 0, 1); PG8_STAGE(PG8_SA(0, 0), a2, voffA);
;             PG8_BAR; PG8_WAIT_L(0); PG8_MMA(1, 0, At, B0); PG8_BAR; PG8_SCHED;
;             PG8_STAGE(PG8_SB(0, 1), b2 + hstep, voffB);
;             PG8_WAIT_V(6); PG8_BAR; PG8_MMA(1, 1, At, B1); PG8_BAR;
;             PG8_LDB(B0, 1, 0); PG8_SCHED; PG8_LDA(At, 1, 0); PG8_STAGE(PG8_SA(0, 1), a2 + hstep, voffA);
	s_waitcnt lgkmcnt(0)
	s_setprio 1
	v_mfma_f32_16x16x32_bf16 v[124:127], v[218:221], v[168:171], v[124:127]
	v_mfma_f32_16x16x32_bf16 v[120:123], v[226:229], v[168:171], v[120:123]
	v_mfma_f32_16x16x32_bf16 v[108:111], v[218:221], v[176:179], v[108:111]
	v_mfma_f32_16x16x32_bf16 v[104:107], v[226:229], v[176:179], v[104:107]
	v_mfma_f32_16x16x32_bf16 v[92:95], v[218:221], v[188:191], v[92:95]
	v_mfma_f32_16x16x32_bf16 v[88:91], v[226:229], v[188:191], v[88:91]
	v_mfma_f32_16x16x32_bf16 v[76:79], v[218:221], v[210:213], v[76:79]
	v_mfma_f32_16x16x32_bf16 v[72:75], v[226:229], v[210:213], v[72:75]
	v_mfma_f32_16x16x32_bf16 v[124:127], v[222:225], v[172:175], v[124:127]
	v_mfma_f32_16x16x32_bf16 v[120:123], v[230:233], v[172:175], v[120:123]
	v_mfma_f32_16x16x32_bf16 v[108:111], v[222:225], v[180:183], v[108:111]
	v_mfma_f32_16x16x32_bf16 v[104:107], v[230:233], v[180:183], v[104:107]
	v_mfma_f32_16x16x32_bf16 v[92:95], v[222:225], v[206:209], v[92:95]
	v_mfma_f32_16x16x32_bf16 v[88:91], v[230:233], v[206:209], v[88:91]
	v_mfma_f32_16x16x32_bf16 v[76:79], v[222:225], v[214:217], v[76:79]
	v_mfma_f32_16x16x32_bf16 v[72:75], v[230:233], v[214:217], v[72:75]
	s_setprio 0
	s_mov_b32 m0, s39
	s_barrier
	ds_read_b128 v[168:171], v150 offset:16384
	ds_read_b128 v[172:175], v150 offset:17408
	ds_read_b128 v[176:179], v150 offset:18432
	ds_read_b128 v[180:183], v150 offset:19456
	ds_read_b128 v[188:191], v150 offset:20480
	ds_read_b128 v[206:209], v150 offset:21504
	ds_read_b128 v[210:213], v150 offset:22528
	global_load_lds_dwordx4 v128, s[42:43]
	s_mov_b32 m0, s51
	ds_read_b128 v[214:217], v150 offset:23552
	global_load_lds_dwordx4 v132, s[42:43]
	s_barrier
	s_waitcnt lgkmcnt(0)
	s_setprio 1
	v_mfma_f32_16x16x32_bf16 v[52:55], v[144:147], v[168:171], v[52:55]
	v_mfma_f32_16x16x32_bf16 v[48:51], v[160:163], v[168:171], v[48:51]
	v_mfma_f32_16x16x32_bf16 v[36:39], v[144:147], v[176:179], v[36:39]
	v_mfma_f32_16x16x32_bf16 v[32:35], v[160:163], v[176:179], v[32:35]
	v_mfma_f32_16x16x32_bf16 v[20:23], v[144:147], v[188:191], v[20:23]
	v_mfma_f32_16x16x32_bf16 v[16:19], v[160:163], v[188:191], v[16:19]
	v_mfma_f32_16x16x32_bf16 v[4:7], v[144:147], v[210:213], v[4:7]
	v_mfma_f32_16x16x32_bf16 v[0:3], v[160:163], v[210:213], v[0:3]
	v_mfma_f32_16x16x32_bf16 v[52:55], v[156:159], v[172:175], v[52:55]
	v_mfma_f32_16x16x32_bf16 v[48:51], v[164:167], v[172:175], v[48:51]
	v_mfma_f32_16x16x32_bf16 v[36:39], v[156:159], v[180:183], v[36:39]
	v_mfma_f32_16x16x32_bf16 v[32:35], v[164:167], v[180:183], v[32:35]
	v_mfma_f32_16x16x32_bf16 v[20:23], v[156:159], v[206:209], v[20:23]
	v_mfma_f32_16x16x32_bf16 v[16:19], v[164:167], v[206:209], v[16:19]
	v_mfma_f32_16x16x32_bf16 v[4:7], v[156:159], v[214:217], v[4:7]
	v_mfma_f32_16x16x32_bf16 v[0:3], v[164:167], v[214:217], v[0:3]
	s_setprio 0
	s_barrier
	s_add_i32 s4, s62, s50
	s_mov_b32 m0, s4
	s_add_u32 s0, s40, 0x80000
	s_addc_u32 s1, s41, 0
	global_load_lds_dwordx4 v130, s[0:1]
	s_add_i32 m0, s4, 0x2000
	s_nop 0
	global_load_lds_dwordx4 v134, s[0:1]
	s_waitcnt vmcnt(6)
	s_barrier
	s_setprio 1
	v_mfma_f32_16x16x32_bf16 v[60:63], v[218:221], v[168:171], v[60:63]
	v_mfma_f32_16x16x32_bf16 v[56:59], v[226:229], v[168:171], v[56:59]
	v_mfma_f32_16x16x32_bf16 v[44:47], v[218:221], v[176:179], v[44:47]
	v_mfma_f32_16x16x32_bf16 v[40:43], v[226:229], v[176:179], v[40:43]
	v_mfma_f32_16x16x32_bf16 v[28:31], v[218:221], v[188:191], v[28:31]
	v_mfma_f32_16x16x32_bf16 v[24:27], v[226:229], v[188:191], v[24:27]
	v_mfma_f32_16x16x32_bf16 v[12:15], v[218:221], v[210:213], v[12:15]
	v_mfma_f32_16x16x32_bf16 v[8:11], v[226:229], v[210:213], v[8:11]
	v_mfma_f32_16x16x32_bf16 v[60:63], v[222:225], v[172:175], v[60:63]
	v_mfma_f32_16x16x32_bf16 v[56:59], v[230:233], v[172:175], v[56:59]
	v_mfma_f32_16x16x32_bf16 v[44:47], v[222:225], v[180:183], v[44:47]
	v_mfma_f32_16x16x32_bf16 v[40:43], v[230:233], v[180:183], v[40:43]
	v_mfma_f32_16x16x32_bf16 v[28:31], v[222:225], v[206:209], v[28:31]
	v_mfma_f32_16x16x32_bf16 v[24:27], v[230:233], v[206:209], v[24:27]
	v_mfma_f32_16x16x32_bf16 v[12:15], v[222:225], v[214:217], v[12:15]
	v_mfma_f32_16x16x32_bf16 v[8:11], v[230:233], v[214:217], v[8:11]
	s_setprio 0
	s_add_i32 s4, 0, 0x18000
	s_barrier
	ds_read_b128 v[144:147], v202
	ds_read_b128 v[156:159], v202 offset:1024
	ds_read_b128 v[160:163], v202 offset:2048
	ds_read_b128 v[164:167], v202 offset:3072
	s_add_u32 s0, s42, 0x80000
	s_addc_u32 s1, s43, 0
	s_mov_b32 m0, s52
	ds_read_b128 v[168:171], v150 offset:32768
	ds_read_b128 v[172:175], v150 offset:33792
	ds_read_b128 v[176:179], v150 offset:34816
	ds_read_b128 v[180:183], v150 offset:35840
	ds_read_b128 v[188:191], v150 offset:36864
	ds_read_b128 v[206:209], v150 offset:37888
	ds_read_b128 v[210:213], v150 offset:38912
	global_load_lds_dwordx4 v128, s[0:1]
	s_mov_b32 m0, s53
	ds_read_b128 v[214:217], v150 offset:39936
	global_load_lds_dwordx4 v132, s[0:1]
	s_waitcnt lgkmcnt(8)
	s_barrier
; #define PG8_STAGE(bufoff, gbase, voff) do { _Pragma("unroll") for (int _i = 0; _i < 2; ++_i) \
;         __builtin_amdgcn_global_load_lds((const unsigned*)((const char*)(gbase) + (voff)[_i]), (LAS unsigned*)(lds + (bufoff) + ldsw + _i * 8192), 16, 0, 0); } while (0)
; #define PG8_LDA(dst, b, h) do { _Pragma("unroll") for (int m = 0; m < 4; ++m) _Pragma("unroll") for (int k = 0; k < 2; ++k) dst[m][k] = *(const LAS bf16x8*)(lds + PG8_SA(b, h) + aoff + m * 2048 + k * 1024); } while (0)
; #define PG8_LDB(dst, b, h) do { _Pragma("unroll") for (int n = 0; n < 2; ++n) _Pragma("unroll") for (int k = 0; k < 2; ++k) dst[n][k] = *(const LAS bf16x8*)(lds + PG8_SB(b, h) + boff + n * 2048 + k * 1024); } while (0)
; #define PG8_MMA(ai, bj, At, Bt) do { __builtin_amdgcn_s_setprio(1); _Pragma("unroll") for (int m = 0; m < 4; ++m) _Pragma("unroll") for (int n = 0; n < 2; ++n) _Pragma("unroll") for (int k = 0; k < 2; ++k) \
;         acc[ai][bj][m][n] = __builtin_amdgcn_mfma_f32_16x16x32_bf16(Bt[n][k], At[m][k], acc[ai][bj][m][n], 0, 0, 0); __builtin_amdgcn_s_setprio(0); } while (0)
; #define PG8_WAIT_V(n) asm volatile("s_waitcnt vmcnt(" #n ")" ::: "memory")
; #define PG8_WAIT_L(n) asm volatile("s_waitcnt lgkmcnt(" #n ")" ::: "memory")
; #define PG8_BAR __builtin_amdgcn_s_barrier()
; #define PG8_SCHED __builtin_amdgcn_sched_barrier(0)
; template <class Epi, class Sched>
; DI void gemm_phase(LAS unsigned char* lds, const Gemm g, const Sched& S, const Epi& E) {
;     ...
;             PG8_WAIT_L(8); PG8_BAR; PG8_WAIT_L(0); PG8_MMA(0, 0, At, B0); PG8_BAR; PG8_SCHED;
;             PG8_LDB(B1, 1, 1); PG8_STAGE(PG8_SB(1, 0), b3, voffB);
;             PG8_BAR; PG8_WAIT_L(0); PG8_MMA(0, 1, At, B1); PG8_BAR;
;             PG8_LDA(At, 1, 1); PG8_STAGE(PG8_SA(1, 0), a3, voffA);
;             PG8_BAR; PG8_WAIT_L(0); PG8_MMA(1, 0, At, B0); PG8_BAR; PG8_SCHED;
;             PG8_STAGE(PG8_SB(1, 1), b3 + hstep, voffB);
;             PG8_WAIT_V(6); PG8_BAR; PG8_MMA(1, 1, At, B1); PG8_BAR;
	s_waitcnt lgkmcnt(0)
	s_setprio 1
	v_mfma_f32_16x16x32_bf16 v[116:119], v[144:147], v[168:171], v[116:119]
	v_mfma_f32_16x16x32_bf16 v[112:115], v[160:163], v[168:171], v[112:115]
	v_mfma_f32_16x16x32_bf16 v[100:103], v[144:147], v[176:179], v[100:103]
	v_mfma_f32_16x16x32_bf16 v[96:99], v[160:163], v[176:179], v[96:99]
	v_mfma_f32_16x16x32_bf16 v[84:87], v[144:147], v[188:191], v[84:87]
	v_mfma_f32_16x16x32_bf16 v[80:83], v[160:163], v[188:191], v[80:83]
	v_mfma_f32_16x16x32_bf16 v[68:71], v[144:147], v[210:213], v[68:71]
	v_mfma_f32_16x16x32_bf16 v[64:67], v[160:163], v[210:213], v[64:67]
	v_mfma_f32_16x16x32_bf16 v[116:119], v[156:159], v[172:175], v[116:119]
	v_mfma_f32_16x16x32_bf16 v[112:115], v[164:167], v[172:175], v[112:115]
	v_mfma_f32_16x16x32_bf16 v[100:103], v[156:159], v[180:183], v[100:103]
	v_mfma_f32_16x16x32_bf16 v[96:99], v[164:167], v[180:183], v[96:99]
	v_mfma_f32_16x16x32_bf16 v[84:87], v[156:159], v[206:209], v[84:87]
	v_mfma_f32_16x16x32_bf16 v[80:83], v[164:167], v[206:209], v[80:83]
	v_mfma_f32_16x16x32_bf16 v[68:71], v[156:159], v[214:217], v[68:71]
	v_mfma_f32_16x16x32_bf16 v[64:67], v[164:167], v[214:217], v[64:67]
	s_setprio 0
	s_barrier
	s_add_i32 s5, 0, 0x1c000
	s_add_i32 s0, s4, s50
	s_add_i32 m0, s0, 0xffffff80
	ds_read_b128 v[218:221], v203
	ds_read_b128 v[222:225], v203 offset:1024
	ds_read_b128 v[226:229], v203 offset:2048
	global_load_lds_dwordx4 v130, s[40:41] offset:128
	s_add_i32 m0, s0, 0x1f80
	ds_read_b128 v[230:233], v203 offset:3072
	global_load_lds_dwordx4 v134, s[40:41] offset:128
	s_barrier
	s_waitcnt lgkmcnt(0)
	s_setprio 1
	v_mfma_f32_16x16x32_bf16 v[124:127], v[218:221], v[168:171], v[124:127]
	v_mfma_f32_16x16x32_bf16 v[120:123], v[226:229], v[168:171], v[120:123]
	v_mfma_f32_16x16x32_bf16 v[108:111], v[218:221], v[176:179], v[108:111]
	v_mfma_f32_16x16x32_bf16 v[104:107], v[226:229], v[176:179], v[104:107]
	v_mfma_f32_16x16x32_bf16 v[92:95], v[218:221], v[188:191], v[92:95]
	v_mfma_f32_16x16x32_bf16 v[88:91], v[226:229], v[188:191], v[88:91]
	v_mfma_f32_16x16x32_bf16 v[76:79], v[218:221], v[210:213], v[76:79]
	v_mfma_f32_16x16x32_bf16 v[72:75], v[226:229], v[210:213], v[72:75]
	v_mfma_f32_16x16x32_bf16 v[124:127], v[222:225], v[172:175], v[124:127]
	v_mfma_f32_16x16x32_bf16 v[120:123], v[230:233], v[172:175], v[120:123]
	v_mfma_f32_16x16x32_bf16 v[108:111], v[222:225], v[180:183], v[108:111]
	v_mfma_f32_16x16x32_bf16 v[104:107], v[230:233], v[180:183], v[104:107]
	v_mfma_f32_16x16x32_bf16 v[92:95], v[222:225], v[206:209], v[92:95]
	v_mfma_f32_16x16x32_bf16 v[88:91], v[230:233], v[206:209], v[88:91]
	v_mfma_f32_16x16x32_bf16 v[76:79], v[222:225], v[214:217], v[76:79]
	v_mfma_f32_16x16x32_bf16 v[72:75], v[230:233], v[214:217], v[72:75]
	s_setprio 0
	s_add_i32 m0, s57, 0xffffff80
	s_barrier
	ds_read_b128 v[168:171], v150 offset:49152
	ds_read_b128 v[172:175], v150 offset:50176
	ds_read_b128 v[176:179], v150 offset:51200
	ds_read_b128 v[180:183], v150 offset:52224
	ds_read_b128 v[188:191], v150 offset:53248
	ds_read_b128 v[206:209], v150 offset:54272
	ds_read_b128 v[210:213], v150 offset:55296
	global_load_lds_dwordx4 v128, s[42:43] offset:128
	s_add_i32 m0, s58, 0xffffff80
	ds_read_b128 v[214:217], v150 offset:56320
	global_load_lds_dwordx4 v132, s[42:43] offset:128
	s_barrier
	s_waitcnt lgkmcnt(0)
	s_setprio 1
	v_mfma_f32_16x16x32_bf16 v[52:55], v[144:147], v[168:171], v[52:55]
	v_mfma_f32_16x16x32_bf16 v[48:51], v[160:163], v[168:171], v[48:51]
	v_mfma_f32_16x16x32_bf16 v[36:39], v[144:147], v[176:179], v[36:39]
	v_mfma_f32_16x16x32_bf16 v[32:35], v[160:163], v[176:179], v[32:35]
	v_mfma_f32_16x16x32_bf16 v[20:23], v[144:147], v[188:191], v[20:23]
	v_mfma_f32_16x16x32_bf16 v[16:19], v[160:163], v[188:191], v[16:19]
	v_mfma_f32_16x16x32_bf16 v[4:7], v[144:147], v[210:213], v[4:7]
	v_mfma_f32_16x16x32_bf16 v[0:3], v[160:163], v[210:213], v[0:3]
	v_mfma_f32_16x16x32_bf16 v[52:55], v[156:159], v[172:175], v[52:55]
	v_mfma_f32_16x16x32_bf16 v[48:51], v[164:167], v[172:175], v[48:51]
	v_mfma_f32_16x16x32_bf16 v[36:39], v[156:159], v[180:183], v[36:39]
	v_mfma_f32_16x16x32_bf16 v[32:35], v[164:167], v[180:183], v[32:35]
	v_mfma_f32_16x16x32_bf16 v[20:23], v[156:159], v[206:209], v[20:23]
	v_mfma_f32_16x16x32_bf16 v[16:19], v[164:167], v[206:209], v[16:19]
	v_mfma_f32_16x16x32_bf16 v[4:7], v[156:159], v[214:217], v[4:7]
	v_mfma_f32_16x16x32_bf16 v[0:3], v[164:167], v[214:217], v[0:3]
	s_setprio 0
	s_barrier
	s_add_i32 s4, s5, s50
	s_mov_b32 m0, s4
	s_add_u32 s0, s40, 0x80080
	s_addc_u32 s1, s41, 0
	global_load_lds_dwordx4 v130, s[0:1]
	s_add_i32 m0, s4, 0x2000
	s_nop 0
	global_load_lds_dwordx4 v134, s[0:1]
	s_add_i32 s68, s68, 2
	s_add_u32 s8, s8, 0x100
	s_addc_u32 s9, s9, 0
	s_add_u32 s66, s66, 0x100
	s_addc_u32 s67, s67, 0
	s_cmp_gt_u32 s68, 29
	s_waitcnt vmcnt(6)
	s_barrier
	s_setprio 1
	v_mfma_f32_16x16x32_bf16 v[60:63], v[218:221], v[168:171], v[60:63]
	v_mfma_f32_16x16x32_bf16 v[56:59], v[226:229], v[168:171], v[56:59]
	v_mfma_f32_16x16x32_bf16 v[44:47], v[218:221], v[176:179], v[44:47]
	v_mfma_f32_16x16x32_bf16 v[40:43], v[226:229], v[176:179], v[40:43]
	v_mfma_f32_16x16x32_bf16 v[28:31], v[218:221], v[188:191], v[28:31]
	v_mfma_f32_16x16x32_bf16 v[24:27], v[226:229], v[188:191], v[24:27]
	v_mfma_f32_16x16x32_bf16 v[12:15], v[218:221], v[210:213], v[12:15]
	v_mfma_f32_16x16x32_bf16 v[8:11], v[226:229], v[210:213], v[8:11]
	v_mfma_f32_16x16x32_bf16 v[60:63], v[222:225], v[172:175], v[60:63]
	v_mfma_f32_16x16x32_bf16 v[56:59], v[230:233], v[172:175], v[56:59]
	v_mfma_f32_16x16x32_bf16 v[44:47], v[222:225], v[180:183], v[44:47]
	v_mfma_f32_16x16x32_bf16 v[40:43], v[230:233], v[180:183], v[40:43]
	v_mfma_f32_16x16x32_bf16 v[28:31], v[222:225], v[206:209], v[28:31]
	v_mfma_f32_16x16x32_bf16 v[24:27], v[230:233], v[206:209], v[24:27]
	v_mfma_f32_16x16x32_bf16 v[12:15], v[222:225], v[214:217], v[12:15]
	v_mfma_f32_16x16x32_bf16 v[8:11], v[230:233], v[214:217], v[8:11]
	s_setprio 0
	s_barrier
	s_cbranch_scc0 .LBB0_1668

;     DI size_t aoff(const Unit& u, size_t tstep) const { return (size_t)u.pm * tstep; }
;     DI size_t boff(const Unit& u, size_t tstep) const { return (size_t)u.pn * tstep; }
;     DI bool next(int i, Unit& u) const { const long L = (long)i * G + c; if (L >= np) return false; u.pm = pmv; u.pn = (int)(L % nN); u.ks = (int)(L / nN); return true; }
;     DI size_t aoff(const Unit& u, size_t) const { return (size_t)u.ks * kbytes; }
;     DI size_t boff(const Unit& u, size_t tstep) const { return (size_t)u.pn * tstep + (size_t)u.ks * kbytes; }
;     DI bool next(int i, Unit& u) const { Unit t; if (!S.next(i / 3, t)) return false; u.pm = t.pm; u.pn = t.pn; u.ks = i % 3; return true; }
;     DI size_t aoff(const Unit& u, size_t tstep) const { return (u.ks < 2 ? offU : offOA) + (size_t)u.pm * tstep; }
; #define PG8_WAIT_L(n) asm volatile("s_waitcnt lgkmcnt(" #n ")" ::: "memory")
; #define PG8_BAR __builtin_amdgcn_s_barrier()
; template <class Epi, class Sched>
; DI void gemm_phase(LAS unsigned char* lds, const Gemm g, const Sched& S, const Epi& E) {
;     ...
;         const bool has_next = S.next(ui + 1, nxt);
;         const char* nA = has_next ? (const char*)g.A + S.aoff(nxt, tstep) : cA; const char* nB = has_next ? (const char*)g.Bt + S.boff(nxt, tstep) : cB;
;         for (int t = 0; t < nt; t += 2) {
;             if constexpr (Epi::HAS_MID) { if (t == E.mid_t(nt)) { int fr3 = fr, fq3 = fq; asm volatile("" : "+v"(fr3), "+v"(fq3)); E.mid(acc, cur, wr, wc, fr3, fq3); } }
;             const bool last = (t == nt - 2);
;             const char* a1 = cA + (size_t)(t + 1) * kstep;
;             const char* a2 = last ? nA : cA + (size_t)(t + 2) * kstep; const char* b2 = last ? nB : cB + (size_t)(t + 2) * kstep;
;             const char* a3 = a2 + kstep; const char* b3 = b2 + kstep;
;             PG8_LDB(B0, 0, 0); PG8_SCHED; PG8_LDA(At, 0, 0); PG8_STAGE(PG8_SA(1, 1), a1 + hstep, voffA);
;             PG8_WAIT_L(8); PG8_BAR; PG8_WAIT_L(0); PG8_MMA(0, 0, At, B0); PG8_BAR; PG8_SCHED;
;             PG8_LDB(B1, 0, 1); PG8_STAGE(PG8_SB(0, 0), b2, voffB);
;             PG8_BAR; PG8_WAIT_L(0); PG8_MMA(0, 1, At, B1); PG8_BAR;
;             PG8_LDA(At, 0, 1); PG8_STAGE(PG8_SA(0, 0), a2, voffA);
;             PG8_BAR; PG8_WAIT_L(0); PG8_MMA(1, 0, At, B0); PG8_BAR; PG8_SCHED;
;             PG8_STAGE(PG8_SB(0, 1), b2 + hstep, voffB);
.LBB0_1774:
	s_add_u32 s28, s38, s28
	s_addc_u32 s29, s39, s29
	s_and_b64 s[0:1], s[8:9], exec
	s_cselect_b32 s15, s29, s37
	s_cselect_b32 s17, s28, s36
	s_add_u32 s8, s36, 0x160080
	s_addc_u32 s9, s37, 0
	s_add_u32 s64, s30, 0x100
	v_mov_b32_e32 v0, 0
	s_addc_u32 s65, s31, 0
	s_mov_b32 s66, -2
	ds_read_b128 v[146:149], v141
	ds_read_b128 v[154:157], v141 offset:1024
	ds_read_b128 v[158:161], v141 offset:2048
	ds_read_b128 v[162:165], v141 offset:3072
	s_mov_b32 m0, s56
	ds_read_b128 v[166:169], v142
	ds_read_b128 v[170:173], v142 offset:1024
	ds_read_b128 v[174:177], v142 offset:2048
	ds_read_b128 v[178:181], v142 offset:3072
	ds_read_b128 v[188:191], v142 offset:4096
	ds_read_b128 v[206:209], v142 offset:5120
	ds_read_b128 v[210:213], v142 offset:6144
	global_load_lds_dwordx4 v132, s[8:9]
	s_mov_b32 m0, s57
	ds_read_b128 v[214:217], v142 offset:7168
	global_load_lds_dwordx4 v134, s[8:9]
	s_add_u32 s0, s8, 0xffea0080
	s_addc_u32 s1, s9, -1
	s_cmp_eq_u32 s66, 4
	s_cselect_b32 s37, s15, s1
	s_cselect_b32 s36, s17, s0
	s_cselect_b32 s31, s19, s65
	s_cselect_b32 s30, s18, s64
	s_waitcnt lgkmcnt(8)
	s_barrier
	s_waitcnt lgkmcnt(0)
	s_setprio 1
	v_mfma_f32_16x16x32_bf16 v[124:127], v[146:149], v[166:169], 0
	v_mfma_f32_16x16x32_bf16 v[120:123], v[158:161], v[166:169], 0
	v_mfma_f32_16x16x32_bf16 v[116:119], v[146:149], v[174:177], 0
	v_mfma_f32_16x16x32_bf16 v[112:115], v[158:161], v[174:177], 0
	v_mfma_f32_16x16x32_bf16 v[104:107], v[146:149], v[188:191], 0
	v_mfma_f32_16x16x32_bf16 v[96:99], v[158:161], v[188:191], 0
	v_mfma_f32_16x16x32_bf16 v[88:91], v[146:149], v[210:213], 0
	v_mfma_f32_16x16x32_bf16 v[80:83], v[158:161], v[210:213], 0
	v_mfma_f32_16x16x32_bf16 v[124:127], v[154:157], v[170:173], v[124:127]
	v_mfma_f32_16x16x32_bf16 v[120:123], v[162:165], v[170:173], v[120:123]
	v_mfma_f32_16x16x32_bf16 v[116:119], v[154:157], v[178:181], v[116:119]
	v_mfma_f32_16x16x32_bf16 v[112:115], v[162:165], v[178:181], v[112:115]
	v_mfma_f32_16x16x32_bf16 v[104:107], v[154:157], v[206:209], v[104:107]
	v_mfma_f32_16x16x32_bf16 v[96:99], v[162:165], v[206:209], v[96:99]
	v_mfma_f32_16x16x32_bf16 v[88:91], v[154:157], v[214:217], v[88:91]
	v_mfma_f32_16x16x32_bf16 v[80:83], v[162:165], v[214:217], v[80:83]
	s_setprio 0
	s_barrier
	s_mov_b32 m0, s58
	ds_read_b128 v[218:221], v143
	ds_read_b128 v[222:225], v143 offset:1024
	ds_read_b128 v[226:229], v143 offset:2048
	global_load_lds_dwordx4 v130, s[30:31]
	s_mov_b32 m0, s59
	ds_read_b128 v[230:233], v143 offset:3072
	global_load_lds_dwordx4 v128, s[30:31]
	s_barrier
	s_waitcnt lgkmcnt(0)
	s_setprio 1
	v_mfma_f32_16x16x32_bf16 v[108:111], v[218:221], v[166:169], 0
	v_mfma_f32_16x16x32_bf16 v[100:103], v[226:229], v[166:169], 0
	v_mfma_f32_16x16x32_bf16 v[92:95], v[218:221], v[174:177], 0
	v_mfma_f32_16x16x32_bf16 v[84:87], v[226:229], v[174:177], 0
	v_mfma_f32_16x16x32_bf16 v[76:79], v[218:221], v[188:191], 0
	v_mfma_f32_16x16x32_bf16 v[72:75], v[226:229], v[188:191], 0
	v_mfma_f32_16x16x32_bf16 v[68:71], v[218:221], v[210:213], 0
	v_mfma_f32_16x16x32_bf16 v[64:67], v[226:229], v[210:213], 0
	v_mfma_f32_16x16x32_bf16 v[108:111], v[222:225], v[170:173], v[108:111]
	v_mfma_f32_16x16x32_bf16 v[100:103], v[230:233], v[170:173], v[100:103]
	v_mfma_f32_16x16x32_bf16 v[92:95], v[222:225], v[178:181], v[92:95]
	v_mfma_f32_16x16x32_bf16 v[84:87], v[230:233], v[178:181], v[84:87]
	v_mfma_f32_16x16x32_bf16 v[76:79], v[222:225], v[206:209], v[76:79]
	v_mfma_f32_16x16x32_bf16 v[72:75], v[230:233], v[206:209], v[72:75]
	v_mfma_f32_16x16x32_bf16 v[68:71], v[222:225], v[214:217], v[68:71]
	v_mfma_f32_16x16x32_bf16 v[64:67], v[230:233], v[214:217], v[64:67]
	s_setprio 0
	s_mov_b32 m0, s40
	s_barrier
	ds_read_b128 v[166:169], v142 offset:16384
	ds_read_b128 v[170:173], v142 offset:17408
	ds_read_b128 v[174:177], v142 offset:18432
	ds_read_b128 v[178:181], v142 offset:19456
	ds_read_b128 v[188:191], v142 offset:20480
	ds_read_b128 v[206:209], v142 offset:21504
	ds_read_b128 v[210:213], v142 offset:22528
	global_load_lds_dwordx4 v130, s[36:37]
	s_mov_b32 m0, s41
	ds_read_b128 v[214:217], v142 offset:23552
	global_load_lds_dwordx4 v128, s[36:37]
	s_barrier
	s_waitcnt lgkmcnt(0)
	s_setprio 1
	v_mfma_f32_16x16x32_bf16 v[60:63], v[146:149], v[166:169], 0
	v_mfma_f32_16x16x32_bf16 v[56:59], v[158:161], v[166:169], 0
	v_mfma_f32_16x16x32_bf16 v[52:55], v[146:149], v[174:177], 0
	v_mfma_f32_16x16x32_bf16 v[48:51], v[158:161], v[174:177], 0
	v_mfma_f32_16x16x32_bf16 v[40:43], v[146:149], v[188:191], 0
	v_mfma_f32_16x16x32_bf16 v[32:35], v[158:161], v[188:191], 0
	v_mfma_f32_16x16x32_bf16 v[24:27], v[146:149], v[210:213], 0
	v_mfma_f32_16x16x32_bf16 v[16:19], v[158:161], v[210:213], 0
	v_mfma_f32_16x16x32_bf16 v[60:63], v[154:157], v[170:173], v[60:63]
	v_mfma_f32_16x16x32_bf16 v[56:59], v[162:165], v[170:173], v[56:59]
	v_mfma_f32_16x16x32_bf16 v[52:55], v[154:157], v[178:181], v[52:55]
	v_mfma_f32_16x16x32_bf16 v[48:51], v[162:165], v[178:181], v[48:51]
	v_mfma_f32_16x16x32_bf16 v[40:43], v[154:157], v[206:209], v[40:43]
	v_mfma_f32_16x16x32_bf16 v[32:35], v[162:165], v[206:209], v[32:35]
	v_mfma_f32_16x16x32_bf16 v[24:27], v[154:157], v[214:217], v[24:27]
	v_mfma_f32_16x16x32_bf16 v[16:19], v[162:165], v[214:217], v[16:19]
	s_setprio 0
	s_barrier
	s_add_u32 s0, s30, 0x160000
	s_addc_u32 s1, s31, 0
	s_mov_b32 m0, s60
	s_nop 0
	global_load_lds_dwordx4 v130, s[0:1]
	s_mov_b32 m0, s61
	s_nop 0
	global_load_lds_dwordx4 v128, s[0:1]
	s_waitcnt vmcnt(6)
	s_barrier
; #define PG8_STAGE(bufoff, gbase, voff) do { _Pragma("unroll") for (int _i = 0; _i < 2; ++_i) \
;         __builtin_amdgcn_global_load_lds((const unsigned*)((const char*)(gbase) + (voff)[_i]), (LAS unsigned*)(lds + (bufoff) + ldsw + _i * 8192), 16, 0, 0); } while (0)
; #define PG8_LDA(dst, b, h) do { _Pragma("unroll") for (int m = 0; m < 4; ++m) _Pragma("unroll") for (int k = 0; k < 2; ++k) dst[m][k] = *(const LAS bf16x8*)(lds + PG8_SA(b, h) + aoff + m * 2048 + k * 1024); } while (0)
; #define PG8_LDB(dst, b, h) do { _Pragma("unroll") for (int n = 0; n < 2; ++n) _Pragma("unroll") for (int k = 0; k < 2; ++k) dst[n][k] = *(const LAS bf16x8*)(lds + PG8_SB(b, h) + boff + n * 2048 + k * 1024); } while (0)
; #define PG8_MMA(ai, bj, At, Bt) do { __builtin_amdgcn_s_setprio(1); _Pragma("unroll") for (int m = 0; m < 4; ++m) _Pragma("unroll") for (int n = 0; n < 2; ++n) _Pragma("unroll") for (int k = 0; k < 2; ++k) \
;         acc[ai][bj][m][n] = __builtin_amdgcn_mfma_f32_16x16x32_bf16(Bt[n][k], At[m][k], acc[ai][bj][m][n], 0, 0, 0); __builtin_amdgcn_s_setprio(0); } while (0)
; #define PG8_WAIT_V(n) asm volatile("s_waitcnt vmcnt(" #n ")" ::: "memory")
; #define PG8_WAIT_L(n) asm volatile("s_waitcnt lgkmcnt(" #n ")" ::: "memory")
; #define PG8_BAR __builtin_amdgcn_s_barrier()
; #define PG8_SCHED __builtin_amdgcn_sched_barrier(0)
; template <class Epi, class Sched>
; DI void gemm_phase(LAS unsigned char* lds, const Gemm g, const Sched& S, const Epi& E) {
;     ...
;             PG8_WAIT_V(6); PG8_BAR; PG8_MMA(1, 1, At, B1); PG8_BAR;
;             PG8_LDB(B0, 1, 0); PG8_SCHED; PG8_LDA(At, 1, 0); PG8_STAGE(PG8_SA(0, 1), a2 + hstep, voffA);
;             PG8_WAIT_L(8); PG8_BAR; PG8_WAIT_L(0); PG8_MMA(0, 0, At, B0); PG8_BAR; PG8_SCHED;
;             PG8_LDB(B1, 1, 1); PG8_STAGE(PG8_SB(1, 0), b3, voffB);
;             PG8_BAR; PG8_WAIT_L(0); PG8_MMA(0, 1, At, B1); PG8_BAR;
;             PG8_LDA(At, 1, 1); PG8_STAGE(PG8_SA(1, 0), a3, voffA);
	s_setprio 1
	v_mfma_f32_16x16x32_bf16 v[44:47], v[218:221], v[166:169], 0
	v_mfma_f32_16x16x32_bf16 v[36:39], v[226:229], v[166:169], 0
	v_mfma_f32_16x16x32_bf16 v[28:31], v[218:221], v[174:177], 0
	v_mfma_f32_16x16x32_bf16 v[20:23], v[226:229], v[174:177], 0
	v_mfma_f32_16x16x32_bf16 v[12:15], v[218:221], v[188:191], 0
	v_mfma_f32_16x16x32_bf16 v[8:11], v[226:229], v[188:191], 0
	v_mfma_f32_16x16x32_bf16 v[4:7], v[218:221], v[210:213], 0
	v_mfma_f32_16x16x32_bf16 v[0:3], v[226:229], v[210:213], 0
	v_mfma_f32_16x16x32_bf16 v[44:47], v[222:225], v[170:173], v[44:47]
	v_mfma_f32_16x16x32_bf16 v[36:39], v[230:233], v[170:173], v[36:39]
	v_mfma_f32_16x16x32_bf16 v[28:31], v[222:225], v[178:181], v[28:31]
	v_mfma_f32_16x16x32_bf16 v[20:23], v[230:233], v[178:181], v[20:23]
	v_mfma_f32_16x16x32_bf16 v[12:15], v[222:225], v[206:209], v[12:15]
	v_mfma_f32_16x16x32_bf16 v[8:11], v[230:233], v[206:209], v[8:11]
	v_mfma_f32_16x16x32_bf16 v[4:7], v[222:225], v[214:217], v[4:7]
	v_mfma_f32_16x16x32_bf16 v[0:3], v[230:233], v[214:217], v[0:3]
	s_setprio 0
	s_barrier
	ds_read_b128 v[146:149], v144
	ds_read_b128 v[154:157], v144 offset:1024
	ds_read_b128 v[158:161], v144 offset:2048
	ds_read_b128 v[162:165], v144 offset:3072
	s_add_u32 s0, s36, 0x160000
	s_addc_u32 s1, s37, 0
	s_mov_b32 m0, s42
	ds_read_b128 v[166:169], v142 offset:32768
	ds_read_b128 v[170:173], v142 offset:33792
	ds_read_b128 v[174:177], v142 offset:34816
	ds_read_b128 v[178:181], v142 offset:35840
	ds_read_b128 v[188:191], v142 offset:36864
	ds_read_b128 v[206:209], v142 offset:37888
	ds_read_b128 v[210:213], v142 offset:38912
	global_load_lds_dwordx4 v130, s[0:1]
	s_mov_b32 m0, s43
	ds_read_b128 v[214:217], v142 offset:39936
	global_load_lds_dwordx4 v128, s[0:1]
	s_waitcnt lgkmcnt(8)
	s_barrier
	s_waitcnt lgkmcnt(0)
	s_setprio 1
	v_mfma_f32_16x16x32_bf16 v[124:127], v[146:149], v[166:169], v[124:127]
	v_mfma_f32_16x16x32_bf16 v[120:123], v[158:161], v[166:169], v[120:123]
	v_mfma_f32_16x16x32_bf16 v[116:119], v[146:149], v[174:177], v[116:119]
	v_mfma_f32_16x16x32_bf16 v[112:115], v[158:161], v[174:177], v[112:115]
	v_mfma_f32_16x16x32_bf16 v[104:107], v[146:149], v[188:191], v[104:107]
	v_mfma_f32_16x16x32_bf16 v[96:99], v[158:161], v[188:191], v[96:99]
	v_mfma_f32_16x16x32_bf16 v[88:91], v[146:149], v[210:213], v[88:91]
	v_mfma_f32_16x16x32_bf16 v[80:83], v[158:161], v[210:213], v[80:83]
	v_mfma_f32_16x16x32_bf16 v[124:127], v[154:157], v[170:173], v[124:127]
	v_mfma_f32_16x16x32_bf16 v[120:123], v[162:165], v[170:173], v[120:123]
	v_mfma_f32_16x16x32_bf16 v[116:119], v[154:157], v[178:181], v[116:119]
	v_mfma_f32_16x16x32_bf16 v[112:115], v[162:165], v[178:181], v[112:115]
	v_mfma_f32_16x16x32_bf16 v[104:107], v[154:157], v[206:209], v[104:107]
	v_mfma_f32_16x16x32_bf16 v[96:99], v[162:165], v[206:209], v[96:99]
	v_mfma_f32_16x16x32_bf16 v[88:91], v[154:157], v[214:217], v[88:91]
	v_mfma_f32_16x16x32_bf16 v[80:83], v[162:165], v[214:217], v[80:83]
	s_setprio 0
	s_barrier
	s_add_i32 s4, 0, 0x1c000
	s_add_i32 s0, s62, s35
	v_add_u32_e32 v145, s4, v140
	s_add_i32 m0, s0, 0xffffff80
	ds_read_b128 v[218:221], v145
	ds_read_b128 v[222:225], v145 offset:1024
	ds_read_b128 v[226:229], v145 offset:2048
	global_load_lds_dwordx4 v130, s[30:31] offset:128
	s_add_i32 m0, s0, 0x1f80
	ds_read_b128 v[230:233], v145 offset:3072
	global_load_lds_dwordx4 v128, s[30:31] offset:128
	s_barrier
	s_waitcnt lgkmcnt(0)
	s_setprio 1
	v_mfma_f32_16x16x32_bf16 v[108:111], v[218:221], v[166:169], v[108:111]
	v_mfma_f32_16x16x32_bf16 v[100:103], v[226:229], v[166:169], v[100:103]
	v_mfma_f32_16x16x32_bf16 v[92:95], v[218:221], v[174:177], v[92:95]
	v_mfma_f32_16x16x32_bf16 v[84:87], v[226:229], v[174:177], v[84:87]
	v_mfma_f32_16x16x32_bf16 v[76:79], v[218:221], v[188:191], v[76:79]
	v_mfma_f32_16x16x32_bf16 v[72:75], v[226:229], v[188:191], v[72:75]
	v_mfma_f32_16x16x32_bf16 v[68:71], v[218:221], v[210:213], v[68:71]
	v_mfma_f32_16x16x32_bf16 v[64:67], v[226:229], v[210:213], v[64:67]
	v_mfma_f32_16x16x32_bf16 v[108:111], v[222:225], v[170:173], v[108:111]
	v_mfma_f32_16x16x32_bf16 v[100:103], v[230:233], v[170:173], v[100:103]
	v_mfma_f32_16x16x32_bf16 v[92:95], v[222:225], v[178:181], v[92:95]
	v_mfma_f32_16x16x32_bf16 v[84:87], v[230:233], v[178:181], v[84:87]
	v_mfma_f32_16x16x32_bf16 v[76:79], v[222:225], v[206:209], v[76:79]
	v_mfma_f32_16x16x32_bf16 v[72:75], v[230:233], v[206:209], v[72:75]
	v_mfma_f32_16x16x32_bf16 v[68:71], v[222:225], v[214:217], v[68:71]
	v_mfma_f32_16x16x32_bf16 v[64:67], v[230:233], v[214:217], v[64:67]
	s_setprio 0
	s_add_i32 m0, s54, 0xffffff80
	s_barrier
	ds_read_b128 v[166:169], v142 offset:49152
	ds_read_b128 v[170:173], v142 offset:50176
	ds_read_b128 v[174:177], v142 offset:51200
	ds_read_b128 v[178:181], v142 offset:52224
	ds_read_b128 v[188:191], v142 offset:53248
	ds_read_b128 v[206:209], v142 offset:54272
	ds_read_b128 v[210:213], v142 offset:55296
	global_load_lds_dwordx4 v130, s[36:37] offset:128
	s_add_i32 m0, s55, 0xffffff80
	ds_read_b128 v[214:217], v142 offset:56320
	global_load_lds_dwordx4 v128, s[36:37] offset:128
	s_barrier
; #define PG8_STAGE(bufoff, gbase, voff) do { _Pragma("unroll") for (int _i = 0; _i < 2; ++_i) \
;         __builtin_amdgcn_global_load_lds((const unsigned*)((const char*)(gbase) + (voff)[_i]), (LAS unsigned*)(lds + (bufoff) + ldsw + _i * 8192), 16, 0, 0); } while (0)
; #define PG8_LDA(dst, b, h) do { _Pragma("unroll") for (int m = 0; m < 4; ++m) _Pragma("unroll") for (int k = 0; k < 2; ++k) dst[m][k] = *(const LAS bf16x8*)(lds + PG8_SA(b, h) + aoff + m * 2048 + k * 1024); } while (0)
; #define PG8_LDB(dst, b, h) do { _Pragma("unroll") for (int n = 0; n < 2; ++n) _Pragma("unroll") for (int k = 0; k < 2; ++k) dst[n][k] = *(const LAS bf16x8*)(lds + PG8_SB(b, h) + boff + n * 2048 + k * 1024); } while (0)
; #define PG8_WAIT_V(n) asm volatile("s_waitcnt vmcnt(" #n ")" ::: "memory")
; #define PG8_WAIT_L(n) asm volatile("s_waitcnt lgkmcnt(" #n ")" ::: "memory")
; #define PG8_BAR __builtin_amdgcn_s_barrier()
; #define PG8_SCHED __builtin_amdgcn_sched_barrier(0)
; template <class Epi, class Sched>
; DI void gemm_phase(LAS unsigned char* lds, const Gemm g, const Sched& S, const Epi& E) {
;     ...
;             PG8_LDB(B0, 0, 0); PG8_SCHED; PG8_LDA(At, 0, 0); PG8_STAGE(PG8_SA(1, 1), a1 + hstep, voffA);
;             PG8_WAIT_L(8); PG8_BAR; PG8_WAIT_L(0); PG8_MMA(0, 0, At, B0); PG8_BAR; PG8_SCHED;
;             PG8_LDB(B1, 0, 1); PG8_STAGE(PG8_SB(0, 0), b2, voffB);
;             PG8_BAR; PG8_WAIT_L(0); PG8_MMA(0, 1, At, B1); PG8_BAR;
;             PG8_LDA(At, 0, 1); PG8_STAGE(PG8_SA(0, 0), a2, voffA);
;             PG8_BAR; PG8_WAIT_L(0); PG8_MMA(1, 0, At, B0); PG8_BAR; PG8_SCHED;
;             PG8_STAGE(PG8_SB(0, 1), b2 + hstep, voffB);
;             PG8_WAIT_V(6); PG8_BAR; PG8_MMA(1, 1, At, B1); PG8_BAR;
;             PG8_LDB(B0, 1, 0); PG8_SCHED; PG8_LDA(At, 1, 0); PG8_STAGE(PG8_SA(0, 1), a2 + hstep, voffA);
;             PG8_WAIT_L(8); PG8_BAR; PG8_WAIT_L(0); PG8_MMA(0, 0, At, B0); PG8_BAR; PG8_SCHED;
;             PG8_LDB(B1, 1, 1); PG8_STAGE(PG8_SB(1, 0), b3, voffB);
;             PG8_BAR; PG8_WAIT_L(0); PG8_MMA(0, 1, At, B1); PG8_BAR;
;             PG8_LDA(At, 1, 1); PG8_STAGE(PG8_SA(1, 0), a3, voffA);
;             PG8_BAR; PG8_WAIT_L(0); PG8_MMA(1, 0, At, B0); PG8_BAR; PG8_SCHED;
;             PG8_STAGE(PG8_SB(1, 1), b3 + hstep, voffB);
;             PG8_WAIT_V(6); PG8_BAR; PG8_MMA(1, 1, At, B1); PG8_BAR;
	s_waitcnt lgkmcnt(0)
	s_setprio 1
	v_mfma_f32_16x16x32_bf16 v[60:63], v[146:149], v[166:169], v[60:63]
	v_mfma_f32_16x16x32_bf16 v[56:59], v[158:161], v[166:169], v[56:59]
	v_mfma_f32_16x16x32_bf16 v[52:55], v[146:149], v[174:177], v[52:55]
	v_mfma_f32_16x16x32_bf16 v[48:51], v[158:161], v[174:177], v[48:51]
	v_mfma_f32_16x16x32_bf16 v[40:43], v[146:149], v[188:191], v[40:43]
	v_mfma_f32_16x16x32_bf16 v[32:35], v[158:161], v[188:191], v[32:35]
	v_mfma_f32_16x16x32_bf16 v[24:27], v[146:149], v[210:213], v[24:27]
	v_mfma_f32_16x16x32_bf16 v[16:19], v[158:161], v[210:213], v[16:19]
	v_mfma_f32_16x16x32_bf16 v[60:63], v[154:157], v[170:173], v[60:63]
	v_mfma_f32_16x16x32_bf16 v[56:59], v[162:165], v[170:173], v[56:59]
	v_mfma_f32_16x16x32_bf16 v[52:55], v[154:157], v[178:181], v[52:55]
	v_mfma_f32_16x16x32_bf16 v[48:51], v[162:165], v[178:181], v[48:51]
	v_mfma_f32_16x16x32_bf16 v[40:43], v[154:157], v[206:209], v[40:43]
	v_mfma_f32_16x16x32_bf16 v[32:35], v[162:165], v[206:209], v[32:35]
	v_mfma_f32_16x16x32_bf16 v[24:27], v[154:157], v[214:217], v[24:27]
	v_mfma_f32_16x16x32_bf16 v[16:19], v[162:165], v[214:217], v[16:19]
	s_setprio 0
	s_barrier
	s_add_i32 s4, s4, s35
	s_mov_b32 m0, s4
	s_add_u32 s0, s30, 0x160080
	s_addc_u32 s1, s31, 0
	global_load_lds_dwordx4 v130, s[0:1]
	s_add_i32 m0, s4, 0x2000
	s_nop 0
	global_load_lds_dwordx4 v128, s[0:1]
	s_add_i32 s66, s66, 2
	s_add_u32 s8, s8, 0x100
	s_addc_u32 s9, s9, 0
	s_add_u32 s64, s64, 0x100
	s_addc_u32 s65, s65, 0
	s_cmp_gt_u32 s66, 5
	s_waitcnt vmcnt(6)
	s_barrier
	s_setprio 1
	v_mfma_f32_16x16x32_bf16 v[44:47], v[218:221], v[166:169], v[44:47]
	v_mfma_f32_16x16x32_bf16 v[36:39], v[226:229], v[166:169], v[36:39]
	v_mfma_f32_16x16x32_bf16 v[28:31], v[218:221], v[174:177], v[28:31]
	v_mfma_f32_16x16x32_bf16 v[20:23], v[226:229], v[174:177], v[20:23]
	v_mfma_f32_16x16x32_bf16 v[12:15], v[218:221], v[188:191], v[12:15]
	v_mfma_f32_16x16x32_bf16 v[8:11], v[226:229], v[188:191], v[8:11]
	v_mfma_f32_16x16x32_bf16 v[4:7], v[218:221], v[210:213], v[4:7]
	v_mfma_f32_16x16x32_bf16 v[0:3], v[226:229], v[210:213], v[0:3]
	v_mfma_f32_16x16x32_bf16 v[44:47], v[222:225], v[170:173], v[44:47]
	v_mfma_f32_16x16x32_bf16 v[36:39], v[230:233], v[170:173], v[36:39]
	v_mfma_f32_16x16x32_bf16 v[28:31], v[222:225], v[178:181], v[28:31]
	v_mfma_f32_16x16x32_bf16 v[20:23], v[230:233], v[178:181], v[20:23]
	v_mfma_f32_16x16x32_bf16 v[12:15], v[222:225], v[206:209], v[12:15]
	v_mfma_f32_16x16x32_bf16 v[8:11], v[230:233], v[206:209], v[8:11]
	v_mfma_f32_16x16x32_bf16 v[4:7], v[222:225], v[214:217], v[4:7]
	v_mfma_f32_16x16x32_bf16 v[0:3], v[230:233], v[214:217], v[0:3]
	s_setprio 0
	s_barrier
	s_cbranch_scc0 .LBB0_1775
	s_branch .Lpeel_done_1775
.LBB0_1775:
	ds_read_b128 v[146:149], v141
	ds_read_b128 v[154:157], v141 offset:1024
	ds_read_b128 v[158:161], v141 offset:2048
	ds_read_b128 v[162:165], v141 offset:3072
	s_mov_b32 m0, s56
	ds_read_b128 v[166:169], v142
	ds_read_b128 v[170:173], v142 offset:1024
	ds_read_b128 v[174:177], v142 offset:2048
	ds_read_b128 v[178:181], v142 offset:3072
	ds_read_b128 v[188:191], v142 offset:4096
	ds_read_b128 v[206:209], v142 offset:5120
	ds_read_b128 v[210:213], v142 offset:6144
	global_load_lds_dwordx4 v132, s[8:9]
	s_mov_b32 m0, s57
	ds_read_b128 v[214:217], v142 offset:7168
	global_load_lds_dwordx4 v134, s[8:9]
	s_add_u32 s0, s8, 0xffea0080
	s_addc_u32 s1, s9, -1
	s_cmp_eq_u32 s66, 4
	s_cselect_b32 s37, s15, s1
	s_cselect_b32 s36, s17, s0
	s_cselect_b32 s31, s19, s65
	s_cselect_b32 s30, s18, s64
	s_waitcnt lgkmcnt(8)
	s_barrier
	s_waitcnt lgkmcnt(0)
	s_setprio 1
	v_mfma_f32_16x16x32_bf16 v[124:127], v[146:149], v[166:169], v[124:127]
	v_mfma_f32_16x16x32_bf16 v[120:123], v[158:161], v[166:169], v[120:123]
	v_mfma_f32_16x16x32_bf16 v[116:119], v[146:149], v[174:177], v[116:119]
	v_mfma_f32_16x16x32_bf16 v[112:115], v[158:161], v[174:177], v[112:115]
	v_mfma_f32_16x16x32_bf16 v[104:107], v[146:149], v[188:191], v[104:107]
	v_mfma_f32_16x16x32_bf16 v[96:99], v[158:161], v[188:191], v[96:99]
	v_mfma_f32_16x16x32_bf16 v[88:91], v[146:149], v[210:213], v[88:91]
	v_mfma_f32_16x16x32_bf16 v[80:83], v[158:161], v[210:213], v[80:83]
	v_mfma_f32_16x16x32_bf16 v[124:127], v[154:157], v[170:173], v[124:127]
	v_mfma_f32_16x16x32_bf16 v[120:123], v[162:165], v[170:173], v[120:123]
	v_mfma_f32_16x16x32_bf16 v[116:119], v[154:157], v[178:181], v[116:119]
	v_mfma_f32_16x16x32_bf16 v[112:115], v[162:165], v[178:181], v[112:115]
	v_mfma_f32_16x16x32_bf16 v[104:107], v[154:157], v[206:209], v[104:107]
	v_mfma_f32_16x16x32_bf16 v[96:99], v[162:165], v[206:209], v[96:99]
	v_mfma_f32_16x16x32_bf16 v[88:91], v[154:157], v[214:217], v[88:91]
	v_mfma_f32_16x16x32_bf16 v[80:83], v[162:165], v[214:217], v[80:83]
	s_setprio 0
	s_barrier
	s_mov_b32 m0, s58
	ds_read_b128 v[218:221], v143
	ds_read_b128 v[222:225], v143 offset:1024
	ds_read_b128 v[226:229], v143 offset:2048
	global_load_lds_dwordx4 v130, s[30:31]
	s_mov_b32 m0, s59
	ds_read_b128 v[230:233], v143 offset:3072
	global_load_lds_dwordx4 v128, s[30:31]
	s_barrier
; #define PG8_STAGE(bufoff, gbase, voff) do { _Pragma("unroll") for (int _i = 0; _i < 2; ++_i) \
;         __builtin_amdgcn_global_load_lds((const unsigned*)((const char*)(gbase) + (voff)[_i]), (LAS unsigned*)(lds + (bufoff) + ldsw + _i * 8192), 16, 0, 0); } while (0)
; #define PG8_LDA(dst, b, h) do { _Pragma("unroll") for (int m = 0; m < 4; ++m) _Pragma("unroll") for (int k = 0; k < 2; ++k) dst[m][k] = *(const LAS bf16x8*)(lds + PG8_SA(b, h) + aoff + m * 2048 + k * 1024); } while (0)
; #define PG8_LDB(dst, b, h) do { _Pragma("unroll") for (int n = 0; n < 2; ++n) _Pragma("unroll") for (int k = 0; k < 2; ++k) dst[n][k] = *(const LAS bf16x8*)(lds + PG8_SB(b, h) + boff + n * 2048 + k * 1024); } while (0)
; #define PG8_MMA(ai, bj, At, Bt) do { __builtin_amdgcn_s_setprio(1); _Pragma("unroll") for (int m = 0; m < 4; ++m) _Pragma("unroll") for (int n = 0; n < 2; ++n) _Pragma("unroll") for (int k = 0; k < 2; ++k) \
;         acc[ai][bj][m][n] = __builtin_amdgcn_mfma_f32_16x16x32_bf16(Bt[n][k], At[m][k], acc[ai][bj][m][n], 0, 0, 0); __builtin_amdgcn_s_setprio(0); } while (0)
; #define PG8_WAIT_V(n) asm volatile("s_waitcnt vmcnt(" #n ")" ::: "memory")
; #define PG8_WAIT_L(n) asm volatile("s_waitcnt lgkmcnt(" #n ")" ::: "memory")
; #define PG8_BAR __builtin_amdgcn_s_barrier()
; #define PG8_SCHED __builtin_amdgcn_sched_barrier(0)
; template <class Epi, class Sched>
; DI void gemm_phase(LAS unsigned char* lds, const Gemm g, const Sched& S, const Epi& E) {
;     ...
;             PG8_BAR; PG8_WAIT_L(0); PG8_MMA(0, 1, At, B1); PG8_BAR;
;             PG8_LDA(At, 0, 1); PG8_STAGE(PG8_SA(0, 0), a2, voffA);
;             PG8_BAR; PG8_WAIT_L(0); PG8_MMA(1, 0, At, B0); PG8_BAR; PG8_SCHED;
;             PG8_STAGE(PG8_SB(0, 1), b2 + hstep, voffB);
;             PG8_WAIT_V(6); PG8_BAR; PG8_MMA(1, 1, At, B1); PG8_BAR;
;             PG8_LDB(B0, 1, 0); PG8_SCHED; PG8_LDA(At, 1, 0); PG8_STAGE(PG8_SA(0, 1), a2 + hstep, voffA);
	s_waitcnt lgkmcnt(0)
	s_setprio 1
	v_mfma_f32_16x16x32_bf16 v[108:111], v[218:221], v[166:169], v[108:111]
	v_mfma_f32_16x16x32_bf16 v[100:103], v[226:229], v[166:169], v[100:103]
	v_mfma_f32_16x16x32_bf16 v[92:95], v[218:221], v[174:177], v[92:95]
	v_mfma_f32_16x16x32_bf16 v[84:87], v[226:229], v[174:177], v[84:87]
	v_mfma_f32_16x16x32_bf16 v[76:79], v[218:221], v[188:191], v[76:79]
	v_mfma_f32_16x16x32_bf16 v[72:75], v[226:229], v[188:191], v[72:75]
	v_mfma_f32_16x16x32_bf16 v[68:71], v[218:221], v[210:213], v[68:71]
	v_mfma_f32_16x16x32_bf16 v[64:67], v[226:229], v[210:213], v[64:67]
	v_mfma_f32_16x16x32_bf16 v[108:111], v[222:225], v[170:173], v[108:111]
	v_mfma_f32_16x16x32_bf16 v[100:103], v[230:233], v[170:173], v[100:103]
	v_mfma_f32_16x16x32_bf16 v[92:95], v[222:225], v[178:181], v[92:95]
	v_mfma_f32_16x16x32_bf16 v[84:87], v[230:233], v[178:181], v[84:87]
	v_mfma_f32_16x16x32_bf16 v[76:79], v[222:225], v[206:209], v[76:79]
	v_mfma_f32_16x16x32_bf16 v[72:75], v[230:233], v[206:209], v[72:75]
	v_mfma_f32_16x16x32_bf16 v[68:71], v[222:225], v[214:217], v[68:71]
	v_mfma_f32_16x16x32_bf16 v[64:67], v[230:233], v[214:217], v[64:67]
	s_setprio 0
	s_mov_b32 m0, s40
	s_barrier
	ds_read_b128 v[166:169], v142 offset:16384
	ds_read_b128 v[170:173], v142 offset:17408
	ds_read_b128 v[174:177], v142 offset:18432
	ds_read_b128 v[178:181], v142 offset:19456
	ds_read_b128 v[188:191], v142 offset:20480
	ds_read_b128 v[206:209], v142 offset:21504
	ds_read_b128 v[210:213], v142 offset:22528
	global_load_lds_dwordx4 v130, s[36:37]
	s_mov_b32 m0, s41
	ds_read_b128 v[214:217], v142 offset:23552
	global_load_lds_dwordx4 v128, s[36:37]
	s_barrier
	s_waitcnt lgkmcnt(0)
	s_setprio 1
	v_mfma_f32_16x16x32_bf16 v[60:63], v[146:149], v[166:169], v[60:63]
	v_mfma_f32_16x16x32_bf16 v[56:59], v[158:161], v[166:169], v[56:59]
	v_mfma_f32_16x16x32_bf16 v[52:55], v[146:149], v[174:177], v[52:55]
	v_mfma_f32_16x16x32_bf16 v[48:51], v[158:161], v[174:177], v[48:51]
	v_mfma_f32_16x16x32_bf16 v[40:43], v[146:149], v[188:191], v[40:43]
	v_mfma_f32_16x16x32_bf16 v[32:35], v[158:161], v[188:191], v[32:35]
	v_mfma_f32_16x16x32_bf16 v[24:27], v[146:149], v[210:213], v[24:27]
	v_mfma_f32_16x16x32_bf16 v[16:19], v[158:161], v[210:213], v[16:19]
	v_mfma_f32_16x16x32_bf16 v[60:63], v[154:157], v[170:173], v[60:63]
	v_mfma_f32_16x16x32_bf16 v[56:59], v[162:165], v[170:173], v[56:59]
	v_mfma_f32_16x16x32_bf16 v[52:55], v[154:157], v[178:181], v[52:55]
	v_mfma_f32_16x16x32_bf16 v[48:51], v[162:165], v[178:181], v[48:51]
	v_mfma_f32_16x16x32_bf16 v[40:43], v[154:157], v[206:209], v[40:43]
	v_mfma_f32_16x16x32_bf16 v[32:35], v[162:165], v[206:209], v[32:35]
	v_mfma_f32_16x16x32_bf16 v[24:27], v[154:157], v[214:217], v[24:27]
	v_mfma_f32_16x16x32_bf16 v[16:19], v[162:165], v[214:217], v[16:19]
	s_setprio 0
	s_barrier
	s_add_u32 s0, s30, 0x160000
	s_addc_u32 s1, s31, 0
	s_mov_b32 m0, s60
	s_nop 0
	global_load_lds_dwordx4 v130, s[0:1]
	s_mov_b32 m0, s61
	s_nop 0
	global_load_lds_dwordx4 v128, s[0:1]
	s_waitcnt vmcnt(6)
	s_barrier
	s_setprio 1
	v_mfma_f32_16x16x32_bf16 v[44:47], v[218:221], v[166:169], v[44:47]
	v_mfma_f32_16x16x32_bf16 v[36:39], v[226:229], v[166:169], v[36:39]
	v_mfma_f32_16x16x32_bf16 v[28:31], v[218:221], v[174:177], v[28:31]
	v_mfma_f32_16x16x32_bf16 v[20:23], v[226:229], v[174:177], v[20:23]
	v_mfma_f32_16x16x32_bf16 v[12:15], v[218:221], v[188:191], v[12:15]
	v_mfma_f32_16x16x32_bf16 v[8:11], v[226:229], v[188:191], v[8:11]
	v_mfma_f32_16x16x32_bf16 v[4:7], v[218:221], v[210:213], v[4:7]
	v_mfma_f32_16x16x32_bf16 v[0:3], v[226:229], v[210:213], v[0:3]
	v_mfma_f32_16x16x32_bf16 v[44:47], v[222:225], v[170:173], v[44:47]
	v_mfma_f32_16x16x32_bf16 v[36:39], v[230:233], v[170:173], v[36:39]
	v_mfma_f32_16x16x32_bf16 v[28:31], v[222:225], v[178:181], v[28:31]
	v_mfma_f32_16x16x32_bf16 v[20:23], v[230:233], v[178:181], v[20:23]
	v_mfma_f32_16x16x32_bf16 v[12:15], v[222:225], v[206:209], v[12:15]
	v_mfma_f32_16x16x32_bf16 v[8:11], v[230:233], v[206:209], v[8:11]
	v_mfma_f32_16x16x32_bf16 v[4:7], v[222:225], v[214:217], v[4:7]
	v_mfma_f32_16x16x32_bf16 v[0:3], v[230:233], v[214:217], v[0:3]
	s_setprio 0
	s_barrier
	ds_read_b128 v[146:149], v144
	ds_read_b128 v[154:157], v144 offset:1024
	ds_read_b128 v[158:161], v144 offset:2048
	ds_read_b128 v[162:165], v144 offset:3072
	s_add_u32 s0, s36, 0x160000
	s_addc_u32 s1, s37, 0
	s_mov_b32 m0, s42
	ds_read_b128 v[166:169], v142 offset:32768
	ds_read_b128 v[170:173], v142 offset:33792
	ds_read_b128 v[174:177], v142 offset:34816
	ds_read_b128 v[178:181], v142 offset:35840
	ds_read_b128 v[188:191], v142 offset:36864
	ds_read_b128 v[206:209], v142 offset:37888
	ds_read_b128 v[210:213], v142 offset:38912
	global_load_lds_dwordx4 v130, s[0:1]
	s_mov_b32 m0, s43
	ds_read_b128 v[214:217], v142 offset:39936
	global_load_lds_dwordx4 v128, s[0:1]
	s_waitcnt lgkmcnt(8)
	s_barrier
; #define PG8_STAGE(bufoff, gbase, voff) do { _Pragma("unroll") for (int _i = 0; _i < 2; ++_i) \
;         __builtin_amdgcn_global_load_lds((const unsigned*)((const char*)(gbase) + (voff)[_i]), (LAS unsigned*)(lds + (bufoff) + ldsw + _i * 8192), 16, 0, 0); } while (0)
; #define PG8_LDA(dst, b, h) do { _Pragma("unroll") for (int m = 0; m < 4; ++m) _Pragma("unroll") for (int k = 0; k < 2; ++k) dst[m][k] = *(const LAS bf16x8*)(lds + PG8_SA(b, h) + aoff + m * 2048 + k * 1024); } while (0)
; #define PG8_LDB(dst, b, h) do { _Pragma("unroll") for (int n = 0; n < 2; ++n) _Pragma("unroll") for (int k = 0; k < 2; ++k) dst[n][k] = *(const LAS bf16x8*)(lds + PG8_SB(b, h) + boff + n * 2048 + k * 1024); } while (0)
; #define PG8_MMA(ai, bj, At, Bt) do { __builtin_amdgcn_s_setprio(1); _Pragma("unroll") for (int m = 0; m < 4; ++m) _Pragma("unroll") for (int n = 0; n < 2; ++n) _Pragma("unroll") for (int k = 0; k < 2; ++k) \
;         acc[ai][bj][m][n] = __builtin_amdgcn_mfma_f32_16x16x32_bf16(Bt[n][k], At[m][k], acc[ai][bj][m][n], 0, 0, 0); __builtin_amdgcn_s_setprio(0); } while (0)
; #define PG8_WAIT_V(n) asm volatile("s_waitcnt vmcnt(" #n ")" ::: "memory")
; #define PG8_WAIT_L(n) asm volatile("s_waitcnt lgkmcnt(" #n ")" ::: "memory")
; #define PG8_BAR __builtin_amdgcn_s_barrier()
; #define PG8_SCHED __builtin_amdgcn_sched_barrier(0)
; template <class Epi, class Sched>
; DI void gemm_phase(LAS unsigned char* lds, const Gemm g, const Sched& S, const Epi& E) {
;     ...
;             PG8_WAIT_L(8); PG8_BAR; PG8_WAIT_L(0); PG8_MMA(0, 0, At, B0); PG8_BAR; PG8_SCHED;
;             PG8_LDB(B1, 1, 1); PG8_STAGE(PG8_SB(1, 0), b3, voffB);
;             PG8_BAR; PG8_WAIT_L(0); PG8_MMA(0, 1, At, B1); PG8_BAR;
;             PG8_LDA(At, 1, 1); PG8_STAGE(PG8_SA(1, 0), a3, voffA);
;             PG8_BAR; PG8_WAIT_L(0); PG8_MMA(1, 0, At, B0); PG8_BAR; PG8_SCHED;
;             PG8_STAGE(PG8_SB(1, 1), b3 + hstep, voffB);
;             PG8_WAIT_V(6); PG8_BAR; PG8_MMA(1, 1, At, B1); PG8_BAR;
	s_waitcnt lgkmcnt(0)
	s_setprio 1
	v_mfma_f32_16x16x32_bf16 v[124:127], v[146:149], v[166:169], v[124:127]
	v_mfma_f32_16x16x32_bf16 v[120:123], v[158:161], v[166:169], v[120:123]
	v_mfma_f32_16x16x32_bf16 v[116:119], v[146:149], v[174:177], v[116:119]
	v_mfma_f32_16x16x32_bf16 v[112:115], v[158:161], v[174:177], v[112:115]
	v_mfma_f32_16x16x32_bf16 v[104:107], v[146:149], v[188:191], v[104:107]
	v_mfma_f32_16x16x32_bf16 v[96:99], v[158:161], v[188:191], v[96:99]
	v_mfma_f32_16x16x32_bf16 v[88:91], v[146:149], v[210:213], v[88:91]
	v_mfma_f32_16x16x32_bf16 v[80:83], v[158:161], v[210:213], v[80:83]
	v_mfma_f32_16x16x32_bf16 v[124:127], v[154:157], v[170:173], v[124:127]
	v_mfma_f32_16x16x32_bf16 v[120:123], v[162:165], v[170:173], v[120:123]
	v_mfma_f32_16x16x32_bf16 v[116:119], v[154:157], v[178:181], v[116:119]
	v_mfma_f32_16x16x32_bf16 v[112:115], v[162:165], v[178:181], v[112:115]
	v_mfma_f32_16x16x32_bf16 v[104:107], v[154:157], v[206:209], v[104:107]
	v_mfma_f32_16x16x32_bf16 v[96:99], v[162:165], v[206:209], v[96:99]
	v_mfma_f32_16x16x32_bf16 v[88:91], v[154:157], v[214:217], v[88:91]
	v_mfma_f32_16x16x32_bf16 v[80:83], v[162:165], v[214:217], v[80:83]
	s_setprio 0
	s_barrier
	s_add_i32 s4, 0, 0x1c000
	s_add_i32 s0, s62, s35
	v_add_u32_e32 v145, s4, v140
	s_add_i32 m0, s0, 0xffffff80
	ds_read_b128 v[218:221], v145
	ds_read_b128 v[222:225], v145 offset:1024
	ds_read_b128 v[226:229], v145 offset:2048
	global_load_lds_dwordx4 v130, s[30:31] offset:128
	s_add_i32 m0, s0, 0x1f80
	ds_read_b128 v[230:233], v145 offset:3072
	global_load_lds_dwordx4 v128, s[30:31] offset:128
	s_barrier
	s_waitcnt lgkmcnt(0)
	s_setprio 1
	v_mfma_f32_16x16x32_bf16 v[108:111], v[218:221], v[166:169], v[108:111]
	v_mfma_f32_16x16x32_bf16 v[100:103], v[226:229], v[166:169], v[100:103]
	v_mfma_f32_16x16x32_bf16 v[92:95], v[218:221], v[174:177], v[92:95]
	v_mfma_f32_16x16x32_bf16 v[84:87], v[226:229], v[174:177], v[84:87]
	v_mfma_f32_16x16x32_bf16 v[76:79], v[218:221], v[188:191], v[76:79]
	v_mfma_f32_16x16x32_bf16 v[72:75], v[226:229], v[188:191], v[72:75]
	v_mfma_f32_16x16x32_bf16 v[68:71], v[218:221], v[210:213], v[68:71]
	v_mfma_f32_16x16x32_bf16 v[64:67], v[226:229], v[210:213], v[64:67]
	v_mfma_f32_16x16x32_bf16 v[108:111], v[222:225], v[170:173], v[108:111]
	v_mfma_f32_16x16x32_bf16 v[100:103], v[230:233], v[170:173], v[100:103]
	v_mfma_f32_16x16x32_bf16 v[92:95], v[222:225], v[178:181], v[92:95]
	v_mfma_f32_16x16x32_bf16 v[84:87], v[230:233], v[178:181], v[84:87]
	v_mfma_f32_16x16x32_bf16 v[76:79], v[222:225], v[206:209], v[76:79]
	v_mfma_f32_16x16x32_bf16 v[72:75], v[230:233], v[206:209], v[72:75]
	v_mfma_f32_16x16x32_bf16 v[68:71], v[222:225], v[214:217], v[68:71]
	v_mfma_f32_16x16x32_bf16 v[64:67], v[230:233], v[214:217], v[64:67]
	s_setprio 0
	s_add_i32 m0, s54, 0xffffff80
	s_barrier
	ds_read_b128 v[166:169], v142 offset:49152
	ds_read_b128 v[170:173], v142 offset:50176
	ds_read_b128 v[174:177], v142 offset:51200
	ds_read_b128 v[178:181], v142 offset:52224
	ds_read_b128 v[188:191], v142 offset:53248
	ds_read_b128 v[206:209], v142 offset:54272
	ds_read_b128 v[210:213], v142 offset:55296
	global_load_lds_dwordx4 v130, s[36:37] offset:128
	s_add_i32 m0, s55, 0xffffff80
	ds_read_b128 v[214:217], v142 offset:56320
	global_load_lds_dwordx4 v128, s[36:37] offset:128
	s_barrier
	s_waitcnt lgkmcnt(0)
	s_setprio 1
	v_mfma_f32_16x16x32_bf16 v[60:63], v[146:149], v[166:169], v[60:63]
	v_mfma_f32_16x16x32_bf16 v[56:59], v[158:161], v[166:169], v[56:59]
	v_mfma_f32_16x16x32_bf16 v[52:55], v[146:149], v[174:177], v[52:55]
	v_mfma_f32_16x16x32_bf16 v[48:51], v[158:161], v[174:177], v[48:51]
	v_mfma_f32_16x16x32_bf16 v[40:43], v[146:149], v[188:191], v[40:43]
	v_mfma_f32_16x16x32_bf16 v[32:35], v[158:161], v[188:191], v[32:35]
	v_mfma_f32_16x16x32_bf16 v[24:27], v[146:149], v[210:213], v[24:27]
	v_mfma_f32_16x16x32_bf16 v[16:19], v[158:161], v[210:213], v[16:19]
	v_mfma_f32_16x16x32_bf16 v[60:63], v[154:157], v[170:173], v[60:63]
	v_mfma_f32_16x16x32_bf16 v[56:59], v[162:165], v[170:173], v[56:59]
	v_mfma_f32_16x16x32_bf16 v[52:55], v[154:157], v[178:181], v[52:55]
	v_mfma_f32_16x16x32_bf16 v[48:51], v[162:165], v[178:181], v[48:51]
	v_mfma_f32_16x16x32_bf16 v[40:43], v[154:157], v[206:209], v[40:43]
	v_mfma_f32_16x16x32_bf16 v[32:35], v[162:165], v[206:209], v[32:35]
	v_mfma_f32_16x16x32_bf16 v[24:27], v[154:157], v[214:217], v[24:27]
	v_mfma_f32_16x16x32_bf16 v[16:19], v[162:165], v[214:217], v[16:19]
	s_setprio 0
	s_barrier
	s_add_i32 s4, s4, s35
	s_mov_b32 m0, s4
	s_add_u32 s0, s30, 0x160080
	s_addc_u32 s1, s31, 0
	global_load_lds_dwordx4 v130, s[0:1]
	s_add_i32 m0, s4, 0x2000
	s_nop 0
	global_load_lds_dwordx4 v128, s[0:1]
	s_add_i32 s66, s66, 2
	s_add_u32 s8, s8, 0x100
	s_addc_u32 s9, s9, 0
	s_add_u32 s64, s64, 0x100
	s_addc_u32 s65, s65, 0
	s_cmp_gt_u32 s66, 5
	s_waitcnt vmcnt(6)
	s_barrier
	s_setprio 1
	v_mfma_f32_16x16x32_bf16 v[44:47], v[218:221], v[166:169], v[44:47]
	v_mfma_f32_16x16x32_bf16 v[36:39], v[226:229], v[166:169], v[36:39]
	v_mfma_f32_16x16x32_bf16 v[28:31], v[218:221], v[174:177], v[28:31]
	v_mfma_f32_16x16x32_bf16 v[20:23], v[226:229], v[174:177], v[20:23]
	v_mfma_f32_16x16x32_bf16 v[12:15], v[218:221], v[188:191], v[12:15]
	v_mfma_f32_16x16x32_bf16 v[8:11], v[226:229], v[188:191], v[8:11]
	v_mfma_f32_16x16x32_bf16 v[4:7], v[218:221], v[210:213], v[4:7]
	v_mfma_f32_16x16x32_bf16 v[0:3], v[226:229], v[210:213], v[0:3]
	v_mfma_f32_16x16x32_bf16 v[44:47], v[222:225], v[170:173], v[44:47]
	v_mfma_f32_16x16x32_bf16 v[36:39], v[230:233], v[170:173], v[36:39]
	v_mfma_f32_16x16x32_bf16 v[28:31], v[222:225], v[178:181], v[28:31]
	v_mfma_f32_16x16x32_bf16 v[20:23], v[230:233], v[178:181], v[20:23]
	v_mfma_f32_16x16x32_bf16 v[12:15], v[222:225], v[206:209], v[12:15]
	v_mfma_f32_16x16x32_bf16 v[8:11], v[230:233], v[206:209], v[8:11]
	v_mfma_f32_16x16x32_bf16 v[4:7], v[222:225], v[214:217], v[4:7]
	v_mfma_f32_16x16x32_bf16 v[0:3], v[230:233], v[214:217], v[0:3]
	s_setprio 0
	s_barrier
	s_cbranch_scc0 .LBB0_1775
